# GEMM mainloops: snake MFMA order within 8-groups so only one operand changes between consecutive MFMAs (power)
# baseline (speedup 1.0000x reference)
; #define PG8_STAGE(bufoff, gbase, voff) do { _Pragma("unroll") for (int _i = 0; _i < 2; ++_i) \
;         __builtin_amdgcn_global_load_lds((const unsigned*)((const char*)(gbase) + (voff)[_i]), (LAS unsigned*)(lds + (bufoff) + ldsw + _i * 8192), 16, 0, 0); } while (0)
; #define PG8_LDA(dst, b, h) do { _Pragma("unroll") for (int m = 0; m < 4; ++m) _Pragma("unroll") for (int k = 0; k < 2; ++k) dst[m][k] = *(const LAS bf16x8*)(lds + PG8_SA(b, h) + aoff + m * 2048 + k * 1024); } while (0)
; #define PG8_LDB(dst, b, h) do { _Pragma("unroll") for (int n = 0; n < 2; ++n) _Pragma("unroll") for (int k = 0; k < 2; ++k) dst[n][k] = *(const LAS bf16x8*)(lds + PG8_SB(b, h) + boff + n * 2048 + k * 1024); } while (0)
; #define PG8_MMA(ai, bj, At, Bt) do { __builtin_amdgcn_s_setprio(1); _Pragma("unroll") for (int m = 0; m < 4; ++m) _Pragma("unroll") for (int n = 0; n < 2; ++n) _Pragma("unroll") for (int k = 0; k < 2; ++k) \
;         acc[ai][bj][m][n] = __builtin_amdgcn_mfma_f32_16x16x32_bf16(Bt[n][k], At[m][k], acc[ai][bj][m][n], 0, 0, 0); __builtin_amdgcn_s_setprio(0); } while (0)
; #define PG8_WAIT_V(n) asm volatile("s_waitcnt vmcnt(" #n ")" ::: "memory")
; #define PG8_WAIT_L(n) asm volatile("s_waitcnt lgkmcnt(" #n ")" ::: "memory")
; #define PG8_BAR __builtin_amdgcn_s_barrier()
; #define PG8_SCHED __builtin_amdgcn_sched_barrier(0)
; template <class Epi, bool ALIGN_EPI = PG8_ALIGN>
; __device__ __forceinline__ void gemm_phase(LAS unsigned char* lds, const Gemm g, const StaticOrder S, const Epi E) {
;     ...
;             PG8_LDB(B0, 0, 0); PG8_LDB(B1, 0, 1); PG8_SCHED; PG8_LDA(At, 0, 0); PG8_STAGE(PG8_SA(1, 1), a1 + hstepA, voffA);
;             PG8_WAIT_V(8); PG8_WAIT_L(0); PG8_BAR; PG8_MMA(0, 0, At, B0); PG8_MMA(0, 1, At, B1); PG8_BAR; PG8_SCHED;
;             PG8_LDA(At, 0, 1); PG8_STAGE(PG8_SB(0, 0), b2, voffB); PG8_STAGE(PG8_SB(0, 1), b2 + hstepB, voffB); PG8_STAGE(PG8_SA(0, 0), a2, voffA);
;             PG8_WAIT_V(8); PG8_WAIT_L(0); PG8_BAR; PG8_MMA(1, 0, At, B0); PG8_MMA(1, 1, At, B1); PG8_BAR; PG8_SCHED;
.LBB0_335:
	ds_read_b128 v[150:153], v147
	ds_read_b128 v[154:157], v147 offset:1024
	ds_read_b128 v[158:161], v147 offset:2048
	ds_read_b128 v[162:165], v147 offset:3072
	ds_read_b128 v[166:169], v148
	ds_read_b128 v[170:173], v148 offset:1024
	ds_read_b128 v[174:177], v148 offset:2048
	ds_read_b128 v[178:181], v148 offset:3072
	s_add_u32 s58, s50, 0xfff80080
	s_addc_u32 s59, s51, -1
	s_cmp_eq_u32 s74, 28
	s_cselect_b32 s61, s14, s59
	s_cselect_b32 s60, s35, s58
	s_cselect_b32 s59, s11, s73
	s_cselect_b32 s58, s43, s72
	v_lshl_add_u64 v[182:183], s[50:51], 0, v[136:137]
	s_add_i32 m0, s65, 0xc000
	ds_read_b128 v[186:189], v149
	ds_read_b128 v[190:193], v149 offset:1024
	ds_read_b128 v[194:197], v149 offset:2048
	ds_read_b128 v[198:201], v149 offset:3072
	ds_read_b128 v[202:205], v149 offset:4096
	ds_read_b128 v[206:209], v149 offset:5120
	ds_read_b128 v[210:213], v149 offset:6144
	ds_read_b128 v[214:217], v149 offset:7168
	global_load_lds_dwordx4 v[182:183], off
	v_lshl_add_u64 v[182:183], s[50:51], 0, v[138:139]
	s_add_i32 m0, s65, 0xe000
	s_nop 0
	global_load_lds_dwordx4 v[182:183], off
	s_waitcnt vmcnt(8)
	s_waitcnt lgkmcnt(0)
	s_barrier
	s_setprio 1
	s_waitcnt lgkmcnt(0)
	v_mfma_f32_16x16x32_bf16 v[124:127], v[150:153], v[186:189], v[124:127]
	v_mfma_f32_16x16x32_bf16 v[116:119], v[158:161], v[186:189], v[116:119]
	v_mfma_f32_16x16x32_bf16 v[100:103], v[158:161], v[194:197], v[100:103]
	v_mfma_f32_16x16x32_bf16 v[108:111], v[150:153], v[194:197], v[108:111]
	v_mfma_f32_16x16x32_bf16 v[92:95], v[150:153], v[202:205], v[92:95]
	v_mfma_f32_16x16x32_bf16 v[84:87], v[158:161], v[202:205], v[84:87]
	v_mfma_f32_16x16x32_bf16 v[68:71], v[158:161], v[210:213], v[68:71]
	v_mfma_f32_16x16x32_bf16 v[76:79], v[150:153], v[210:213], v[76:79]
	v_mfma_f32_16x16x32_bf16 v[124:127], v[154:157], v[190:193], v[124:127]
	v_mfma_f32_16x16x32_bf16 v[116:119], v[162:165], v[190:193], v[116:119]
	v_mfma_f32_16x16x32_bf16 v[100:103], v[162:165], v[198:201], v[100:103]
	v_mfma_f32_16x16x32_bf16 v[108:111], v[154:157], v[198:201], v[108:111]
	v_mfma_f32_16x16x32_bf16 v[92:95], v[154:157], v[206:209], v[92:95]
	v_mfma_f32_16x16x32_bf16 v[84:87], v[162:165], v[206:209], v[84:87]
	v_mfma_f32_16x16x32_bf16 v[68:71], v[162:165], v[214:217], v[68:71]
	v_mfma_f32_16x16x32_bf16 v[76:79], v[154:157], v[214:217], v[76:79]
	s_setprio 0
	s_setprio 1
	v_mfma_f32_16x16x32_bf16 v[120:123], v[166:169], v[186:189], v[120:123]
	v_mfma_f32_16x16x32_bf16 v[112:115], v[174:177], v[186:189], v[112:115]
	v_mfma_f32_16x16x32_bf16 v[96:99], v[174:177], v[194:197], v[96:99]
	v_mfma_f32_16x16x32_bf16 v[104:107], v[166:169], v[194:197], v[104:107]
	v_mfma_f32_16x16x32_bf16 v[88:91], v[166:169], v[202:205], v[88:91]
	v_mfma_f32_16x16x32_bf16 v[80:83], v[174:177], v[202:205], v[80:83]
	v_mfma_f32_16x16x32_bf16 v[64:67], v[174:177], v[210:213], v[64:67]
	v_mfma_f32_16x16x32_bf16 v[72:75], v[166:169], v[210:213], v[72:75]
	v_mfma_f32_16x16x32_bf16 v[120:123], v[170:173], v[190:193], v[120:123]
	v_mfma_f32_16x16x32_bf16 v[112:115], v[178:181], v[190:193], v[112:115]
	v_mfma_f32_16x16x32_bf16 v[96:99], v[178:181], v[198:201], v[96:99]
	v_mfma_f32_16x16x32_bf16 v[104:107], v[170:173], v[198:201], v[104:107]
	v_mfma_f32_16x16x32_bf16 v[88:91], v[170:173], v[206:209], v[88:91]
	v_mfma_f32_16x16x32_bf16 v[80:83], v[178:181], v[206:209], v[80:83]
	v_mfma_f32_16x16x32_bf16 v[64:67], v[178:181], v[214:217], v[64:67]
	v_mfma_f32_16x16x32_bf16 v[72:75], v[170:173], v[214:217], v[72:75]
	s_setprio 0
	s_barrier
	s_add_i32 s75, s17, s62
	v_lshl_add_u64 v[182:183], s[58:59], 0, v[132:133]
	s_mov_b32 m0, s75
	ds_read_b128 v[186:189], v149 offset:16384
	ds_read_b128 v[190:193], v149 offset:17408
	ds_read_b128 v[194:197], v149 offset:18432
	ds_read_b128 v[198:201], v149 offset:19456
	ds_read_b128 v[202:205], v149 offset:20480
	ds_read_b128 v[206:209], v149 offset:21504
	ds_read_b128 v[210:213], v149 offset:22528
	ds_read_b128 v[214:217], v149 offset:23552
	global_load_lds_dwordx4 v[182:183], off
	s_add_i32 m0, s75, 0x2000
	s_add_u32 s76, s58, 0x80000
	v_lshl_add_u64 v[218:219], s[58:59], 0, v[128:129]
	s_addc_u32 s77, s59, 0
	s_add_i32 s75, s33, s62
	global_load_lds_dwordx4 v[218:219], off
	v_lshl_add_u64 v[220:221], s[76:77], 0, v[132:133]
	s_mov_b32 m0, s75
	v_lshl_add_u64 v[222:223], s[60:61], 0, v[130:131]
	global_load_lds_dwordx4 v[220:221], off
	v_lshl_add_u64 v[220:221], s[76:77], 0, v[128:129]
	s_add_i32 m0, s75, 0x2000
	s_nop 0
	global_load_lds_dwordx4 v[220:221], off
	v_lshl_add_u64 v[220:221], s[60:61], 0, v[134:135]
	s_mov_b32 m0, s65
	s_nop 0
	global_load_lds_dwordx4 v[220:221], off
	s_mov_b32 m0, s66
	s_nop 0
	global_load_lds_dwordx4 v[222:223], off
	s_waitcnt vmcnt(8)
	s_waitcnt lgkmcnt(0)
	s_barrier
; #define PG8_STAGE(bufoff, gbase, voff) do { _Pragma("unroll") for (int _i = 0; _i < 2; ++_i) \
;         __builtin_amdgcn_global_load_lds((const unsigned*)((const char*)(gbase) + (voff)[_i]), (LAS unsigned*)(lds + (bufoff) + ldsw + _i * 8192), 16, 0, 0); } while (0)
; #define PG8_LDA(dst, b, h) do { _Pragma("unroll") for (int m = 0; m < 4; ++m) _Pragma("unroll") for (int k = 0; k < 2; ++k) dst[m][k] = *(const LAS bf16x8*)(lds + PG8_SA(b, h) + aoff + m * 2048 + k * 1024); } while (0)
; #define PG8_LDB(dst, b, h) do { _Pragma("unroll") for (int n = 0; n < 2; ++n) _Pragma("unroll") for (int k = 0; k < 2; ++k) dst[n][k] = *(const LAS bf16x8*)(lds + PG8_SB(b, h) + boff + n * 2048 + k * 1024); } while (0)
; #define PG8_MMA(ai, bj, At, Bt) do { __builtin_amdgcn_s_setprio(1); _Pragma("unroll") for (int m = 0; m < 4; ++m) _Pragma("unroll") for (int n = 0; n < 2; ++n) _Pragma("unroll") for (int k = 0; k < 2; ++k) \
;         acc[ai][bj][m][n] = __builtin_amdgcn_mfma_f32_16x16x32_bf16(Bt[n][k], At[m][k], acc[ai][bj][m][n], 0, 0, 0); __builtin_amdgcn_s_setprio(0); } while (0)
; #define PG8_WAIT_V(n) asm volatile("s_waitcnt vmcnt(" #n ")" ::: "memory")
; #define PG8_WAIT_L(n) asm volatile("s_waitcnt lgkmcnt(" #n ")" ::: "memory")
; #define PG8_BAR __builtin_amdgcn_s_barrier()
; #define PG8_SCHED __builtin_amdgcn_sched_barrier(0)
; template <class Epi, bool ALIGN_EPI = PG8_ALIGN>
; __device__ __forceinline__ void gemm_phase(LAS unsigned char* lds, const Gemm g, const StaticOrder S, const Epi E) {
;     ...
;             PG8_WAIT_V(8); PG8_WAIT_L(0); PG8_BAR; PG8_MMA(1, 0, At, B0); PG8_MMA(1, 1, At, B1); PG8_BAR; PG8_SCHED;
;             PG8_LDB(B0, 1, 0); PG8_LDB(B1, 1, 1); PG8_SCHED; PG8_LDA(At, 1, 0); PG8_STAGE(PG8_SA(0, 1), a2 + hstepA, voffA);
;             PG8_WAIT_V(8); PG8_WAIT_L(0); PG8_BAR; PG8_MMA(0, 0, At, B0); PG8_MMA(0, 1, At, B1); PG8_BAR; PG8_SCHED;
	s_setprio 1
	s_waitcnt lgkmcnt(0)
	v_mfma_f32_16x16x32_bf16 v[60:63], v[150:153], v[186:189], v[60:63]
	v_mfma_f32_16x16x32_bf16 v[52:55], v[158:161], v[186:189], v[52:55]
	v_mfma_f32_16x16x32_bf16 v[36:39], v[158:161], v[194:197], v[36:39]
	v_mfma_f32_16x16x32_bf16 v[44:47], v[150:153], v[194:197], v[44:47]
	v_mfma_f32_16x16x32_bf16 v[28:31], v[150:153], v[202:205], v[28:31]
	v_mfma_f32_16x16x32_bf16 v[20:23], v[158:161], v[202:205], v[20:23]
	v_mfma_f32_16x16x32_bf16 v[4:7], v[158:161], v[210:213], v[4:7]
	v_mfma_f32_16x16x32_bf16 v[12:15], v[150:153], v[210:213], v[12:15]
	v_mfma_f32_16x16x32_bf16 v[60:63], v[154:157], v[190:193], v[60:63]
	v_mfma_f32_16x16x32_bf16 v[52:55], v[162:165], v[190:193], v[52:55]
	v_mfma_f32_16x16x32_bf16 v[36:39], v[162:165], v[198:201], v[36:39]
	v_mfma_f32_16x16x32_bf16 v[44:47], v[154:157], v[198:201], v[44:47]
	v_mfma_f32_16x16x32_bf16 v[28:31], v[154:157], v[206:209], v[28:31]
	v_mfma_f32_16x16x32_bf16 v[20:23], v[162:165], v[206:209], v[20:23]
	v_mfma_f32_16x16x32_bf16 v[4:7], v[162:165], v[214:217], v[4:7]
	v_mfma_f32_16x16x32_bf16 v[12:15], v[154:157], v[214:217], v[12:15]
	s_setprio 0
	s_setprio 1
	v_mfma_f32_16x16x32_bf16 v[56:59], v[166:169], v[186:189], v[56:59]
	v_mfma_f32_16x16x32_bf16 v[48:51], v[174:177], v[186:189], v[48:51]
	v_mfma_f32_16x16x32_bf16 v[32:35], v[174:177], v[194:197], v[32:35]
	v_mfma_f32_16x16x32_bf16 v[40:43], v[166:169], v[194:197], v[40:43]
	v_mfma_f32_16x16x32_bf16 v[24:27], v[166:169], v[202:205], v[24:27]
	v_mfma_f32_16x16x32_bf16 v[16:19], v[174:177], v[202:205], v[16:19]
	v_mfma_f32_16x16x32_bf16 v[0:3], v[174:177], v[210:213], v[0:3]
	v_mfma_f32_16x16x32_bf16 v[8:11], v[166:169], v[210:213], v[8:11]
	v_mfma_f32_16x16x32_bf16 v[56:59], v[170:173], v[190:193], v[56:59]
	v_mfma_f32_16x16x32_bf16 v[48:51], v[178:181], v[190:193], v[48:51]
	v_mfma_f32_16x16x32_bf16 v[32:35], v[178:181], v[198:201], v[32:35]
	v_mfma_f32_16x16x32_bf16 v[40:43], v[170:173], v[198:201], v[40:43]
	v_mfma_f32_16x16x32_bf16 v[24:27], v[170:173], v[206:209], v[24:27]
	v_mfma_f32_16x16x32_bf16 v[16:19], v[178:181], v[206:209], v[16:19]
	v_mfma_f32_16x16x32_bf16 v[0:3], v[178:181], v[214:217], v[0:3]
	v_mfma_f32_16x16x32_bf16 v[8:11], v[170:173], v[214:217], v[8:11]
	s_setprio 0
	s_barrier
	s_add_i32 s75, 0, 0x18000
	s_add_i32 s76, 0, 0x1c000
	v_add_u32_e32 v162, s75, v145
	v_add_u32_e32 v178, s76, v145
	ds_read_b128 v[150:153], v162
	ds_read_b128 v[154:157], v162 offset:1024
	ds_read_b128 v[158:161], v162 offset:2048
	ds_read_b128 v[162:165], v162 offset:3072
	ds_read_b128 v[166:169], v178
	ds_read_b128 v[170:173], v178 offset:1024
	ds_read_b128 v[174:177], v178 offset:2048
	ds_read_b128 v[178:181], v178 offset:3072
	s_add_u32 s60, s60, 0x80000
	s_addc_u32 s61, s61, 0
	s_mov_b32 m0, s67
	v_lshl_add_u64 v[224:225], s[60:61], 0, v[134:135]
	ds_read_b128 v[186:189], v149 offset:32768
	ds_read_b128 v[190:193], v149 offset:33792
	ds_read_b128 v[194:197], v149 offset:34816
	ds_read_b128 v[198:201], v149 offset:35840
	ds_read_b128 v[202:205], v149 offset:36864
	ds_read_b128 v[206:209], v149 offset:37888
	ds_read_b128 v[210:213], v149 offset:38912
	ds_read_b128 v[214:217], v149 offset:39936
	global_load_lds_dwordx4 v[224:225], off
	v_lshl_add_u64 v[224:225], s[60:61], 0, v[130:131]
	s_mov_b32 m0, s68
	s_nop 0
	global_load_lds_dwordx4 v[224:225], off
	s_waitcnt vmcnt(8)
	s_waitcnt lgkmcnt(0)
	s_barrier
	s_setprio 1
	s_waitcnt lgkmcnt(0)
	v_mfma_f32_16x16x32_bf16 v[124:127], v[150:153], v[186:189], v[124:127]
	v_mfma_f32_16x16x32_bf16 v[116:119], v[158:161], v[186:189], v[116:119]
	v_mfma_f32_16x16x32_bf16 v[100:103], v[158:161], v[194:197], v[100:103]
	v_mfma_f32_16x16x32_bf16 v[108:111], v[150:153], v[194:197], v[108:111]
	v_mfma_f32_16x16x32_bf16 v[92:95], v[150:153], v[202:205], v[92:95]
	v_mfma_f32_16x16x32_bf16 v[84:87], v[158:161], v[202:205], v[84:87]
	v_mfma_f32_16x16x32_bf16 v[68:71], v[158:161], v[210:213], v[68:71]
	v_mfma_f32_16x16x32_bf16 v[76:79], v[150:153], v[210:213], v[76:79]
	v_mfma_f32_16x16x32_bf16 v[124:127], v[154:157], v[190:193], v[124:127]
	v_mfma_f32_16x16x32_bf16 v[116:119], v[162:165], v[190:193], v[116:119]
	v_mfma_f32_16x16x32_bf16 v[100:103], v[162:165], v[198:201], v[100:103]
	v_mfma_f32_16x16x32_bf16 v[108:111], v[154:157], v[198:201], v[108:111]
	v_mfma_f32_16x16x32_bf16 v[92:95], v[154:157], v[206:209], v[92:95]
	v_mfma_f32_16x16x32_bf16 v[84:87], v[162:165], v[206:209], v[84:87]
	v_mfma_f32_16x16x32_bf16 v[68:71], v[162:165], v[214:217], v[68:71]
	v_mfma_f32_16x16x32_bf16 v[76:79], v[154:157], v[214:217], v[76:79]
	s_setprio 0
	s_setprio 1
	v_mfma_f32_16x16x32_bf16 v[120:123], v[166:169], v[186:189], v[120:123]
	v_mfma_f32_16x16x32_bf16 v[112:115], v[174:177], v[186:189], v[112:115]
	v_mfma_f32_16x16x32_bf16 v[96:99], v[174:177], v[194:197], v[96:99]
	v_mfma_f32_16x16x32_bf16 v[104:107], v[166:169], v[194:197], v[104:107]
	v_mfma_f32_16x16x32_bf16 v[88:91], v[166:169], v[202:205], v[88:91]
	v_mfma_f32_16x16x32_bf16 v[80:83], v[174:177], v[202:205], v[80:83]
	v_mfma_f32_16x16x32_bf16 v[64:67], v[174:177], v[210:213], v[64:67]
	v_mfma_f32_16x16x32_bf16 v[72:75], v[166:169], v[210:213], v[72:75]
	v_mfma_f32_16x16x32_bf16 v[120:123], v[170:173], v[190:193], v[120:123]
	v_mfma_f32_16x16x32_bf16 v[112:115], v[178:181], v[190:193], v[112:115]
	v_mfma_f32_16x16x32_bf16 v[96:99], v[178:181], v[198:201], v[96:99]
	v_mfma_f32_16x16x32_bf16 v[104:107], v[170:173], v[198:201], v[104:107]
	v_mfma_f32_16x16x32_bf16 v[88:91], v[170:173], v[206:209], v[88:91]
	v_mfma_f32_16x16x32_bf16 v[80:83], v[178:181], v[206:209], v[80:83]
	v_mfma_f32_16x16x32_bf16 v[64:67], v[178:181], v[214:217], v[64:67]
	v_mfma_f32_16x16x32_bf16 v[72:75], v[170:173], v[214:217], v[72:75]
	s_setprio 0
	s_barrier
; #define PG8_STAGE(bufoff, gbase, voff) do { _Pragma("unroll") for (int _i = 0; _i < 2; ++_i) \
;         __builtin_amdgcn_global_load_lds((const unsigned*)((const char*)(gbase) + (voff)[_i]), (LAS unsigned*)(lds + (bufoff) + ldsw + _i * 8192), 16, 0, 0); } while (0)
; #define PG8_LDA(dst, b, h) do { _Pragma("unroll") for (int m = 0; m < 4; ++m) _Pragma("unroll") for (int k = 0; k < 2; ++k) dst[m][k] = *(const LAS bf16x8*)(lds + PG8_SA(b, h) + aoff + m * 2048 + k * 1024); } while (0)
; #define PG8_MMA(ai, bj, At, Bt) do { __builtin_amdgcn_s_setprio(1); _Pragma("unroll") for (int m = 0; m < 4; ++m) _Pragma("unroll") for (int n = 0; n < 2; ++n) _Pragma("unroll") for (int k = 0; k < 2; ++k) \
;         acc[ai][bj][m][n] = __builtin_amdgcn_mfma_f32_16x16x32_bf16(Bt[n][k], At[m][k], acc[ai][bj][m][n], 0, 0, 0); __builtin_amdgcn_s_setprio(0); } while (0)
; #define PG8_WAIT_V(n) asm volatile("s_waitcnt vmcnt(" #n ")" ::: "memory")
; #define PG8_WAIT_L(n) asm volatile("s_waitcnt lgkmcnt(" #n ")" ::: "memory")
; #define PG8_BAR __builtin_amdgcn_s_barrier()
; #define PG8_SCHED __builtin_amdgcn_sched_barrier(0)
; template <class Epi, bool ALIGN_EPI = PG8_ALIGN>
; __device__ __forceinline__ void gemm_phase(LAS unsigned char* lds, const Gemm g, const StaticOrder S, const Epi E) {
;     ...
;             PG8_LDA(At, 1, 1); PG8_STAGE(PG8_SB(1, 0), b3, voffB); PG8_STAGE(PG8_SB(1, 1), b3 + hstepB, voffB); PG8_STAGE(PG8_SA(1, 0), a3, voffA);
;             PG8_WAIT_V(8); PG8_WAIT_L(0); PG8_BAR; PG8_MMA(1, 0, At, B0); PG8_MMA(1, 1, At, B1); PG8_BAR; PG8_SCHED;
;         }
	s_add_i32 s60, s75, s62
	v_lshl_add_u64 v[182:183], v[182:183], 0, s[6:7]
	s_mov_b32 m0, s60
	ds_read_b128 v[186:189], v149 offset:49152
	ds_read_b128 v[190:193], v149 offset:50176
	ds_read_b128 v[194:197], v149 offset:51200
	ds_read_b128 v[198:201], v149 offset:52224
	ds_read_b128 v[202:205], v149 offset:53248
	ds_read_b128 v[206:209], v149 offset:54272
	ds_read_b128 v[210:213], v149 offset:55296
	ds_read_b128 v[214:217], v149 offset:56320
	global_load_lds_dwordx4 v[182:183], off
	s_add_i32 m0, s60, 0x2000
	s_add_u32 s58, s58, 0x80080
	v_lshl_add_u64 v[182:183], v[218:219], 0, s[6:7]
	s_addc_u32 s59, s59, 0
	s_add_i32 s60, s76, s62
	global_load_lds_dwordx4 v[182:183], off
	v_lshl_add_u64 v[182:183], s[58:59], 0, v[132:133]
	s_mov_b32 m0, s60
	s_nop 0
	global_load_lds_dwordx4 v[182:183], off
	v_lshl_add_u64 v[182:183], s[58:59], 0, v[128:129]
	s_add_i32 m0, s60, 0x2000
	s_nop 0
	global_load_lds_dwordx4 v[182:183], off
	v_lshl_add_u64 v[182:183], v[220:221], 0, s[6:7]
	s_mov_b32 m0, s70
	s_nop 0
	global_load_lds_dwordx4 v[182:183], off
	v_lshl_add_u64 v[182:183], v[222:223], 0, s[6:7]
	s_mov_b32 m0, s71
	s_nop 0
	global_load_lds_dwordx4 v[182:183], off
	s_waitcnt vmcnt(8)
	s_waitcnt lgkmcnt(0)
	s_barrier
	s_setprio 1
	s_waitcnt lgkmcnt(0)
	v_mfma_f32_16x16x32_bf16 v[60:63], v[150:153], v[186:189], v[60:63]
	v_mfma_f32_16x16x32_bf16 v[52:55], v[158:161], v[186:189], v[52:55]
	v_mfma_f32_16x16x32_bf16 v[36:39], v[158:161], v[194:197], v[36:39]
	v_mfma_f32_16x16x32_bf16 v[44:47], v[150:153], v[194:197], v[44:47]
	v_mfma_f32_16x16x32_bf16 v[28:31], v[150:153], v[202:205], v[28:31]
	v_mfma_f32_16x16x32_bf16 v[20:23], v[158:161], v[202:205], v[20:23]
	v_mfma_f32_16x16x32_bf16 v[4:7], v[158:161], v[210:213], v[4:7]
	v_mfma_f32_16x16x32_bf16 v[12:15], v[150:153], v[210:213], v[12:15]
	v_mfma_f32_16x16x32_bf16 v[60:63], v[154:157], v[190:193], v[60:63]
	v_mfma_f32_16x16x32_bf16 v[52:55], v[162:165], v[190:193], v[52:55]
	v_mfma_f32_16x16x32_bf16 v[36:39], v[162:165], v[198:201], v[36:39]
	v_mfma_f32_16x16x32_bf16 v[44:47], v[154:157], v[198:201], v[44:47]
	v_mfma_f32_16x16x32_bf16 v[28:31], v[154:157], v[206:209], v[28:31]
	v_mfma_f32_16x16x32_bf16 v[20:23], v[162:165], v[206:209], v[20:23]
	v_mfma_f32_16x16x32_bf16 v[4:7], v[162:165], v[214:217], v[4:7]
	v_mfma_f32_16x16x32_bf16 v[12:15], v[154:157], v[214:217], v[12:15]
	s_setprio 0
	s_setprio 1
	v_mfma_f32_16x16x32_bf16 v[56:59], v[166:169], v[186:189], v[56:59]
	v_mfma_f32_16x16x32_bf16 v[48:51], v[174:177], v[186:189], v[48:51]
	v_mfma_f32_16x16x32_bf16 v[32:35], v[174:177], v[194:197], v[32:35]
	v_mfma_f32_16x16x32_bf16 v[40:43], v[166:169], v[194:197], v[40:43]
	v_mfma_f32_16x16x32_bf16 v[24:27], v[166:169], v[202:205], v[24:27]
	v_mfma_f32_16x16x32_bf16 v[16:19], v[174:177], v[202:205], v[16:19]
	v_mfma_f32_16x16x32_bf16 v[0:3], v[174:177], v[210:213], v[0:3]
	v_mfma_f32_16x16x32_bf16 v[8:11], v[166:169], v[210:213], v[8:11]
	v_mfma_f32_16x16x32_bf16 v[56:59], v[170:173], v[190:193], v[56:59]
	v_mfma_f32_16x16x32_bf16 v[48:51], v[178:181], v[190:193], v[48:51]
	v_mfma_f32_16x16x32_bf16 v[32:35], v[178:181], v[198:201], v[32:35]
	v_mfma_f32_16x16x32_bf16 v[40:43], v[170:173], v[198:201], v[40:43]
	v_mfma_f32_16x16x32_bf16 v[24:27], v[170:173], v[206:209], v[24:27]
	v_mfma_f32_16x16x32_bf16 v[16:19], v[178:181], v[206:209], v[16:19]
	v_mfma_f32_16x16x32_bf16 v[0:3], v[178:181], v[214:217], v[0:3]
	v_mfma_f32_16x16x32_bf16 v[8:11], v[170:173], v[214:217], v[8:11]
	s_setprio 0
	s_barrier
	s_add_i32 s74, s74, 2
	s_add_u32 s50, s50, 0x100
	s_addc_u32 s51, s51, 0
	s_add_u32 s72, s72, 0x100
	s_addc_u32 s73, s73, 0
	s_cmp_gt_u32 s74, 29
	s_cbranch_scc0 .LBB0_335
	s_and_b64 vcc, exec, s[8:9]
	s_cbranch_vccz .LBB0_338
	s_barrier

; #define PG8_STAGE(bufoff, gbase, voff) do { _Pragma("unroll") for (int _i = 0; _i < 2; ++_i) \
;         __builtin_amdgcn_global_load_lds((const unsigned*)((const char*)(gbase) + (voff)[_i]), (LAS unsigned*)(lds + (bufoff) + ldsw + _i * 8192), 16, 0, 0); } while (0)
; #define PG8_LDA(dst, b, h) do { _Pragma("unroll") for (int m = 0; m < 4; ++m) _Pragma("unroll") for (int k = 0; k < 2; ++k) dst[m][k] = *(const LAS bf16x8*)(lds + PG8_SA(b, h) + aoff + m * 2048 + k * 1024); } while (0)
; #define PG8_LDB(dst, b, h) do { _Pragma("unroll") for (int n = 0; n < 2; ++n) _Pragma("unroll") for (int k = 0; k < 2; ++k) dst[n][k] = *(const LAS bf16x8*)(lds + PG8_SB(b, h) + boff + n * 2048 + k * 1024); } while (0)
; #define PG8_MMA(ai, bj, At, Bt) do { __builtin_amdgcn_s_setprio(1); _Pragma("unroll") for (int m = 0; m < 4; ++m) _Pragma("unroll") for (int n = 0; n < 2; ++n) _Pragma("unroll") for (int k = 0; k < 2; ++k) \
;         acc[ai][bj][m][n] = __builtin_amdgcn_mfma_f32_16x16x32_bf16(Bt[n][k], At[m][k], acc[ai][bj][m][n], 0, 0, 0); __builtin_amdgcn_s_setprio(0); } while (0)
; #define PG8_WAIT_V(n) asm volatile("s_waitcnt vmcnt(" #n ")" ::: "memory")
; #define PG8_WAIT_L(n) asm volatile("s_waitcnt lgkmcnt(" #n ")" ::: "memory")
; #define PG8_BAR __builtin_amdgcn_s_barrier()
; #define PG8_SCHED __builtin_amdgcn_sched_barrier(0)
; template <class Epi, bool ALIGN_EPI = PG8_ALIGN>
; __device__ __forceinline__ void gemm_phase(LAS unsigned char* lds, const Gemm g, const StaticOrder S, const Epi E) {
;     ...
;             PG8_LDB(B0, 0, 0); PG8_LDB(B1, 0, 1); PG8_SCHED; PG8_LDA(At, 0, 0); PG8_STAGE(PG8_SA(1, 1), a1 + hstepA, voffA);
;             PG8_WAIT_V(8); PG8_WAIT_L(0); PG8_BAR; PG8_MMA(0, 0, At, B0); PG8_MMA(0, 1, At, B1); PG8_BAR; PG8_SCHED;
;             PG8_LDA(At, 0, 1); PG8_STAGE(PG8_SB(0, 0), b2, voffB); PG8_STAGE(PG8_SB(0, 1), b2 + hstepB, voffB); PG8_STAGE(PG8_SA(0, 0), a2, voffA);
;             PG8_WAIT_V(8); PG8_WAIT_L(0); PG8_BAR; PG8_MMA(1, 0, At, B0); PG8_MMA(1, 1, At, B1); PG8_BAR; PG8_SCHED;
.LBB0_420:
	ds_read_b128 v[146:149], v151
	ds_read_b128 v[154:157], v151 offset:1024
	ds_read_b128 v[158:161], v151 offset:2048
	ds_read_b128 v[162:165], v151 offset:3072
	ds_read_b128 v[166:169], v152
	ds_read_b128 v[170:173], v152 offset:1024
	ds_read_b128 v[174:177], v152 offset:2048
	ds_read_b128 v[178:181], v152 offset:3072
	s_add_u32 s35, s12, 0xffea0080
	s_addc_u32 s48, s13, -1
	s_cmpk_eq_i32 s34, 0x54
	s_cselect_b32 s51, s1, s48
	s_cselect_b32 s50, s0, s35
	s_cselect_b32 s49, s47, s33
	s_cselect_b32 s48, s46, s17
	v_lshl_add_u64 v[182:183], s[12:13], 0, v[138:139]
	s_add_i32 m0, s59, 0xc000
	ds_read_b128 v[186:189], v153
	ds_read_b128 v[190:193], v153 offset:1024
	ds_read_b128 v[194:197], v153 offset:2048
	ds_read_b128 v[198:201], v153 offset:3072
	ds_read_b128 v[202:205], v153 offset:4096
	ds_read_b128 v[206:209], v153 offset:5120
	ds_read_b128 v[210:213], v153 offset:6144
	ds_read_b128 v[214:217], v153 offset:7168
	global_load_lds_dwordx4 v[182:183], off
	v_lshl_add_u64 v[182:183], s[12:13], 0, v[140:141]
	s_add_i32 m0, s59, 0xe000
	s_nop 0
	global_load_lds_dwordx4 v[182:183], off
	s_waitcnt vmcnt(8)
	s_waitcnt lgkmcnt(0)
	s_barrier
	s_setprio 1
	s_waitcnt lgkmcnt(0)
	v_mfma_f32_16x16x32_bf16 v[124:127], v[146:149], v[186:189], v[124:127]
	v_mfma_f32_16x16x32_bf16 v[120:123], v[158:161], v[186:189], v[120:123]
	v_mfma_f32_16x16x32_bf16 v[104:107], v[158:161], v[194:197], v[104:107]
	v_mfma_f32_16x16x32_bf16 v[108:111], v[146:149], v[194:197], v[108:111]
	v_mfma_f32_16x16x32_bf16 v[92:95], v[146:149], v[202:205], v[92:95]
	v_mfma_f32_16x16x32_bf16 v[88:91], v[158:161], v[202:205], v[88:91]
	v_mfma_f32_16x16x32_bf16 v[72:75], v[158:161], v[210:213], v[72:75]
	v_mfma_f32_16x16x32_bf16 v[76:79], v[146:149], v[210:213], v[76:79]
	v_mfma_f32_16x16x32_bf16 v[124:127], v[154:157], v[190:193], v[124:127]
	v_mfma_f32_16x16x32_bf16 v[120:123], v[162:165], v[190:193], v[120:123]
	v_mfma_f32_16x16x32_bf16 v[104:107], v[162:165], v[198:201], v[104:107]
	v_mfma_f32_16x16x32_bf16 v[108:111], v[154:157], v[198:201], v[108:111]
	v_mfma_f32_16x16x32_bf16 v[92:95], v[154:157], v[206:209], v[92:95]
	v_mfma_f32_16x16x32_bf16 v[88:91], v[162:165], v[206:209], v[88:91]
	v_mfma_f32_16x16x32_bf16 v[72:75], v[162:165], v[214:217], v[72:75]
	v_mfma_f32_16x16x32_bf16 v[76:79], v[154:157], v[214:217], v[76:79]
	s_setprio 0
	s_setprio 1
	v_mfma_f32_16x16x32_bf16 v[116:119], v[166:169], v[186:189], v[116:119]
	v_mfma_f32_16x16x32_bf16 v[112:115], v[174:177], v[186:189], v[112:115]
	v_mfma_f32_16x16x32_bf16 v[96:99], v[174:177], v[194:197], v[96:99]
	v_mfma_f32_16x16x32_bf16 v[100:103], v[166:169], v[194:197], v[100:103]
	v_mfma_f32_16x16x32_bf16 v[84:87], v[166:169], v[202:205], v[84:87]
	v_mfma_f32_16x16x32_bf16 v[80:83], v[174:177], v[202:205], v[80:83]
	v_mfma_f32_16x16x32_bf16 v[64:67], v[174:177], v[210:213], v[64:67]
	v_mfma_f32_16x16x32_bf16 v[68:71], v[166:169], v[210:213], v[68:71]
	v_mfma_f32_16x16x32_bf16 v[116:119], v[170:173], v[190:193], v[116:119]
	v_mfma_f32_16x16x32_bf16 v[112:115], v[178:181], v[190:193], v[112:115]
	v_mfma_f32_16x16x32_bf16 v[96:99], v[178:181], v[198:201], v[96:99]
	v_mfma_f32_16x16x32_bf16 v[100:103], v[170:173], v[198:201], v[100:103]
	v_mfma_f32_16x16x32_bf16 v[84:87], v[170:173], v[206:209], v[84:87]
	v_mfma_f32_16x16x32_bf16 v[80:83], v[178:181], v[206:209], v[80:83]
	v_mfma_f32_16x16x32_bf16 v[64:67], v[178:181], v[214:217], v[64:67]
	v_mfma_f32_16x16x32_bf16 v[68:71], v[170:173], v[214:217], v[68:71]
	s_setprio 0
	s_barrier
	s_add_i32 s35, s68, s58
	v_lshl_add_u64 v[182:183], s[48:49], 0, v[130:131]
	s_mov_b32 m0, s35
	ds_read_b128 v[186:189], v153 offset:16384
	ds_read_b128 v[190:193], v153 offset:17408
	ds_read_b128 v[194:197], v153 offset:18432
	ds_read_b128 v[198:201], v153 offset:19456
	ds_read_b128 v[202:205], v153 offset:20480
	ds_read_b128 v[206:209], v153 offset:21504
	ds_read_b128 v[210:213], v153 offset:22528
	ds_read_b128 v[214:217], v153 offset:23552
	global_load_lds_dwordx4 v[182:183], off
	s_add_i32 m0, s35, 0x2000
	s_add_u32 s72, s48, 0x160000
	v_lshl_add_u64 v[218:219], s[48:49], 0, v[134:135]
	s_addc_u32 s73, s49, 0
	s_add_i32 s35, s69, s58
	global_load_lds_dwordx4 v[218:219], off
	v_lshl_add_u64 v[220:221], s[72:73], 0, v[130:131]
	s_mov_b32 m0, s35
	v_lshl_add_u64 v[222:223], s[50:51], 0, v[132:133]
	global_load_lds_dwordx4 v[220:221], off
	v_lshl_add_u64 v[220:221], s[72:73], 0, v[134:135]
	s_add_i32 m0, s35, 0x2000
	s_nop 0
	global_load_lds_dwordx4 v[220:221], off
	v_lshl_add_u64 v[220:221], s[50:51], 0, v[128:129]
	s_mov_b32 m0, s59
	s_nop 0
	global_load_lds_dwordx4 v[220:221], off
	s_mov_b32 m0, s60
	s_nop 0
	global_load_lds_dwordx4 v[222:223], off
	s_waitcnt vmcnt(8)
	s_waitcnt lgkmcnt(0)
	s_barrier
; #define PG8_STAGE(bufoff, gbase, voff) do { _Pragma("unroll") for (int _i = 0; _i < 2; ++_i) \
;         __builtin_amdgcn_global_load_lds((const unsigned*)((const char*)(gbase) + (voff)[_i]), (LAS unsigned*)(lds + (bufoff) + ldsw + _i * 8192), 16, 0, 0); } while (0)
; #define PG8_LDA(dst, b, h) do { _Pragma("unroll") for (int m = 0; m < 4; ++m) _Pragma("unroll") for (int k = 0; k < 2; ++k) dst[m][k] = *(const LAS bf16x8*)(lds + PG8_SA(b, h) + aoff + m * 2048 + k * 1024); } while (0)
; #define PG8_LDB(dst, b, h) do { _Pragma("unroll") for (int n = 0; n < 2; ++n) _Pragma("unroll") for (int k = 0; k < 2; ++k) dst[n][k] = *(const LAS bf16x8*)(lds + PG8_SB(b, h) + boff + n * 2048 + k * 1024); } while (0)
; #define PG8_MMA(ai, bj, At, Bt) do { __builtin_amdgcn_s_setprio(1); _Pragma("unroll") for (int m = 0; m < 4; ++m) _Pragma("unroll") for (int n = 0; n < 2; ++n) _Pragma("unroll") for (int k = 0; k < 2; ++k) \
;         acc[ai][bj][m][n] = __builtin_amdgcn_mfma_f32_16x16x32_bf16(Bt[n][k], At[m][k], acc[ai][bj][m][n], 0, 0, 0); __builtin_amdgcn_s_setprio(0); } while (0)
; #define PG8_WAIT_V(n) asm volatile("s_waitcnt vmcnt(" #n ")" ::: "memory")
; #define PG8_WAIT_L(n) asm volatile("s_waitcnt lgkmcnt(" #n ")" ::: "memory")
; #define PG8_BAR __builtin_amdgcn_s_barrier()
; #define PG8_SCHED __builtin_amdgcn_sched_barrier(0)
; template <class Epi, bool ALIGN_EPI = PG8_ALIGN>
; __device__ __forceinline__ void gemm_phase(LAS unsigned char* lds, const Gemm g, const StaticOrder S, const Epi E) {
;     ...
;             PG8_WAIT_V(8); PG8_WAIT_L(0); PG8_BAR; PG8_MMA(1, 0, At, B0); PG8_MMA(1, 1, At, B1); PG8_BAR; PG8_SCHED;
;             PG8_LDB(B0, 1, 0); PG8_LDB(B1, 1, 1); PG8_SCHED; PG8_LDA(At, 1, 0); PG8_STAGE(PG8_SA(0, 1), a2 + hstepA, voffA);
;             PG8_WAIT_V(8); PG8_WAIT_L(0); PG8_BAR; PG8_MMA(0, 0, At, B0); PG8_MMA(0, 1, At, B1); PG8_BAR; PG8_SCHED;
	s_setprio 1
	s_waitcnt lgkmcnt(0)
	v_mfma_f32_16x16x32_bf16 v[60:63], v[146:149], v[186:189], v[60:63]
	v_mfma_f32_16x16x32_bf16 v[56:59], v[158:161], v[186:189], v[56:59]
	v_mfma_f32_16x16x32_bf16 v[40:43], v[158:161], v[194:197], v[40:43]
	v_mfma_f32_16x16x32_bf16 v[44:47], v[146:149], v[194:197], v[44:47]
	v_mfma_f32_16x16x32_bf16 v[28:31], v[146:149], v[202:205], v[28:31]
	v_mfma_f32_16x16x32_bf16 v[24:27], v[158:161], v[202:205], v[24:27]
	v_mfma_f32_16x16x32_bf16 v[8:11], v[158:161], v[210:213], v[8:11]
	v_mfma_f32_16x16x32_bf16 v[12:15], v[146:149], v[210:213], v[12:15]
	v_mfma_f32_16x16x32_bf16 v[60:63], v[154:157], v[190:193], v[60:63]
	v_mfma_f32_16x16x32_bf16 v[56:59], v[162:165], v[190:193], v[56:59]
	v_mfma_f32_16x16x32_bf16 v[40:43], v[162:165], v[198:201], v[40:43]
	v_mfma_f32_16x16x32_bf16 v[44:47], v[154:157], v[198:201], v[44:47]
	v_mfma_f32_16x16x32_bf16 v[28:31], v[154:157], v[206:209], v[28:31]
	v_mfma_f32_16x16x32_bf16 v[24:27], v[162:165], v[206:209], v[24:27]
	v_mfma_f32_16x16x32_bf16 v[8:11], v[162:165], v[214:217], v[8:11]
	v_mfma_f32_16x16x32_bf16 v[12:15], v[154:157], v[214:217], v[12:15]
	s_setprio 0
	s_setprio 1
	v_mfma_f32_16x16x32_bf16 v[52:55], v[166:169], v[186:189], v[52:55]
	v_mfma_f32_16x16x32_bf16 v[48:51], v[174:177], v[186:189], v[48:51]
	v_mfma_f32_16x16x32_bf16 v[32:35], v[174:177], v[194:197], v[32:35]
	v_mfma_f32_16x16x32_bf16 v[36:39], v[166:169], v[194:197], v[36:39]
	v_mfma_f32_16x16x32_bf16 v[20:23], v[166:169], v[202:205], v[20:23]
	v_mfma_f32_16x16x32_bf16 v[16:19], v[174:177], v[202:205], v[16:19]
	v_mfma_f32_16x16x32_bf16 v[0:3], v[174:177], v[210:213], v[0:3]
	v_mfma_f32_16x16x32_bf16 v[4:7], v[166:169], v[210:213], v[4:7]
	v_mfma_f32_16x16x32_bf16 v[52:55], v[170:173], v[190:193], v[52:55]
	v_mfma_f32_16x16x32_bf16 v[48:51], v[178:181], v[190:193], v[48:51]
	v_mfma_f32_16x16x32_bf16 v[32:35], v[178:181], v[198:201], v[32:35]
	v_mfma_f32_16x16x32_bf16 v[36:39], v[170:173], v[198:201], v[36:39]
	v_mfma_f32_16x16x32_bf16 v[20:23], v[170:173], v[206:209], v[20:23]
	v_mfma_f32_16x16x32_bf16 v[16:19], v[178:181], v[206:209], v[16:19]
	v_mfma_f32_16x16x32_bf16 v[0:3], v[178:181], v[214:217], v[0:3]
	v_mfma_f32_16x16x32_bf16 v[4:7], v[170:173], v[214:217], v[4:7]
	s_setprio 0
	s_barrier
	s_add_i32 s35, 0, 0x18000
	s_add_i32 s72, 0, 0x1c000
	v_add_u32_e32 v162, s35, v150
	v_add_u32_e32 v178, s72, v150
	ds_read_b128 v[146:149], v162
	ds_read_b128 v[154:157], v162 offset:1024
	ds_read_b128 v[158:161], v162 offset:2048
	ds_read_b128 v[162:165], v162 offset:3072
	ds_read_b128 v[166:169], v178
	ds_read_b128 v[170:173], v178 offset:1024
	ds_read_b128 v[174:177], v178 offset:2048
	ds_read_b128 v[178:181], v178 offset:3072
	s_add_u32 s50, s50, 0x160000
	s_addc_u32 s51, s51, 0
	s_mov_b32 m0, s61
	v_lshl_add_u64 v[224:225], s[50:51], 0, v[128:129]
	ds_read_b128 v[186:189], v153 offset:32768
	ds_read_b128 v[190:193], v153 offset:33792
	ds_read_b128 v[194:197], v153 offset:34816
	ds_read_b128 v[198:201], v153 offset:35840
	ds_read_b128 v[202:205], v153 offset:36864
	ds_read_b128 v[206:209], v153 offset:37888
	ds_read_b128 v[210:213], v153 offset:38912
	ds_read_b128 v[214:217], v153 offset:39936
	global_load_lds_dwordx4 v[224:225], off
	v_lshl_add_u64 v[224:225], s[50:51], 0, v[132:133]
	s_mov_b32 m0, s62
	s_nop 0
	global_load_lds_dwordx4 v[224:225], off
	s_waitcnt vmcnt(8)
	s_waitcnt lgkmcnt(0)
	s_barrier
	s_setprio 1
	s_waitcnt lgkmcnt(0)
	v_mfma_f32_16x16x32_bf16 v[124:127], v[146:149], v[186:189], v[124:127]
	v_mfma_f32_16x16x32_bf16 v[120:123], v[158:161], v[186:189], v[120:123]
	v_mfma_f32_16x16x32_bf16 v[104:107], v[158:161], v[194:197], v[104:107]
	v_mfma_f32_16x16x32_bf16 v[108:111], v[146:149], v[194:197], v[108:111]
	v_mfma_f32_16x16x32_bf16 v[92:95], v[146:149], v[202:205], v[92:95]
	v_mfma_f32_16x16x32_bf16 v[88:91], v[158:161], v[202:205], v[88:91]
	v_mfma_f32_16x16x32_bf16 v[72:75], v[158:161], v[210:213], v[72:75]
	v_mfma_f32_16x16x32_bf16 v[76:79], v[146:149], v[210:213], v[76:79]
	v_mfma_f32_16x16x32_bf16 v[124:127], v[154:157], v[190:193], v[124:127]
	v_mfma_f32_16x16x32_bf16 v[120:123], v[162:165], v[190:193], v[120:123]
	v_mfma_f32_16x16x32_bf16 v[104:107], v[162:165], v[198:201], v[104:107]
	v_mfma_f32_16x16x32_bf16 v[108:111], v[154:157], v[198:201], v[108:111]
	v_mfma_f32_16x16x32_bf16 v[92:95], v[154:157], v[206:209], v[92:95]
	v_mfma_f32_16x16x32_bf16 v[88:91], v[162:165], v[206:209], v[88:91]
	v_mfma_f32_16x16x32_bf16 v[72:75], v[162:165], v[214:217], v[72:75]
	v_mfma_f32_16x16x32_bf16 v[76:79], v[154:157], v[214:217], v[76:79]
	s_setprio 0
	s_setprio 1
	v_mfma_f32_16x16x32_bf16 v[116:119], v[166:169], v[186:189], v[116:119]
	v_mfma_f32_16x16x32_bf16 v[112:115], v[174:177], v[186:189], v[112:115]
	v_mfma_f32_16x16x32_bf16 v[96:99], v[174:177], v[194:197], v[96:99]
	v_mfma_f32_16x16x32_bf16 v[100:103], v[166:169], v[194:197], v[100:103]
	v_mfma_f32_16x16x32_bf16 v[84:87], v[166:169], v[202:205], v[84:87]
	v_mfma_f32_16x16x32_bf16 v[80:83], v[174:177], v[202:205], v[80:83]
	v_mfma_f32_16x16x32_bf16 v[64:67], v[174:177], v[210:213], v[64:67]
	v_mfma_f32_16x16x32_bf16 v[68:71], v[166:169], v[210:213], v[68:71]
	v_mfma_f32_16x16x32_bf16 v[116:119], v[170:173], v[190:193], v[116:119]
	v_mfma_f32_16x16x32_bf16 v[112:115], v[178:181], v[190:193], v[112:115]
	v_mfma_f32_16x16x32_bf16 v[96:99], v[178:181], v[198:201], v[96:99]
	v_mfma_f32_16x16x32_bf16 v[100:103], v[170:173], v[198:201], v[100:103]
	v_mfma_f32_16x16x32_bf16 v[84:87], v[170:173], v[206:209], v[84:87]
	v_mfma_f32_16x16x32_bf16 v[80:83], v[178:181], v[206:209], v[80:83]
	v_mfma_f32_16x16x32_bf16 v[64:67], v[178:181], v[214:217], v[64:67]
	v_mfma_f32_16x16x32_bf16 v[68:71], v[170:173], v[214:217], v[68:71]
	s_setprio 0
	s_barrier
; #define PG8_STAGE(bufoff, gbase, voff) do { _Pragma("unroll") for (int _i = 0; _i < 2; ++_i) \
;         __builtin_amdgcn_global_load_lds((const unsigned*)((const char*)(gbase) + (voff)[_i]), (LAS unsigned*)(lds + (bufoff) + ldsw + _i * 8192), 16, 0, 0); } while (0)
; #define PG8_LDA(dst, b, h) do { _Pragma("unroll") for (int m = 0; m < 4; ++m) _Pragma("unroll") for (int k = 0; k < 2; ++k) dst[m][k] = *(const LAS bf16x8*)(lds + PG8_SA(b, h) + aoff + m * 2048 + k * 1024); } while (0)
; #define PG8_MMA(ai, bj, At, Bt) do { __builtin_amdgcn_s_setprio(1); _Pragma("unroll") for (int m = 0; m < 4; ++m) _Pragma("unroll") for (int n = 0; n < 2; ++n) _Pragma("unroll") for (int k = 0; k < 2; ++k) \
;         acc[ai][bj][m][n] = __builtin_amdgcn_mfma_f32_16x16x32_bf16(Bt[n][k], At[m][k], acc[ai][bj][m][n], 0, 0, 0); __builtin_amdgcn_s_setprio(0); } while (0)
; #define PG8_WAIT_V(n) asm volatile("s_waitcnt vmcnt(" #n ")" ::: "memory")
; #define PG8_WAIT_L(n) asm volatile("s_waitcnt lgkmcnt(" #n ")" ::: "memory")
; #define PG8_BAR __builtin_amdgcn_s_barrier()
; #define PG8_SCHED __builtin_amdgcn_sched_barrier(0)
; template <class Epi, bool ALIGN_EPI = PG8_ALIGN>
; __device__ __forceinline__ void gemm_phase(LAS unsigned char* lds, const Gemm g, const StaticOrder S, const Epi E) {
;     ...
;             PG8_LDA(At, 1, 1); PG8_STAGE(PG8_SB(1, 0), b3, voffB); PG8_STAGE(PG8_SB(1, 1), b3 + hstepB, voffB); PG8_STAGE(PG8_SA(1, 0), a3, voffA);
;             PG8_WAIT_V(8); PG8_WAIT_L(0); PG8_BAR; PG8_MMA(1, 0, At, B0); PG8_MMA(1, 1, At, B1); PG8_BAR; PG8_SCHED;
;         }
	s_add_i32 s35, s35, s58
	v_lshl_add_u64 v[182:183], v[182:183], 0, s[10:11]
	s_mov_b32 m0, s35
	ds_read_b128 v[186:189], v153 offset:49152
	ds_read_b128 v[190:193], v153 offset:50176
	ds_read_b128 v[194:197], v153 offset:51200
	ds_read_b128 v[198:201], v153 offset:52224
	ds_read_b128 v[202:205], v153 offset:53248
	ds_read_b128 v[206:209], v153 offset:54272
	ds_read_b128 v[210:213], v153 offset:55296
	ds_read_b128 v[214:217], v153 offset:56320
	global_load_lds_dwordx4 v[182:183], off
	s_add_i32 m0, s35, 0x2000
	s_add_u32 s48, s48, 0x160080
	v_lshl_add_u64 v[182:183], v[218:219], 0, s[10:11]
	s_addc_u32 s49, s49, 0
	s_add_i32 s35, s72, s58
	global_load_lds_dwordx4 v[182:183], off
	v_lshl_add_u64 v[182:183], s[48:49], 0, v[130:131]
	s_mov_b32 m0, s35
	s_nop 0
	global_load_lds_dwordx4 v[182:183], off
	v_lshl_add_u64 v[182:183], s[48:49], 0, v[134:135]
	s_add_i32 m0, s35, 0x2000
	s_nop 0
	global_load_lds_dwordx4 v[182:183], off
	v_lshl_add_u64 v[182:183], v[220:221], 0, s[10:11]
	s_mov_b32 m0, s65
	s_nop 0
	global_load_lds_dwordx4 v[182:183], off
	v_lshl_add_u64 v[182:183], v[222:223], 0, s[10:11]
	s_mov_b32 m0, s66
	s_nop 0
	global_load_lds_dwordx4 v[182:183], off
	s_waitcnt vmcnt(8)
	s_waitcnt lgkmcnt(0)
	s_barrier
	s_setprio 1
	s_waitcnt lgkmcnt(0)
	v_mfma_f32_16x16x32_bf16 v[60:63], v[146:149], v[186:189], v[60:63]
	v_mfma_f32_16x16x32_bf16 v[56:59], v[158:161], v[186:189], v[56:59]
	v_mfma_f32_16x16x32_bf16 v[40:43], v[158:161], v[194:197], v[40:43]
	v_mfma_f32_16x16x32_bf16 v[44:47], v[146:149], v[194:197], v[44:47]
	v_mfma_f32_16x16x32_bf16 v[28:31], v[146:149], v[202:205], v[28:31]
	v_mfma_f32_16x16x32_bf16 v[24:27], v[158:161], v[202:205], v[24:27]
	v_mfma_f32_16x16x32_bf16 v[8:11], v[158:161], v[210:213], v[8:11]
	v_mfma_f32_16x16x32_bf16 v[12:15], v[146:149], v[210:213], v[12:15]
	v_mfma_f32_16x16x32_bf16 v[60:63], v[154:157], v[190:193], v[60:63]
	v_mfma_f32_16x16x32_bf16 v[56:59], v[162:165], v[190:193], v[56:59]
	v_mfma_f32_16x16x32_bf16 v[40:43], v[162:165], v[198:201], v[40:43]
	v_mfma_f32_16x16x32_bf16 v[44:47], v[154:157], v[198:201], v[44:47]
	v_mfma_f32_16x16x32_bf16 v[28:31], v[154:157], v[206:209], v[28:31]
	v_mfma_f32_16x16x32_bf16 v[24:27], v[162:165], v[206:209], v[24:27]
	v_mfma_f32_16x16x32_bf16 v[8:11], v[162:165], v[214:217], v[8:11]
	v_mfma_f32_16x16x32_bf16 v[12:15], v[154:157], v[214:217], v[12:15]
	s_setprio 0
	s_setprio 1
	v_mfma_f32_16x16x32_bf16 v[52:55], v[166:169], v[186:189], v[52:55]
	v_mfma_f32_16x16x32_bf16 v[48:51], v[174:177], v[186:189], v[48:51]
	v_mfma_f32_16x16x32_bf16 v[32:35], v[174:177], v[194:197], v[32:35]
	v_mfma_f32_16x16x32_bf16 v[36:39], v[166:169], v[194:197], v[36:39]
	v_mfma_f32_16x16x32_bf16 v[20:23], v[166:169], v[202:205], v[20:23]
	v_mfma_f32_16x16x32_bf16 v[16:19], v[174:177], v[202:205], v[16:19]
	v_mfma_f32_16x16x32_bf16 v[0:3], v[174:177], v[210:213], v[0:3]
	v_mfma_f32_16x16x32_bf16 v[4:7], v[166:169], v[210:213], v[4:7]
	v_mfma_f32_16x16x32_bf16 v[52:55], v[170:173], v[190:193], v[52:55]
	v_mfma_f32_16x16x32_bf16 v[48:51], v[178:181], v[190:193], v[48:51]
	v_mfma_f32_16x16x32_bf16 v[32:35], v[178:181], v[198:201], v[32:35]
	v_mfma_f32_16x16x32_bf16 v[36:39], v[170:173], v[198:201], v[36:39]
	v_mfma_f32_16x16x32_bf16 v[20:23], v[170:173], v[206:209], v[20:23]
	v_mfma_f32_16x16x32_bf16 v[16:19], v[178:181], v[206:209], v[16:19]
	v_mfma_f32_16x16x32_bf16 v[0:3], v[178:181], v[214:217], v[0:3]
	v_mfma_f32_16x16x32_bf16 v[4:7], v[170:173], v[214:217], v[4:7]
	s_setprio 0
	s_barrier
	s_add_i32 s34, s34, 2
	s_add_u32 s12, s12, 0x100
	s_addc_u32 s13, s13, 0
	s_add_u32 s17, s17, 0x100
	s_addc_u32 s33, s33, 0
	s_cmpk_gt_u32 s34, 0x55
	s_cbranch_scc0 .LBB0_420
	s_and_b64 vcc, exec, s[42:43]
	s_cbranch_vccz .LBB0_423
	s_barrier

; #define PG8_STAGE(bufoff, gbase, voff) do { _Pragma("unroll") for (int _i = 0; _i < 2; ++_i) \
;         __builtin_amdgcn_global_load_lds((const unsigned*)((const char*)(gbase) + (voff)[_i]), (LAS unsigned*)(lds + (bufoff) + ldsw + _i * 8192), 16, 0, 0); } while (0)
; #define PG8_LDA(dst, b, h) do { _Pragma("unroll") for (int m = 0; m < 4; ++m) _Pragma("unroll") for (int k = 0; k < 2; ++k) dst[m][k] = *(const LAS bf16x8*)(lds + PG8_SA(b, h) + aoff + m * 2048 + k * 1024); } while (0)
; #define PG8_LDB(dst, b, h) do { _Pragma("unroll") for (int n = 0; n < 2; ++n) _Pragma("unroll") for (int k = 0; k < 2; ++k) dst[n][k] = *(const LAS bf16x8*)(lds + PG8_SB(b, h) + boff + n * 2048 + k * 1024); } while (0)
; #define PG8_MMA(ai, bj, At, Bt) do { __builtin_amdgcn_s_setprio(1); _Pragma("unroll") for (int m = 0; m < 4; ++m) _Pragma("unroll") for (int n = 0; n < 2; ++n) _Pragma("unroll") for (int k = 0; k < 2; ++k) \
;         acc[ai][bj][m][n] = __builtin_amdgcn_mfma_f32_16x16x32_bf16(Bt[n][k], At[m][k], acc[ai][bj][m][n], 0, 0, 0); __builtin_amdgcn_s_setprio(0); } while (0)
; #define PG8_WAIT_V(n) asm volatile("s_waitcnt vmcnt(" #n ")" ::: "memory")
; #define PG8_WAIT_L(n) asm volatile("s_waitcnt lgkmcnt(" #n ")" ::: "memory")
; #define PG8_BAR __builtin_amdgcn_s_barrier()
; #define PG8_SCHED __builtin_amdgcn_sched_barrier(0)
; template <class Epi, bool ALIGN_EPI = PG8_ALIGN>
; __device__ __forceinline__ void gemm_phase(LAS unsigned char* lds, const Gemm g, const StaticOrder S, const Epi E) {
;     ...
;             PG8_LDB(B0, 0, 0); PG8_LDB(B1, 0, 1); PG8_SCHED; PG8_LDA(At, 0, 0); PG8_STAGE(PG8_SA(1, 1), a1 + hstepA, voffA);
;             PG8_WAIT_V(8); PG8_WAIT_L(0); PG8_BAR; PG8_MMA(0, 0, At, B0); PG8_MMA(0, 1, At, B1); PG8_BAR; PG8_SCHED;
;             PG8_LDA(At, 0, 1); PG8_STAGE(PG8_SB(0, 0), b2, voffB); PG8_STAGE(PG8_SB(0, 1), b2 + hstepB, voffB); PG8_STAGE(PG8_SA(0, 0), a2, voffA);
;             PG8_WAIT_V(8); PG8_WAIT_L(0); PG8_BAR; PG8_MMA(1, 0, At, B0); PG8_MMA(1, 1, At, B1); PG8_BAR; PG8_SCHED;
.LBB0_507:
	ds_read_b128 v[144:147], v160
	ds_read_b128 v[164:167], v160 offset:1024
	ds_read_b128 v[168:171], v160 offset:2048
	ds_read_b128 v[172:175], v160 offset:3072
	ds_read_b128 v[176:179], v161
	ds_read_b128 v[180:183], v161 offset:1024
	ds_read_b128 v[186:189], v161 offset:2048
	ds_read_b128 v[190:193], v161 offset:3072
	s_add_u32 s42, s52, 0xfff80080
	s_addc_u32 s43, s53, -1
	s_cmp_eq_u32 s35, 28
	s_cselect_b32 s61, s14, s43
	s_cselect_b32 s60, s16, s42
	s_cselect_b32 s59, s11, s34
	s_cselect_b32 s58, s17, s33
	v_lshl_add_u64 v[226:227], s[52:53], 0, v[136:137]
	s_add_i32 m0, s63, 0xc000
	ds_read_b128 v[194:197], v162
	ds_read_b128 v[198:201], v162 offset:1024
	ds_read_b128 v[202:205], v162 offset:2048
	ds_read_b128 v[206:209], v162 offset:3072
	ds_read_b128 v[210:213], v162 offset:4096
	ds_read_b128 v[214:217], v162 offset:5120
	ds_read_b128 v[218:221], v162 offset:6144
	ds_read_b128 v[222:225], v162 offset:7168
	global_load_lds_dwordx4 v[226:227], off
	v_lshl_add_u64 v[226:227], s[52:53], 0, v[138:139]
	s_add_i32 m0, s63, 0xe000
	s_nop 0
	global_load_lds_dwordx4 v[226:227], off
	s_waitcnt vmcnt(8)
	s_waitcnt lgkmcnt(0)
	s_barrier
	s_setprio 1
	s_waitcnt lgkmcnt(0)
	v_mfma_f32_16x16x32_bf16 v[124:127], v[144:147], v[194:197], v[124:127]
	v_mfma_f32_16x16x32_bf16 v[120:123], v[168:171], v[194:197], v[120:123]
	v_mfma_f32_16x16x32_bf16 v[112:115], v[168:171], v[202:205], v[112:115]
	v_mfma_f32_16x16x32_bf16 v[116:119], v[144:147], v[202:205], v[116:119]
	v_mfma_f32_16x16x32_bf16 v[108:111], v[144:147], v[210:213], v[108:111]
	v_mfma_f32_16x16x32_bf16 v[104:107], v[168:171], v[210:213], v[104:107]
	v_mfma_f32_16x16x32_bf16 v[96:99], v[168:171], v[218:221], v[96:99]
	v_mfma_f32_16x16x32_bf16 v[100:103], v[144:147], v[218:221], v[100:103]
	v_mfma_f32_16x16x32_bf16 v[124:127], v[164:167], v[198:201], v[124:127]
	v_mfma_f32_16x16x32_bf16 v[120:123], v[172:175], v[198:201], v[120:123]
	v_mfma_f32_16x16x32_bf16 v[112:115], v[172:175], v[206:209], v[112:115]
	v_mfma_f32_16x16x32_bf16 v[116:119], v[164:167], v[206:209], v[116:119]
	v_mfma_f32_16x16x32_bf16 v[108:111], v[164:167], v[214:217], v[108:111]
	v_mfma_f32_16x16x32_bf16 v[104:107], v[172:175], v[214:217], v[104:107]
	v_mfma_f32_16x16x32_bf16 v[96:99], v[172:175], v[222:225], v[96:99]
	v_mfma_f32_16x16x32_bf16 v[100:103], v[164:167], v[222:225], v[100:103]
	s_setprio 0
	s_setprio 1
	v_mfma_f32_16x16x32_bf16 v[60:63], v[176:179], v[194:197], v[60:63]
	v_mfma_f32_16x16x32_bf16 v[56:59], v[186:189], v[194:197], v[56:59]
	v_mfma_f32_16x16x32_bf16 v[48:51], v[186:189], v[202:205], v[48:51]
	v_mfma_f32_16x16x32_bf16 v[52:55], v[176:179], v[202:205], v[52:55]
	v_mfma_f32_16x16x32_bf16 v[44:47], v[176:179], v[210:213], v[44:47]
	v_mfma_f32_16x16x32_bf16 v[40:43], v[186:189], v[210:213], v[40:43]
	v_mfma_f32_16x16x32_bf16 v[32:35], v[186:189], v[218:221], v[32:35]
	v_mfma_f32_16x16x32_bf16 v[36:39], v[176:179], v[218:221], v[36:39]
	v_mfma_f32_16x16x32_bf16 v[60:63], v[180:183], v[198:201], v[60:63]
	v_mfma_f32_16x16x32_bf16 v[56:59], v[190:193], v[198:201], v[56:59]
	v_mfma_f32_16x16x32_bf16 v[48:51], v[190:193], v[206:209], v[48:51]
	v_mfma_f32_16x16x32_bf16 v[52:55], v[180:183], v[206:209], v[52:55]
	v_mfma_f32_16x16x32_bf16 v[44:47], v[180:183], v[214:217], v[44:47]
	v_mfma_f32_16x16x32_bf16 v[40:43], v[190:193], v[214:217], v[40:43]
	v_mfma_f32_16x16x32_bf16 v[32:35], v[190:193], v[222:225], v[32:35]
	v_mfma_f32_16x16x32_bf16 v[36:39], v[180:183], v[222:225], v[36:39]
	s_setprio 0
	s_barrier
	s_add_i32 s42, s72, s62
	v_lshl_add_u64 v[226:227], s[58:59], 0, v[130:131]
	s_mov_b32 m0, s42
	ds_read_b128 v[194:197], v162 offset:16384
	ds_read_b128 v[198:201], v162 offset:17408
	ds_read_b128 v[202:205], v162 offset:18432
	ds_read_b128 v[206:209], v162 offset:19456
	ds_read_b128 v[210:213], v162 offset:20480
	ds_read_b128 v[214:217], v162 offset:21504
	ds_read_b128 v[218:221], v162 offset:22528
	ds_read_b128 v[222:225], v162 offset:23552
	global_load_lds_dwordx4 v[226:227], off
	s_add_i32 m0, s42, 0x2000
	s_add_u32 s42, s58, 0x80000
	v_lshl_add_u64 v[228:229], s[58:59], 0, v[134:135]
	s_addc_u32 s43, s59, 0
	s_add_i32 s47, s73, s62
	global_load_lds_dwordx4 v[228:229], off
	v_lshl_add_u64 v[230:231], s[42:43], 0, v[130:131]
	s_mov_b32 m0, s47
	v_lshl_add_u64 v[232:233], s[60:61], 0, v[132:133]
	global_load_lds_dwordx4 v[230:231], off
	v_lshl_add_u64 v[230:231], s[42:43], 0, v[134:135]
	s_add_i32 m0, s47, 0x2000
	s_nop 0
	global_load_lds_dwordx4 v[230:231], off
	v_lshl_add_u64 v[230:231], s[60:61], 0, v[128:129]
	s_mov_b32 m0, s63
	s_nop 0
	global_load_lds_dwordx4 v[230:231], off
	s_mov_b32 m0, s64
	s_nop 0
	global_load_lds_dwordx4 v[232:233], off
	s_waitcnt vmcnt(8)
	s_waitcnt lgkmcnt(0)
	s_barrier
; #define PG8_STAGE(bufoff, gbase, voff) do { _Pragma("unroll") for (int _i = 0; _i < 2; ++_i) \
;         __builtin_amdgcn_global_load_lds((const unsigned*)((const char*)(gbase) + (voff)[_i]), (LAS unsigned*)(lds + (bufoff) + ldsw + _i * 8192), 16, 0, 0); } while (0)
; #define PG8_LDA(dst, b, h) do { _Pragma("unroll") for (int m = 0; m < 4; ++m) _Pragma("unroll") for (int k = 0; k < 2; ++k) dst[m][k] = *(const LAS bf16x8*)(lds + PG8_SA(b, h) + aoff + m * 2048 + k * 1024); } while (0)
; #define PG8_LDB(dst, b, h) do { _Pragma("unroll") for (int n = 0; n < 2; ++n) _Pragma("unroll") for (int k = 0; k < 2; ++k) dst[n][k] = *(const LAS bf16x8*)(lds + PG8_SB(b, h) + boff + n * 2048 + k * 1024); } while (0)
; #define PG8_MMA(ai, bj, At, Bt) do { __builtin_amdgcn_s_setprio(1); _Pragma("unroll") for (int m = 0; m < 4; ++m) _Pragma("unroll") for (int n = 0; n < 2; ++n) _Pragma("unroll") for (int k = 0; k < 2; ++k) \
;         acc[ai][bj][m][n] = __builtin_amdgcn_mfma_f32_16x16x32_bf16(Bt[n][k], At[m][k], acc[ai][bj][m][n], 0, 0, 0); __builtin_amdgcn_s_setprio(0); } while (0)
; #define PG8_WAIT_V(n) asm volatile("s_waitcnt vmcnt(" #n ")" ::: "memory")
; #define PG8_WAIT_L(n) asm volatile("s_waitcnt lgkmcnt(" #n ")" ::: "memory")
; #define PG8_BAR __builtin_amdgcn_s_barrier()
; #define PG8_SCHED __builtin_amdgcn_sched_barrier(0)
; template <class Epi, bool ALIGN_EPI = PG8_ALIGN>
; __device__ __forceinline__ void gemm_phase(LAS unsigned char* lds, const Gemm g, const StaticOrder S, const Epi E) {
;     ...
;             PG8_WAIT_V(8); PG8_WAIT_L(0); PG8_BAR; PG8_MMA(1, 0, At, B0); PG8_MMA(1, 1, At, B1); PG8_BAR; PG8_SCHED;
;             PG8_LDB(B0, 1, 0); PG8_LDB(B1, 1, 1); PG8_SCHED; PG8_LDA(At, 1, 0); PG8_STAGE(PG8_SA(0, 1), a2 + hstepA, voffA);
;             PG8_WAIT_V(8); PG8_WAIT_L(0); PG8_BAR; PG8_MMA(0, 0, At, B0); PG8_MMA(0, 1, At, B1); PG8_BAR; PG8_SCHED;
	s_setprio 1
	s_waitcnt lgkmcnt(0)
	v_mfma_f32_16x16x32_bf16 v[92:95], v[144:147], v[194:197], v[92:95]
	v_mfma_f32_16x16x32_bf16 v[88:91], v[168:171], v[194:197], v[88:91]
	v_mfma_f32_16x16x32_bf16 v[80:83], v[168:171], v[202:205], v[80:83]
	v_mfma_f32_16x16x32_bf16 v[84:87], v[144:147], v[202:205], v[84:87]
	v_mfma_f32_16x16x32_bf16 v[76:79], v[144:147], v[210:213], v[76:79]
	v_mfma_f32_16x16x32_bf16 v[72:75], v[168:171], v[210:213], v[72:75]
	v_mfma_f32_16x16x32_bf16 v[64:67], v[168:171], v[218:221], v[64:67]
	v_mfma_f32_16x16x32_bf16 v[68:71], v[144:147], v[218:221], v[68:71]
	v_mfma_f32_16x16x32_bf16 v[92:95], v[164:167], v[198:201], v[92:95]
	v_mfma_f32_16x16x32_bf16 v[88:91], v[172:175], v[198:201], v[88:91]
	v_mfma_f32_16x16x32_bf16 v[80:83], v[172:175], v[206:209], v[80:83]
	v_mfma_f32_16x16x32_bf16 v[84:87], v[164:167], v[206:209], v[84:87]
	v_mfma_f32_16x16x32_bf16 v[76:79], v[164:167], v[214:217], v[76:79]
	v_mfma_f32_16x16x32_bf16 v[72:75], v[172:175], v[214:217], v[72:75]
	v_mfma_f32_16x16x32_bf16 v[64:67], v[172:175], v[222:225], v[64:67]
	v_mfma_f32_16x16x32_bf16 v[68:71], v[164:167], v[222:225], v[68:71]
	s_setprio 0
	s_setprio 1
	v_mfma_f32_16x16x32_bf16 v[28:31], v[176:179], v[194:197], v[28:31]
	v_mfma_f32_16x16x32_bf16 v[24:27], v[186:189], v[194:197], v[24:27]
	v_mfma_f32_16x16x32_bf16 v[16:19], v[186:189], v[202:205], v[16:19]
	v_mfma_f32_16x16x32_bf16 v[20:23], v[176:179], v[202:205], v[20:23]
	v_mfma_f32_16x16x32_bf16 v[12:15], v[176:179], v[210:213], v[12:15]
	v_mfma_f32_16x16x32_bf16 v[8:11], v[186:189], v[210:213], v[8:11]
	v_mfma_f32_16x16x32_bf16 v[0:3], v[186:189], v[218:221], v[0:3]
	v_mfma_f32_16x16x32_bf16 v[4:7], v[176:179], v[218:221], v[4:7]
	v_mfma_f32_16x16x32_bf16 v[28:31], v[180:183], v[198:201], v[28:31]
	v_mfma_f32_16x16x32_bf16 v[24:27], v[190:193], v[198:201], v[24:27]
	v_mfma_f32_16x16x32_bf16 v[16:19], v[190:193], v[206:209], v[16:19]
	v_mfma_f32_16x16x32_bf16 v[20:23], v[180:183], v[206:209], v[20:23]
	v_mfma_f32_16x16x32_bf16 v[12:15], v[180:183], v[214:217], v[12:15]
	v_mfma_f32_16x16x32_bf16 v[8:11], v[190:193], v[214:217], v[8:11]
	v_mfma_f32_16x16x32_bf16 v[0:3], v[190:193], v[222:225], v[0:3]
	v_mfma_f32_16x16x32_bf16 v[4:7], v[180:183], v[222:225], v[4:7]
	s_setprio 0
	s_barrier
	s_add_i32 s47, 0, 0x18000
	s_add_i32 s76, 0, 0x1c000
	v_add_u32_e32 v172, s47, v156
	v_add_u32_e32 v190, s76, v156
	ds_read_b128 v[144:147], v172
	ds_read_b128 v[164:167], v172 offset:1024
	ds_read_b128 v[168:171], v172 offset:2048
	ds_read_b128 v[172:175], v172 offset:3072
	ds_read_b128 v[176:179], v190
	ds_read_b128 v[180:183], v190 offset:1024
	ds_read_b128 v[186:189], v190 offset:2048
	ds_read_b128 v[190:193], v190 offset:3072
	s_add_u32 s42, s60, 0x80000
	s_addc_u32 s43, s61, 0
	s_mov_b32 m0, s65
	v_lshl_add_u64 v[234:235], s[42:43], 0, v[128:129]
	ds_read_b128 v[194:197], v162 offset:32768
	ds_read_b128 v[198:201], v162 offset:33792
	ds_read_b128 v[202:205], v162 offset:34816
	ds_read_b128 v[206:209], v162 offset:35840
	ds_read_b128 v[210:213], v162 offset:36864
	ds_read_b128 v[214:217], v162 offset:37888
	ds_read_b128 v[218:221], v162 offset:38912
	ds_read_b128 v[222:225], v162 offset:39936
	global_load_lds_dwordx4 v[234:235], off
	v_lshl_add_u64 v[234:235], s[42:43], 0, v[132:133]
	s_mov_b32 m0, s66
	s_nop 0
	global_load_lds_dwordx4 v[234:235], off
	s_waitcnt vmcnt(8)
	s_waitcnt lgkmcnt(0)
	s_barrier
	s_setprio 1
	s_waitcnt lgkmcnt(0)
	v_mfma_f32_16x16x32_bf16 v[124:127], v[144:147], v[194:197], v[124:127]
	v_mfma_f32_16x16x32_bf16 v[120:123], v[168:171], v[194:197], v[120:123]
	v_mfma_f32_16x16x32_bf16 v[112:115], v[168:171], v[202:205], v[112:115]
	v_mfma_f32_16x16x32_bf16 v[116:119], v[144:147], v[202:205], v[116:119]
	v_mfma_f32_16x16x32_bf16 v[108:111], v[144:147], v[210:213], v[108:111]
	v_mfma_f32_16x16x32_bf16 v[104:107], v[168:171], v[210:213], v[104:107]
	v_mfma_f32_16x16x32_bf16 v[96:99], v[168:171], v[218:221], v[96:99]
	v_mfma_f32_16x16x32_bf16 v[100:103], v[144:147], v[218:221], v[100:103]
	v_mfma_f32_16x16x32_bf16 v[124:127], v[164:167], v[198:201], v[124:127]
	v_mfma_f32_16x16x32_bf16 v[120:123], v[172:175], v[198:201], v[120:123]
	v_mfma_f32_16x16x32_bf16 v[112:115], v[172:175], v[206:209], v[112:115]
	v_mfma_f32_16x16x32_bf16 v[116:119], v[164:167], v[206:209], v[116:119]
	v_mfma_f32_16x16x32_bf16 v[108:111], v[164:167], v[214:217], v[108:111]
	v_mfma_f32_16x16x32_bf16 v[104:107], v[172:175], v[214:217], v[104:107]
	v_mfma_f32_16x16x32_bf16 v[96:99], v[172:175], v[222:225], v[96:99]
	v_mfma_f32_16x16x32_bf16 v[100:103], v[164:167], v[222:225], v[100:103]
	s_setprio 0
	s_setprio 1
	v_mfma_f32_16x16x32_bf16 v[60:63], v[176:179], v[194:197], v[60:63]
	v_mfma_f32_16x16x32_bf16 v[56:59], v[186:189], v[194:197], v[56:59]
	v_mfma_f32_16x16x32_bf16 v[48:51], v[186:189], v[202:205], v[48:51]
	v_mfma_f32_16x16x32_bf16 v[52:55], v[176:179], v[202:205], v[52:55]
	v_mfma_f32_16x16x32_bf16 v[44:47], v[176:179], v[210:213], v[44:47]
	v_mfma_f32_16x16x32_bf16 v[40:43], v[186:189], v[210:213], v[40:43]
	v_mfma_f32_16x16x32_bf16 v[32:35], v[186:189], v[218:221], v[32:35]
	v_mfma_f32_16x16x32_bf16 v[36:39], v[176:179], v[218:221], v[36:39]
	v_mfma_f32_16x16x32_bf16 v[60:63], v[180:183], v[198:201], v[60:63]
	v_mfma_f32_16x16x32_bf16 v[56:59], v[190:193], v[198:201], v[56:59]
	v_mfma_f32_16x16x32_bf16 v[48:51], v[190:193], v[206:209], v[48:51]
	v_mfma_f32_16x16x32_bf16 v[52:55], v[180:183], v[206:209], v[52:55]
	v_mfma_f32_16x16x32_bf16 v[44:47], v[180:183], v[214:217], v[44:47]
	v_mfma_f32_16x16x32_bf16 v[40:43], v[190:193], v[214:217], v[40:43]
	v_mfma_f32_16x16x32_bf16 v[32:35], v[190:193], v[222:225], v[32:35]
	v_mfma_f32_16x16x32_bf16 v[36:39], v[180:183], v[222:225], v[36:39]
	s_setprio 0
	s_barrier
; #define PG8_STAGE(bufoff, gbase, voff) do { _Pragma("unroll") for (int _i = 0; _i < 2; ++_i) \
;         __builtin_amdgcn_global_load_lds((const unsigned*)((const char*)(gbase) + (voff)[_i]), (LAS unsigned*)(lds + (bufoff) + ldsw + _i * 8192), 16, 0, 0); } while (0)
; #define PG8_LDA(dst, b, h) do { _Pragma("unroll") for (int m = 0; m < 4; ++m) _Pragma("unroll") for (int k = 0; k < 2; ++k) dst[m][k] = *(const LAS bf16x8*)(lds + PG8_SA(b, h) + aoff + m * 2048 + k * 1024); } while (0)
; #define PG8_MMA(ai, bj, At, Bt) do { __builtin_amdgcn_s_setprio(1); _Pragma("unroll") for (int m = 0; m < 4; ++m) _Pragma("unroll") for (int n = 0; n < 2; ++n) _Pragma("unroll") for (int k = 0; k < 2; ++k) \
;         acc[ai][bj][m][n] = __builtin_amdgcn_mfma_f32_16x16x32_bf16(Bt[n][k], At[m][k], acc[ai][bj][m][n], 0, 0, 0); __builtin_amdgcn_s_setprio(0); } while (0)
; #define PG8_WAIT_V(n) asm volatile("s_waitcnt vmcnt(" #n ")" ::: "memory")
; #define PG8_WAIT_L(n) asm volatile("s_waitcnt lgkmcnt(" #n ")" ::: "memory")
; #define PG8_BAR __builtin_amdgcn_s_barrier()
; #define PG8_SCHED __builtin_amdgcn_sched_barrier(0)
; template <class Epi, bool ALIGN_EPI = PG8_ALIGN>
; __device__ __forceinline__ void gemm_phase(LAS unsigned char* lds, const Gemm g, const StaticOrder S, const Epi E) {
;     ...
;             PG8_LDA(At, 1, 1); PG8_STAGE(PG8_SB(1, 0), b3, voffB); PG8_STAGE(PG8_SB(1, 1), b3 + hstepB, voffB); PG8_STAGE(PG8_SA(1, 0), a3, voffA);
;             PG8_WAIT_V(8); PG8_WAIT_L(0); PG8_BAR; PG8_MMA(1, 0, At, B0); PG8_MMA(1, 1, At, B1); PG8_BAR; PG8_SCHED;
;         }
	s_add_i32 s42, s47, s62
	v_lshl_add_u64 v[226:227], v[226:227], 0, s[6:7]
	s_mov_b32 m0, s42
	ds_read_b128 v[194:197], v162 offset:49152
	ds_read_b128 v[198:201], v162 offset:50176
	ds_read_b128 v[202:205], v162 offset:51200
	ds_read_b128 v[206:209], v162 offset:52224
	ds_read_b128 v[210:213], v162 offset:53248
	ds_read_b128 v[214:217], v162 offset:54272
	ds_read_b128 v[218:221], v162 offset:55296
	ds_read_b128 v[222:225], v162 offset:56320
	global_load_lds_dwordx4 v[226:227], off
	s_add_i32 m0, s42, 0x2000
	s_add_u32 s42, s58, 0x80080
	v_lshl_add_u64 v[226:227], v[228:229], 0, s[6:7]
	s_addc_u32 s43, s59, 0
	s_add_i32 s47, s76, s62
	global_load_lds_dwordx4 v[226:227], off
	v_lshl_add_u64 v[226:227], s[42:43], 0, v[130:131]
	s_mov_b32 m0, s47
	s_nop 0
	global_load_lds_dwordx4 v[226:227], off
	v_lshl_add_u64 v[226:227], s[42:43], 0, v[134:135]
	s_add_i32 m0, s47, 0x2000
	s_nop 0
	global_load_lds_dwordx4 v[226:227], off
	v_lshl_add_u64 v[226:227], v[230:231], 0, s[6:7]
	s_mov_b32 m0, s69
	s_nop 0
	global_load_lds_dwordx4 v[226:227], off
	v_lshl_add_u64 v[226:227], v[232:233], 0, s[6:7]
	s_mov_b32 m0, s70
	s_nop 0
	global_load_lds_dwordx4 v[226:227], off
	s_waitcnt vmcnt(8)
	s_waitcnt lgkmcnt(0)
	s_barrier
	s_setprio 1
	s_waitcnt lgkmcnt(0)
	v_mfma_f32_16x16x32_bf16 v[92:95], v[144:147], v[194:197], v[92:95]
	v_mfma_f32_16x16x32_bf16 v[88:91], v[168:171], v[194:197], v[88:91]
	v_mfma_f32_16x16x32_bf16 v[80:83], v[168:171], v[202:205], v[80:83]
	v_mfma_f32_16x16x32_bf16 v[84:87], v[144:147], v[202:205], v[84:87]
	v_mfma_f32_16x16x32_bf16 v[76:79], v[144:147], v[210:213], v[76:79]
	v_mfma_f32_16x16x32_bf16 v[72:75], v[168:171], v[210:213], v[72:75]
	v_mfma_f32_16x16x32_bf16 v[64:67], v[168:171], v[218:221], v[64:67]
	v_mfma_f32_16x16x32_bf16 v[68:71], v[144:147], v[218:221], v[68:71]
	v_mfma_f32_16x16x32_bf16 v[92:95], v[164:167], v[198:201], v[92:95]
	v_mfma_f32_16x16x32_bf16 v[88:91], v[172:175], v[198:201], v[88:91]
	v_mfma_f32_16x16x32_bf16 v[80:83], v[172:175], v[206:209], v[80:83]
	v_mfma_f32_16x16x32_bf16 v[84:87], v[164:167], v[206:209], v[84:87]
	v_mfma_f32_16x16x32_bf16 v[76:79], v[164:167], v[214:217], v[76:79]
	v_mfma_f32_16x16x32_bf16 v[72:75], v[172:175], v[214:217], v[72:75]
	v_mfma_f32_16x16x32_bf16 v[64:67], v[172:175], v[222:225], v[64:67]
	v_mfma_f32_16x16x32_bf16 v[68:71], v[164:167], v[222:225], v[68:71]
	s_setprio 0
	s_setprio 1
	v_mfma_f32_16x16x32_bf16 v[28:31], v[176:179], v[194:197], v[28:31]
	v_mfma_f32_16x16x32_bf16 v[24:27], v[186:189], v[194:197], v[24:27]
	v_mfma_f32_16x16x32_bf16 v[16:19], v[186:189], v[202:205], v[16:19]
	v_mfma_f32_16x16x32_bf16 v[20:23], v[176:179], v[202:205], v[20:23]
	v_mfma_f32_16x16x32_bf16 v[12:15], v[176:179], v[210:213], v[12:15]
	v_mfma_f32_16x16x32_bf16 v[8:11], v[186:189], v[210:213], v[8:11]
	v_mfma_f32_16x16x32_bf16 v[0:3], v[186:189], v[218:221], v[0:3]
	v_mfma_f32_16x16x32_bf16 v[4:7], v[176:179], v[218:221], v[4:7]
	v_mfma_f32_16x16x32_bf16 v[28:31], v[180:183], v[198:201], v[28:31]
	v_mfma_f32_16x16x32_bf16 v[24:27], v[190:193], v[198:201], v[24:27]
	v_mfma_f32_16x16x32_bf16 v[16:19], v[190:193], v[206:209], v[16:19]
	v_mfma_f32_16x16x32_bf16 v[20:23], v[180:183], v[206:209], v[20:23]
	v_mfma_f32_16x16x32_bf16 v[12:15], v[180:183], v[214:217], v[12:15]
	v_mfma_f32_16x16x32_bf16 v[8:11], v[190:193], v[214:217], v[8:11]
	v_mfma_f32_16x16x32_bf16 v[0:3], v[190:193], v[222:225], v[0:3]
	v_mfma_f32_16x16x32_bf16 v[4:7], v[180:183], v[222:225], v[4:7]
	s_setprio 0
	s_barrier
	s_add_i32 s35, s35, 2
	s_add_u32 s52, s52, 0x100
	s_addc_u32 s53, s53, 0
	s_add_u32 s33, s33, 0x100
	s_addc_u32 s34, s34, 0
	s_cmp_gt_u32 s35, 29
	s_cbranch_scc0 .LBB0_507
	s_and_b64 vcc, exec, s[8:9]
	s_cbranch_vccz .LBB0_510
	s_barrier

; #define PG8_STAGE(bufoff, gbase, voff) do { _Pragma("unroll") for (int _i = 0; _i < 2; ++_i) \
;         __builtin_amdgcn_global_load_lds((const unsigned*)((const char*)(gbase) + (voff)[_i]), (LAS unsigned*)(lds + (bufoff) + ldsw + _i * 8192), 16, 0, 0); } while (0)
; #define PG8_LDA(dst, b, h) do { _Pragma("unroll") for (int m = 0; m < 4; ++m) _Pragma("unroll") for (int k = 0; k < 2; ++k) dst[m][k] = *(const LAS bf16x8*)(lds + PG8_SA(b, h) + aoff + m * 2048 + k * 1024); } while (0)
; #define PG8_LDB(dst, b, h) do { _Pragma("unroll") for (int n = 0; n < 2; ++n) _Pragma("unroll") for (int k = 0; k < 2; ++k) dst[n][k] = *(const LAS bf16x8*)(lds + PG8_SB(b, h) + boff + n * 2048 + k * 1024); } while (0)
; #define PG8_MMA(ai, bj, At, Bt) do { __builtin_amdgcn_s_setprio(1); _Pragma("unroll") for (int m = 0; m < 4; ++m) _Pragma("unroll") for (int n = 0; n < 2; ++n) _Pragma("unroll") for (int k = 0; k < 2; ++k) \
;         acc[ai][bj][m][n] = __builtin_amdgcn_mfma_f32_16x16x32_bf16(Bt[n][k], At[m][k], acc[ai][bj][m][n], 0, 0, 0); __builtin_amdgcn_s_setprio(0); } while (0)
; #define PG8_WAIT_V(n) asm volatile("s_waitcnt vmcnt(" #n ")" ::: "memory")
; #define PG8_WAIT_L(n) asm volatile("s_waitcnt lgkmcnt(" #n ")" ::: "memory")
; #define PG8_BAR __builtin_amdgcn_s_barrier()
; #define PG8_SCHED __builtin_amdgcn_sched_barrier(0)
; template <class Epi, bool ALIGN_EPI = PG8_ALIGN>
; __device__ __forceinline__ void gemm_phase(LAS unsigned char* lds, const Gemm g, const StaticOrder S, const Epi E) {
;     ...
;             PG8_LDB(B0, 0, 0); PG8_LDB(B1, 0, 1); PG8_SCHED; PG8_LDA(At, 0, 0); PG8_STAGE(PG8_SA(1, 1), a1 + hstepA, voffA);
;             PG8_WAIT_V(8); PG8_WAIT_L(0); PG8_BAR; PG8_MMA(0, 0, At, B0); PG8_MMA(0, 1, At, B1); PG8_BAR; PG8_SCHED;
;             PG8_LDA(At, 0, 1); PG8_STAGE(PG8_SB(0, 0), b2, voffB); PG8_STAGE(PG8_SB(0, 1), b2 + hstepB, voffB); PG8_STAGE(PG8_SA(0, 0), a2, voffA);
;             PG8_WAIT_V(8); PG8_WAIT_L(0); PG8_BAR; PG8_MMA(1, 0, At, B0); PG8_MMA(1, 1, At, B1); PG8_BAR; PG8_SCHED;
.LBB0_531:
	ds_read_b128 v[146:149], v161
	ds_read_b128 v[150:153], v161 offset:1024
	ds_read_b128 v[154:157], v161 offset:2048
	ds_read_b128 v[164:167], v161 offset:3072
	ds_read_b128 v[168:171], v162
	ds_read_b128 v[172:175], v162 offset:1024
	ds_read_b128 v[176:179], v162 offset:2048
	ds_read_b128 v[180:183], v162 offset:3072
	s_add_u32 s42, s12, 0xfff80080
	s_addc_u32 s43, s13, -1
	s_cmp_eq_u32 vcc_lo, 28
	s_cselect_b32 s67, s14, s43
	s_cselect_b32 s66, s59, s42
	s_cselect_b32 s65, s53, s97
	s_cselect_b32 s64, s93, s95
	v_lshl_add_u64 v[218:219], s[12:13], 0, v[138:139]
	s_add_i32 m0, s34, 0xc000
	ds_read_b128 v[186:189], v163
	ds_read_b128 v[190:193], v163 offset:1024
	ds_read_b128 v[194:197], v163 offset:2048
	ds_read_b128 v[198:201], v163 offset:3072
	ds_read_b128 v[202:205], v163 offset:4096
	ds_read_b128 v[206:209], v163 offset:5120
	ds_read_b128 v[210:213], v163 offset:6144
	ds_read_b128 v[214:217], v163 offset:7168
	global_load_lds_dwordx4 v[218:219], off
	v_lshl_add_u64 v[218:219], s[12:13], 0, v[140:141]
	s_add_i32 m0, s34, 0xe000
	s_nop 0
	global_load_lds_dwordx4 v[218:219], off
	s_waitcnt vmcnt(8)
	s_waitcnt lgkmcnt(0)
	s_barrier
	s_setprio 1
	s_waitcnt lgkmcnt(0)
	v_mfma_f32_16x16x32_bf16 v[124:127], v[146:149], v[186:189], v[124:127]
	v_mfma_f32_16x16x32_bf16 v[120:123], v[154:157], v[186:189], v[120:123]
	v_mfma_f32_16x16x32_bf16 v[112:115], v[154:157], v[194:197], v[112:115]
	v_mfma_f32_16x16x32_bf16 v[116:119], v[146:149], v[194:197], v[116:119]
	v_mfma_f32_16x16x32_bf16 v[108:111], v[146:149], v[202:205], v[108:111]
	v_mfma_f32_16x16x32_bf16 v[104:107], v[154:157], v[202:205], v[104:107]
	v_mfma_f32_16x16x32_bf16 v[96:99], v[154:157], v[210:213], v[96:99]
	v_mfma_f32_16x16x32_bf16 v[100:103], v[146:149], v[210:213], v[100:103]
	v_mfma_f32_16x16x32_bf16 v[124:127], v[150:153], v[190:193], v[124:127]
	v_mfma_f32_16x16x32_bf16 v[120:123], v[164:167], v[190:193], v[120:123]
	v_mfma_f32_16x16x32_bf16 v[112:115], v[164:167], v[198:201], v[112:115]
	v_mfma_f32_16x16x32_bf16 v[116:119], v[150:153], v[198:201], v[116:119]
	v_mfma_f32_16x16x32_bf16 v[108:111], v[150:153], v[206:209], v[108:111]
	v_mfma_f32_16x16x32_bf16 v[104:107], v[164:167], v[206:209], v[104:107]
	v_mfma_f32_16x16x32_bf16 v[96:99], v[164:167], v[214:217], v[96:99]
	v_mfma_f32_16x16x32_bf16 v[100:103], v[150:153], v[214:217], v[100:103]
	s_setprio 0
	s_setprio 1
	v_mfma_f32_16x16x32_bf16 v[60:63], v[168:171], v[186:189], v[60:63]
	v_mfma_f32_16x16x32_bf16 v[56:59], v[176:179], v[186:189], v[56:59]
	v_mfma_f32_16x16x32_bf16 v[48:51], v[176:179], v[194:197], v[48:51]
	v_mfma_f32_16x16x32_bf16 v[52:55], v[168:171], v[194:197], v[52:55]
	v_mfma_f32_16x16x32_bf16 v[44:47], v[168:171], v[202:205], v[44:47]
	v_mfma_f32_16x16x32_bf16 v[40:43], v[176:179], v[202:205], v[40:43]
	v_mfma_f32_16x16x32_bf16 v[32:35], v[176:179], v[210:213], v[32:35]
	v_mfma_f32_16x16x32_bf16 v[36:39], v[168:171], v[210:213], v[36:39]
	v_mfma_f32_16x16x32_bf16 v[60:63], v[172:175], v[190:193], v[60:63]
	v_mfma_f32_16x16x32_bf16 v[56:59], v[180:183], v[190:193], v[56:59]
	v_mfma_f32_16x16x32_bf16 v[48:51], v[180:183], v[198:201], v[48:51]
	v_mfma_f32_16x16x32_bf16 v[52:55], v[172:175], v[198:201], v[52:55]
	v_mfma_f32_16x16x32_bf16 v[44:47], v[172:175], v[206:209], v[44:47]
	v_mfma_f32_16x16x32_bf16 v[40:43], v[180:183], v[206:209], v[40:43]
	v_mfma_f32_16x16x32_bf16 v[32:35], v[180:183], v[214:217], v[32:35]
	v_mfma_f32_16x16x32_bf16 v[36:39], v[172:175], v[214:217], v[36:39]
	s_setprio 0
	s_barrier
	s_add_i32 s42, s79, s33
	v_lshl_add_u64 v[218:219], s[64:65], 0, v[130:131]
	s_mov_b32 m0, s42
	ds_read_b128 v[186:189], v163 offset:16384
	ds_read_b128 v[190:193], v163 offset:17408
	ds_read_b128 v[194:197], v163 offset:18432
	ds_read_b128 v[198:201], v163 offset:19456
	ds_read_b128 v[202:205], v163 offset:20480
	ds_read_b128 v[206:209], v163 offset:21504
	ds_read_b128 v[210:213], v163 offset:22528
	ds_read_b128 v[214:217], v163 offset:23552
	global_load_lds_dwordx4 v[218:219], off
	s_add_i32 m0, s42, 0x2000
	s_add_u32 s42, s64, 0x80000
	v_lshl_add_u64 v[220:221], s[64:65], 0, v[134:135]
	s_addc_u32 s43, s65, 0
	s_add_i32 s84, s81, s33
	global_load_lds_dwordx4 v[220:221], off
	v_lshl_add_u64 v[222:223], s[42:43], 0, v[130:131]
	s_mov_b32 m0, s84
	v_lshl_add_u64 v[224:225], s[66:67], 0, v[132:133]
	global_load_lds_dwordx4 v[222:223], off
	v_lshl_add_u64 v[222:223], s[42:43], 0, v[134:135]
	s_add_i32 m0, s84, 0x2000
	s_nop 0
	global_load_lds_dwordx4 v[222:223], off
	v_lshl_add_u64 v[222:223], s[66:67], 0, v[128:129]
	s_mov_b32 m0, s34
	s_nop 0
	global_load_lds_dwordx4 v[222:223], off
	s_mov_b32 m0, s35
	s_nop 0
	global_load_lds_dwordx4 v[224:225], off
	s_waitcnt vmcnt(8)
	s_waitcnt lgkmcnt(0)
	s_barrier
; #define PG8_STAGE(bufoff, gbase, voff) do { _Pragma("unroll") for (int _i = 0; _i < 2; ++_i) \
;         __builtin_amdgcn_global_load_lds((const unsigned*)((const char*)(gbase) + (voff)[_i]), (LAS unsigned*)(lds + (bufoff) + ldsw + _i * 8192), 16, 0, 0); } while (0)
; #define PG8_LDA(dst, b, h) do { _Pragma("unroll") for (int m = 0; m < 4; ++m) _Pragma("unroll") for (int k = 0; k < 2; ++k) dst[m][k] = *(const LAS bf16x8*)(lds + PG8_SA(b, h) + aoff + m * 2048 + k * 1024); } while (0)
; #define PG8_LDB(dst, b, h) do { _Pragma("unroll") for (int n = 0; n < 2; ++n) _Pragma("unroll") for (int k = 0; k < 2; ++k) dst[n][k] = *(const LAS bf16x8*)(lds + PG8_SB(b, h) + boff + n * 2048 + k * 1024); } while (0)
; #define PG8_MMA(ai, bj, At, Bt) do { __builtin_amdgcn_s_setprio(1); _Pragma("unroll") for (int m = 0; m < 4; ++m) _Pragma("unroll") for (int n = 0; n < 2; ++n) _Pragma("unroll") for (int k = 0; k < 2; ++k) \
;         acc[ai][bj][m][n] = __builtin_amdgcn_mfma_f32_16x16x32_bf16(Bt[n][k], At[m][k], acc[ai][bj][m][n], 0, 0, 0); __builtin_amdgcn_s_setprio(0); } while (0)
; #define PG8_WAIT_V(n) asm volatile("s_waitcnt vmcnt(" #n ")" ::: "memory")
; #define PG8_WAIT_L(n) asm volatile("s_waitcnt lgkmcnt(" #n ")" ::: "memory")
; #define PG8_BAR __builtin_amdgcn_s_barrier()
; #define PG8_SCHED __builtin_amdgcn_sched_barrier(0)
; template <class Epi, bool ALIGN_EPI = PG8_ALIGN>
; __device__ __forceinline__ void gemm_phase(LAS unsigned char* lds, const Gemm g, const StaticOrder S, const Epi E) {
;     ...
;             PG8_WAIT_V(8); PG8_WAIT_L(0); PG8_BAR; PG8_MMA(1, 0, At, B0); PG8_MMA(1, 1, At, B1); PG8_BAR; PG8_SCHED;
;             PG8_LDB(B0, 1, 0); PG8_LDB(B1, 1, 1); PG8_SCHED; PG8_LDA(At, 1, 0); PG8_STAGE(PG8_SA(0, 1), a2 + hstepA, voffA);
;             PG8_WAIT_V(8); PG8_WAIT_L(0); PG8_BAR; PG8_MMA(0, 0, At, B0); PG8_MMA(0, 1, At, B1); PG8_BAR; PG8_SCHED;
	s_setprio 1
	s_waitcnt lgkmcnt(0)
	v_mfma_f32_16x16x32_bf16 v[92:95], v[146:149], v[186:189], v[92:95]
	v_mfma_f32_16x16x32_bf16 v[88:91], v[154:157], v[186:189], v[88:91]
	v_mfma_f32_16x16x32_bf16 v[80:83], v[154:157], v[194:197], v[80:83]
	v_mfma_f32_16x16x32_bf16 v[84:87], v[146:149], v[194:197], v[84:87]
	v_mfma_f32_16x16x32_bf16 v[76:79], v[146:149], v[202:205], v[76:79]
	v_mfma_f32_16x16x32_bf16 v[72:75], v[154:157], v[202:205], v[72:75]
	v_mfma_f32_16x16x32_bf16 v[64:67], v[154:157], v[210:213], v[64:67]
	v_mfma_f32_16x16x32_bf16 v[68:71], v[146:149], v[210:213], v[68:71]
	v_mfma_f32_16x16x32_bf16 v[92:95], v[150:153], v[190:193], v[92:95]
	v_mfma_f32_16x16x32_bf16 v[88:91], v[164:167], v[190:193], v[88:91]
	v_mfma_f32_16x16x32_bf16 v[80:83], v[164:167], v[198:201], v[80:83]
	v_mfma_f32_16x16x32_bf16 v[84:87], v[150:153], v[198:201], v[84:87]
	v_mfma_f32_16x16x32_bf16 v[76:79], v[150:153], v[206:209], v[76:79]
	v_mfma_f32_16x16x32_bf16 v[72:75], v[164:167], v[206:209], v[72:75]
	v_mfma_f32_16x16x32_bf16 v[64:67], v[164:167], v[214:217], v[64:67]
	v_mfma_f32_16x16x32_bf16 v[68:71], v[150:153], v[214:217], v[68:71]
	s_setprio 0
	s_setprio 1
	v_mfma_f32_16x16x32_bf16 v[28:31], v[168:171], v[186:189], v[28:31]
	v_mfma_f32_16x16x32_bf16 v[24:27], v[176:179], v[186:189], v[24:27]
	v_mfma_f32_16x16x32_bf16 v[16:19], v[176:179], v[194:197], v[16:19]
	v_mfma_f32_16x16x32_bf16 v[20:23], v[168:171], v[194:197], v[20:23]
	v_mfma_f32_16x16x32_bf16 v[12:15], v[168:171], v[202:205], v[12:15]
	v_mfma_f32_16x16x32_bf16 v[8:11], v[176:179], v[202:205], v[8:11]
	v_mfma_f32_16x16x32_bf16 v[0:3], v[176:179], v[210:213], v[0:3]
	v_mfma_f32_16x16x32_bf16 v[4:7], v[168:171], v[210:213], v[4:7]
	v_mfma_f32_16x16x32_bf16 v[28:31], v[172:175], v[190:193], v[28:31]
	v_mfma_f32_16x16x32_bf16 v[24:27], v[180:183], v[190:193], v[24:27]
	v_mfma_f32_16x16x32_bf16 v[16:19], v[180:183], v[198:201], v[16:19]
	v_mfma_f32_16x16x32_bf16 v[20:23], v[172:175], v[198:201], v[20:23]
	v_mfma_f32_16x16x32_bf16 v[12:15], v[172:175], v[206:209], v[12:15]
	v_mfma_f32_16x16x32_bf16 v[8:11], v[180:183], v[206:209], v[8:11]
	v_mfma_f32_16x16x32_bf16 v[0:3], v[180:183], v[214:217], v[0:3]
	v_mfma_f32_16x16x32_bf16 v[4:7], v[172:175], v[214:217], v[4:7]
	s_setprio 0
	s_barrier
	s_add_i32 s84, 0, 0x18000
	s_add_i32 s85, 0, 0x1c000
	v_add_u32_e32 v164, s84, v160
	v_add_u32_e32 v180, s85, v160
	ds_read_b128 v[146:149], v164
	ds_read_b128 v[150:153], v164 offset:1024
	ds_read_b128 v[154:157], v164 offset:2048
	ds_read_b128 v[164:167], v164 offset:3072
	ds_read_b128 v[168:171], v180
	ds_read_b128 v[172:175], v180 offset:1024
	ds_read_b128 v[176:179], v180 offset:2048
	ds_read_b128 v[180:183], v180 offset:3072
	s_add_u32 s42, s66, 0x80000
	s_addc_u32 s43, s67, 0
	s_mov_b32 m0, s49
	v_lshl_add_u64 v[226:227], s[42:43], 0, v[128:129]
	ds_read_b128 v[186:189], v163 offset:32768
	ds_read_b128 v[190:193], v163 offset:33792
	ds_read_b128 v[194:197], v163 offset:34816
	ds_read_b128 v[198:201], v163 offset:35840
	ds_read_b128 v[202:205], v163 offset:36864
	ds_read_b128 v[206:209], v163 offset:37888
	ds_read_b128 v[210:213], v163 offset:38912
	ds_read_b128 v[214:217], v163 offset:39936
	global_load_lds_dwordx4 v[226:227], off
	v_lshl_add_u64 v[226:227], s[42:43], 0, v[132:133]
	s_mov_b32 m0, s51
	s_nop 0
	global_load_lds_dwordx4 v[226:227], off
	s_waitcnt vmcnt(8)
	s_waitcnt lgkmcnt(0)
	s_barrier
	s_setprio 1
	s_waitcnt lgkmcnt(0)
	v_mfma_f32_16x16x32_bf16 v[124:127], v[146:149], v[186:189], v[124:127]
	v_mfma_f32_16x16x32_bf16 v[120:123], v[154:157], v[186:189], v[120:123]
	v_mfma_f32_16x16x32_bf16 v[112:115], v[154:157], v[194:197], v[112:115]
	v_mfma_f32_16x16x32_bf16 v[116:119], v[146:149], v[194:197], v[116:119]
	v_mfma_f32_16x16x32_bf16 v[108:111], v[146:149], v[202:205], v[108:111]
	v_mfma_f32_16x16x32_bf16 v[104:107], v[154:157], v[202:205], v[104:107]
	v_mfma_f32_16x16x32_bf16 v[96:99], v[154:157], v[210:213], v[96:99]
	v_mfma_f32_16x16x32_bf16 v[100:103], v[146:149], v[210:213], v[100:103]
	v_mfma_f32_16x16x32_bf16 v[124:127], v[150:153], v[190:193], v[124:127]
	v_mfma_f32_16x16x32_bf16 v[120:123], v[164:167], v[190:193], v[120:123]
	v_mfma_f32_16x16x32_bf16 v[112:115], v[164:167], v[198:201], v[112:115]
	v_mfma_f32_16x16x32_bf16 v[116:119], v[150:153], v[198:201], v[116:119]
	v_mfma_f32_16x16x32_bf16 v[108:111], v[150:153], v[206:209], v[108:111]
	v_mfma_f32_16x16x32_bf16 v[104:107], v[164:167], v[206:209], v[104:107]
	v_mfma_f32_16x16x32_bf16 v[96:99], v[164:167], v[214:217], v[96:99]
	v_mfma_f32_16x16x32_bf16 v[100:103], v[150:153], v[214:217], v[100:103]
	s_setprio 0
	s_setprio 1
	v_mfma_f32_16x16x32_bf16 v[60:63], v[168:171], v[186:189], v[60:63]
	v_mfma_f32_16x16x32_bf16 v[56:59], v[176:179], v[186:189], v[56:59]
	v_mfma_f32_16x16x32_bf16 v[48:51], v[176:179], v[194:197], v[48:51]
	v_mfma_f32_16x16x32_bf16 v[52:55], v[168:171], v[194:197], v[52:55]
	v_mfma_f32_16x16x32_bf16 v[44:47], v[168:171], v[202:205], v[44:47]
	v_mfma_f32_16x16x32_bf16 v[40:43], v[176:179], v[202:205], v[40:43]
	v_mfma_f32_16x16x32_bf16 v[32:35], v[176:179], v[210:213], v[32:35]
	v_mfma_f32_16x16x32_bf16 v[36:39], v[168:171], v[210:213], v[36:39]
	v_mfma_f32_16x16x32_bf16 v[60:63], v[172:175], v[190:193], v[60:63]
	v_mfma_f32_16x16x32_bf16 v[56:59], v[180:183], v[190:193], v[56:59]
	v_mfma_f32_16x16x32_bf16 v[48:51], v[180:183], v[198:201], v[48:51]
	v_mfma_f32_16x16x32_bf16 v[52:55], v[172:175], v[198:201], v[52:55]
	v_mfma_f32_16x16x32_bf16 v[44:47], v[172:175], v[206:209], v[44:47]
	v_mfma_f32_16x16x32_bf16 v[40:43], v[180:183], v[206:209], v[40:43]
	v_mfma_f32_16x16x32_bf16 v[32:35], v[180:183], v[214:217], v[32:35]
	v_mfma_f32_16x16x32_bf16 v[36:39], v[172:175], v[214:217], v[36:39]
	s_setprio 0
	s_barrier
; #define PG8_STAGE(bufoff, gbase, voff) do { _Pragma("unroll") for (int _i = 0; _i < 2; ++_i) \
;         __builtin_amdgcn_global_load_lds((const unsigned*)((const char*)(gbase) + (voff)[_i]), (LAS unsigned*)(lds + (bufoff) + ldsw + _i * 8192), 16, 0, 0); } while (0)
; #define PG8_LDA(dst, b, h) do { _Pragma("unroll") for (int m = 0; m < 4; ++m) _Pragma("unroll") for (int k = 0; k < 2; ++k) dst[m][k] = *(const LAS bf16x8*)(lds + PG8_SA(b, h) + aoff + m * 2048 + k * 1024); } while (0)
; #define PG8_MMA(ai, bj, At, Bt) do { __builtin_amdgcn_s_setprio(1); _Pragma("unroll") for (int m = 0; m < 4; ++m) _Pragma("unroll") for (int n = 0; n < 2; ++n) _Pragma("unroll") for (int k = 0; k < 2; ++k) \
;         acc[ai][bj][m][n] = __builtin_amdgcn_mfma_f32_16x16x32_bf16(Bt[n][k], At[m][k], acc[ai][bj][m][n], 0, 0, 0); __builtin_amdgcn_s_setprio(0); } while (0)
; #define PG8_WAIT_V(n) asm volatile("s_waitcnt vmcnt(" #n ")" ::: "memory")
; #define PG8_WAIT_L(n) asm volatile("s_waitcnt lgkmcnt(" #n ")" ::: "memory")
; #define PG8_BAR __builtin_amdgcn_s_barrier()
; #define PG8_SCHED __builtin_amdgcn_sched_barrier(0)
; template <class Epi, bool ALIGN_EPI = PG8_ALIGN>
; __device__ __forceinline__ void gemm_phase(LAS unsigned char* lds, const Gemm g, const StaticOrder S, const Epi E) {
;     ...
;             PG8_LDA(At, 1, 1); PG8_STAGE(PG8_SB(1, 0), b3, voffB); PG8_STAGE(PG8_SB(1, 1), b3 + hstepB, voffB); PG8_STAGE(PG8_SA(1, 0), a3, voffA);
;             PG8_WAIT_V(8); PG8_WAIT_L(0); PG8_BAR; PG8_MMA(1, 0, At, B0); PG8_MMA(1, 1, At, B1); PG8_BAR; PG8_SCHED;
;         }
;         if (ALIGN_EPI) { if (wr == 0) PG8_BAR; }
	s_add_i32 s42, s84, s33
	v_lshl_add_u64 v[218:219], v[218:219], 0, s[10:11]
	s_mov_b32 m0, s42
	ds_read_b128 v[186:189], v163 offset:49152
	ds_read_b128 v[190:193], v163 offset:50176
	ds_read_b128 v[194:197], v163 offset:51200
	ds_read_b128 v[198:201], v163 offset:52224
	ds_read_b128 v[202:205], v163 offset:53248
	ds_read_b128 v[206:209], v163 offset:54272
	ds_read_b128 v[210:213], v163 offset:55296
	ds_read_b128 v[214:217], v163 offset:56320
	global_load_lds_dwordx4 v[218:219], off
	s_add_i32 m0, s42, 0x2000
	s_add_u32 s42, s64, 0x80080
	v_lshl_add_u64 v[218:219], v[220:221], 0, s[10:11]
	s_addc_u32 s43, s65, 0
	s_add_i32 s64, s85, s33
	global_load_lds_dwordx4 v[218:219], off
	v_lshl_add_u64 v[218:219], s[42:43], 0, v[130:131]
	s_mov_b32 m0, s64
	s_nop 0
	global_load_lds_dwordx4 v[218:219], off
	v_lshl_add_u64 v[218:219], s[42:43], 0, v[134:135]
	s_add_i32 m0, s64, 0x2000
	s_nop 0
	global_load_lds_dwordx4 v[218:219], off
	v_lshl_add_u64 v[218:219], v[222:223], 0, s[10:11]
	s_mov_b32 m0, s71
	s_nop 0
	global_load_lds_dwordx4 v[218:219], off
	v_lshl_add_u64 v[218:219], v[224:225], 0, s[10:11]
	s_mov_b32 m0, s72
	s_nop 0
	global_load_lds_dwordx4 v[218:219], off
	s_waitcnt vmcnt(8)
	s_waitcnt lgkmcnt(0)
	s_barrier
	s_setprio 1
	s_waitcnt lgkmcnt(0)
	v_mfma_f32_16x16x32_bf16 v[92:95], v[146:149], v[186:189], v[92:95]
	v_mfma_f32_16x16x32_bf16 v[88:91], v[154:157], v[186:189], v[88:91]
	v_mfma_f32_16x16x32_bf16 v[80:83], v[154:157], v[194:197], v[80:83]
	v_mfma_f32_16x16x32_bf16 v[84:87], v[146:149], v[194:197], v[84:87]
	v_mfma_f32_16x16x32_bf16 v[76:79], v[146:149], v[202:205], v[76:79]
	v_mfma_f32_16x16x32_bf16 v[72:75], v[154:157], v[202:205], v[72:75]
	v_mfma_f32_16x16x32_bf16 v[64:67], v[154:157], v[210:213], v[64:67]
	v_mfma_f32_16x16x32_bf16 v[68:71], v[146:149], v[210:213], v[68:71]
	v_mfma_f32_16x16x32_bf16 v[92:95], v[150:153], v[190:193], v[92:95]
	v_mfma_f32_16x16x32_bf16 v[88:91], v[164:167], v[190:193], v[88:91]
	v_mfma_f32_16x16x32_bf16 v[80:83], v[164:167], v[198:201], v[80:83]
	v_mfma_f32_16x16x32_bf16 v[84:87], v[150:153], v[198:201], v[84:87]
	v_mfma_f32_16x16x32_bf16 v[76:79], v[150:153], v[206:209], v[76:79]
	v_mfma_f32_16x16x32_bf16 v[72:75], v[164:167], v[206:209], v[72:75]
	v_mfma_f32_16x16x32_bf16 v[64:67], v[164:167], v[214:217], v[64:67]
	v_mfma_f32_16x16x32_bf16 v[68:71], v[150:153], v[214:217], v[68:71]
	s_setprio 0
	s_setprio 1
	v_mfma_f32_16x16x32_bf16 v[28:31], v[168:171], v[186:189], v[28:31]
	v_mfma_f32_16x16x32_bf16 v[24:27], v[176:179], v[186:189], v[24:27]
	v_mfma_f32_16x16x32_bf16 v[16:19], v[176:179], v[194:197], v[16:19]
	v_mfma_f32_16x16x32_bf16 v[20:23], v[168:171], v[194:197], v[20:23]
	v_mfma_f32_16x16x32_bf16 v[12:15], v[168:171], v[202:205], v[12:15]
	v_mfma_f32_16x16x32_bf16 v[8:11], v[176:179], v[202:205], v[8:11]
	v_mfma_f32_16x16x32_bf16 v[0:3], v[176:179], v[210:213], v[0:3]
	v_mfma_f32_16x16x32_bf16 v[4:7], v[168:171], v[210:213], v[4:7]
	v_mfma_f32_16x16x32_bf16 v[28:31], v[172:175], v[190:193], v[28:31]
	v_mfma_f32_16x16x32_bf16 v[24:27], v[180:183], v[190:193], v[24:27]
	v_mfma_f32_16x16x32_bf16 v[16:19], v[180:183], v[198:201], v[16:19]
	v_mfma_f32_16x16x32_bf16 v[20:23], v[172:175], v[198:201], v[20:23]
	v_mfma_f32_16x16x32_bf16 v[12:15], v[172:175], v[206:209], v[12:15]
	v_mfma_f32_16x16x32_bf16 v[8:11], v[180:183], v[206:209], v[8:11]
	v_mfma_f32_16x16x32_bf16 v[0:3], v[180:183], v[214:217], v[0:3]
	v_mfma_f32_16x16x32_bf16 v[4:7], v[172:175], v[214:217], v[4:7]
	s_setprio 0
	s_barrier
	s_add_i32 vcc_lo, vcc_lo, 2
	s_add_u32 s12, s12, 0x100
	s_addc_u32 s13, s13, 0
	s_add_u32 s95, s95, 0x100
	s_addc_u32 s97, s97, 0
	s_cmp_gt_u32 vcc_lo, 29
	s_cbranch_scc0 .LBB0_531
	s_and_b64 vcc, exec, s[46:47]
	s_cbranch_vccz .LBB0_534
	s_barrier

; #define PG8_STAGE(bufoff, gbase, voff) do { _Pragma("unroll") for (int _i = 0; _i < 2; ++_i) \
;         __builtin_amdgcn_global_load_lds((const unsigned*)((const char*)(gbase) + (voff)[_i]), (LAS unsigned*)(lds + (bufoff) + ldsw + _i * 8192), 16, 0, 0); } while (0)
; #define PG8_LDA(dst, b, h) do { _Pragma("unroll") for (int m = 0; m < 4; ++m) _Pragma("unroll") for (int k = 0; k < 2; ++k) dst[m][k] = *(const LAS bf16x8*)(lds + PG8_SA(b, h) + aoff + m * 2048 + k * 1024); } while (0)
; #define PG8_LDB(dst, b, h) do { _Pragma("unroll") for (int n = 0; n < 2; ++n) _Pragma("unroll") for (int k = 0; k < 2; ++k) dst[n][k] = *(const LAS bf16x8*)(lds + PG8_SB(b, h) + boff + n * 2048 + k * 1024); } while (0)
; #define PG8_MMA(ai, bj, At, Bt) do { __builtin_amdgcn_s_setprio(1); _Pragma("unroll") for (int m = 0; m < 4; ++m) _Pragma("unroll") for (int n = 0; n < 2; ++n) _Pragma("unroll") for (int k = 0; k < 2; ++k) \
;         acc[ai][bj][m][n] = __builtin_amdgcn_mfma_f32_16x16x32_bf16(Bt[n][k], At[m][k], acc[ai][bj][m][n], 0, 0, 0); __builtin_amdgcn_s_setprio(0); } while (0)
; #define PG8_WAIT_V(n) asm volatile("s_waitcnt vmcnt(" #n ")" ::: "memory")
; #define PG8_WAIT_L(n) asm volatile("s_waitcnt lgkmcnt(" #n ")" ::: "memory")
; #define PG8_BAR __builtin_amdgcn_s_barrier()
; #define PG8_SCHED __builtin_amdgcn_sched_barrier(0)
; template <class Epi, bool ALIGN_EPI = PG8_ALIGN>
; __device__ __forceinline__ void gemm_phase(LAS unsigned char* lds, const Gemm g, const StaticOrder S, const Epi E) {
;     ...
;             const bool last = (t == nt - 2);
;             const char* a1 = cA + (size_t)(t + 1) * kstep;
;             const char* a2 = last ? nA : cA + (size_t)(t + 2) * kstep; const char* b2 = last ? nB : cB + (size_t)(t + 2) * kstep;
;             const char* a3 = a2 + kstep; const char* b3 = b2 + kstep;
;             PG8_LDB(B0, 0, 0); PG8_LDB(B1, 0, 1); PG8_SCHED; PG8_LDA(At, 0, 0); PG8_STAGE(PG8_SA(1, 1), a1 + hstepA, voffA);
;             PG8_WAIT_V(8); PG8_WAIT_L(0); PG8_BAR; PG8_MMA(0, 0, At, B0); PG8_MMA(0, 1, At, B1); PG8_BAR; PG8_SCHED;
;             PG8_LDA(At, 0, 1); PG8_STAGE(PG8_SB(0, 0), b2, voffB); PG8_STAGE(PG8_SB(0, 1), b2 + hstepB, voffB); PG8_STAGE(PG8_SA(0, 0), a2, voffA);
.LBB0_869:
	ds_read_b128 v[160:163], v156
	ds_read_b128 v[164:167], v156 offset:1024
	ds_read_b128 v[168:171], v156 offset:2048
	ds_read_b128 v[172:175], v156 offset:3072
	ds_read_b128 v[176:179], v157
	ds_read_b128 v[180:183], v157 offset:1024
	ds_read_b128 v[186:189], v157 offset:2048
	ds_read_b128 v[190:193], v157 offset:3072
	s_add_u32 s0, s50, 0xfffe0080
	s_addc_u32 s1, s51, -1
	s_cmp_eq_u32 s71, 4
	s_cselect_b32 s55, s29, s1
	s_cselect_b32 s54, s66, s0
	s_cselect_b32 s53, s27, s69
	s_cselect_b32 s52, s67, s68
	v_lshl_add_u64 v[226:227], s[50:51], 0, v[136:137]
	s_add_i32 m0, s25, 0xc000
	ds_read_b128 v[194:197], v158
	ds_read_b128 v[198:201], v158 offset:1024
	ds_read_b128 v[202:205], v158 offset:2048
	ds_read_b128 v[206:209], v158 offset:3072
	ds_read_b128 v[210:213], v158 offset:4096
	ds_read_b128 v[214:217], v158 offset:5120
	ds_read_b128 v[218:221], v158 offset:6144
	ds_read_b128 v[222:225], v158 offset:7168
	global_load_lds_dwordx4 v[226:227], off
	v_lshl_add_u64 v[226:227], s[50:51], 0, v[138:139]
	s_add_i32 m0, s25, 0xe000
	s_nop 0
	global_load_lds_dwordx4 v[226:227], off
	s_waitcnt vmcnt(8)
	s_waitcnt lgkmcnt(0)
	s_barrier
	s_setprio 1
	s_waitcnt lgkmcnt(0)
	v_mfma_f32_16x16x32_bf16 v[124:127], v[160:163], v[194:197], v[124:127]
	v_mfma_f32_16x16x32_bf16 v[120:123], v[168:171], v[194:197], v[120:123]
	v_mfma_f32_16x16x32_bf16 v[112:115], v[168:171], v[202:205], v[112:115]
	v_mfma_f32_16x16x32_bf16 v[116:119], v[160:163], v[202:205], v[116:119]
	v_mfma_f32_16x16x32_bf16 v[108:111], v[160:163], v[210:213], v[108:111]
	v_mfma_f32_16x16x32_bf16 v[104:107], v[168:171], v[210:213], v[104:107]
	v_mfma_f32_16x16x32_bf16 v[96:99], v[168:171], v[218:221], v[96:99]
	v_mfma_f32_16x16x32_bf16 v[100:103], v[160:163], v[218:221], v[100:103]
	v_mfma_f32_16x16x32_bf16 v[124:127], v[164:167], v[198:201], v[124:127]
	v_mfma_f32_16x16x32_bf16 v[120:123], v[172:175], v[198:201], v[120:123]
	v_mfma_f32_16x16x32_bf16 v[112:115], v[172:175], v[206:209], v[112:115]
	v_mfma_f32_16x16x32_bf16 v[116:119], v[164:167], v[206:209], v[116:119]
	v_mfma_f32_16x16x32_bf16 v[108:111], v[164:167], v[214:217], v[108:111]
	v_mfma_f32_16x16x32_bf16 v[104:107], v[172:175], v[214:217], v[104:107]
	v_mfma_f32_16x16x32_bf16 v[96:99], v[172:175], v[222:225], v[96:99]
	v_mfma_f32_16x16x32_bf16 v[100:103], v[164:167], v[222:225], v[100:103]
	s_setprio 0
	s_setprio 1
	v_mfma_f32_16x16x32_bf16 v[84:87], v[176:179], v[194:197], v[84:87]
	v_mfma_f32_16x16x32_bf16 v[76:79], v[186:189], v[194:197], v[76:79]
	v_mfma_f32_16x16x32_bf16 v[64:67], v[186:189], v[202:205], v[64:67]
	v_mfma_f32_16x16x32_bf16 v[68:71], v[176:179], v[202:205], v[68:71]
	v_mfma_f32_16x16x32_bf16 v[52:55], v[176:179], v[210:213], v[52:55]
	v_mfma_f32_16x16x32_bf16 v[48:51], v[186:189], v[210:213], v[48:51]
	v_mfma_f32_16x16x32_bf16 v[32:35], v[186:189], v[218:221], v[32:35]
	v_mfma_f32_16x16x32_bf16 v[40:43], v[176:179], v[218:221], v[40:43]
	v_mfma_f32_16x16x32_bf16 v[84:87], v[180:183], v[198:201], v[84:87]
	v_mfma_f32_16x16x32_bf16 v[76:79], v[190:193], v[198:201], v[76:79]
	v_mfma_f32_16x16x32_bf16 v[64:67], v[190:193], v[206:209], v[64:67]
	v_mfma_f32_16x16x32_bf16 v[68:71], v[180:183], v[206:209], v[68:71]
	v_mfma_f32_16x16x32_bf16 v[52:55], v[180:183], v[214:217], v[52:55]
	v_mfma_f32_16x16x32_bf16 v[48:51], v[190:193], v[214:217], v[48:51]
	v_mfma_f32_16x16x32_bf16 v[32:35], v[190:193], v[222:225], v[32:35]
	v_mfma_f32_16x16x32_bf16 v[40:43], v[180:183], v[222:225], v[40:43]
	s_setprio 0
	s_barrier
	s_add_i32 s0, s62, s14
	v_lshl_add_u64 v[226:227], s[52:53], 0, v[132:133]
	s_mov_b32 m0, s0
	ds_read_b128 v[194:197], v158 offset:16384
	ds_read_b128 v[198:201], v158 offset:17408
	ds_read_b128 v[202:205], v158 offset:18432
	ds_read_b128 v[206:209], v158 offset:19456
	ds_read_b128 v[210:213], v158 offset:20480
	ds_read_b128 v[214:217], v158 offset:21504
	ds_read_b128 v[218:221], v158 offset:22528
	ds_read_b128 v[222:225], v158 offset:23552
	global_load_lds_dwordx4 v[226:227], off
	s_add_i32 m0, s0, 0x2000
	s_add_u32 s0, s52, 0x20000
	v_lshl_add_u64 v[228:229], s[52:53], 0, v[128:129]
	s_addc_u32 s1, s53, 0
	s_add_i32 s42, s63, s14
	global_load_lds_dwordx4 v[228:229], off
	v_lshl_add_u64 v[230:231], s[0:1], 0, v[132:133]
	s_mov_b32 m0, s42
	v_lshl_add_u64 v[232:233], s[54:55], 0, v[130:131]
	global_load_lds_dwordx4 v[230:231], off
	v_lshl_add_u64 v[230:231], s[0:1], 0, v[128:129]
	s_add_i32 m0, s42, 0x2000
	s_nop 0
	global_load_lds_dwordx4 v[230:231], off
	v_lshl_add_u64 v[230:231], s[54:55], 0, v[134:135]
	s_mov_b32 m0, s25
	s_nop 0
	global_load_lds_dwordx4 v[230:231], off
	s_mov_b32 m0, s33
	s_nop 0
	global_load_lds_dwordx4 v[232:233], off
	s_waitcnt vmcnt(8)
	s_waitcnt lgkmcnt(0)
	s_barrier
; #define PG8_STAGE(bufoff, gbase, voff) do { _Pragma("unroll") for (int _i = 0; _i < 2; ++_i) \
;         __builtin_amdgcn_global_load_lds((const unsigned*)((const char*)(gbase) + (voff)[_i]), (LAS unsigned*)(lds + (bufoff) + ldsw + _i * 8192), 16, 0, 0); } while (0)
; #define PG8_LDA(dst, b, h) do { _Pragma("unroll") for (int m = 0; m < 4; ++m) _Pragma("unroll") for (int k = 0; k < 2; ++k) dst[m][k] = *(const LAS bf16x8*)(lds + PG8_SA(b, h) + aoff + m * 2048 + k * 1024); } while (0)
; #define PG8_LDB(dst, b, h) do { _Pragma("unroll") for (int n = 0; n < 2; ++n) _Pragma("unroll") for (int k = 0; k < 2; ++k) dst[n][k] = *(const LAS bf16x8*)(lds + PG8_SB(b, h) + boff + n * 2048 + k * 1024); } while (0)
; #define PG8_MMA(ai, bj, At, Bt) do { __builtin_amdgcn_s_setprio(1); _Pragma("unroll") for (int m = 0; m < 4; ++m) _Pragma("unroll") for (int n = 0; n < 2; ++n) _Pragma("unroll") for (int k = 0; k < 2; ++k) \
;         acc[ai][bj][m][n] = __builtin_amdgcn_mfma_f32_16x16x32_bf16(Bt[n][k], At[m][k], acc[ai][bj][m][n], 0, 0, 0); __builtin_amdgcn_s_setprio(0); } while (0)
; #define PG8_WAIT_V(n) asm volatile("s_waitcnt vmcnt(" #n ")" ::: "memory")
; #define PG8_WAIT_L(n) asm volatile("s_waitcnt lgkmcnt(" #n ")" ::: "memory")
; #define PG8_BAR __builtin_amdgcn_s_barrier()
; #define PG8_SCHED __builtin_amdgcn_sched_barrier(0)
; template <class Epi, bool ALIGN_EPI = PG8_ALIGN>
; __device__ __forceinline__ void gemm_phase(LAS unsigned char* lds, const Gemm g, const StaticOrder S, const Epi E) {
;     ...
;             PG8_WAIT_V(8); PG8_WAIT_L(0); PG8_BAR; PG8_MMA(1, 0, At, B0); PG8_MMA(1, 1, At, B1); PG8_BAR; PG8_SCHED;
;             PG8_LDB(B0, 1, 0); PG8_LDB(B1, 1, 1); PG8_SCHED; PG8_LDA(At, 1, 0); PG8_STAGE(PG8_SA(0, 1), a2 + hstepA, voffA);
;             PG8_WAIT_V(8); PG8_WAIT_L(0); PG8_BAR; PG8_MMA(0, 0, At, B0); PG8_MMA(0, 1, At, B1); PG8_BAR; PG8_SCHED;
	s_setprio 1
	s_waitcnt lgkmcnt(0)
	v_mfma_f32_16x16x32_bf16 v[92:95], v[160:163], v[194:197], v[92:95]
	v_mfma_f32_16x16x32_bf16 v[88:91], v[168:171], v[194:197], v[88:91]
	v_mfma_f32_16x16x32_bf16 v[72:75], v[168:171], v[202:205], v[72:75]
	v_mfma_f32_16x16x32_bf16 v[80:83], v[160:163], v[202:205], v[80:83]
	v_mfma_f32_16x16x32_bf16 v[60:63], v[160:163], v[210:213], v[60:63]
	v_mfma_f32_16x16x32_bf16 v[56:59], v[168:171], v[210:213], v[56:59]
	v_mfma_f32_16x16x32_bf16 v[36:39], v[168:171], v[218:221], v[36:39]
	v_mfma_f32_16x16x32_bf16 v[44:47], v[160:163], v[218:221], v[44:47]
	v_mfma_f32_16x16x32_bf16 v[92:95], v[164:167], v[198:201], v[92:95]
	v_mfma_f32_16x16x32_bf16 v[88:91], v[172:175], v[198:201], v[88:91]
	v_mfma_f32_16x16x32_bf16 v[72:75], v[172:175], v[206:209], v[72:75]
	v_mfma_f32_16x16x32_bf16 v[80:83], v[164:167], v[206:209], v[80:83]
	v_mfma_f32_16x16x32_bf16 v[60:63], v[164:167], v[214:217], v[60:63]
	v_mfma_f32_16x16x32_bf16 v[56:59], v[172:175], v[214:217], v[56:59]
	v_mfma_f32_16x16x32_bf16 v[36:39], v[172:175], v[222:225], v[36:39]
	v_mfma_f32_16x16x32_bf16 v[44:47], v[164:167], v[222:225], v[44:47]
	s_setprio 0
	s_setprio 1
	v_mfma_f32_16x16x32_bf16 v[28:31], v[176:179], v[194:197], v[28:31]
	v_mfma_f32_16x16x32_bf16 v[24:27], v[186:189], v[194:197], v[24:27]
	v_mfma_f32_16x16x32_bf16 v[16:19], v[186:189], v[202:205], v[16:19]
	v_mfma_f32_16x16x32_bf16 v[20:23], v[176:179], v[202:205], v[20:23]
	v_mfma_f32_16x16x32_bf16 v[12:15], v[176:179], v[210:213], v[12:15]
	v_mfma_f32_16x16x32_bf16 v[8:11], v[186:189], v[210:213], v[8:11]
	v_mfma_f32_16x16x32_bf16 v[0:3], v[186:189], v[218:221], v[0:3]
	v_mfma_f32_16x16x32_bf16 v[4:7], v[176:179], v[218:221], v[4:7]
	v_mfma_f32_16x16x32_bf16 v[28:31], v[180:183], v[198:201], v[28:31]
	v_mfma_f32_16x16x32_bf16 v[24:27], v[190:193], v[198:201], v[24:27]
	v_mfma_f32_16x16x32_bf16 v[16:19], v[190:193], v[206:209], v[16:19]
	v_mfma_f32_16x16x32_bf16 v[20:23], v[180:183], v[206:209], v[20:23]
	v_mfma_f32_16x16x32_bf16 v[12:15], v[180:183], v[214:217], v[12:15]
	v_mfma_f32_16x16x32_bf16 v[8:11], v[190:193], v[214:217], v[8:11]
	v_mfma_f32_16x16x32_bf16 v[0:3], v[190:193], v[222:225], v[0:3]
	v_mfma_f32_16x16x32_bf16 v[4:7], v[180:183], v[222:225], v[4:7]
	s_setprio 0
	s_barrier
	s_add_i32 s42, 0, 0x18000
	v_add_u32_e32 v159, s42, v154
	s_add_i32 s43, 0, 0x1c000
	ds_read_b128 v[160:163], v159
	ds_read_b128 v[164:167], v159 offset:1024
	ds_read_b128 v[168:171], v159 offset:2048
	ds_read_b128 v[172:175], v159 offset:3072
	v_add_u32_e32 v159, s43, v154
	ds_read_b128 v[176:179], v159
	ds_read_b128 v[180:183], v159 offset:1024
	ds_read_b128 v[186:189], v159 offset:2048
	ds_read_b128 v[190:193], v159 offset:3072
	s_add_u32 s0, s54, 0x20000
	s_addc_u32 s1, s55, 0
	s_mov_b32 m0, s34
	v_lshl_add_u64 v[234:235], s[0:1], 0, v[134:135]
	ds_read_b128 v[194:197], v158 offset:32768
	ds_read_b128 v[198:201], v158 offset:33792
	ds_read_b128 v[202:205], v158 offset:34816
	ds_read_b128 v[206:209], v158 offset:35840
	ds_read_b128 v[210:213], v158 offset:36864
	ds_read_b128 v[214:217], v158 offset:37888
	ds_read_b128 v[218:221], v158 offset:38912
	ds_read_b128 v[222:225], v158 offset:39936
	global_load_lds_dwordx4 v[234:235], off
	v_lshl_add_u64 v[234:235], s[0:1], 0, v[130:131]
	s_mov_b32 m0, s35
	s_nop 0
	global_load_lds_dwordx4 v[234:235], off
	s_waitcnt vmcnt(8)
	s_waitcnt lgkmcnt(0)
	s_barrier
	s_setprio 1
	s_waitcnt lgkmcnt(0)
	v_mfma_f32_16x16x32_bf16 v[124:127], v[160:163], v[194:197], v[124:127]
	v_mfma_f32_16x16x32_bf16 v[120:123], v[168:171], v[194:197], v[120:123]
	v_mfma_f32_16x16x32_bf16 v[112:115], v[168:171], v[202:205], v[112:115]
	v_mfma_f32_16x16x32_bf16 v[116:119], v[160:163], v[202:205], v[116:119]
	v_mfma_f32_16x16x32_bf16 v[108:111], v[160:163], v[210:213], v[108:111]
	v_mfma_f32_16x16x32_bf16 v[104:107], v[168:171], v[210:213], v[104:107]
	v_mfma_f32_16x16x32_bf16 v[96:99], v[168:171], v[218:221], v[96:99]
	v_mfma_f32_16x16x32_bf16 v[100:103], v[160:163], v[218:221], v[100:103]
	v_mfma_f32_16x16x32_bf16 v[124:127], v[164:167], v[198:201], v[124:127]
	v_mfma_f32_16x16x32_bf16 v[120:123], v[172:175], v[198:201], v[120:123]
	v_mfma_f32_16x16x32_bf16 v[112:115], v[172:175], v[206:209], v[112:115]
	v_mfma_f32_16x16x32_bf16 v[116:119], v[164:167], v[206:209], v[116:119]
	v_mfma_f32_16x16x32_bf16 v[108:111], v[164:167], v[214:217], v[108:111]
	v_mfma_f32_16x16x32_bf16 v[104:107], v[172:175], v[214:217], v[104:107]
	v_mfma_f32_16x16x32_bf16 v[96:99], v[172:175], v[222:225], v[96:99]
	v_mfma_f32_16x16x32_bf16 v[100:103], v[164:167], v[222:225], v[100:103]
	s_setprio 0
	s_setprio 1
	v_mfma_f32_16x16x32_bf16 v[84:87], v[176:179], v[194:197], v[84:87]
	v_mfma_f32_16x16x32_bf16 v[76:79], v[186:189], v[194:197], v[76:79]
	v_mfma_f32_16x16x32_bf16 v[64:67], v[186:189], v[202:205], v[64:67]
	v_mfma_f32_16x16x32_bf16 v[68:71], v[176:179], v[202:205], v[68:71]
	v_mfma_f32_16x16x32_bf16 v[52:55], v[176:179], v[210:213], v[52:55]
	v_mfma_f32_16x16x32_bf16 v[48:51], v[186:189], v[210:213], v[48:51]
	v_mfma_f32_16x16x32_bf16 v[32:35], v[186:189], v[218:221], v[32:35]
	v_mfma_f32_16x16x32_bf16 v[40:43], v[176:179], v[218:221], v[40:43]
	v_mfma_f32_16x16x32_bf16 v[84:87], v[180:183], v[198:201], v[84:87]
	v_mfma_f32_16x16x32_bf16 v[76:79], v[190:193], v[198:201], v[76:79]
	v_mfma_f32_16x16x32_bf16 v[64:67], v[190:193], v[206:209], v[64:67]
	v_mfma_f32_16x16x32_bf16 v[68:71], v[180:183], v[206:209], v[68:71]
	v_mfma_f32_16x16x32_bf16 v[52:55], v[180:183], v[214:217], v[52:55]
	v_mfma_f32_16x16x32_bf16 v[48:51], v[190:193], v[214:217], v[48:51]
	v_mfma_f32_16x16x32_bf16 v[32:35], v[190:193], v[222:225], v[32:35]
	v_mfma_f32_16x16x32_bf16 v[40:43], v[180:183], v[222:225], v[40:43]
	s_setprio 0
	s_barrier
; #define PG8_STAGE(bufoff, gbase, voff) do { _Pragma("unroll") for (int _i = 0; _i < 2; ++_i) \
;         __builtin_amdgcn_global_load_lds((const unsigned*)((const char*)(gbase) + (voff)[_i]), (LAS unsigned*)(lds + (bufoff) + ldsw + _i * 8192), 16, 0, 0); } while (0)
; #define PG8_LDA(dst, b, h) do { _Pragma("unroll") for (int m = 0; m < 4; ++m) _Pragma("unroll") for (int k = 0; k < 2; ++k) dst[m][k] = *(const LAS bf16x8*)(lds + PG8_SA(b, h) + aoff + m * 2048 + k * 1024); } while (0)
; #define PG8_MMA(ai, bj, At, Bt) do { __builtin_amdgcn_s_setprio(1); _Pragma("unroll") for (int m = 0; m < 4; ++m) _Pragma("unroll") for (int n = 0; n < 2; ++n) _Pragma("unroll") for (int k = 0; k < 2; ++k) \
;         acc[ai][bj][m][n] = __builtin_amdgcn_mfma_f32_16x16x32_bf16(Bt[n][k], At[m][k], acc[ai][bj][m][n], 0, 0, 0); __builtin_amdgcn_s_setprio(0); } while (0)
; #define PG8_WAIT_V(n) asm volatile("s_waitcnt vmcnt(" #n ")" ::: "memory")
; #define PG8_WAIT_L(n) asm volatile("s_waitcnt lgkmcnt(" #n ")" ::: "memory")
; #define PG8_BAR __builtin_amdgcn_s_barrier()
; #define PG8_SCHED __builtin_amdgcn_sched_barrier(0)
; template <class Epi, bool ALIGN_EPI = PG8_ALIGN>
; __device__ __forceinline__ void gemm_phase(LAS unsigned char* lds, const Gemm g, const StaticOrder S, const Epi E) {
;     ...
;             PG8_LDA(At, 1, 1); PG8_STAGE(PG8_SB(1, 0), b3, voffB); PG8_STAGE(PG8_SB(1, 1), b3 + hstepB, voffB); PG8_STAGE(PG8_SA(1, 0), a3, voffA);
;             PG8_WAIT_V(8); PG8_WAIT_L(0); PG8_BAR; PG8_MMA(1, 0, At, B0); PG8_MMA(1, 1, At, B1); PG8_BAR; PG8_SCHED;
;         }
;         if (ALIGN_EPI) { if (wr == 0) PG8_BAR; }
	s_add_i32 s0, s42, s14
	v_lshl_add_u64 v[226:227], v[226:227], 0, s[12:13]
	s_mov_b32 m0, s0
	ds_read_b128 v[194:197], v158 offset:49152
	ds_read_b128 v[198:201], v158 offset:50176
	ds_read_b128 v[202:205], v158 offset:51200
	ds_read_b128 v[206:209], v158 offset:52224
	ds_read_b128 v[210:213], v158 offset:53248
	ds_read_b128 v[214:217], v158 offset:54272
	ds_read_b128 v[218:221], v158 offset:55296
	ds_read_b128 v[222:225], v158 offset:56320
	global_load_lds_dwordx4 v[226:227], off
	s_add_i32 m0, s0, 0x2000
	s_add_u32 s0, s52, 0x20080
	v_lshl_add_u64 v[226:227], v[228:229], 0, s[12:13]
	s_addc_u32 s1, s53, 0
	s_add_i32 s42, s43, s14
	global_load_lds_dwordx4 v[226:227], off
	v_lshl_add_u64 v[226:227], s[0:1], 0, v[132:133]
	s_mov_b32 m0, s42
	s_nop 0
	global_load_lds_dwordx4 v[226:227], off
	v_lshl_add_u64 v[226:227], s[0:1], 0, v[128:129]
	s_add_i32 m0, s42, 0x2000
	s_nop 0
	global_load_lds_dwordx4 v[226:227], off
	v_lshl_add_u64 v[226:227], v[230:231], 0, s[12:13]
	s_mov_b32 m0, s59
	s_nop 0
	global_load_lds_dwordx4 v[226:227], off
	v_lshl_add_u64 v[226:227], v[232:233], 0, s[12:13]
	s_mov_b32 m0, s60
	s_nop 0
	global_load_lds_dwordx4 v[226:227], off
	s_waitcnt vmcnt(8)
	s_waitcnt lgkmcnt(0)
	s_barrier
	s_setprio 1
	s_waitcnt lgkmcnt(0)
	v_mfma_f32_16x16x32_bf16 v[92:95], v[160:163], v[194:197], v[92:95]
	v_mfma_f32_16x16x32_bf16 v[88:91], v[168:171], v[194:197], v[88:91]
	v_mfma_f32_16x16x32_bf16 v[72:75], v[168:171], v[202:205], v[72:75]
	v_mfma_f32_16x16x32_bf16 v[80:83], v[160:163], v[202:205], v[80:83]
	v_mfma_f32_16x16x32_bf16 v[60:63], v[160:163], v[210:213], v[60:63]
	v_mfma_f32_16x16x32_bf16 v[56:59], v[168:171], v[210:213], v[56:59]
	v_mfma_f32_16x16x32_bf16 v[36:39], v[168:171], v[218:221], v[36:39]
	v_mfma_f32_16x16x32_bf16 v[44:47], v[160:163], v[218:221], v[44:47]
	v_mfma_f32_16x16x32_bf16 v[92:95], v[164:167], v[198:201], v[92:95]
	v_mfma_f32_16x16x32_bf16 v[88:91], v[172:175], v[198:201], v[88:91]
	v_mfma_f32_16x16x32_bf16 v[72:75], v[172:175], v[206:209], v[72:75]
	v_mfma_f32_16x16x32_bf16 v[80:83], v[164:167], v[206:209], v[80:83]
	v_mfma_f32_16x16x32_bf16 v[60:63], v[164:167], v[214:217], v[60:63]
	v_mfma_f32_16x16x32_bf16 v[56:59], v[172:175], v[214:217], v[56:59]
	v_mfma_f32_16x16x32_bf16 v[36:39], v[172:175], v[222:225], v[36:39]
	v_mfma_f32_16x16x32_bf16 v[44:47], v[164:167], v[222:225], v[44:47]
	s_setprio 0
	s_setprio 1
	v_mfma_f32_16x16x32_bf16 v[28:31], v[176:179], v[194:197], v[28:31]
	v_mfma_f32_16x16x32_bf16 v[24:27], v[186:189], v[194:197], v[24:27]
	v_mfma_f32_16x16x32_bf16 v[16:19], v[186:189], v[202:205], v[16:19]
	v_mfma_f32_16x16x32_bf16 v[20:23], v[176:179], v[202:205], v[20:23]
	v_mfma_f32_16x16x32_bf16 v[12:15], v[176:179], v[210:213], v[12:15]
	v_mfma_f32_16x16x32_bf16 v[8:11], v[186:189], v[210:213], v[8:11]
	v_mfma_f32_16x16x32_bf16 v[0:3], v[186:189], v[218:221], v[0:3]
	v_mfma_f32_16x16x32_bf16 v[4:7], v[176:179], v[218:221], v[4:7]
	v_mfma_f32_16x16x32_bf16 v[28:31], v[180:183], v[198:201], v[28:31]
	v_mfma_f32_16x16x32_bf16 v[24:27], v[190:193], v[198:201], v[24:27]
	v_mfma_f32_16x16x32_bf16 v[16:19], v[190:193], v[206:209], v[16:19]
	v_mfma_f32_16x16x32_bf16 v[20:23], v[180:183], v[206:209], v[20:23]
	v_mfma_f32_16x16x32_bf16 v[12:15], v[180:183], v[214:217], v[12:15]
	v_mfma_f32_16x16x32_bf16 v[8:11], v[190:193], v[214:217], v[8:11]
	v_mfma_f32_16x16x32_bf16 v[0:3], v[190:193], v[222:225], v[0:3]
	v_mfma_f32_16x16x32_bf16 v[4:7], v[180:183], v[222:225], v[4:7]
	s_setprio 0
	s_barrier
	s_add_i32 s71, s71, 2
	s_add_u32 s50, s50, 0x100
	s_addc_u32 s51, s51, 0
	s_add_u32 s68, s68, 0x100
	s_addc_u32 s69, s69, 0
	s_cmp_gt_u32 s71, 5
	s_cbranch_scc0 .LBB0_869
	s_and_b64 vcc, exec, s[22:23]
	s_cbranch_vccz .LBB0_872
	s_barrier

; #define PG8_STAGE(bufoff, gbase, voff) do { _Pragma("unroll") for (int _i = 0; _i < 2; ++_i) \
;         __builtin_amdgcn_global_load_lds((const unsigned*)((const char*)(gbase) + (voff)[_i]), (LAS unsigned*)(lds + (bufoff) + ldsw + _i * 8192), 16, 0, 0); } while (0)
; #define PG8_LDA(dst, b, h) do { _Pragma("unroll") for (int m = 0; m < 4; ++m) _Pragma("unroll") for (int k = 0; k < 2; ++k) dst[m][k] = *(const LAS bf16x8*)(lds + PG8_SA(b, h) + aoff + m * 2048 + k * 1024); } while (0)
; #define PG8_LDB(dst, b, h) do { _Pragma("unroll") for (int n = 0; n < 2; ++n) _Pragma("unroll") for (int k = 0; k < 2; ++k) dst[n][k] = *(const LAS bf16x8*)(lds + PG8_SB(b, h) + boff + n * 2048 + k * 1024); } while (0)
; #define PG8_MMA(ai, bj, At, Bt) do { __builtin_amdgcn_s_setprio(1); _Pragma("unroll") for (int m = 0; m < 4; ++m) _Pragma("unroll") for (int n = 0; n < 2; ++n) _Pragma("unroll") for (int k = 0; k < 2; ++k) \
;         acc[ai][bj][m][n] = __builtin_amdgcn_mfma_f32_16x16x32_bf16(Bt[n][k], At[m][k], acc[ai][bj][m][n], 0, 0, 0); __builtin_amdgcn_s_setprio(0); } while (0)
; #define PG8_WAIT_V(n) asm volatile("s_waitcnt vmcnt(" #n ")" ::: "memory")
; #define PG8_WAIT_L(n) asm volatile("s_waitcnt lgkmcnt(" #n ")" ::: "memory")
; template <class Epi, bool ALIGN_EPI = PG8_ALIGN>
; __device__ __forceinline__ void gemm_phase(LAS unsigned char* lds, const Gemm g, const StaticOrder S, const Epi E) {
;     ...
;         const bool has_next = S.next(ui + 1, nxt);
;         const char* nA = has_next ? (const char*)g.A + (size_t)nxt.pm * tstepA : cA; const char* nB = has_next ? (const char*)g.Bt + (size_t)nxt.pn * tstepB : cB;
;         for (int t = 0; t < nt; t += 2) {
;             const bool last = (t == nt - 2);
;             const char* a1 = cA + (size_t)(t + 1) * kstep;
;             const char* a2 = last ? nA : cA + (size_t)(t + 2) * kstep; const char* b2 = last ? nB : cB + (size_t)(t + 2) * kstep;
;             const char* a3 = a2 + kstep; const char* b3 = b2 + kstep;
;             PG8_LDB(B0, 0, 0); PG8_LDB(B1, 0, 1); PG8_SCHED; PG8_LDA(At, 0, 0); PG8_STAGE(PG8_SA(1, 1), a1 + hstepA, voffA);
;             PG8_WAIT_V(8); PG8_WAIT_L(0); PG8_BAR; PG8_MMA(0, 0, At, B0); PG8_MMA(0, 1, At, B1); PG8_BAR; PG8_SCHED;
;             PG8_LDA(At, 0, 1); PG8_STAGE(PG8_SB(0, 0), b2, voffB); PG8_STAGE(PG8_SB(0, 1), b2 + hstepB, voffB); PG8_STAGE(PG8_SA(0, 0), a2, voffA);
.LBB0_893:
	s_add_u32 s42, s44, s60
	s_addc_u32 s43, s45, 0
	s_add_u32 s61, s42, 0x100
	s_addc_u32 s62, s43, 0
	s_and_b64 s[0:1], s[58:59], exec
	s_cselect_b32 s63, s29, s62
	s_cselect_b32 s62, s83, s61
	s_add_u32 s0, s36, s60
	s_addc_u32 s1, s37, 0
	s_add_u32 s60, s0, 0x100
	s_addc_u32 s61, s1, 0
	s_and_b64 s[0:1], s[58:59], exec
	s_cselect_b32 s65, s27, s61
	s_cselect_b32 s64, s90, s60
	s_add_u32 s68, s42, 0x10080
	ds_read_b128 v[152:155], v148
	ds_read_b128 v[156:159], v148 offset:1024
	ds_read_b128 v[160:163], v148 offset:2048
	ds_read_b128 v[164:167], v148 offset:3072
	ds_read_b128 v[168:171], v149
	ds_read_b128 v[172:175], v149 offset:1024
	ds_read_b128 v[176:179], v149 offset:2048
	ds_read_b128 v[180:183], v149 offset:3072
	s_addc_u32 s69, s43, 0
	s_add_i32 vcc_hi, s78, s17
	s_add_i32 m0, s25, 0xc000
	s_add_i32 s1, s25, 0xe000
	s_add_i32 s0, vcc_hi, 0x2000
	s_add_u32 s66, s64, 0x10000
	s_addc_u32 s67, s65, 0
	s_add_i32 s43, s79, s17
	s_add_i32 s42, s43, 0x2000
	s_add_i32 vcc_lo, 0, 0x18000
	s_add_i32 s97, 0, 0x1c000
	s_add_u32 s60, s62, 0x10000
	s_addc_u32 s61, s63, 0
	s_add_i32 s95, vcc_lo, s17
	s_add_i32 s92, s95, 0x2000
	s_add_u32 s58, s64, 0x10080
	s_addc_u32 s59, s65, 0
	s_add_i32 s93, s97, s17
	s_add_i32 s91, s93, 0x2000
	v_lshl_add_u64 v[218:219], s[68:69], 0, v[128:129]
	ds_read_b128 v[186:189], v150
	ds_read_b128 v[190:193], v150 offset:1024
	ds_read_b128 v[194:197], v150 offset:2048
	ds_read_b128 v[198:201], v150 offset:3072
	ds_read_b128 v[202:205], v150 offset:4096
	ds_read_b128 v[206:209], v150 offset:5120
	ds_read_b128 v[210:213], v150 offset:6144
	ds_read_b128 v[214:217], v150 offset:7168
	global_load_lds_dwordx4 v[218:219], off
	v_lshl_add_u64 v[218:219], s[68:69], 0, v[132:133]
	s_mov_b32 m0, s1
	s_nop 0
	global_load_lds_dwordx4 v[218:219], off
	s_waitcnt vmcnt(8)
	s_waitcnt lgkmcnt(0)
	s_barrier
	s_setprio 1
	s_waitcnt lgkmcnt(0)
	v_mfma_f32_16x16x32_bf16 v[124:127], v[152:155], v[186:189], v[124:127]
	v_mfma_f32_16x16x32_bf16 v[120:123], v[160:163], v[186:189], v[120:123]
	v_mfma_f32_16x16x32_bf16 v[112:115], v[160:163], v[194:197], v[112:115]
	v_mfma_f32_16x16x32_bf16 v[116:119], v[152:155], v[194:197], v[116:119]
	v_mfma_f32_16x16x32_bf16 v[108:111], v[152:155], v[202:205], v[108:111]
	v_mfma_f32_16x16x32_bf16 v[104:107], v[160:163], v[202:205], v[104:107]
	v_mfma_f32_16x16x32_bf16 v[96:99], v[160:163], v[210:213], v[96:99]
	v_mfma_f32_16x16x32_bf16 v[100:103], v[152:155], v[210:213], v[100:103]
	v_mfma_f32_16x16x32_bf16 v[124:127], v[156:159], v[190:193], v[124:127]
	v_mfma_f32_16x16x32_bf16 v[120:123], v[164:167], v[190:193], v[120:123]
	v_mfma_f32_16x16x32_bf16 v[112:115], v[164:167], v[198:201], v[112:115]
	v_mfma_f32_16x16x32_bf16 v[116:119], v[156:159], v[198:201], v[116:119]
	v_mfma_f32_16x16x32_bf16 v[108:111], v[156:159], v[206:209], v[108:111]
	v_mfma_f32_16x16x32_bf16 v[104:107], v[164:167], v[206:209], v[104:107]
	v_mfma_f32_16x16x32_bf16 v[96:99], v[164:167], v[214:217], v[96:99]
	v_mfma_f32_16x16x32_bf16 v[100:103], v[156:159], v[214:217], v[100:103]
	s_setprio 0
	s_setprio 1
	v_mfma_f32_16x16x32_bf16 v[84:87], v[168:171], v[186:189], v[84:87]
	v_mfma_f32_16x16x32_bf16 v[76:79], v[176:179], v[186:189], v[76:79]
	v_mfma_f32_16x16x32_bf16 v[60:63], v[176:179], v[194:197], v[60:63]
	v_mfma_f32_16x16x32_bf16 v[68:71], v[168:171], v[194:197], v[68:71]
	v_mfma_f32_16x16x32_bf16 v[52:55], v[168:171], v[202:205], v[52:55]
	v_mfma_f32_16x16x32_bf16 v[44:47], v[176:179], v[202:205], v[44:47]
	v_mfma_f32_16x16x32_bf16 v[32:35], v[176:179], v[210:213], v[32:35]
	v_mfma_f32_16x16x32_bf16 v[36:39], v[168:171], v[210:213], v[36:39]
	v_mfma_f32_16x16x32_bf16 v[84:87], v[172:175], v[190:193], v[84:87]
	v_mfma_f32_16x16x32_bf16 v[76:79], v[180:183], v[190:193], v[76:79]
	v_mfma_f32_16x16x32_bf16 v[60:63], v[180:183], v[198:201], v[60:63]
	v_mfma_f32_16x16x32_bf16 v[68:71], v[172:175], v[198:201], v[68:71]
	v_mfma_f32_16x16x32_bf16 v[52:55], v[172:175], v[206:209], v[52:55]
	v_mfma_f32_16x16x32_bf16 v[44:47], v[180:183], v[206:209], v[44:47]
	v_mfma_f32_16x16x32_bf16 v[32:35], v[180:183], v[214:217], v[32:35]
	v_mfma_f32_16x16x32_bf16 v[36:39], v[172:175], v[214:217], v[36:39]
	s_setprio 0
	s_barrier
	s_mov_b32 m0, vcc_hi
	v_lshl_add_u64 v[218:219], s[64:65], 0, v[130:131]
	ds_read_b128 v[186:189], v150 offset:16384
	ds_read_b128 v[190:193], v150 offset:17408
	ds_read_b128 v[194:197], v150 offset:18432
	ds_read_b128 v[198:201], v150 offset:19456
	ds_read_b128 v[202:205], v150 offset:20480
	ds_read_b128 v[206:209], v150 offset:21504
	ds_read_b128 v[210:213], v150 offset:22528
	ds_read_b128 v[214:217], v150 offset:23552
	global_load_lds_dwordx4 v[218:219], off
	v_lshl_add_u64 v[220:221], s[64:65], 0, v[134:135]
	s_mov_b32 m0, s0
	v_lshl_add_u64 v[222:223], s[66:67], 0, v[130:131]
	global_load_lds_dwordx4 v[220:221], off
	s_mov_b32 m0, s43
	v_lshl_add_u64 v[224:225], s[62:63], 0, v[132:133]
	global_load_lds_dwordx4 v[222:223], off
	v_lshl_add_u64 v[222:223], s[66:67], 0, v[134:135]
	s_mov_b32 m0, s42
	s_nop 0
	global_load_lds_dwordx4 v[222:223], off
	v_lshl_add_u64 v[222:223], s[62:63], 0, v[128:129]
	s_mov_b32 m0, s25
	s_nop 0
	global_load_lds_dwordx4 v[222:223], off
	s_mov_b32 m0, s33
	s_nop 0
	global_load_lds_dwordx4 v[224:225], off
	s_waitcnt vmcnt(8)
	s_waitcnt lgkmcnt(0)
	s_barrier
; #define PG8_STAGE(bufoff, gbase, voff) do { _Pragma("unroll") for (int _i = 0; _i < 2; ++_i) \
;         __builtin_amdgcn_global_load_lds((const unsigned*)((const char*)(gbase) + (voff)[_i]), (LAS unsigned*)(lds + (bufoff) + ldsw + _i * 8192), 16, 0, 0); } while (0)
; #define PG8_LDA(dst, b, h) do { _Pragma("unroll") for (int m = 0; m < 4; ++m) _Pragma("unroll") for (int k = 0; k < 2; ++k) dst[m][k] = *(const LAS bf16x8*)(lds + PG8_SA(b, h) + aoff + m * 2048 + k * 1024); } while (0)
; #define PG8_LDB(dst, b, h) do { _Pragma("unroll") for (int n = 0; n < 2; ++n) _Pragma("unroll") for (int k = 0; k < 2; ++k) dst[n][k] = *(const LAS bf16x8*)(lds + PG8_SB(b, h) + boff + n * 2048 + k * 1024); } while (0)
; #define PG8_MMA(ai, bj, At, Bt) do { __builtin_amdgcn_s_setprio(1); _Pragma("unroll") for (int m = 0; m < 4; ++m) _Pragma("unroll") for (int n = 0; n < 2; ++n) _Pragma("unroll") for (int k = 0; k < 2; ++k) \
;         acc[ai][bj][m][n] = __builtin_amdgcn_mfma_f32_16x16x32_bf16(Bt[n][k], At[m][k], acc[ai][bj][m][n], 0, 0, 0); __builtin_amdgcn_s_setprio(0); } while (0)
; #define PG8_WAIT_V(n) asm volatile("s_waitcnt vmcnt(" #n ")" ::: "memory")
; #define PG8_WAIT_L(n) asm volatile("s_waitcnt lgkmcnt(" #n ")" ::: "memory")
; #define PG8_BAR __builtin_amdgcn_s_barrier()
; #define PG8_SCHED __builtin_amdgcn_sched_barrier(0)
; template <class Epi, bool ALIGN_EPI = PG8_ALIGN>
; __device__ __forceinline__ void gemm_phase(LAS unsigned char* lds, const Gemm g, const StaticOrder S, const Epi E) {
;     ...
;             PG8_WAIT_V(8); PG8_WAIT_L(0); PG8_BAR; PG8_MMA(1, 0, At, B0); PG8_MMA(1, 1, At, B1); PG8_BAR; PG8_SCHED;
;             PG8_LDB(B0, 1, 0); PG8_LDB(B1, 1, 1); PG8_SCHED; PG8_LDA(At, 1, 0); PG8_STAGE(PG8_SA(0, 1), a2 + hstepA, voffA);
;             PG8_WAIT_V(8); PG8_WAIT_L(0); PG8_BAR; PG8_MMA(0, 0, At, B0); PG8_MMA(0, 1, At, B1); PG8_BAR; PG8_SCHED;
	s_setprio 1
	s_waitcnt lgkmcnt(0)
	v_mfma_f32_16x16x32_bf16 v[92:95], v[152:155], v[186:189], v[92:95]
	v_mfma_f32_16x16x32_bf16 v[88:91], v[160:163], v[186:189], v[88:91]
	v_mfma_f32_16x16x32_bf16 v[72:75], v[160:163], v[194:197], v[72:75]
	v_mfma_f32_16x16x32_bf16 v[80:83], v[152:155], v[194:197], v[80:83]
	v_mfma_f32_16x16x32_bf16 v[64:67], v[152:155], v[202:205], v[64:67]
	v_mfma_f32_16x16x32_bf16 v[56:59], v[160:163], v[202:205], v[56:59]
	v_mfma_f32_16x16x32_bf16 v[40:43], v[160:163], v[210:213], v[40:43]
	v_mfma_f32_16x16x32_bf16 v[48:51], v[152:155], v[210:213], v[48:51]
	v_mfma_f32_16x16x32_bf16 v[92:95], v[156:159], v[190:193], v[92:95]
	v_mfma_f32_16x16x32_bf16 v[88:91], v[164:167], v[190:193], v[88:91]
	v_mfma_f32_16x16x32_bf16 v[72:75], v[164:167], v[198:201], v[72:75]
	v_mfma_f32_16x16x32_bf16 v[80:83], v[156:159], v[198:201], v[80:83]
	v_mfma_f32_16x16x32_bf16 v[64:67], v[156:159], v[206:209], v[64:67]
	v_mfma_f32_16x16x32_bf16 v[56:59], v[164:167], v[206:209], v[56:59]
	v_mfma_f32_16x16x32_bf16 v[40:43], v[164:167], v[214:217], v[40:43]
	v_mfma_f32_16x16x32_bf16 v[48:51], v[156:159], v[214:217], v[48:51]
	s_setprio 0
	s_setprio 1
	v_mfma_f32_16x16x32_bf16 v[28:31], v[168:171], v[186:189], v[28:31]
	v_mfma_f32_16x16x32_bf16 v[24:27], v[176:179], v[186:189], v[24:27]
	v_mfma_f32_16x16x32_bf16 v[16:19], v[176:179], v[194:197], v[16:19]
	v_mfma_f32_16x16x32_bf16 v[20:23], v[168:171], v[194:197], v[20:23]
	v_mfma_f32_16x16x32_bf16 v[12:15], v[168:171], v[202:205], v[12:15]
	v_mfma_f32_16x16x32_bf16 v[8:11], v[176:179], v[202:205], v[8:11]
	v_mfma_f32_16x16x32_bf16 v[0:3], v[176:179], v[210:213], v[0:3]
	v_mfma_f32_16x16x32_bf16 v[4:7], v[168:171], v[210:213], v[4:7]
	v_mfma_f32_16x16x32_bf16 v[28:31], v[172:175], v[190:193], v[28:31]
	v_mfma_f32_16x16x32_bf16 v[24:27], v[180:183], v[190:193], v[24:27]
	v_mfma_f32_16x16x32_bf16 v[16:19], v[180:183], v[198:201], v[16:19]
	v_mfma_f32_16x16x32_bf16 v[20:23], v[172:175], v[198:201], v[20:23]
	v_mfma_f32_16x16x32_bf16 v[12:15], v[172:175], v[206:209], v[12:15]
	v_mfma_f32_16x16x32_bf16 v[8:11], v[180:183], v[206:209], v[8:11]
	v_mfma_f32_16x16x32_bf16 v[0:3], v[180:183], v[214:217], v[0:3]
	v_mfma_f32_16x16x32_bf16 v[4:7], v[172:175], v[214:217], v[4:7]
	s_setprio 0
	s_barrier
	v_add_u32_e32 v151, vcc_lo, v141
	ds_read_b128 v[152:155], v151
	ds_read_b128 v[156:159], v151 offset:1024
	ds_read_b128 v[160:163], v151 offset:2048
	ds_read_b128 v[164:167], v151 offset:3072
	v_add_u32_e32 v151, s97, v141
	ds_read_b128 v[168:171], v151
	ds_read_b128 v[172:175], v151 offset:1024
	ds_read_b128 v[176:179], v151 offset:2048
	ds_read_b128 v[180:183], v151 offset:3072
	s_mov_b32 m0, s34
	v_lshl_add_u64 v[226:227], s[60:61], 0, v[128:129]
	ds_read_b128 v[186:189], v150 offset:32768
	ds_read_b128 v[190:193], v150 offset:33792
	ds_read_b128 v[194:197], v150 offset:34816
	ds_read_b128 v[198:201], v150 offset:35840
	ds_read_b128 v[202:205], v150 offset:36864
	ds_read_b128 v[206:209], v150 offset:37888
	ds_read_b128 v[210:213], v150 offset:38912
	ds_read_b128 v[214:217], v150 offset:39936
	global_load_lds_dwordx4 v[226:227], off
	v_lshl_add_u64 v[226:227], s[60:61], 0, v[132:133]
	s_mov_b32 m0, s35
	s_nop 0
	global_load_lds_dwordx4 v[226:227], off
	s_waitcnt vmcnt(8)
	s_waitcnt lgkmcnt(0)
	s_barrier
	s_setprio 1
	s_waitcnt lgkmcnt(0)
	v_mfma_f32_16x16x32_bf16 v[124:127], v[152:155], v[186:189], v[124:127]
	v_mfma_f32_16x16x32_bf16 v[120:123], v[160:163], v[186:189], v[120:123]
	v_mfma_f32_16x16x32_bf16 v[112:115], v[160:163], v[194:197], v[112:115]
	v_mfma_f32_16x16x32_bf16 v[116:119], v[152:155], v[194:197], v[116:119]
	v_mfma_f32_16x16x32_bf16 v[108:111], v[152:155], v[202:205], v[108:111]
	v_mfma_f32_16x16x32_bf16 v[104:107], v[160:163], v[202:205], v[104:107]
	v_mfma_f32_16x16x32_bf16 v[96:99], v[160:163], v[210:213], v[96:99]
	v_mfma_f32_16x16x32_bf16 v[100:103], v[152:155], v[210:213], v[100:103]
	v_mfma_f32_16x16x32_bf16 v[124:127], v[156:159], v[190:193], v[124:127]
	v_mfma_f32_16x16x32_bf16 v[120:123], v[164:167], v[190:193], v[120:123]
	v_mfma_f32_16x16x32_bf16 v[112:115], v[164:167], v[198:201], v[112:115]
	v_mfma_f32_16x16x32_bf16 v[116:119], v[156:159], v[198:201], v[116:119]
	v_mfma_f32_16x16x32_bf16 v[108:111], v[156:159], v[206:209], v[108:111]
	v_mfma_f32_16x16x32_bf16 v[104:107], v[164:167], v[206:209], v[104:107]
	v_mfma_f32_16x16x32_bf16 v[96:99], v[164:167], v[214:217], v[96:99]
	v_mfma_f32_16x16x32_bf16 v[100:103], v[156:159], v[214:217], v[100:103]
	s_setprio 0
	s_setprio 1
	v_mfma_f32_16x16x32_bf16 v[84:87], v[168:171], v[186:189], v[84:87]
	v_mfma_f32_16x16x32_bf16 v[76:79], v[176:179], v[186:189], v[76:79]
	v_mfma_f32_16x16x32_bf16 v[60:63], v[176:179], v[194:197], v[60:63]
	v_mfma_f32_16x16x32_bf16 v[68:71], v[168:171], v[194:197], v[68:71]
	v_mfma_f32_16x16x32_bf16 v[52:55], v[168:171], v[202:205], v[52:55]
	v_mfma_f32_16x16x32_bf16 v[44:47], v[176:179], v[202:205], v[44:47]
	v_mfma_f32_16x16x32_bf16 v[32:35], v[176:179], v[210:213], v[32:35]
	v_mfma_f32_16x16x32_bf16 v[36:39], v[168:171], v[210:213], v[36:39]
	v_mfma_f32_16x16x32_bf16 v[84:87], v[172:175], v[190:193], v[84:87]
	v_mfma_f32_16x16x32_bf16 v[76:79], v[180:183], v[190:193], v[76:79]
	v_mfma_f32_16x16x32_bf16 v[60:63], v[180:183], v[198:201], v[60:63]
	v_mfma_f32_16x16x32_bf16 v[68:71], v[172:175], v[198:201], v[68:71]
	v_mfma_f32_16x16x32_bf16 v[52:55], v[172:175], v[206:209], v[52:55]
	v_mfma_f32_16x16x32_bf16 v[44:47], v[180:183], v[206:209], v[44:47]
	v_mfma_f32_16x16x32_bf16 v[32:35], v[180:183], v[214:217], v[32:35]
	v_mfma_f32_16x16x32_bf16 v[36:39], v[172:175], v[214:217], v[36:39]
	s_setprio 0
	s_barrier
; #define PG8_STAGE(bufoff, gbase, voff) do { _Pragma("unroll") for (int _i = 0; _i < 2; ++_i) \
;         __builtin_amdgcn_global_load_lds((const unsigned*)((const char*)(gbase) + (voff)[_i]), (LAS unsigned*)(lds + (bufoff) + ldsw + _i * 8192), 16, 0, 0); } while (0)
; #define PG8_LDA(dst, b, h) do { _Pragma("unroll") for (int m = 0; m < 4; ++m) _Pragma("unroll") for (int k = 0; k < 2; ++k) dst[m][k] = *(const LAS bf16x8*)(lds + PG8_SA(b, h) + aoff + m * 2048 + k * 1024); } while (0)
; #define PG8_MMA(ai, bj, At, Bt) do { __builtin_amdgcn_s_setprio(1); _Pragma("unroll") for (int m = 0; m < 4; ++m) _Pragma("unroll") for (int n = 0; n < 2; ++n) _Pragma("unroll") for (int k = 0; k < 2; ++k) \
;         acc[ai][bj][m][n] = __builtin_amdgcn_mfma_f32_16x16x32_bf16(Bt[n][k], At[m][k], acc[ai][bj][m][n], 0, 0, 0); __builtin_amdgcn_s_setprio(0); } while (0)
; #define PG8_WAIT_V(n) asm volatile("s_waitcnt vmcnt(" #n ")" ::: "memory")
; #define PG8_WAIT_L(n) asm volatile("s_waitcnt lgkmcnt(" #n ")" ::: "memory")
; #define PG8_BAR __builtin_amdgcn_s_barrier()
; #define PG8_SCHED __builtin_amdgcn_sched_barrier(0)
; template <class Epi, bool ALIGN_EPI = PG8_ALIGN>
; __device__ __forceinline__ void gemm_phase(LAS unsigned char* lds, const Gemm g, const StaticOrder S, const Epi E) {
;     ...
;             PG8_LDA(At, 1, 1); PG8_STAGE(PG8_SB(1, 0), b3, voffB); PG8_STAGE(PG8_SB(1, 1), b3 + hstepB, voffB); PG8_STAGE(PG8_SA(1, 0), a3, voffA);
;             PG8_WAIT_V(8); PG8_WAIT_L(0); PG8_BAR; PG8_MMA(1, 0, At, B0); PG8_MMA(1, 1, At, B1); PG8_BAR; PG8_SCHED;
;         }
;         if (ALIGN_EPI) { if (wr == 0) PG8_BAR; }
	s_mov_b32 m0, s95
	v_lshl_add_u64 v[218:219], v[218:219], 0, s[12:13]
	ds_read_b128 v[186:189], v150 offset:49152
	ds_read_b128 v[190:193], v150 offset:50176
	ds_read_b128 v[194:197], v150 offset:51200
	ds_read_b128 v[198:201], v150 offset:52224
	ds_read_b128 v[202:205], v150 offset:53248
	ds_read_b128 v[206:209], v150 offset:54272
	ds_read_b128 v[210:213], v150 offset:55296
	ds_read_b128 v[214:217], v150 offset:56320
	global_load_lds_dwordx4 v[218:219], off
	v_lshl_add_u64 v[218:219], v[220:221], 0, s[12:13]
	s_mov_b32 m0, s92
	s_nop 0
	global_load_lds_dwordx4 v[218:219], off
	v_lshl_add_u64 v[218:219], s[58:59], 0, v[130:131]
	s_mov_b32 m0, s93
	s_nop 0
	global_load_lds_dwordx4 v[218:219], off
	v_lshl_add_u64 v[218:219], s[58:59], 0, v[134:135]
	s_mov_b32 m0, s91
	s_nop 0
	global_load_lds_dwordx4 v[218:219], off
	v_lshl_add_u64 v[218:219], v[222:223], 0, s[12:13]
	s_mov_b32 m0, s75
	s_nop 0
	global_load_lds_dwordx4 v[218:219], off
	v_lshl_add_u64 v[218:219], v[224:225], 0, s[12:13]
	s_mov_b32 m0, s76
	s_nop 0
	global_load_lds_dwordx4 v[218:219], off
	s_waitcnt vmcnt(8)
	s_waitcnt lgkmcnt(0)
	s_barrier
	s_setprio 1
	s_waitcnt lgkmcnt(0)
	v_mfma_f32_16x16x32_bf16 v[92:95], v[152:155], v[186:189], v[92:95]
	v_mfma_f32_16x16x32_bf16 v[88:91], v[160:163], v[186:189], v[88:91]
	v_mfma_f32_16x16x32_bf16 v[72:75], v[160:163], v[194:197], v[72:75]
	v_mfma_f32_16x16x32_bf16 v[80:83], v[152:155], v[194:197], v[80:83]
	v_mfma_f32_16x16x32_bf16 v[64:67], v[152:155], v[202:205], v[64:67]
	v_mfma_f32_16x16x32_bf16 v[56:59], v[160:163], v[202:205], v[56:59]
	v_mfma_f32_16x16x32_bf16 v[40:43], v[160:163], v[210:213], v[40:43]
	v_mfma_f32_16x16x32_bf16 v[48:51], v[152:155], v[210:213], v[48:51]
	v_mfma_f32_16x16x32_bf16 v[92:95], v[156:159], v[190:193], v[92:95]
	v_mfma_f32_16x16x32_bf16 v[88:91], v[164:167], v[190:193], v[88:91]
	v_mfma_f32_16x16x32_bf16 v[72:75], v[164:167], v[198:201], v[72:75]
	v_mfma_f32_16x16x32_bf16 v[80:83], v[156:159], v[198:201], v[80:83]
	v_mfma_f32_16x16x32_bf16 v[64:67], v[156:159], v[206:209], v[64:67]
	v_mfma_f32_16x16x32_bf16 v[56:59], v[164:167], v[206:209], v[56:59]
	v_mfma_f32_16x16x32_bf16 v[40:43], v[164:167], v[214:217], v[40:43]
	v_mfma_f32_16x16x32_bf16 v[48:51], v[156:159], v[214:217], v[48:51]
	s_setprio 0
	s_setprio 1
	v_mfma_f32_16x16x32_bf16 v[28:31], v[168:171], v[186:189], v[28:31]
	v_mfma_f32_16x16x32_bf16 v[24:27], v[176:179], v[186:189], v[24:27]
	v_mfma_f32_16x16x32_bf16 v[16:19], v[176:179], v[194:197], v[16:19]
	v_mfma_f32_16x16x32_bf16 v[20:23], v[168:171], v[194:197], v[20:23]
	v_mfma_f32_16x16x32_bf16 v[12:15], v[168:171], v[202:205], v[12:15]
	v_mfma_f32_16x16x32_bf16 v[8:11], v[176:179], v[202:205], v[8:11]
	v_mfma_f32_16x16x32_bf16 v[0:3], v[176:179], v[210:213], v[0:3]
	v_mfma_f32_16x16x32_bf16 v[4:7], v[168:171], v[210:213], v[4:7]
	v_mfma_f32_16x16x32_bf16 v[28:31], v[172:175], v[190:193], v[28:31]
	v_mfma_f32_16x16x32_bf16 v[24:27], v[180:183], v[190:193], v[24:27]
	v_mfma_f32_16x16x32_bf16 v[16:19], v[180:183], v[198:201], v[16:19]
	v_mfma_f32_16x16x32_bf16 v[20:23], v[172:175], v[198:201], v[20:23]
	v_mfma_f32_16x16x32_bf16 v[12:15], v[172:175], v[206:209], v[12:15]
	v_mfma_f32_16x16x32_bf16 v[8:11], v[180:183], v[206:209], v[8:11]
	v_mfma_f32_16x16x32_bf16 v[0:3], v[180:183], v[214:217], v[0:3]
	v_mfma_f32_16x16x32_bf16 v[4:7], v[172:175], v[214:217], v[4:7]
	s_setprio 0
	s_barrier
	s_movk_i32 s60, 0x100
	s_andn2_b64 vcc, exec, s[54:55]
	s_mov_b64 s[58:59], -1
	s_mov_b64 s[54:55], 0
	s_cbranch_vccz .LBB0_893
	s_and_b64 vcc, exec, s[22:23]
	v_readlane_b32 s90, v238, 37
	s_cbranch_vccz .LBB0_896
	s_barrier

; #define PG8_STAGE(bufoff, gbase, voff) do { _Pragma("unroll") for (int _i = 0; _i < 2; ++_i) \
;         __builtin_amdgcn_global_load_lds((const unsigned*)((const char*)(gbase) + (voff)[_i]), (LAS unsigned*)(lds + (bufoff) + ldsw + _i * 8192), 16, 0, 0); } while (0)
; #define PG8_LDA(dst, b, h) do { _Pragma("unroll") for (int m = 0; m < 4; ++m) _Pragma("unroll") for (int k = 0; k < 2; ++k) dst[m][k] = *(const LAS bf16x8*)(lds + PG8_SA(b, h) + aoff + m * 2048 + k * 1024); } while (0)
; #define PG8_LDB(dst, b, h) do { _Pragma("unroll") for (int n = 0; n < 2; ++n) _Pragma("unroll") for (int k = 0; k < 2; ++k) dst[n][k] = *(const LAS bf16x8*)(lds + PG8_SB(b, h) + boff + n * 2048 + k * 1024); } while (0)
; #define PG8_MMA(ai, bj, At, Bt) do { __builtin_amdgcn_s_setprio(1); _Pragma("unroll") for (int m = 0; m < 4; ++m) _Pragma("unroll") for (int n = 0; n < 2; ++n) _Pragma("unroll") for (int k = 0; k < 2; ++k) \
;         acc[ai][bj][m][n] = __builtin_amdgcn_mfma_f32_16x16x32_bf16(Bt[n][k], At[m][k], acc[ai][bj][m][n], 0, 0, 0); __builtin_amdgcn_s_setprio(0); } while (0)
; #define PG8_WAIT_V(n) asm volatile("s_waitcnt vmcnt(" #n ")" ::: "memory")
; #define PG8_WAIT_L(n) asm volatile("s_waitcnt lgkmcnt(" #n ")" ::: "memory")
; template <class Epi, bool ALIGN_EPI = PG8_ALIGN>
; __device__ __forceinline__ void gemm_phase(LAS unsigned char* lds, const Gemm g, const StaticOrder S, const Epi E) {
;     ...
;         const bool has_next = S.next(ui + 1, nxt);
;         const char* nA = has_next ? (const char*)g.A + (size_t)nxt.pm * tstepA : cA; const char* nB = has_next ? (const char*)g.Bt + (size_t)nxt.pn * tstepB : cB;
;         for (int t = 0; t < nt; t += 2) {
;             const bool last = (t == nt - 2);
;             const char* a1 = cA + (size_t)(t + 1) * kstep;
;             const char* a2 = last ? nA : cA + (size_t)(t + 2) * kstep; const char* b2 = last ? nB : cB + (size_t)(t + 2) * kstep;
;             const char* a3 = a2 + kstep; const char* b3 = b2 + kstep;
;             PG8_LDB(B0, 0, 0); PG8_LDB(B1, 0, 1); PG8_SCHED; PG8_LDA(At, 0, 0); PG8_STAGE(PG8_SA(1, 1), a1 + hstepA, voffA);
;             PG8_WAIT_V(8); PG8_WAIT_L(0); PG8_BAR; PG8_MMA(0, 0, At, B0); PG8_MMA(0, 1, At, B1); PG8_BAR; PG8_SCHED;
;             PG8_LDA(At, 0, 1); PG8_STAGE(PG8_SB(0, 0), b2, voffB); PG8_STAGE(PG8_SB(0, 1), b2 + hstepB, voffB); PG8_STAGE(PG8_SA(0, 0), a2, voffA);
.LBB0_917:
	s_add_u32 s42, s50, s60
	s_addc_u32 s43, s51, 0
	s_add_u32 s61, s42, 0x100
	s_addc_u32 s62, s43, 0
	s_and_b64 s[0:1], s[58:59], exec
	s_cselect_b32 s63, s27, s62
	s_cselect_b32 s62, s81, s61
	s_add_u32 s0, s36, s60
	s_addc_u32 s1, s37, 0
	s_add_u32 s60, s0, 0x100
	s_addc_u32 s61, s1, 0
	s_and_b64 s[0:1], s[58:59], exec
	s_cselect_b32 s65, s25, s61
	s_cselect_b32 s64, s82, s60
	s_add_u32 s68, s42, 0x10080
	ds_read_b128 v[146:149], v143
	ds_read_b128 v[150:153], v143 offset:1024
	ds_read_b128 v[154:157], v143 offset:2048
	ds_read_b128 v[158:161], v143 offset:3072
	ds_read_b128 v[162:165], v144
	ds_read_b128 v[166:169], v144 offset:1024
	ds_read_b128 v[170:173], v144 offset:2048
	ds_read_b128 v[174:177], v144 offset:3072
	s_addc_u32 s69, s43, 0
	s_add_i32 s42, s77, s17
	s_add_i32 m0, s29, 0xc000
	s_add_i32 s0, s29, 0xe000
	s_add_i32 s97, s42, 0x2000
	s_add_u32 s66, s64, 0x10000
	s_addc_u32 s67, s65, 0
	s_add_i32 vcc_hi, s78, s17
	s_add_i32 vcc_lo, vcc_hi, 0x2000
	s_add_i32 s95, 0, 0x18000
	s_add_i32 s93, 0, 0x1c000
	s_add_u32 s60, s62, 0x10000
	s_addc_u32 s61, s63, 0
	s_add_i32 s92, s95, s17
	s_add_i32 s90, s92, 0x2000
	s_add_u32 s58, s64, 0x10080
	s_addc_u32 s59, s65, 0
	s_add_i32 s91, s93, s17
	s_add_i32 s83, s91, 0x2000
	v_lshl_add_u64 v[182:183], s[68:69], 0, v[128:129]
	ds_read_b128 v[178:181], v145
	ds_read_b128 v[186:189], v145 offset:1024
	ds_read_b128 v[190:193], v145 offset:2048
	ds_read_b128 v[194:197], v145 offset:3072
	ds_read_b128 v[198:201], v145 offset:4096
	ds_read_b128 v[202:205], v145 offset:5120
	ds_read_b128 v[206:209], v145 offset:6144
	ds_read_b128 v[210:213], v145 offset:7168
	global_load_lds_dwordx4 v[182:183], off
	v_lshl_add_u64 v[182:183], s[68:69], 0, v[132:133]
	s_mov_b32 m0, s0
	s_nop 0
	global_load_lds_dwordx4 v[182:183], off
	s_waitcnt vmcnt(8)
	s_waitcnt lgkmcnt(0)
	s_barrier
	s_setprio 1
	s_waitcnt lgkmcnt(0)
	v_mfma_f32_16x16x32_bf16 v[124:127], v[146:149], v[178:181], v[124:127]
	v_mfma_f32_16x16x32_bf16 v[120:123], v[154:157], v[178:181], v[120:123]
	v_mfma_f32_16x16x32_bf16 v[112:115], v[154:157], v[190:193], v[112:115]
	v_mfma_f32_16x16x32_bf16 v[116:119], v[146:149], v[190:193], v[116:119]
	v_mfma_f32_16x16x32_bf16 v[108:111], v[146:149], v[198:201], v[108:111]
	v_mfma_f32_16x16x32_bf16 v[104:107], v[154:157], v[198:201], v[104:107]
	v_mfma_f32_16x16x32_bf16 v[96:99], v[154:157], v[206:209], v[96:99]
	v_mfma_f32_16x16x32_bf16 v[100:103], v[146:149], v[206:209], v[100:103]
	v_mfma_f32_16x16x32_bf16 v[124:127], v[150:153], v[186:189], v[124:127]
	v_mfma_f32_16x16x32_bf16 v[120:123], v[158:161], v[186:189], v[120:123]
	v_mfma_f32_16x16x32_bf16 v[112:115], v[158:161], v[194:197], v[112:115]
	v_mfma_f32_16x16x32_bf16 v[116:119], v[150:153], v[194:197], v[116:119]
	v_mfma_f32_16x16x32_bf16 v[108:111], v[150:153], v[202:205], v[108:111]
	v_mfma_f32_16x16x32_bf16 v[104:107], v[158:161], v[202:205], v[104:107]
	v_mfma_f32_16x16x32_bf16 v[96:99], v[158:161], v[210:213], v[96:99]
	v_mfma_f32_16x16x32_bf16 v[100:103], v[150:153], v[210:213], v[100:103]
	s_setprio 0
	s_setprio 1
	v_mfma_f32_16x16x32_bf16 v[76:79], v[162:165], v[178:181], v[76:79]
	v_mfma_f32_16x16x32_bf16 v[72:75], v[170:173], v[178:181], v[72:75]
	v_mfma_f32_16x16x32_bf16 v[56:59], v[170:173], v[190:193], v[56:59]
	v_mfma_f32_16x16x32_bf16 v[64:67], v[162:165], v[190:193], v[64:67]
	v_mfma_f32_16x16x32_bf16 v[52:55], v[162:165], v[198:201], v[52:55]
	v_mfma_f32_16x16x32_bf16 v[48:51], v[170:173], v[198:201], v[48:51]
	v_mfma_f32_16x16x32_bf16 v[32:35], v[170:173], v[206:209], v[32:35]
	v_mfma_f32_16x16x32_bf16 v[36:39], v[162:165], v[206:209], v[36:39]
	v_mfma_f32_16x16x32_bf16 v[76:79], v[166:169], v[186:189], v[76:79]
	v_mfma_f32_16x16x32_bf16 v[72:75], v[174:177], v[186:189], v[72:75]
	v_mfma_f32_16x16x32_bf16 v[56:59], v[174:177], v[194:197], v[56:59]
	v_mfma_f32_16x16x32_bf16 v[64:67], v[166:169], v[194:197], v[64:67]
	v_mfma_f32_16x16x32_bf16 v[52:55], v[166:169], v[202:205], v[52:55]
	v_mfma_f32_16x16x32_bf16 v[48:51], v[174:177], v[202:205], v[48:51]
	v_mfma_f32_16x16x32_bf16 v[32:35], v[174:177], v[210:213], v[32:35]
	v_mfma_f32_16x16x32_bf16 v[36:39], v[166:169], v[210:213], v[36:39]
	s_setprio 0
	s_barrier
	s_mov_b32 m0, s42
	v_lshl_add_u64 v[182:183], s[64:65], 0, v[130:131]
	ds_read_b128 v[178:181], v145 offset:16384
	ds_read_b128 v[186:189], v145 offset:17408
	ds_read_b128 v[190:193], v145 offset:18432
	ds_read_b128 v[194:197], v145 offset:19456
	ds_read_b128 v[198:201], v145 offset:20480
	ds_read_b128 v[202:205], v145 offset:21504
	ds_read_b128 v[206:209], v145 offset:22528
	ds_read_b128 v[210:213], v145 offset:23552
	global_load_lds_dwordx4 v[182:183], off
	v_lshl_add_u64 v[214:215], s[64:65], 0, v[134:135]
	s_mov_b32 m0, s97
	v_lshl_add_u64 v[216:217], s[66:67], 0, v[130:131]
	global_load_lds_dwordx4 v[214:215], off
	s_mov_b32 m0, vcc_hi
	v_lshl_add_u64 v[218:219], s[62:63], 0, v[132:133]
	global_load_lds_dwordx4 v[216:217], off
	v_lshl_add_u64 v[216:217], s[66:67], 0, v[134:135]
	s_mov_b32 m0, vcc_lo
	s_nop 0
	global_load_lds_dwordx4 v[216:217], off
	v_lshl_add_u64 v[216:217], s[62:63], 0, v[128:129]
	s_mov_b32 m0, s29
	s_nop 0
	global_load_lds_dwordx4 v[216:217], off
	s_mov_b32 m0, s33
	s_nop 0
	global_load_lds_dwordx4 v[218:219], off
	s_waitcnt vmcnt(8)
	s_waitcnt lgkmcnt(0)
	s_barrier
; #define PG8_STAGE(bufoff, gbase, voff) do { _Pragma("unroll") for (int _i = 0; _i < 2; ++_i) \
;         __builtin_amdgcn_global_load_lds((const unsigned*)((const char*)(gbase) + (voff)[_i]), (LAS unsigned*)(lds + (bufoff) + ldsw + _i * 8192), 16, 0, 0); } while (0)
; #define PG8_LDA(dst, b, h) do { _Pragma("unroll") for (int m = 0; m < 4; ++m) _Pragma("unroll") for (int k = 0; k < 2; ++k) dst[m][k] = *(const LAS bf16x8*)(lds + PG8_SA(b, h) + aoff + m * 2048 + k * 1024); } while (0)
; #define PG8_LDB(dst, b, h) do { _Pragma("unroll") for (int n = 0; n < 2; ++n) _Pragma("unroll") for (int k = 0; k < 2; ++k) dst[n][k] = *(const LAS bf16x8*)(lds + PG8_SB(b, h) + boff + n * 2048 + k * 1024); } while (0)
; #define PG8_MMA(ai, bj, At, Bt) do { __builtin_amdgcn_s_setprio(1); _Pragma("unroll") for (int m = 0; m < 4; ++m) _Pragma("unroll") for (int n = 0; n < 2; ++n) _Pragma("unroll") for (int k = 0; k < 2; ++k) \
;         acc[ai][bj][m][n] = __builtin_amdgcn_mfma_f32_16x16x32_bf16(Bt[n][k], At[m][k], acc[ai][bj][m][n], 0, 0, 0); __builtin_amdgcn_s_setprio(0); } while (0)
; #define PG8_WAIT_V(n) asm volatile("s_waitcnt vmcnt(" #n ")" ::: "memory")
; #define PG8_WAIT_L(n) asm volatile("s_waitcnt lgkmcnt(" #n ")" ::: "memory")
; #define PG8_BAR __builtin_amdgcn_s_barrier()
; #define PG8_SCHED __builtin_amdgcn_sched_barrier(0)
; template <class Epi, bool ALIGN_EPI = PG8_ALIGN>
; __device__ __forceinline__ void gemm_phase(LAS unsigned char* lds, const Gemm g, const StaticOrder S, const Epi E) {
;     ...
;             PG8_WAIT_V(8); PG8_WAIT_L(0); PG8_BAR; PG8_MMA(1, 0, At, B0); PG8_MMA(1, 1, At, B1); PG8_BAR; PG8_SCHED;
;             PG8_LDB(B0, 1, 0); PG8_LDB(B1, 1, 1); PG8_SCHED; PG8_LDA(At, 1, 0); PG8_STAGE(PG8_SA(0, 1), a2 + hstepA, voffA);
;             PG8_WAIT_V(8); PG8_WAIT_L(0); PG8_BAR; PG8_MMA(0, 0, At, B0); PG8_MMA(0, 1, At, B1); PG8_BAR; PG8_SCHED;
	s_setprio 1
	s_waitcnt lgkmcnt(0)
	v_mfma_f32_16x16x32_bf16 v[92:95], v[146:149], v[178:181], v[92:95]
	v_mfma_f32_16x16x32_bf16 v[88:91], v[154:157], v[178:181], v[88:91]
	v_mfma_f32_16x16x32_bf16 v[80:83], v[154:157], v[190:193], v[80:83]
	v_mfma_f32_16x16x32_bf16 v[84:87], v[146:149], v[190:193], v[84:87]
	v_mfma_f32_16x16x32_bf16 v[68:71], v[146:149], v[198:201], v[68:71]
	v_mfma_f32_16x16x32_bf16 v[60:63], v[154:157], v[198:201], v[60:63]
	v_mfma_f32_16x16x32_bf16 v[40:43], v[154:157], v[206:209], v[40:43]
	v_mfma_f32_16x16x32_bf16 v[44:47], v[146:149], v[206:209], v[44:47]
	v_mfma_f32_16x16x32_bf16 v[92:95], v[150:153], v[186:189], v[92:95]
	v_mfma_f32_16x16x32_bf16 v[88:91], v[158:161], v[186:189], v[88:91]
	v_mfma_f32_16x16x32_bf16 v[80:83], v[158:161], v[194:197], v[80:83]
	v_mfma_f32_16x16x32_bf16 v[84:87], v[150:153], v[194:197], v[84:87]
	v_mfma_f32_16x16x32_bf16 v[68:71], v[150:153], v[202:205], v[68:71]
	v_mfma_f32_16x16x32_bf16 v[60:63], v[158:161], v[202:205], v[60:63]
	v_mfma_f32_16x16x32_bf16 v[40:43], v[158:161], v[210:213], v[40:43]
	v_mfma_f32_16x16x32_bf16 v[44:47], v[150:153], v[210:213], v[44:47]
	s_setprio 0
	s_setprio 1
	v_mfma_f32_16x16x32_bf16 v[28:31], v[162:165], v[178:181], v[28:31]
	v_mfma_f32_16x16x32_bf16 v[24:27], v[170:173], v[178:181], v[24:27]
	v_mfma_f32_16x16x32_bf16 v[16:19], v[170:173], v[190:193], v[16:19]
	v_mfma_f32_16x16x32_bf16 v[20:23], v[162:165], v[190:193], v[20:23]
	v_mfma_f32_16x16x32_bf16 v[12:15], v[162:165], v[198:201], v[12:15]
	v_mfma_f32_16x16x32_bf16 v[8:11], v[170:173], v[198:201], v[8:11]
	v_mfma_f32_16x16x32_bf16 v[0:3], v[170:173], v[206:209], v[0:3]
	v_mfma_f32_16x16x32_bf16 v[4:7], v[162:165], v[206:209], v[4:7]
	v_mfma_f32_16x16x32_bf16 v[28:31], v[166:169], v[186:189], v[28:31]
	v_mfma_f32_16x16x32_bf16 v[24:27], v[174:177], v[186:189], v[24:27]
	v_mfma_f32_16x16x32_bf16 v[16:19], v[174:177], v[194:197], v[16:19]
	v_mfma_f32_16x16x32_bf16 v[20:23], v[166:169], v[194:197], v[20:23]
	v_mfma_f32_16x16x32_bf16 v[12:15], v[166:169], v[202:205], v[12:15]
	v_mfma_f32_16x16x32_bf16 v[8:11], v[174:177], v[202:205], v[8:11]
	v_mfma_f32_16x16x32_bf16 v[0:3], v[174:177], v[210:213], v[0:3]
	v_mfma_f32_16x16x32_bf16 v[4:7], v[166:169], v[210:213], v[4:7]
	s_setprio 0
	s_barrier
	v_add_u32_e32 v158, s95, v141
	v_add_u32_e32 v174, s93, v141
	ds_read_b128 v[146:149], v158
	ds_read_b128 v[150:153], v158 offset:1024
	ds_read_b128 v[154:157], v158 offset:2048
	ds_read_b128 v[158:161], v158 offset:3072
	ds_read_b128 v[162:165], v174
	ds_read_b128 v[166:169], v174 offset:1024
	ds_read_b128 v[170:173], v174 offset:2048
	ds_read_b128 v[174:177], v174 offset:3072
	s_mov_b32 m0, s34
	v_lshl_add_u64 v[220:221], s[60:61], 0, v[128:129]
	ds_read_b128 v[178:181], v145 offset:32768
	ds_read_b128 v[186:189], v145 offset:33792
	ds_read_b128 v[190:193], v145 offset:34816
	ds_read_b128 v[194:197], v145 offset:35840
	ds_read_b128 v[198:201], v145 offset:36864
	ds_read_b128 v[202:205], v145 offset:37888
	ds_read_b128 v[206:209], v145 offset:38912
	ds_read_b128 v[210:213], v145 offset:39936
	global_load_lds_dwordx4 v[220:221], off
	v_lshl_add_u64 v[220:221], s[60:61], 0, v[132:133]
	s_mov_b32 m0, s35
	s_nop 0
	global_load_lds_dwordx4 v[220:221], off
	s_waitcnt vmcnt(8)
	s_waitcnt lgkmcnt(0)
	s_barrier
	s_setprio 1
	s_waitcnt lgkmcnt(0)
	v_mfma_f32_16x16x32_bf16 v[124:127], v[146:149], v[178:181], v[124:127]
	v_mfma_f32_16x16x32_bf16 v[120:123], v[154:157], v[178:181], v[120:123]
	v_mfma_f32_16x16x32_bf16 v[112:115], v[154:157], v[190:193], v[112:115]
	v_mfma_f32_16x16x32_bf16 v[116:119], v[146:149], v[190:193], v[116:119]
	v_mfma_f32_16x16x32_bf16 v[108:111], v[146:149], v[198:201], v[108:111]
	v_mfma_f32_16x16x32_bf16 v[104:107], v[154:157], v[198:201], v[104:107]
	v_mfma_f32_16x16x32_bf16 v[96:99], v[154:157], v[206:209], v[96:99]
	v_mfma_f32_16x16x32_bf16 v[100:103], v[146:149], v[206:209], v[100:103]
	v_mfma_f32_16x16x32_bf16 v[124:127], v[150:153], v[186:189], v[124:127]
	v_mfma_f32_16x16x32_bf16 v[120:123], v[158:161], v[186:189], v[120:123]
	v_mfma_f32_16x16x32_bf16 v[112:115], v[158:161], v[194:197], v[112:115]
	v_mfma_f32_16x16x32_bf16 v[116:119], v[150:153], v[194:197], v[116:119]
	v_mfma_f32_16x16x32_bf16 v[108:111], v[150:153], v[202:205], v[108:111]
	v_mfma_f32_16x16x32_bf16 v[104:107], v[158:161], v[202:205], v[104:107]
	v_mfma_f32_16x16x32_bf16 v[96:99], v[158:161], v[210:213], v[96:99]
	v_mfma_f32_16x16x32_bf16 v[100:103], v[150:153], v[210:213], v[100:103]
	s_setprio 0
	s_setprio 1
	v_mfma_f32_16x16x32_bf16 v[76:79], v[162:165], v[178:181], v[76:79]
	v_mfma_f32_16x16x32_bf16 v[72:75], v[170:173], v[178:181], v[72:75]
	v_mfma_f32_16x16x32_bf16 v[56:59], v[170:173], v[190:193], v[56:59]
	v_mfma_f32_16x16x32_bf16 v[64:67], v[162:165], v[190:193], v[64:67]
	v_mfma_f32_16x16x32_bf16 v[52:55], v[162:165], v[198:201], v[52:55]
	v_mfma_f32_16x16x32_bf16 v[48:51], v[170:173], v[198:201], v[48:51]
	v_mfma_f32_16x16x32_bf16 v[32:35], v[170:173], v[206:209], v[32:35]
	v_mfma_f32_16x16x32_bf16 v[36:39], v[162:165], v[206:209], v[36:39]
	v_mfma_f32_16x16x32_bf16 v[76:79], v[166:169], v[186:189], v[76:79]
	v_mfma_f32_16x16x32_bf16 v[72:75], v[174:177], v[186:189], v[72:75]
	v_mfma_f32_16x16x32_bf16 v[56:59], v[174:177], v[194:197], v[56:59]
	v_mfma_f32_16x16x32_bf16 v[64:67], v[166:169], v[194:197], v[64:67]
	v_mfma_f32_16x16x32_bf16 v[52:55], v[166:169], v[202:205], v[52:55]
	v_mfma_f32_16x16x32_bf16 v[48:51], v[174:177], v[202:205], v[48:51]
	v_mfma_f32_16x16x32_bf16 v[32:35], v[174:177], v[210:213], v[32:35]
	v_mfma_f32_16x16x32_bf16 v[36:39], v[166:169], v[210:213], v[36:39]
	s_setprio 0
	s_barrier
; #define PG8_STAGE(bufoff, gbase, voff) do { _Pragma("unroll") for (int _i = 0; _i < 2; ++_i) \
;         __builtin_amdgcn_global_load_lds((const unsigned*)((const char*)(gbase) + (voff)[_i]), (LAS unsigned*)(lds + (bufoff) + ldsw + _i * 8192), 16, 0, 0); } while (0)
; #define PG8_LDA(dst, b, h) do { _Pragma("unroll") for (int m = 0; m < 4; ++m) _Pragma("unroll") for (int k = 0; k < 2; ++k) dst[m][k] = *(const LAS bf16x8*)(lds + PG8_SA(b, h) + aoff + m * 2048 + k * 1024); } while (0)
; #define PG8_MMA(ai, bj, At, Bt) do { __builtin_amdgcn_s_setprio(1); _Pragma("unroll") for (int m = 0; m < 4; ++m) _Pragma("unroll") for (int n = 0; n < 2; ++n) _Pragma("unroll") for (int k = 0; k < 2; ++k) \
;         acc[ai][bj][m][n] = __builtin_amdgcn_mfma_f32_16x16x32_bf16(Bt[n][k], At[m][k], acc[ai][bj][m][n], 0, 0, 0); __builtin_amdgcn_s_setprio(0); } while (0)
; #define PG8_WAIT_V(n) asm volatile("s_waitcnt vmcnt(" #n ")" ::: "memory")
; #define PG8_WAIT_L(n) asm volatile("s_waitcnt lgkmcnt(" #n ")" ::: "memory")
; #define PG8_BAR __builtin_amdgcn_s_barrier()
; #define PG8_SCHED __builtin_amdgcn_sched_barrier(0)
; template <class Epi, bool ALIGN_EPI = PG8_ALIGN>
; __device__ __forceinline__ void gemm_phase(LAS unsigned char* lds, const Gemm g, const StaticOrder S, const Epi E) {
;     ...
;             PG8_LDA(At, 1, 1); PG8_STAGE(PG8_SB(1, 0), b3, voffB); PG8_STAGE(PG8_SB(1, 1), b3 + hstepB, voffB); PG8_STAGE(PG8_SA(1, 0), a3, voffA);
;             PG8_WAIT_V(8); PG8_WAIT_L(0); PG8_BAR; PG8_MMA(1, 0, At, B0); PG8_MMA(1, 1, At, B1); PG8_BAR; PG8_SCHED;
;         }
;         if (ALIGN_EPI) { if (wr == 0) PG8_BAR; }
	s_mov_b32 m0, s92
	v_lshl_add_u64 v[182:183], v[182:183], 0, s[12:13]
	ds_read_b128 v[178:181], v145 offset:49152
	ds_read_b128 v[186:189], v145 offset:50176
	ds_read_b128 v[190:193], v145 offset:51200
	ds_read_b128 v[194:197], v145 offset:52224
	ds_read_b128 v[198:201], v145 offset:53248
	ds_read_b128 v[202:205], v145 offset:54272
	ds_read_b128 v[206:209], v145 offset:55296
	ds_read_b128 v[210:213], v145 offset:56320
	global_load_lds_dwordx4 v[182:183], off
	v_lshl_add_u64 v[182:183], v[214:215], 0, s[12:13]
	s_mov_b32 m0, s90
	s_nop 0
	global_load_lds_dwordx4 v[182:183], off
	v_lshl_add_u64 v[182:183], s[58:59], 0, v[130:131]
	s_mov_b32 m0, s91
	s_nop 0
	global_load_lds_dwordx4 v[182:183], off
	v_lshl_add_u64 v[182:183], s[58:59], 0, v[134:135]
	s_mov_b32 m0, s83
	s_nop 0
	global_load_lds_dwordx4 v[182:183], off
	v_lshl_add_u64 v[182:183], v[216:217], 0, s[12:13]
	s_mov_b32 m0, s74
	s_nop 0
	global_load_lds_dwordx4 v[182:183], off
	v_lshl_add_u64 v[182:183], v[218:219], 0, s[12:13]
	s_mov_b32 m0, s75
	s_nop 0
	global_load_lds_dwordx4 v[182:183], off
	s_waitcnt vmcnt(8)
	s_waitcnt lgkmcnt(0)
	s_barrier
	s_setprio 1
	s_waitcnt lgkmcnt(0)
	v_mfma_f32_16x16x32_bf16 v[92:95], v[146:149], v[178:181], v[92:95]
	v_mfma_f32_16x16x32_bf16 v[88:91], v[154:157], v[178:181], v[88:91]
	v_mfma_f32_16x16x32_bf16 v[80:83], v[154:157], v[190:193], v[80:83]
	v_mfma_f32_16x16x32_bf16 v[84:87], v[146:149], v[190:193], v[84:87]
	v_mfma_f32_16x16x32_bf16 v[68:71], v[146:149], v[198:201], v[68:71]
	v_mfma_f32_16x16x32_bf16 v[60:63], v[154:157], v[198:201], v[60:63]
	v_mfma_f32_16x16x32_bf16 v[40:43], v[154:157], v[206:209], v[40:43]
	v_mfma_f32_16x16x32_bf16 v[44:47], v[146:149], v[206:209], v[44:47]
	v_mfma_f32_16x16x32_bf16 v[92:95], v[150:153], v[186:189], v[92:95]
	v_mfma_f32_16x16x32_bf16 v[88:91], v[158:161], v[186:189], v[88:91]
	v_mfma_f32_16x16x32_bf16 v[80:83], v[158:161], v[194:197], v[80:83]
	v_mfma_f32_16x16x32_bf16 v[84:87], v[150:153], v[194:197], v[84:87]
	v_mfma_f32_16x16x32_bf16 v[68:71], v[150:153], v[202:205], v[68:71]
	v_mfma_f32_16x16x32_bf16 v[60:63], v[158:161], v[202:205], v[60:63]
	v_mfma_f32_16x16x32_bf16 v[40:43], v[158:161], v[210:213], v[40:43]
	v_mfma_f32_16x16x32_bf16 v[44:47], v[150:153], v[210:213], v[44:47]
	s_setprio 0
	s_setprio 1
	v_mfma_f32_16x16x32_bf16 v[28:31], v[162:165], v[178:181], v[28:31]
	v_mfma_f32_16x16x32_bf16 v[24:27], v[170:173], v[178:181], v[24:27]
	v_mfma_f32_16x16x32_bf16 v[16:19], v[170:173], v[190:193], v[16:19]
	v_mfma_f32_16x16x32_bf16 v[20:23], v[162:165], v[190:193], v[20:23]
	v_mfma_f32_16x16x32_bf16 v[12:15], v[162:165], v[198:201], v[12:15]
	v_mfma_f32_16x16x32_bf16 v[8:11], v[170:173], v[198:201], v[8:11]
	v_mfma_f32_16x16x32_bf16 v[0:3], v[170:173], v[206:209], v[0:3]
	v_mfma_f32_16x16x32_bf16 v[4:7], v[162:165], v[206:209], v[4:7]
	v_mfma_f32_16x16x32_bf16 v[28:31], v[166:169], v[186:189], v[28:31]
	v_mfma_f32_16x16x32_bf16 v[24:27], v[174:177], v[186:189], v[24:27]
	v_mfma_f32_16x16x32_bf16 v[16:19], v[174:177], v[194:197], v[16:19]
	v_mfma_f32_16x16x32_bf16 v[20:23], v[166:169], v[194:197], v[20:23]
	v_mfma_f32_16x16x32_bf16 v[12:15], v[166:169], v[202:205], v[12:15]
	v_mfma_f32_16x16x32_bf16 v[8:11], v[174:177], v[202:205], v[8:11]
	v_mfma_f32_16x16x32_bf16 v[0:3], v[174:177], v[210:213], v[0:3]
	v_mfma_f32_16x16x32_bf16 v[4:7], v[166:169], v[210:213], v[4:7]
	s_setprio 0
	s_barrier
	s_movk_i32 s60, 0x100
	s_andn2_b64 vcc, exec, s[54:55]
	s_mov_b64 s[58:59], -1
	s_mov_b64 s[54:55], 0
	s_cbranch_vccz .LBB0_917
	s_and_b64 vcc, exec, s[22:23]
	s_cbranch_vccz .LBB0_920
	s_barrier

; #define PG8_STAGE(bufoff, gbase, voff) do { _Pragma("unroll") for (int _i = 0; _i < 2; ++_i) \
;         __builtin_amdgcn_global_load_lds((const unsigned*)((const char*)(gbase) + (voff)[_i]), (LAS unsigned*)(lds + (bufoff) + ldsw + _i * 8192), 16, 0, 0); } while (0)
; #define PG8_LDA(dst, b, h) do { _Pragma("unroll") for (int m = 0; m < 4; ++m) _Pragma("unroll") for (int k = 0; k < 2; ++k) dst[m][k] = *(const LAS bf16x8*)(lds + PG8_SA(b, h) + aoff + m * 2048 + k * 1024); } while (0)
; #define PG8_LDB(dst, b, h) do { _Pragma("unroll") for (int n = 0; n < 2; ++n) _Pragma("unroll") for (int k = 0; k < 2; ++k) dst[n][k] = *(const LAS bf16x8*)(lds + PG8_SB(b, h) + boff + n * 2048 + k * 1024); } while (0)
; #define PG8_MMA(ai, bj, At, Bt) do { __builtin_amdgcn_s_setprio(1); _Pragma("unroll") for (int m = 0; m < 4; ++m) _Pragma("unroll") for (int n = 0; n < 2; ++n) _Pragma("unroll") for (int k = 0; k < 2; ++k) \
;         acc[ai][bj][m][n] = __builtin_amdgcn_mfma_f32_16x16x32_bf16(Bt[n][k], At[m][k], acc[ai][bj][m][n], 0, 0, 0); __builtin_amdgcn_s_setprio(0); } while (0)
; #define PG8_WAIT_V(n) asm volatile("s_waitcnt vmcnt(" #n ")" ::: "memory")
; #define PG8_WAIT_L(n) asm volatile("s_waitcnt lgkmcnt(" #n ")" ::: "memory")
; #define PG8_BAR __builtin_amdgcn_s_barrier()
; #define PG8_SCHED __builtin_amdgcn_sched_barrier(0)
; template <class Epi, bool ALIGN_EPI = PG8_ALIGN>
; __device__ __forceinline__ void gemm_phase(LAS unsigned char* lds, const Gemm g, const StaticOrder S, const Epi E) {
;     ...
;             const bool last = (t == nt - 2);
;             const char* a1 = cA + (size_t)(t + 1) * kstep;
;             const char* a2 = last ? nA : cA + (size_t)(t + 2) * kstep; const char* b2 = last ? nB : cB + (size_t)(t + 2) * kstep;
;             const char* a3 = a2 + kstep; const char* b3 = b2 + kstep;
;             PG8_LDB(B0, 0, 0); PG8_LDB(B1, 0, 1); PG8_SCHED; PG8_LDA(At, 0, 0); PG8_STAGE(PG8_SA(1, 1), a1 + hstepA, voffA);
;             PG8_WAIT_V(8); PG8_WAIT_L(0); PG8_BAR; PG8_MMA(0, 0, At, B0); PG8_MMA(0, 1, At, B1); PG8_BAR; PG8_SCHED;
;             PG8_LDA(At, 0, 1); PG8_STAGE(PG8_SB(0, 0), b2, voffB); PG8_STAGE(PG8_SB(0, 1), b2 + hstepB, voffB); PG8_STAGE(PG8_SA(0, 0), a2, voffA);
.LBB0_1205:
	ds_read_b128 v[146:149], v151
	ds_read_b128 v[154:157], v151 offset:1024
	ds_read_b128 v[158:161], v151 offset:2048
	ds_read_b128 v[162:165], v151 offset:3072
	ds_read_b128 v[166:169], v152
	ds_read_b128 v[170:173], v152 offset:1024
	ds_read_b128 v[174:177], v152 offset:2048
	ds_read_b128 v[178:181], v152 offset:3072
	s_add_u32 s35, s46, 0xfff80080
	s_addc_u32 s37, s47, -1
	s_cmp_eq_u32 s34, 28
	s_cselect_b32 s51, s13, s37
	s_cselect_b32 s50, s14, s35
	s_cselect_b32 s49, s16, s33
	s_cselect_b32 s48, s17, s29
	v_lshl_add_u64 v[182:183], s[46:47], 0, v[138:139]
	s_add_i32 m0, s45, 0xc000
	ds_read_b128 v[186:189], v153
	ds_read_b128 v[190:193], v153 offset:1024
	ds_read_b128 v[194:197], v153 offset:2048
	ds_read_b128 v[198:201], v153 offset:3072
	ds_read_b128 v[202:205], v153 offset:4096
	ds_read_b128 v[206:209], v153 offset:5120
	ds_read_b128 v[210:213], v153 offset:6144
	ds_read_b128 v[214:217], v153 offset:7168
	global_load_lds_dwordx4 v[182:183], off
	v_lshl_add_u64 v[182:183], s[46:47], 0, v[140:141]
	s_add_i32 m0, s45, 0xe000
	s_nop 0
	global_load_lds_dwordx4 v[182:183], off
	s_waitcnt vmcnt(8)
	s_waitcnt lgkmcnt(0)
	s_barrier
	s_setprio 1
	s_waitcnt lgkmcnt(0)
	v_mfma_f32_16x16x32_bf16 v[124:127], v[146:149], v[186:189], v[124:127]
	v_mfma_f32_16x16x32_bf16 v[120:123], v[158:161], v[186:189], v[120:123]
	v_mfma_f32_16x16x32_bf16 v[104:107], v[158:161], v[194:197], v[104:107]
	v_mfma_f32_16x16x32_bf16 v[108:111], v[146:149], v[194:197], v[108:111]
	v_mfma_f32_16x16x32_bf16 v[92:95], v[146:149], v[202:205], v[92:95]
	v_mfma_f32_16x16x32_bf16 v[88:91], v[158:161], v[202:205], v[88:91]
	v_mfma_f32_16x16x32_bf16 v[72:75], v[158:161], v[210:213], v[72:75]
	v_mfma_f32_16x16x32_bf16 v[76:79], v[146:149], v[210:213], v[76:79]
	v_mfma_f32_16x16x32_bf16 v[124:127], v[154:157], v[190:193], v[124:127]
	v_mfma_f32_16x16x32_bf16 v[120:123], v[162:165], v[190:193], v[120:123]
	v_mfma_f32_16x16x32_bf16 v[104:107], v[162:165], v[198:201], v[104:107]
	v_mfma_f32_16x16x32_bf16 v[108:111], v[154:157], v[198:201], v[108:111]
	v_mfma_f32_16x16x32_bf16 v[92:95], v[154:157], v[206:209], v[92:95]
	v_mfma_f32_16x16x32_bf16 v[88:91], v[162:165], v[206:209], v[88:91]
	v_mfma_f32_16x16x32_bf16 v[72:75], v[162:165], v[214:217], v[72:75]
	v_mfma_f32_16x16x32_bf16 v[76:79], v[154:157], v[214:217], v[76:79]
	s_setprio 0
	s_setprio 1
	v_mfma_f32_16x16x32_bf16 v[116:119], v[166:169], v[186:189], v[116:119]
	v_mfma_f32_16x16x32_bf16 v[112:115], v[174:177], v[186:189], v[112:115]
	v_mfma_f32_16x16x32_bf16 v[96:99], v[174:177], v[194:197], v[96:99]
	v_mfma_f32_16x16x32_bf16 v[100:103], v[166:169], v[194:197], v[100:103]
	v_mfma_f32_16x16x32_bf16 v[84:87], v[166:169], v[202:205], v[84:87]
	v_mfma_f32_16x16x32_bf16 v[80:83], v[174:177], v[202:205], v[80:83]
	v_mfma_f32_16x16x32_bf16 v[64:67], v[174:177], v[210:213], v[64:67]
	v_mfma_f32_16x16x32_bf16 v[68:71], v[166:169], v[210:213], v[68:71]
	v_mfma_f32_16x16x32_bf16 v[116:119], v[170:173], v[190:193], v[116:119]
	v_mfma_f32_16x16x32_bf16 v[112:115], v[178:181], v[190:193], v[112:115]
	v_mfma_f32_16x16x32_bf16 v[96:99], v[178:181], v[198:201], v[96:99]
	v_mfma_f32_16x16x32_bf16 v[100:103], v[170:173], v[198:201], v[100:103]
	v_mfma_f32_16x16x32_bf16 v[84:87], v[170:173], v[206:209], v[84:87]
	v_mfma_f32_16x16x32_bf16 v[80:83], v[178:181], v[206:209], v[80:83]
	v_mfma_f32_16x16x32_bf16 v[64:67], v[178:181], v[214:217], v[64:67]
	v_mfma_f32_16x16x32_bf16 v[68:71], v[170:173], v[214:217], v[68:71]
	s_setprio 0
	s_barrier
	s_add_i32 s35, s61, s52
	v_lshl_add_u64 v[182:183], s[48:49], 0, v[130:131]
	s_mov_b32 m0, s35
	ds_read_b128 v[186:189], v153 offset:16384
	ds_read_b128 v[190:193], v153 offset:17408
	ds_read_b128 v[194:197], v153 offset:18432
	ds_read_b128 v[198:201], v153 offset:19456
	ds_read_b128 v[202:205], v153 offset:20480
	ds_read_b128 v[206:209], v153 offset:21504
	ds_read_b128 v[210:213], v153 offset:22528
	ds_read_b128 v[214:217], v153 offset:23552
	global_load_lds_dwordx4 v[182:183], off
	s_add_i32 m0, s35, 0x2000
	s_add_u32 s64, s48, 0x80000
	v_lshl_add_u64 v[218:219], s[48:49], 0, v[134:135]
	s_addc_u32 s65, s49, 0
	s_add_i32 s35, s62, s52
	global_load_lds_dwordx4 v[218:219], off
	v_lshl_add_u64 v[220:221], s[64:65], 0, v[130:131]
	s_mov_b32 m0, s35
	v_lshl_add_u64 v[222:223], s[50:51], 0, v[132:133]
	global_load_lds_dwordx4 v[220:221], off
	v_lshl_add_u64 v[220:221], s[64:65], 0, v[134:135]
	s_add_i32 m0, s35, 0x2000
	s_nop 0
	global_load_lds_dwordx4 v[220:221], off
	v_lshl_add_u64 v[220:221], s[50:51], 0, v[128:129]
	s_mov_b32 m0, s45
	s_nop 0
	global_load_lds_dwordx4 v[220:221], off
	s_mov_b32 m0, s53
	s_nop 0
	global_load_lds_dwordx4 v[222:223], off
	s_waitcnt vmcnt(8)
	s_waitcnt lgkmcnt(0)
	s_barrier
; #define PG8_STAGE(bufoff, gbase, voff) do { _Pragma("unroll") for (int _i = 0; _i < 2; ++_i) \
;         __builtin_amdgcn_global_load_lds((const unsigned*)((const char*)(gbase) + (voff)[_i]), (LAS unsigned*)(lds + (bufoff) + ldsw + _i * 8192), 16, 0, 0); } while (0)
; #define PG8_LDA(dst, b, h) do { _Pragma("unroll") for (int m = 0; m < 4; ++m) _Pragma("unroll") for (int k = 0; k < 2; ++k) dst[m][k] = *(const LAS bf16x8*)(lds + PG8_SA(b, h) + aoff + m * 2048 + k * 1024); } while (0)
; #define PG8_LDB(dst, b, h) do { _Pragma("unroll") for (int n = 0; n < 2; ++n) _Pragma("unroll") for (int k = 0; k < 2; ++k) dst[n][k] = *(const LAS bf16x8*)(lds + PG8_SB(b, h) + boff + n * 2048 + k * 1024); } while (0)
; #define PG8_MMA(ai, bj, At, Bt) do { __builtin_amdgcn_s_setprio(1); _Pragma("unroll") for (int m = 0; m < 4; ++m) _Pragma("unroll") for (int n = 0; n < 2; ++n) _Pragma("unroll") for (int k = 0; k < 2; ++k) \
;         acc[ai][bj][m][n] = __builtin_amdgcn_mfma_f32_16x16x32_bf16(Bt[n][k], At[m][k], acc[ai][bj][m][n], 0, 0, 0); __builtin_amdgcn_s_setprio(0); } while (0)
; #define PG8_WAIT_V(n) asm volatile("s_waitcnt vmcnt(" #n ")" ::: "memory")
; #define PG8_WAIT_L(n) asm volatile("s_waitcnt lgkmcnt(" #n ")" ::: "memory")
; #define PG8_BAR __builtin_amdgcn_s_barrier()
; #define PG8_SCHED __builtin_amdgcn_sched_barrier(0)
; template <class Epi, bool ALIGN_EPI = PG8_ALIGN>
; __device__ __forceinline__ void gemm_phase(LAS unsigned char* lds, const Gemm g, const StaticOrder S, const Epi E) {
;     ...
;             PG8_WAIT_V(8); PG8_WAIT_L(0); PG8_BAR; PG8_MMA(1, 0, At, B0); PG8_MMA(1, 1, At, B1); PG8_BAR; PG8_SCHED;
;             PG8_LDB(B0, 1, 0); PG8_LDB(B1, 1, 1); PG8_SCHED; PG8_LDA(At, 1, 0); PG8_STAGE(PG8_SA(0, 1), a2 + hstepA, voffA);
;             PG8_WAIT_V(8); PG8_WAIT_L(0); PG8_BAR; PG8_MMA(0, 0, At, B0); PG8_MMA(0, 1, At, B1); PG8_BAR; PG8_SCHED;
	s_setprio 1
	s_waitcnt lgkmcnt(0)
	v_mfma_f32_16x16x32_bf16 v[60:63], v[146:149], v[186:189], v[60:63]
	v_mfma_f32_16x16x32_bf16 v[56:59], v[158:161], v[186:189], v[56:59]
	v_mfma_f32_16x16x32_bf16 v[40:43], v[158:161], v[194:197], v[40:43]
	v_mfma_f32_16x16x32_bf16 v[44:47], v[146:149], v[194:197], v[44:47]
	v_mfma_f32_16x16x32_bf16 v[28:31], v[146:149], v[202:205], v[28:31]
	v_mfma_f32_16x16x32_bf16 v[24:27], v[158:161], v[202:205], v[24:27]
	v_mfma_f32_16x16x32_bf16 v[8:11], v[158:161], v[210:213], v[8:11]
	v_mfma_f32_16x16x32_bf16 v[12:15], v[146:149], v[210:213], v[12:15]
	v_mfma_f32_16x16x32_bf16 v[60:63], v[154:157], v[190:193], v[60:63]
	v_mfma_f32_16x16x32_bf16 v[56:59], v[162:165], v[190:193], v[56:59]
	v_mfma_f32_16x16x32_bf16 v[40:43], v[162:165], v[198:201], v[40:43]
	v_mfma_f32_16x16x32_bf16 v[44:47], v[154:157], v[198:201], v[44:47]
	v_mfma_f32_16x16x32_bf16 v[28:31], v[154:157], v[206:209], v[28:31]
	v_mfma_f32_16x16x32_bf16 v[24:27], v[162:165], v[206:209], v[24:27]
	v_mfma_f32_16x16x32_bf16 v[8:11], v[162:165], v[214:217], v[8:11]
	v_mfma_f32_16x16x32_bf16 v[12:15], v[154:157], v[214:217], v[12:15]
	s_setprio 0
	s_setprio 1
	v_mfma_f32_16x16x32_bf16 v[52:55], v[166:169], v[186:189], v[52:55]
	v_mfma_f32_16x16x32_bf16 v[48:51], v[174:177], v[186:189], v[48:51]
	v_mfma_f32_16x16x32_bf16 v[32:35], v[174:177], v[194:197], v[32:35]
	v_mfma_f32_16x16x32_bf16 v[36:39], v[166:169], v[194:197], v[36:39]
	v_mfma_f32_16x16x32_bf16 v[20:23], v[166:169], v[202:205], v[20:23]
	v_mfma_f32_16x16x32_bf16 v[16:19], v[174:177], v[202:205], v[16:19]
	v_mfma_f32_16x16x32_bf16 v[0:3], v[174:177], v[210:213], v[0:3]
	v_mfma_f32_16x16x32_bf16 v[4:7], v[166:169], v[210:213], v[4:7]
	v_mfma_f32_16x16x32_bf16 v[52:55], v[170:173], v[190:193], v[52:55]
	v_mfma_f32_16x16x32_bf16 v[48:51], v[178:181], v[190:193], v[48:51]
	v_mfma_f32_16x16x32_bf16 v[32:35], v[178:181], v[198:201], v[32:35]
	v_mfma_f32_16x16x32_bf16 v[36:39], v[170:173], v[198:201], v[36:39]
	v_mfma_f32_16x16x32_bf16 v[20:23], v[170:173], v[206:209], v[20:23]
	v_mfma_f32_16x16x32_bf16 v[16:19], v[178:181], v[206:209], v[16:19]
	v_mfma_f32_16x16x32_bf16 v[0:3], v[178:181], v[214:217], v[0:3]
	v_mfma_f32_16x16x32_bf16 v[4:7], v[170:173], v[214:217], v[4:7]
	s_setprio 0
	s_barrier
	s_add_i32 s35, 0, 0x18000
	s_add_i32 s37, 0, 0x1c000
	v_add_u32_e32 v162, s35, v150
	v_add_u32_e32 v178, s37, v150
	ds_read_b128 v[146:149], v162
	ds_read_b128 v[154:157], v162 offset:1024
	ds_read_b128 v[158:161], v162 offset:2048
	ds_read_b128 v[162:165], v162 offset:3072
	ds_read_b128 v[166:169], v178
	ds_read_b128 v[170:173], v178 offset:1024
	ds_read_b128 v[174:177], v178 offset:2048
	ds_read_b128 v[178:181], v178 offset:3072
	s_add_u32 s50, s50, 0x80000
	s_addc_u32 s51, s51, 0
	s_mov_b32 m0, s54
	v_lshl_add_u64 v[224:225], s[50:51], 0, v[128:129]
	ds_read_b128 v[186:189], v153 offset:32768
	ds_read_b128 v[190:193], v153 offset:33792
	ds_read_b128 v[194:197], v153 offset:34816
	ds_read_b128 v[198:201], v153 offset:35840
	ds_read_b128 v[202:205], v153 offset:36864
	ds_read_b128 v[206:209], v153 offset:37888
	ds_read_b128 v[210:213], v153 offset:38912
	ds_read_b128 v[214:217], v153 offset:39936
	global_load_lds_dwordx4 v[224:225], off
	v_lshl_add_u64 v[224:225], s[50:51], 0, v[132:133]
	s_mov_b32 m0, s55
	s_nop 0
	global_load_lds_dwordx4 v[224:225], off
	s_waitcnt vmcnt(8)
	s_waitcnt lgkmcnt(0)
	s_barrier
	s_setprio 1
	s_waitcnt lgkmcnt(0)
	v_mfma_f32_16x16x32_bf16 v[124:127], v[146:149], v[186:189], v[124:127]
	v_mfma_f32_16x16x32_bf16 v[120:123], v[158:161], v[186:189], v[120:123]
	v_mfma_f32_16x16x32_bf16 v[104:107], v[158:161], v[194:197], v[104:107]
	v_mfma_f32_16x16x32_bf16 v[108:111], v[146:149], v[194:197], v[108:111]
	v_mfma_f32_16x16x32_bf16 v[92:95], v[146:149], v[202:205], v[92:95]
	v_mfma_f32_16x16x32_bf16 v[88:91], v[158:161], v[202:205], v[88:91]
	v_mfma_f32_16x16x32_bf16 v[72:75], v[158:161], v[210:213], v[72:75]
	v_mfma_f32_16x16x32_bf16 v[76:79], v[146:149], v[210:213], v[76:79]
	v_mfma_f32_16x16x32_bf16 v[124:127], v[154:157], v[190:193], v[124:127]
	v_mfma_f32_16x16x32_bf16 v[120:123], v[162:165], v[190:193], v[120:123]
	v_mfma_f32_16x16x32_bf16 v[104:107], v[162:165], v[198:201], v[104:107]
	v_mfma_f32_16x16x32_bf16 v[108:111], v[154:157], v[198:201], v[108:111]
	v_mfma_f32_16x16x32_bf16 v[92:95], v[154:157], v[206:209], v[92:95]
	v_mfma_f32_16x16x32_bf16 v[88:91], v[162:165], v[206:209], v[88:91]
	v_mfma_f32_16x16x32_bf16 v[72:75], v[162:165], v[214:217], v[72:75]
	v_mfma_f32_16x16x32_bf16 v[76:79], v[154:157], v[214:217], v[76:79]
	s_setprio 0
	s_setprio 1
	v_mfma_f32_16x16x32_bf16 v[116:119], v[166:169], v[186:189], v[116:119]
	v_mfma_f32_16x16x32_bf16 v[112:115], v[174:177], v[186:189], v[112:115]
	v_mfma_f32_16x16x32_bf16 v[96:99], v[174:177], v[194:197], v[96:99]
	v_mfma_f32_16x16x32_bf16 v[100:103], v[166:169], v[194:197], v[100:103]
	v_mfma_f32_16x16x32_bf16 v[84:87], v[166:169], v[202:205], v[84:87]
	v_mfma_f32_16x16x32_bf16 v[80:83], v[174:177], v[202:205], v[80:83]
	v_mfma_f32_16x16x32_bf16 v[64:67], v[174:177], v[210:213], v[64:67]
	v_mfma_f32_16x16x32_bf16 v[68:71], v[166:169], v[210:213], v[68:71]
	v_mfma_f32_16x16x32_bf16 v[116:119], v[170:173], v[190:193], v[116:119]
	v_mfma_f32_16x16x32_bf16 v[112:115], v[178:181], v[190:193], v[112:115]
	v_mfma_f32_16x16x32_bf16 v[96:99], v[178:181], v[198:201], v[96:99]
	v_mfma_f32_16x16x32_bf16 v[100:103], v[170:173], v[198:201], v[100:103]
	v_mfma_f32_16x16x32_bf16 v[84:87], v[170:173], v[206:209], v[84:87]
	v_mfma_f32_16x16x32_bf16 v[80:83], v[178:181], v[206:209], v[80:83]
	v_mfma_f32_16x16x32_bf16 v[64:67], v[178:181], v[214:217], v[64:67]
	v_mfma_f32_16x16x32_bf16 v[68:71], v[170:173], v[214:217], v[68:71]
	s_setprio 0
	s_barrier
; #define PG8_STAGE(bufoff, gbase, voff) do { _Pragma("unroll") for (int _i = 0; _i < 2; ++_i) \
;         __builtin_amdgcn_global_load_lds((const unsigned*)((const char*)(gbase) + (voff)[_i]), (LAS unsigned*)(lds + (bufoff) + ldsw + _i * 8192), 16, 0, 0); } while (0)
; #define PG8_LDA(dst, b, h) do { _Pragma("unroll") for (int m = 0; m < 4; ++m) _Pragma("unroll") for (int k = 0; k < 2; ++k) dst[m][k] = *(const LAS bf16x8*)(lds + PG8_SA(b, h) + aoff + m * 2048 + k * 1024); } while (0)
; #define PG8_MMA(ai, bj, At, Bt) do { __builtin_amdgcn_s_setprio(1); _Pragma("unroll") for (int m = 0; m < 4; ++m) _Pragma("unroll") for (int n = 0; n < 2; ++n) _Pragma("unroll") for (int k = 0; k < 2; ++k) \
;         acc[ai][bj][m][n] = __builtin_amdgcn_mfma_f32_16x16x32_bf16(Bt[n][k], At[m][k], acc[ai][bj][m][n], 0, 0, 0); __builtin_amdgcn_s_setprio(0); } while (0)
; #define PG8_WAIT_V(n) asm volatile("s_waitcnt vmcnt(" #n ")" ::: "memory")
; #define PG8_WAIT_L(n) asm volatile("s_waitcnt lgkmcnt(" #n ")" ::: "memory")
; #define PG8_BAR __builtin_amdgcn_s_barrier()
; #define PG8_SCHED __builtin_amdgcn_sched_barrier(0)
; template <class Epi, bool ALIGN_EPI = PG8_ALIGN>
; __device__ __forceinline__ void gemm_phase(LAS unsigned char* lds, const Gemm g, const StaticOrder S, const Epi E) {
;     ...
;             PG8_LDA(At, 1, 1); PG8_STAGE(PG8_SB(1, 0), b3, voffB); PG8_STAGE(PG8_SB(1, 1), b3 + hstepB, voffB); PG8_STAGE(PG8_SA(1, 0), a3, voffA);
;             PG8_WAIT_V(8); PG8_WAIT_L(0); PG8_BAR; PG8_MMA(1, 0, At, B0); PG8_MMA(1, 1, At, B1); PG8_BAR; PG8_SCHED;
;         }
;         if (ALIGN_EPI) { if (wr == 0) PG8_BAR; }
	s_add_i32 s35, s35, s52
	v_lshl_add_u64 v[182:183], v[182:183], 0, s[24:25]
	s_mov_b32 m0, s35
	ds_read_b128 v[186:189], v153 offset:49152
	ds_read_b128 v[190:193], v153 offset:50176
	ds_read_b128 v[194:197], v153 offset:51200
	ds_read_b128 v[198:201], v153 offset:52224
	ds_read_b128 v[202:205], v153 offset:53248
	ds_read_b128 v[206:209], v153 offset:54272
	ds_read_b128 v[210:213], v153 offset:55296
	ds_read_b128 v[214:217], v153 offset:56320
	global_load_lds_dwordx4 v[182:183], off
	s_add_i32 m0, s35, 0x2000
	s_add_u32 s48, s48, 0x80080
	v_lshl_add_u64 v[182:183], v[218:219], 0, s[24:25]
	s_addc_u32 s49, s49, 0
	s_add_i32 s35, s37, s52
	global_load_lds_dwordx4 v[182:183], off
	v_lshl_add_u64 v[182:183], s[48:49], 0, v[130:131]
	s_mov_b32 m0, s35
	s_nop 0
	global_load_lds_dwordx4 v[182:183], off
	v_lshl_add_u64 v[182:183], s[48:49], 0, v[134:135]
	s_add_i32 m0, s35, 0x2000
	s_nop 0
	global_load_lds_dwordx4 v[182:183], off
	v_lshl_add_u64 v[182:183], v[220:221], 0, s[24:25]
	s_mov_b32 m0, s58
	s_nop 0
	global_load_lds_dwordx4 v[182:183], off
	v_lshl_add_u64 v[182:183], v[222:223], 0, s[24:25]
	s_mov_b32 m0, s59
	s_nop 0
	global_load_lds_dwordx4 v[182:183], off
	s_waitcnt vmcnt(8)
	s_waitcnt lgkmcnt(0)
	s_barrier
	s_setprio 1
	s_waitcnt lgkmcnt(0)
	v_mfma_f32_16x16x32_bf16 v[60:63], v[146:149], v[186:189], v[60:63]
	v_mfma_f32_16x16x32_bf16 v[56:59], v[158:161], v[186:189], v[56:59]
	v_mfma_f32_16x16x32_bf16 v[40:43], v[158:161], v[194:197], v[40:43]
	v_mfma_f32_16x16x32_bf16 v[44:47], v[146:149], v[194:197], v[44:47]
	v_mfma_f32_16x16x32_bf16 v[28:31], v[146:149], v[202:205], v[28:31]
	v_mfma_f32_16x16x32_bf16 v[24:27], v[158:161], v[202:205], v[24:27]
	v_mfma_f32_16x16x32_bf16 v[8:11], v[158:161], v[210:213], v[8:11]
	v_mfma_f32_16x16x32_bf16 v[12:15], v[146:149], v[210:213], v[12:15]
	v_mfma_f32_16x16x32_bf16 v[60:63], v[154:157], v[190:193], v[60:63]
	v_mfma_f32_16x16x32_bf16 v[56:59], v[162:165], v[190:193], v[56:59]
	v_mfma_f32_16x16x32_bf16 v[40:43], v[162:165], v[198:201], v[40:43]
	v_mfma_f32_16x16x32_bf16 v[44:47], v[154:157], v[198:201], v[44:47]
	v_mfma_f32_16x16x32_bf16 v[28:31], v[154:157], v[206:209], v[28:31]
	v_mfma_f32_16x16x32_bf16 v[24:27], v[162:165], v[206:209], v[24:27]
	v_mfma_f32_16x16x32_bf16 v[8:11], v[162:165], v[214:217], v[8:11]
	v_mfma_f32_16x16x32_bf16 v[12:15], v[154:157], v[214:217], v[12:15]
	s_setprio 0
	s_setprio 1
	v_mfma_f32_16x16x32_bf16 v[52:55], v[166:169], v[186:189], v[52:55]
	v_mfma_f32_16x16x32_bf16 v[48:51], v[174:177], v[186:189], v[48:51]
	v_mfma_f32_16x16x32_bf16 v[32:35], v[174:177], v[194:197], v[32:35]
	v_mfma_f32_16x16x32_bf16 v[36:39], v[166:169], v[194:197], v[36:39]
	v_mfma_f32_16x16x32_bf16 v[20:23], v[166:169], v[202:205], v[20:23]
	v_mfma_f32_16x16x32_bf16 v[16:19], v[174:177], v[202:205], v[16:19]
	v_mfma_f32_16x16x32_bf16 v[0:3], v[174:177], v[210:213], v[0:3]
	v_mfma_f32_16x16x32_bf16 v[4:7], v[166:169], v[210:213], v[4:7]
	v_mfma_f32_16x16x32_bf16 v[52:55], v[170:173], v[190:193], v[52:55]
	v_mfma_f32_16x16x32_bf16 v[48:51], v[178:181], v[190:193], v[48:51]
	v_mfma_f32_16x16x32_bf16 v[32:35], v[178:181], v[198:201], v[32:35]
	v_mfma_f32_16x16x32_bf16 v[36:39], v[170:173], v[198:201], v[36:39]
	v_mfma_f32_16x16x32_bf16 v[20:23], v[170:173], v[206:209], v[20:23]
	v_mfma_f32_16x16x32_bf16 v[16:19], v[178:181], v[206:209], v[16:19]
	v_mfma_f32_16x16x32_bf16 v[0:3], v[178:181], v[214:217], v[0:3]
	v_mfma_f32_16x16x32_bf16 v[4:7], v[170:173], v[214:217], v[4:7]
	s_setprio 0
	s_barrier
	s_add_i32 s34, s34, 2
	s_add_u32 s46, s46, 0x100
	s_addc_u32 s47, s47, 0
	s_add_u32 s29, s29, 0x100
	s_addc_u32 s33, s33, 0
	s_cmp_gt_u32 s34, 29
	s_cbranch_scc0 .LBB0_1205
	s_and_b64 vcc, exec, s[26:27]
	s_cbranch_vccz .LBB0_1208
	s_barrier

; #define PG8_STAGE(bufoff, gbase, voff) do { _Pragma("unroll") for (int _i = 0; _i < 2; ++_i) \
;         __builtin_amdgcn_global_load_lds((const unsigned*)((const char*)(gbase) + (voff)[_i]), (LAS unsigned*)(lds + (bufoff) + ldsw + _i * 8192), 16, 0, 0); } while (0)
; #define PG8_LDA(dst, b, h) do { _Pragma("unroll") for (int m = 0; m < 4; ++m) _Pragma("unroll") for (int k = 0; k < 2; ++k) dst[m][k] = *(const LAS bf16x8*)(lds + PG8_SA(b, h) + aoff + m * 2048 + k * 1024); } while (0)
; #define PG8_LDB(dst, b, h) do { _Pragma("unroll") for (int n = 0; n < 2; ++n) _Pragma("unroll") for (int k = 0; k < 2; ++k) dst[n][k] = *(const LAS bf16x8*)(lds + PG8_SB(b, h) + boff + n * 2048 + k * 1024); } while (0)
; #define PG8_MMA(ai, bj, At, Bt) do { __builtin_amdgcn_s_setprio(1); _Pragma("unroll") for (int m = 0; m < 4; ++m) _Pragma("unroll") for (int n = 0; n < 2; ++n) _Pragma("unroll") for (int k = 0; k < 2; ++k) \
;         acc[ai][bj][m][n] = __builtin_amdgcn_mfma_f32_16x16x32_bf16(Bt[n][k], At[m][k], acc[ai][bj][m][n], 0, 0, 0); __builtin_amdgcn_s_setprio(0); } while (0)
; #define PG8_WAIT_V(n) asm volatile("s_waitcnt vmcnt(" #n ")" ::: "memory")
; #define PG8_WAIT_L(n) asm volatile("s_waitcnt lgkmcnt(" #n ")" ::: "memory")
; #define PG8_BAR __builtin_amdgcn_s_barrier()
; #define PG8_SCHED __builtin_amdgcn_sched_barrier(0)
; template <class Epi, bool ALIGN_EPI = PG8_ALIGN>
; __device__ __forceinline__ void gemm_phase(LAS unsigned char* lds, const Gemm g, const StaticOrder S, const Epi E) {
;     ...
;             const bool last = (t == nt - 2);
;             const char* a1 = cA + (size_t)(t + 1) * kstep;
;             const char* a2 = last ? nA : cA + (size_t)(t + 2) * kstep; const char* b2 = last ? nB : cB + (size_t)(t + 2) * kstep;
;             const char* a3 = a2 + kstep; const char* b3 = b2 + kstep;
;             PG8_LDB(B0, 0, 0); PG8_LDB(B1, 0, 1); PG8_SCHED; PG8_LDA(At, 0, 0); PG8_STAGE(PG8_SA(1, 1), a1 + hstepA, voffA);
;             PG8_WAIT_V(8); PG8_WAIT_L(0); PG8_BAR; PG8_MMA(0, 0, At, B0); PG8_MMA(0, 1, At, B1); PG8_BAR; PG8_SCHED;
;             PG8_LDA(At, 0, 1); PG8_STAGE(PG8_SB(0, 0), b2, voffB); PG8_STAGE(PG8_SB(0, 1), b2 + hstepB, voffB); PG8_STAGE(PG8_SA(0, 0), a2, voffA);
.LBB0_1300:
	ds_read_b128 v[144:147], v161
	ds_read_b128 v[166:169], v161 offset:1024
	ds_read_b128 v[170:173], v161 offset:2048
	ds_read_b128 v[174:177], v161 offset:3072
	ds_read_b128 v[178:181], v162
	ds_read_b128 v[186:189], v162 offset:1024
	ds_read_b128 v[190:193], v162 offset:2048
	ds_read_b128 v[194:197], v162 offset:3072
	s_add_u32 s54, s52, 0xfff80080
	s_addc_u32 s55, s53, -1
	s_cmp_eq_u32 s73, 28
	s_cselect_b32 s57, s47, s55
	s_cselect_b32 s56, s69, s54
	s_cselect_b32 s55, s45, s72
	s_cselect_b32 s54, s70, s71
	v_lshl_add_u64 v[148:149], s[52:53], 0, v[136:137]
	s_add_i32 m0, s17, 0xc000
	ds_read_b128 v[198:201], v163
	ds_read_b128 v[202:205], v163 offset:1024
	ds_read_b128 v[206:209], v163 offset:2048
	ds_read_b128 v[210:213], v163 offset:3072
	ds_read_b128 v[214:217], v163 offset:4096
	ds_read_b128 v[218:221], v163 offset:5120
	ds_read_b128 v[222:225], v163 offset:6144
	ds_read_b128 v[226:229], v163 offset:7168
	global_load_lds_dwordx4 v[148:149], off
	v_lshl_add_u64 v[148:149], s[52:53], 0, v[138:139]
	s_add_i32 m0, s17, 0xe000
	s_nop 0
	global_load_lds_dwordx4 v[148:149], off
	s_waitcnt vmcnt(8)
	s_waitcnt lgkmcnt(0)
	s_barrier
	s_setprio 1
	s_waitcnt lgkmcnt(0)
	v_mfma_f32_16x16x32_bf16 v[124:127], v[144:147], v[198:201], v[124:127]
	v_mfma_f32_16x16x32_bf16 v[120:123], v[170:173], v[198:201], v[120:123]
	v_mfma_f32_16x16x32_bf16 v[112:115], v[170:173], v[206:209], v[112:115]
	v_mfma_f32_16x16x32_bf16 v[116:119], v[144:147], v[206:209], v[116:119]
	v_mfma_f32_16x16x32_bf16 v[108:111], v[144:147], v[214:217], v[108:111]
	v_mfma_f32_16x16x32_bf16 v[104:107], v[170:173], v[214:217], v[104:107]
	v_mfma_f32_16x16x32_bf16 v[96:99], v[170:173], v[222:225], v[96:99]
	v_mfma_f32_16x16x32_bf16 v[100:103], v[144:147], v[222:225], v[100:103]
	v_mfma_f32_16x16x32_bf16 v[124:127], v[166:169], v[202:205], v[124:127]
	v_mfma_f32_16x16x32_bf16 v[120:123], v[174:177], v[202:205], v[120:123]
	v_mfma_f32_16x16x32_bf16 v[112:115], v[174:177], v[210:213], v[112:115]
	v_mfma_f32_16x16x32_bf16 v[116:119], v[166:169], v[210:213], v[116:119]
	v_mfma_f32_16x16x32_bf16 v[108:111], v[166:169], v[218:221], v[108:111]
	v_mfma_f32_16x16x32_bf16 v[104:107], v[174:177], v[218:221], v[104:107]
	v_mfma_f32_16x16x32_bf16 v[96:99], v[174:177], v[226:229], v[96:99]
	v_mfma_f32_16x16x32_bf16 v[100:103], v[166:169], v[226:229], v[100:103]
	s_setprio 0
	s_setprio 1
	v_mfma_f32_16x16x32_bf16 v[68:71], v[178:181], v[198:201], v[68:71]
	v_mfma_f32_16x16x32_bf16 v[64:67], v[190:193], v[198:201], v[64:67]
	v_mfma_f32_16x16x32_bf16 v[48:51], v[190:193], v[206:209], v[48:51]
	v_mfma_f32_16x16x32_bf16 v[56:59], v[178:181], v[206:209], v[56:59]
	v_mfma_f32_16x16x32_bf16 v[44:47], v[178:181], v[214:217], v[44:47]
	v_mfma_f32_16x16x32_bf16 v[40:43], v[190:193], v[214:217], v[40:43]
	v_mfma_f32_16x16x32_bf16 v[32:35], v[190:193], v[222:225], v[32:35]
	v_mfma_f32_16x16x32_bf16 v[36:39], v[178:181], v[222:225], v[36:39]
	v_mfma_f32_16x16x32_bf16 v[68:71], v[186:189], v[202:205], v[68:71]
	v_mfma_f32_16x16x32_bf16 v[64:67], v[194:197], v[202:205], v[64:67]
	v_mfma_f32_16x16x32_bf16 v[48:51], v[194:197], v[210:213], v[48:51]
	v_mfma_f32_16x16x32_bf16 v[56:59], v[186:189], v[210:213], v[56:59]
	v_mfma_f32_16x16x32_bf16 v[44:47], v[186:189], v[218:221], v[44:47]
	v_mfma_f32_16x16x32_bf16 v[40:43], v[194:197], v[218:221], v[40:43]
	v_mfma_f32_16x16x32_bf16 v[32:35], v[194:197], v[226:229], v[32:35]
	v_mfma_f32_16x16x32_bf16 v[36:39], v[186:189], v[226:229], v[36:39]
	s_setprio 0
	s_barrier
	s_add_i32 s74, s62, s16
	v_lshl_add_u64 v[148:149], s[54:55], 0, v[130:131]
	s_mov_b32 m0, s74
	ds_read_b128 v[198:201], v163 offset:16384
	ds_read_b128 v[202:205], v163 offset:17408
	ds_read_b128 v[206:209], v163 offset:18432
	ds_read_b128 v[210:213], v163 offset:19456
	ds_read_b128 v[214:217], v163 offset:20480
	ds_read_b128 v[218:221], v163 offset:21504
	ds_read_b128 v[222:225], v163 offset:22528
	ds_read_b128 v[226:229], v163 offset:23552
	global_load_lds_dwordx4 v[148:149], off
	s_add_i32 m0, s74, 0x2000
	s_add_u32 s74, s54, 0x80000
	v_lshl_add_u64 v[182:183], s[54:55], 0, v[134:135]
	s_addc_u32 s75, s55, 0
	s_add_i32 s76, s63, s16
	global_load_lds_dwordx4 v[182:183], off
	v_lshl_add_u64 v[230:231], s[74:75], 0, v[130:131]
	s_mov_b32 m0, s76
	v_lshl_add_u64 v[232:233], s[56:57], 0, v[132:133]
	global_load_lds_dwordx4 v[230:231], off
	v_lshl_add_u64 v[230:231], s[74:75], 0, v[134:135]
	s_add_i32 m0, s76, 0x2000
	s_nop 0
	global_load_lds_dwordx4 v[230:231], off
	v_lshl_add_u64 v[230:231], s[56:57], 0, v[128:129]
	s_mov_b32 m0, s17
	s_nop 0
	global_load_lds_dwordx4 v[230:231], off
	s_mov_b32 m0, s33
	s_nop 0
	global_load_lds_dwordx4 v[232:233], off
	s_waitcnt vmcnt(8)
	s_waitcnt lgkmcnt(0)
	s_barrier
; #define PG8_STAGE(bufoff, gbase, voff) do { _Pragma("unroll") for (int _i = 0; _i < 2; ++_i) \
;         __builtin_amdgcn_global_load_lds((const unsigned*)((const char*)(gbase) + (voff)[_i]), (LAS unsigned*)(lds + (bufoff) + ldsw + _i * 8192), 16, 0, 0); } while (0)
; #define PG8_LDA(dst, b, h) do { _Pragma("unroll") for (int m = 0; m < 4; ++m) _Pragma("unroll") for (int k = 0; k < 2; ++k) dst[m][k] = *(const LAS bf16x8*)(lds + PG8_SA(b, h) + aoff + m * 2048 + k * 1024); } while (0)
; #define PG8_LDB(dst, b, h) do { _Pragma("unroll") for (int n = 0; n < 2; ++n) _Pragma("unroll") for (int k = 0; k < 2; ++k) dst[n][k] = *(const LAS bf16x8*)(lds + PG8_SB(b, h) + boff + n * 2048 + k * 1024); } while (0)
; #define PG8_MMA(ai, bj, At, Bt) do { __builtin_amdgcn_s_setprio(1); _Pragma("unroll") for (int m = 0; m < 4; ++m) _Pragma("unroll") for (int n = 0; n < 2; ++n) _Pragma("unroll") for (int k = 0; k < 2; ++k) \
;         acc[ai][bj][m][n] = __builtin_amdgcn_mfma_f32_16x16x32_bf16(Bt[n][k], At[m][k], acc[ai][bj][m][n], 0, 0, 0); __builtin_amdgcn_s_setprio(0); } while (0)
; #define PG8_WAIT_V(n) asm volatile("s_waitcnt vmcnt(" #n ")" ::: "memory")
; #define PG8_WAIT_L(n) asm volatile("s_waitcnt lgkmcnt(" #n ")" ::: "memory")
; #define PG8_BAR __builtin_amdgcn_s_barrier()
; #define PG8_SCHED __builtin_amdgcn_sched_barrier(0)
; template <class Epi, bool ALIGN_EPI = PG8_ALIGN>
; __device__ __forceinline__ void gemm_phase(LAS unsigned char* lds, const Gemm g, const StaticOrder S, const Epi E) {
;     ...
;             PG8_WAIT_V(8); PG8_WAIT_L(0); PG8_BAR; PG8_MMA(1, 0, At, B0); PG8_MMA(1, 1, At, B1); PG8_BAR; PG8_SCHED;
;             PG8_LDB(B0, 1, 0); PG8_LDB(B1, 1, 1); PG8_SCHED; PG8_LDA(At, 1, 0); PG8_STAGE(PG8_SA(0, 1), a2 + hstepA, voffA);
;             PG8_WAIT_V(8); PG8_WAIT_L(0); PG8_BAR; PG8_MMA(0, 0, At, B0); PG8_MMA(0, 1, At, B1); PG8_BAR; PG8_SCHED;
	s_setprio 1
	s_waitcnt lgkmcnt(0)
	v_mfma_f32_16x16x32_bf16 v[92:95], v[144:147], v[198:201], v[92:95]
	v_mfma_f32_16x16x32_bf16 v[88:91], v[170:173], v[198:201], v[88:91]
	v_mfma_f32_16x16x32_bf16 v[80:83], v[170:173], v[206:209], v[80:83]
	v_mfma_f32_16x16x32_bf16 v[84:87], v[144:147], v[206:209], v[84:87]
	v_mfma_f32_16x16x32_bf16 v[76:79], v[144:147], v[214:217], v[76:79]
	v_mfma_f32_16x16x32_bf16 v[72:75], v[170:173], v[214:217], v[72:75]
	v_mfma_f32_16x16x32_bf16 v[52:55], v[170:173], v[222:225], v[52:55]
	v_mfma_f32_16x16x32_bf16 v[60:63], v[144:147], v[222:225], v[60:63]
	v_mfma_f32_16x16x32_bf16 v[92:95], v[166:169], v[202:205], v[92:95]
	v_mfma_f32_16x16x32_bf16 v[88:91], v[174:177], v[202:205], v[88:91]
	v_mfma_f32_16x16x32_bf16 v[80:83], v[174:177], v[210:213], v[80:83]
	v_mfma_f32_16x16x32_bf16 v[84:87], v[166:169], v[210:213], v[84:87]
	v_mfma_f32_16x16x32_bf16 v[76:79], v[166:169], v[218:221], v[76:79]
	v_mfma_f32_16x16x32_bf16 v[72:75], v[174:177], v[218:221], v[72:75]
	v_mfma_f32_16x16x32_bf16 v[52:55], v[174:177], v[226:229], v[52:55]
	v_mfma_f32_16x16x32_bf16 v[60:63], v[166:169], v[226:229], v[60:63]
	s_setprio 0
	s_setprio 1
	v_mfma_f32_16x16x32_bf16 v[28:31], v[178:181], v[198:201], v[28:31]
	v_mfma_f32_16x16x32_bf16 v[24:27], v[190:193], v[198:201], v[24:27]
	v_mfma_f32_16x16x32_bf16 v[16:19], v[190:193], v[206:209], v[16:19]
	v_mfma_f32_16x16x32_bf16 v[20:23], v[178:181], v[206:209], v[20:23]
	v_mfma_f32_16x16x32_bf16 v[12:15], v[178:181], v[214:217], v[12:15]
	v_mfma_f32_16x16x32_bf16 v[8:11], v[190:193], v[214:217], v[8:11]
	v_mfma_f32_16x16x32_bf16 v[0:3], v[190:193], v[222:225], v[0:3]
	v_mfma_f32_16x16x32_bf16 v[4:7], v[178:181], v[222:225], v[4:7]
	v_mfma_f32_16x16x32_bf16 v[28:31], v[186:189], v[202:205], v[28:31]
	v_mfma_f32_16x16x32_bf16 v[24:27], v[194:197], v[202:205], v[24:27]
	v_mfma_f32_16x16x32_bf16 v[16:19], v[194:197], v[210:213], v[16:19]
	v_mfma_f32_16x16x32_bf16 v[20:23], v[186:189], v[210:213], v[20:23]
	v_mfma_f32_16x16x32_bf16 v[12:15], v[186:189], v[218:221], v[12:15]
	v_mfma_f32_16x16x32_bf16 v[8:11], v[194:197], v[218:221], v[8:11]
	v_mfma_f32_16x16x32_bf16 v[0:3], v[194:197], v[226:229], v[0:3]
	v_mfma_f32_16x16x32_bf16 v[4:7], v[186:189], v[226:229], v[4:7]
	s_setprio 0
	s_barrier
	s_add_i32 s74, 0, 0x18000
	v_add_u32_e32 v165, s74, v159
	s_add_i32 s75, 0, 0x1c000
	ds_read_b128 v[144:147], v165
	ds_read_b128 v[166:169], v165 offset:1024
	ds_read_b128 v[170:173], v165 offset:2048
	ds_read_b128 v[174:177], v165 offset:3072
	v_add_u32_e32 v165, s75, v159
	ds_read_b128 v[178:181], v165
	ds_read_b128 v[186:189], v165 offset:1024
	ds_read_b128 v[190:193], v165 offset:2048
	ds_read_b128 v[194:197], v165 offset:3072
	s_add_u32 s56, s56, 0x80000
	s_addc_u32 s57, s57, 0
	s_mov_b32 m0, s34
	v_lshl_add_u64 v[234:235], s[56:57], 0, v[128:129]
	ds_read_b128 v[198:201], v163 offset:32768
	ds_read_b128 v[202:205], v163 offset:33792
	ds_read_b128 v[206:209], v163 offset:34816
	ds_read_b128 v[210:213], v163 offset:35840
	ds_read_b128 v[214:217], v163 offset:36864
	ds_read_b128 v[218:221], v163 offset:37888
	ds_read_b128 v[222:225], v163 offset:38912
	ds_read_b128 v[226:229], v163 offset:39936
	global_load_lds_dwordx4 v[234:235], off
	v_lshl_add_u64 v[234:235], s[56:57], 0, v[132:133]
	s_mov_b32 m0, s35
	s_nop 0
	global_load_lds_dwordx4 v[234:235], off
	s_waitcnt vmcnt(8)
	s_waitcnt lgkmcnt(0)
	s_barrier
	s_setprio 1
	s_waitcnt lgkmcnt(0)
	v_mfma_f32_16x16x32_bf16 v[124:127], v[144:147], v[198:201], v[124:127]
	v_mfma_f32_16x16x32_bf16 v[120:123], v[170:173], v[198:201], v[120:123]
	v_mfma_f32_16x16x32_bf16 v[112:115], v[170:173], v[206:209], v[112:115]
	v_mfma_f32_16x16x32_bf16 v[116:119], v[144:147], v[206:209], v[116:119]
	v_mfma_f32_16x16x32_bf16 v[108:111], v[144:147], v[214:217], v[108:111]
	v_mfma_f32_16x16x32_bf16 v[104:107], v[170:173], v[214:217], v[104:107]
	v_mfma_f32_16x16x32_bf16 v[96:99], v[170:173], v[222:225], v[96:99]
	v_mfma_f32_16x16x32_bf16 v[100:103], v[144:147], v[222:225], v[100:103]
	v_mfma_f32_16x16x32_bf16 v[124:127], v[166:169], v[202:205], v[124:127]
	v_mfma_f32_16x16x32_bf16 v[120:123], v[174:177], v[202:205], v[120:123]
	v_mfma_f32_16x16x32_bf16 v[112:115], v[174:177], v[210:213], v[112:115]
	v_mfma_f32_16x16x32_bf16 v[116:119], v[166:169], v[210:213], v[116:119]
	v_mfma_f32_16x16x32_bf16 v[108:111], v[166:169], v[218:221], v[108:111]
	v_mfma_f32_16x16x32_bf16 v[104:107], v[174:177], v[218:221], v[104:107]
	v_mfma_f32_16x16x32_bf16 v[96:99], v[174:177], v[226:229], v[96:99]
	v_mfma_f32_16x16x32_bf16 v[100:103], v[166:169], v[226:229], v[100:103]
	s_setprio 0
	s_setprio 1
	v_mfma_f32_16x16x32_bf16 v[68:71], v[178:181], v[198:201], v[68:71]
	v_mfma_f32_16x16x32_bf16 v[64:67], v[190:193], v[198:201], v[64:67]
	v_mfma_f32_16x16x32_bf16 v[48:51], v[190:193], v[206:209], v[48:51]
	v_mfma_f32_16x16x32_bf16 v[56:59], v[178:181], v[206:209], v[56:59]
	v_mfma_f32_16x16x32_bf16 v[44:47], v[178:181], v[214:217], v[44:47]
	v_mfma_f32_16x16x32_bf16 v[40:43], v[190:193], v[214:217], v[40:43]
	v_mfma_f32_16x16x32_bf16 v[32:35], v[190:193], v[222:225], v[32:35]
	v_mfma_f32_16x16x32_bf16 v[36:39], v[178:181], v[222:225], v[36:39]
	v_mfma_f32_16x16x32_bf16 v[68:71], v[186:189], v[202:205], v[68:71]
	v_mfma_f32_16x16x32_bf16 v[64:67], v[194:197], v[202:205], v[64:67]
	v_mfma_f32_16x16x32_bf16 v[48:51], v[194:197], v[210:213], v[48:51]
	v_mfma_f32_16x16x32_bf16 v[56:59], v[186:189], v[210:213], v[56:59]
	v_mfma_f32_16x16x32_bf16 v[44:47], v[186:189], v[218:221], v[44:47]
	v_mfma_f32_16x16x32_bf16 v[40:43], v[194:197], v[218:221], v[40:43]
	v_mfma_f32_16x16x32_bf16 v[32:35], v[194:197], v[226:229], v[32:35]
	v_mfma_f32_16x16x32_bf16 v[36:39], v[186:189], v[226:229], v[36:39]
	s_setprio 0
	s_barrier
; #define PG8_STAGE(bufoff, gbase, voff) do { _Pragma("unroll") for (int _i = 0; _i < 2; ++_i) \
;         __builtin_amdgcn_global_load_lds((const unsigned*)((const char*)(gbase) + (voff)[_i]), (LAS unsigned*)(lds + (bufoff) + ldsw + _i * 8192), 16, 0, 0); } while (0)
; #define PG8_LDA(dst, b, h) do { _Pragma("unroll") for (int m = 0; m < 4; ++m) _Pragma("unroll") for (int k = 0; k < 2; ++k) dst[m][k] = *(const LAS bf16x8*)(lds + PG8_SA(b, h) + aoff + m * 2048 + k * 1024); } while (0)
; #define PG8_MMA(ai, bj, At, Bt) do { __builtin_amdgcn_s_setprio(1); _Pragma("unroll") for (int m = 0; m < 4; ++m) _Pragma("unroll") for (int n = 0; n < 2; ++n) _Pragma("unroll") for (int k = 0; k < 2; ++k) \
;         acc[ai][bj][m][n] = __builtin_amdgcn_mfma_f32_16x16x32_bf16(Bt[n][k], At[m][k], acc[ai][bj][m][n], 0, 0, 0); __builtin_amdgcn_s_setprio(0); } while (0)
; #define PG8_WAIT_V(n) asm volatile("s_waitcnt vmcnt(" #n ")" ::: "memory")
; #define PG8_WAIT_L(n) asm volatile("s_waitcnt lgkmcnt(" #n ")" ::: "memory")
; #define PG8_BAR __builtin_amdgcn_s_barrier()
; #define PG8_SCHED __builtin_amdgcn_sched_barrier(0)
; template <class Epi, bool ALIGN_EPI = PG8_ALIGN>
; __device__ __forceinline__ void gemm_phase(LAS unsigned char* lds, const Gemm g, const StaticOrder S, const Epi E) {
;     ...
;             PG8_LDA(At, 1, 1); PG8_STAGE(PG8_SB(1, 0), b3, voffB); PG8_STAGE(PG8_SB(1, 1), b3 + hstepB, voffB); PG8_STAGE(PG8_SA(1, 0), a3, voffA);
;             PG8_WAIT_V(8); PG8_WAIT_L(0); PG8_BAR; PG8_MMA(1, 0, At, B0); PG8_MMA(1, 1, At, B1); PG8_BAR; PG8_SCHED;
;         }
;         if (ALIGN_EPI) { if (wr == 0) PG8_BAR; }
	s_add_i32 s56, s74, s16
	v_lshl_add_u64 v[148:149], v[148:149], 0, s[26:27]
	s_mov_b32 m0, s56
	ds_read_b128 v[198:201], v163 offset:49152
	ds_read_b128 v[202:205], v163 offset:50176
	ds_read_b128 v[206:209], v163 offset:51200
	ds_read_b128 v[210:213], v163 offset:52224
	ds_read_b128 v[214:217], v163 offset:53248
	ds_read_b128 v[218:221], v163 offset:54272
	ds_read_b128 v[222:225], v163 offset:55296
	ds_read_b128 v[226:229], v163 offset:56320
	global_load_lds_dwordx4 v[148:149], off
	s_add_i32 m0, s56, 0x2000
	s_add_u32 s54, s54, 0x80080
	v_lshl_add_u64 v[148:149], v[182:183], 0, s[26:27]
	s_addc_u32 s55, s55, 0
	s_add_i32 s56, s75, s16
	global_load_lds_dwordx4 v[148:149], off
	v_lshl_add_u64 v[148:149], s[54:55], 0, v[130:131]
	s_mov_b32 m0, s56
	s_nop 0
	global_load_lds_dwordx4 v[148:149], off
	v_lshl_add_u64 v[148:149], s[54:55], 0, v[134:135]
	s_add_i32 m0, s56, 0x2000
	s_nop 0
	global_load_lds_dwordx4 v[148:149], off
	v_lshl_add_u64 v[148:149], v[230:231], 0, s[26:27]
	s_mov_b32 m0, s59
	s_nop 0
	global_load_lds_dwordx4 v[148:149], off
	v_lshl_add_u64 v[148:149], v[232:233], 0, s[26:27]
	s_mov_b32 m0, s60
	s_nop 0
	global_load_lds_dwordx4 v[148:149], off
	s_waitcnt vmcnt(8)
	s_waitcnt lgkmcnt(0)
	s_barrier
	s_setprio 1
	s_waitcnt lgkmcnt(0)
	v_mfma_f32_16x16x32_bf16 v[92:95], v[144:147], v[198:201], v[92:95]
	v_mfma_f32_16x16x32_bf16 v[88:91], v[170:173], v[198:201], v[88:91]
	v_mfma_f32_16x16x32_bf16 v[80:83], v[170:173], v[206:209], v[80:83]
	v_mfma_f32_16x16x32_bf16 v[84:87], v[144:147], v[206:209], v[84:87]
	v_mfma_f32_16x16x32_bf16 v[76:79], v[144:147], v[214:217], v[76:79]
	v_mfma_f32_16x16x32_bf16 v[72:75], v[170:173], v[214:217], v[72:75]
	v_mfma_f32_16x16x32_bf16 v[52:55], v[170:173], v[222:225], v[52:55]
	v_mfma_f32_16x16x32_bf16 v[60:63], v[144:147], v[222:225], v[60:63]
	v_mfma_f32_16x16x32_bf16 v[92:95], v[166:169], v[202:205], v[92:95]
	v_mfma_f32_16x16x32_bf16 v[88:91], v[174:177], v[202:205], v[88:91]
	v_mfma_f32_16x16x32_bf16 v[80:83], v[174:177], v[210:213], v[80:83]
	v_mfma_f32_16x16x32_bf16 v[84:87], v[166:169], v[210:213], v[84:87]
	v_mfma_f32_16x16x32_bf16 v[76:79], v[166:169], v[218:221], v[76:79]
	v_mfma_f32_16x16x32_bf16 v[72:75], v[174:177], v[218:221], v[72:75]
	v_mfma_f32_16x16x32_bf16 v[52:55], v[174:177], v[226:229], v[52:55]
	v_mfma_f32_16x16x32_bf16 v[60:63], v[166:169], v[226:229], v[60:63]
	s_setprio 0
	s_setprio 1
	v_mfma_f32_16x16x32_bf16 v[28:31], v[178:181], v[198:201], v[28:31]
	v_mfma_f32_16x16x32_bf16 v[24:27], v[190:193], v[198:201], v[24:27]
	v_mfma_f32_16x16x32_bf16 v[16:19], v[190:193], v[206:209], v[16:19]
	v_mfma_f32_16x16x32_bf16 v[20:23], v[178:181], v[206:209], v[20:23]
	v_mfma_f32_16x16x32_bf16 v[12:15], v[178:181], v[214:217], v[12:15]
	v_mfma_f32_16x16x32_bf16 v[8:11], v[190:193], v[214:217], v[8:11]
	v_mfma_f32_16x16x32_bf16 v[0:3], v[190:193], v[222:225], v[0:3]
	v_mfma_f32_16x16x32_bf16 v[4:7], v[178:181], v[222:225], v[4:7]
	v_mfma_f32_16x16x32_bf16 v[28:31], v[186:189], v[202:205], v[28:31]
	v_mfma_f32_16x16x32_bf16 v[24:27], v[194:197], v[202:205], v[24:27]
	v_mfma_f32_16x16x32_bf16 v[16:19], v[194:197], v[210:213], v[16:19]
	v_mfma_f32_16x16x32_bf16 v[20:23], v[186:189], v[210:213], v[20:23]
	v_mfma_f32_16x16x32_bf16 v[12:15], v[186:189], v[218:221], v[12:15]
	v_mfma_f32_16x16x32_bf16 v[8:11], v[194:197], v[218:221], v[8:11]
	v_mfma_f32_16x16x32_bf16 v[0:3], v[194:197], v[226:229], v[0:3]
	v_mfma_f32_16x16x32_bf16 v[4:7], v[186:189], v[226:229], v[4:7]
	s_setprio 0
	s_barrier
	s_add_i32 s73, s73, 2
	s_add_u32 s52, s52, 0x100
	s_addc_u32 s53, s53, 0
	s_add_u32 s71, s71, 0x100
	s_addc_u32 s72, s72, 0
	s_cmp_gt_u32 s73, 29
	s_cbranch_scc0 .LBB0_1300
	s_and_b64 vcc, exec, s[28:29]
	s_cbranch_vccz .LBB0_1303
	s_barrier

; #define PG8_STAGE(bufoff, gbase, voff) do { _Pragma("unroll") for (int _i = 0; _i < 2; ++_i) \
;         __builtin_amdgcn_global_load_lds((const unsigned*)((const char*)(gbase) + (voff)[_i]), (LAS unsigned*)(lds + (bufoff) + ldsw + _i * 8192), 16, 0, 0); } while (0)
; #define PG8_LDA(dst, b, h) do { _Pragma("unroll") for (int m = 0; m < 4; ++m) _Pragma("unroll") for (int k = 0; k < 2; ++k) dst[m][k] = *(const LAS bf16x8*)(lds + PG8_SA(b, h) + aoff + m * 2048 + k * 1024); } while (0)
; #define PG8_LDB(dst, b, h) do { _Pragma("unroll") for (int n = 0; n < 2; ++n) _Pragma("unroll") for (int k = 0; k < 2; ++k) dst[n][k] = *(const LAS bf16x8*)(lds + PG8_SB(b, h) + boff + n * 2048 + k * 1024); } while (0)
; #define PG8_MMA(ai, bj, At, Bt) do { __builtin_amdgcn_s_setprio(1); _Pragma("unroll") for (int m = 0; m < 4; ++m) _Pragma("unroll") for (int n = 0; n < 2; ++n) _Pragma("unroll") for (int k = 0; k < 2; ++k) \
;         acc[ai][bj][m][n] = __builtin_amdgcn_mfma_f32_16x16x32_bf16(Bt[n][k], At[m][k], acc[ai][bj][m][n], 0, 0, 0); __builtin_amdgcn_s_setprio(0); } while (0)
; #define PG8_WAIT_V(n) asm volatile("s_waitcnt vmcnt(" #n ")" ::: "memory")
; #define PG8_WAIT_L(n) asm volatile("s_waitcnt lgkmcnt(" #n ")" ::: "memory")
; #define PG8_BAR __builtin_amdgcn_s_barrier()
; #define PG8_SCHED __builtin_amdgcn_sched_barrier(0)
; template <class Epi, bool ALIGN_EPI = PG8_ALIGN>
; __device__ __forceinline__ void gemm_phase(LAS unsigned char* lds, const Gemm g, const StaticOrder S, const Epi E) {
;     ...
;             const bool last = (t == nt - 2);
;             const char* a1 = cA + (size_t)(t + 1) * kstep;
;             const char* a2 = last ? nA : cA + (size_t)(t + 2) * kstep; const char* b2 = last ? nB : cB + (size_t)(t + 2) * kstep;
;             const char* a3 = a2 + kstep; const char* b3 = b2 + kstep;
;             PG8_LDB(B0, 0, 0); PG8_LDB(B1, 0, 1); PG8_SCHED; PG8_LDA(At, 0, 0); PG8_STAGE(PG8_SA(1, 1), a1 + hstepA, voffA);
;             PG8_WAIT_V(8); PG8_WAIT_L(0); PG8_BAR; PG8_MMA(0, 0, At, B0); PG8_MMA(0, 1, At, B1); PG8_BAR; PG8_SCHED;
;             PG8_LDA(At, 0, 1); PG8_STAGE(PG8_SB(0, 0), b2, voffB); PG8_STAGE(PG8_SB(0, 1), b2 + hstepB, voffB); PG8_STAGE(PG8_SA(0, 0), a2, voffA);
.LBB0_1324:
	ds_read_b128 v[146:149], v143
	ds_read_b128 v[158:161], v143 offset:1024
	ds_read_b128 v[162:165], v143 offset:2048
	ds_read_b128 v[166:169], v143 offset:3072
	ds_read_b128 v[170:173], v144
	ds_read_b128 v[174:177], v144 offset:1024
	ds_read_b128 v[178:181], v144 offset:2048
	ds_read_b128 v[186:189], v144 offset:3072
	s_add_u32 s52, s50, 0xfff80080
	s_addc_u32 s53, s51, -1
	s_cmp_eq_u32 s75, 28
	s_cselect_b32 s55, s45, s53
	s_cselect_b32 s54, s71, s52
	s_cselect_b32 s53, s43, s74
	s_cselect_b32 s52, s72, s73
	v_lshl_add_u64 v[182:183], s[50:51], 0, v[136:137]
	s_add_i32 m0, s35, 0xc000
	ds_read_b128 v[190:193], v145
	ds_read_b128 v[194:197], v145 offset:1024
	ds_read_b128 v[198:201], v145 offset:2048
	ds_read_b128 v[202:205], v145 offset:3072
	ds_read_b128 v[206:209], v145 offset:4096
	ds_read_b128 v[210:213], v145 offset:5120
	ds_read_b128 v[214:217], v145 offset:6144
	ds_read_b128 v[218:221], v145 offset:7168
	global_load_lds_dwordx4 v[182:183], off
	v_lshl_add_u64 v[182:183], s[50:51], 0, v[138:139]
	s_add_i32 m0, s35, 0xe000
	s_nop 0
	global_load_lds_dwordx4 v[182:183], off
	s_waitcnt vmcnt(8)
	s_waitcnt lgkmcnt(0)
	s_barrier
	s_setprio 1
	s_waitcnt lgkmcnt(0)
	v_mfma_f32_16x16x32_bf16 v[124:127], v[146:149], v[190:193], v[124:127]
	v_mfma_f32_16x16x32_bf16 v[120:123], v[162:165], v[190:193], v[120:123]
	v_mfma_f32_16x16x32_bf16 v[112:115], v[162:165], v[198:201], v[112:115]
	v_mfma_f32_16x16x32_bf16 v[116:119], v[146:149], v[198:201], v[116:119]
	v_mfma_f32_16x16x32_bf16 v[108:111], v[146:149], v[206:209], v[108:111]
	v_mfma_f32_16x16x32_bf16 v[104:107], v[162:165], v[206:209], v[104:107]
	v_mfma_f32_16x16x32_bf16 v[96:99], v[162:165], v[214:217], v[96:99]
	v_mfma_f32_16x16x32_bf16 v[100:103], v[146:149], v[214:217], v[100:103]
	v_mfma_f32_16x16x32_bf16 v[124:127], v[158:161], v[194:197], v[124:127]
	v_mfma_f32_16x16x32_bf16 v[120:123], v[166:169], v[194:197], v[120:123]
	v_mfma_f32_16x16x32_bf16 v[112:115], v[166:169], v[202:205], v[112:115]
	v_mfma_f32_16x16x32_bf16 v[116:119], v[158:161], v[202:205], v[116:119]
	v_mfma_f32_16x16x32_bf16 v[108:111], v[158:161], v[210:213], v[108:111]
	v_mfma_f32_16x16x32_bf16 v[104:107], v[166:169], v[210:213], v[104:107]
	v_mfma_f32_16x16x32_bf16 v[96:99], v[166:169], v[218:221], v[96:99]
	v_mfma_f32_16x16x32_bf16 v[100:103], v[158:161], v[218:221], v[100:103]
	s_setprio 0
	s_setprio 1
	v_mfma_f32_16x16x32_bf16 v[80:83], v[170:173], v[190:193], v[80:83]
	v_mfma_f32_16x16x32_bf16 v[72:75], v[178:181], v[190:193], v[72:75]
	v_mfma_f32_16x16x32_bf16 v[60:63], v[178:181], v[198:201], v[60:63]
	v_mfma_f32_16x16x32_bf16 v[68:71], v[170:173], v[198:201], v[68:71]
	v_mfma_f32_16x16x32_bf16 v[52:55], v[170:173], v[206:209], v[52:55]
	v_mfma_f32_16x16x32_bf16 v[48:51], v[178:181], v[206:209], v[48:51]
	v_mfma_f32_16x16x32_bf16 v[32:35], v[178:181], v[214:217], v[32:35]
	v_mfma_f32_16x16x32_bf16 v[36:39], v[170:173], v[214:217], v[36:39]
	v_mfma_f32_16x16x32_bf16 v[80:83], v[174:177], v[194:197], v[80:83]
	v_mfma_f32_16x16x32_bf16 v[72:75], v[186:189], v[194:197], v[72:75]
	v_mfma_f32_16x16x32_bf16 v[60:63], v[186:189], v[202:205], v[60:63]
	v_mfma_f32_16x16x32_bf16 v[68:71], v[174:177], v[202:205], v[68:71]
	v_mfma_f32_16x16x32_bf16 v[52:55], v[174:177], v[210:213], v[52:55]
	v_mfma_f32_16x16x32_bf16 v[48:51], v[186:189], v[210:213], v[48:51]
	v_mfma_f32_16x16x32_bf16 v[32:35], v[186:189], v[218:221], v[32:35]
	v_mfma_f32_16x16x32_bf16 v[36:39], v[174:177], v[218:221], v[36:39]
	s_setprio 0
	s_barrier
	s_add_i32 s76, s64, s34
	v_lshl_add_u64 v[182:183], s[52:53], 0, v[130:131]
	s_mov_b32 m0, s76
	ds_read_b128 v[190:193], v145 offset:16384
	ds_read_b128 v[194:197], v145 offset:17408
	ds_read_b128 v[198:201], v145 offset:18432
	ds_read_b128 v[202:205], v145 offset:19456
	ds_read_b128 v[206:209], v145 offset:20480
	ds_read_b128 v[210:213], v145 offset:21504
	ds_read_b128 v[214:217], v145 offset:22528
	ds_read_b128 v[218:221], v145 offset:23552
	global_load_lds_dwordx4 v[182:183], off
	s_add_i32 m0, s76, 0x2000
	s_add_u32 s76, s52, 0x80000
	v_lshl_add_u64 v[222:223], s[52:53], 0, v[134:135]
	s_addc_u32 s77, s53, 0
	s_add_i32 s78, s65, s34
	global_load_lds_dwordx4 v[222:223], off
	v_lshl_add_u64 v[224:225], s[76:77], 0, v[130:131]
	s_mov_b32 m0, s78
	v_lshl_add_u64 v[226:227], s[54:55], 0, v[132:133]
	global_load_lds_dwordx4 v[224:225], off
	v_lshl_add_u64 v[224:225], s[76:77], 0, v[134:135]
	s_add_i32 m0, s78, 0x2000
	s_nop 0
	global_load_lds_dwordx4 v[224:225], off
	v_lshl_add_u64 v[224:225], s[54:55], 0, v[128:129]
	s_mov_b32 m0, s35
	s_nop 0
	global_load_lds_dwordx4 v[224:225], off
	s_mov_b32 m0, s39
	s_nop 0
	global_load_lds_dwordx4 v[226:227], off
	s_waitcnt vmcnt(8)
	s_waitcnt lgkmcnt(0)
	s_barrier
; #define PG8_STAGE(bufoff, gbase, voff) do { _Pragma("unroll") for (int _i = 0; _i < 2; ++_i) \
;         __builtin_amdgcn_global_load_lds((const unsigned*)((const char*)(gbase) + (voff)[_i]), (LAS unsigned*)(lds + (bufoff) + ldsw + _i * 8192), 16, 0, 0); } while (0)
; #define PG8_LDA(dst, b, h) do { _Pragma("unroll") for (int m = 0; m < 4; ++m) _Pragma("unroll") for (int k = 0; k < 2; ++k) dst[m][k] = *(const LAS bf16x8*)(lds + PG8_SA(b, h) + aoff + m * 2048 + k * 1024); } while (0)
; #define PG8_LDB(dst, b, h) do { _Pragma("unroll") for (int n = 0; n < 2; ++n) _Pragma("unroll") for (int k = 0; k < 2; ++k) dst[n][k] = *(const LAS bf16x8*)(lds + PG8_SB(b, h) + boff + n * 2048 + k * 1024); } while (0)
; #define PG8_MMA(ai, bj, At, Bt) do { __builtin_amdgcn_s_setprio(1); _Pragma("unroll") for (int m = 0; m < 4; ++m) _Pragma("unroll") for (int n = 0; n < 2; ++n) _Pragma("unroll") for (int k = 0; k < 2; ++k) \
;         acc[ai][bj][m][n] = __builtin_amdgcn_mfma_f32_16x16x32_bf16(Bt[n][k], At[m][k], acc[ai][bj][m][n], 0, 0, 0); __builtin_amdgcn_s_setprio(0); } while (0)
; #define PG8_WAIT_V(n) asm volatile("s_waitcnt vmcnt(" #n ")" ::: "memory")
; #define PG8_WAIT_L(n) asm volatile("s_waitcnt lgkmcnt(" #n ")" ::: "memory")
; #define PG8_BAR __builtin_amdgcn_s_barrier()
; #define PG8_SCHED __builtin_amdgcn_sched_barrier(0)
; template <class Epi, bool ALIGN_EPI = PG8_ALIGN>
; __device__ __forceinline__ void gemm_phase(LAS unsigned char* lds, const Gemm g, const StaticOrder S, const Epi E) {
;     ...
;             PG8_WAIT_V(8); PG8_WAIT_L(0); PG8_BAR; PG8_MMA(1, 0, At, B0); PG8_MMA(1, 1, At, B1); PG8_BAR; PG8_SCHED;
;             PG8_LDB(B0, 1, 0); PG8_LDB(B1, 1, 1); PG8_SCHED; PG8_LDA(At, 1, 0); PG8_STAGE(PG8_SA(0, 1), a2 + hstepA, voffA);
;             PG8_WAIT_V(8); PG8_WAIT_L(0); PG8_BAR; PG8_MMA(0, 0, At, B0); PG8_MMA(0, 1, At, B1); PG8_BAR; PG8_SCHED;
	s_setprio 1
	s_waitcnt lgkmcnt(0)
	v_mfma_f32_16x16x32_bf16 v[92:95], v[146:149], v[190:193], v[92:95]
	v_mfma_f32_16x16x32_bf16 v[88:91], v[162:165], v[190:193], v[88:91]
	v_mfma_f32_16x16x32_bf16 v[76:79], v[162:165], v[198:201], v[76:79]
	v_mfma_f32_16x16x32_bf16 v[84:87], v[146:149], v[198:201], v[84:87]
	v_mfma_f32_16x16x32_bf16 v[64:67], v[146:149], v[206:209], v[64:67]
	v_mfma_f32_16x16x32_bf16 v[56:59], v[162:165], v[206:209], v[56:59]
	v_mfma_f32_16x16x32_bf16 v[40:43], v[162:165], v[214:217], v[40:43]
	v_mfma_f32_16x16x32_bf16 v[44:47], v[146:149], v[214:217], v[44:47]
	v_mfma_f32_16x16x32_bf16 v[92:95], v[158:161], v[194:197], v[92:95]
	v_mfma_f32_16x16x32_bf16 v[88:91], v[166:169], v[194:197], v[88:91]
	v_mfma_f32_16x16x32_bf16 v[76:79], v[166:169], v[202:205], v[76:79]
	v_mfma_f32_16x16x32_bf16 v[84:87], v[158:161], v[202:205], v[84:87]
	v_mfma_f32_16x16x32_bf16 v[64:67], v[158:161], v[210:213], v[64:67]
	v_mfma_f32_16x16x32_bf16 v[56:59], v[166:169], v[210:213], v[56:59]
	v_mfma_f32_16x16x32_bf16 v[40:43], v[166:169], v[218:221], v[40:43]
	v_mfma_f32_16x16x32_bf16 v[44:47], v[158:161], v[218:221], v[44:47]
	s_setprio 0
	s_setprio 1
	v_mfma_f32_16x16x32_bf16 v[28:31], v[170:173], v[190:193], v[28:31]
	v_mfma_f32_16x16x32_bf16 v[24:27], v[178:181], v[190:193], v[24:27]
	v_mfma_f32_16x16x32_bf16 v[16:19], v[178:181], v[198:201], v[16:19]
	v_mfma_f32_16x16x32_bf16 v[20:23], v[170:173], v[198:201], v[20:23]
	v_mfma_f32_16x16x32_bf16 v[12:15], v[170:173], v[206:209], v[12:15]
	v_mfma_f32_16x16x32_bf16 v[8:11], v[178:181], v[206:209], v[8:11]
	v_mfma_f32_16x16x32_bf16 v[0:3], v[178:181], v[214:217], v[0:3]
	v_mfma_f32_16x16x32_bf16 v[4:7], v[170:173], v[214:217], v[4:7]
	v_mfma_f32_16x16x32_bf16 v[28:31], v[174:177], v[194:197], v[28:31]
	v_mfma_f32_16x16x32_bf16 v[24:27], v[186:189], v[194:197], v[24:27]
	v_mfma_f32_16x16x32_bf16 v[16:19], v[186:189], v[202:205], v[16:19]
	v_mfma_f32_16x16x32_bf16 v[20:23], v[174:177], v[202:205], v[20:23]
	v_mfma_f32_16x16x32_bf16 v[12:15], v[174:177], v[210:213], v[12:15]
	v_mfma_f32_16x16x32_bf16 v[8:11], v[186:189], v[210:213], v[8:11]
	v_mfma_f32_16x16x32_bf16 v[0:3], v[186:189], v[218:221], v[0:3]
	v_mfma_f32_16x16x32_bf16 v[4:7], v[174:177], v[218:221], v[4:7]
	s_setprio 0
	s_barrier
	s_add_i32 s76, 0, 0x18000
	s_add_i32 s77, 0, 0x1c000
	v_add_u32_e32 v166, s76, v141
	v_add_u32_e32 v186, s77, v141
	ds_read_b128 v[146:149], v166
	ds_read_b128 v[158:161], v166 offset:1024
	ds_read_b128 v[162:165], v166 offset:2048
	ds_read_b128 v[166:169], v166 offset:3072
	ds_read_b128 v[170:173], v186
	ds_read_b128 v[174:177], v186 offset:1024
	ds_read_b128 v[178:181], v186 offset:2048
	ds_read_b128 v[186:189], v186 offset:3072
	s_add_u32 s54, s54, 0x80000
	s_addc_u32 s55, s55, 0
	s_mov_b32 m0, s58
	v_lshl_add_u64 v[228:229], s[54:55], 0, v[128:129]
	ds_read_b128 v[190:193], v145 offset:32768
	ds_read_b128 v[194:197], v145 offset:33792
	ds_read_b128 v[198:201], v145 offset:34816
	ds_read_b128 v[202:205], v145 offset:35840
	ds_read_b128 v[206:209], v145 offset:36864
	ds_read_b128 v[210:213], v145 offset:37888
	ds_read_b128 v[214:217], v145 offset:38912
	ds_read_b128 v[218:221], v145 offset:39936
	global_load_lds_dwordx4 v[228:229], off
	v_lshl_add_u64 v[228:229], s[54:55], 0, v[132:133]
	s_mov_b32 m0, s59
	s_nop 0
	global_load_lds_dwordx4 v[228:229], off
	s_waitcnt vmcnt(8)
	s_waitcnt lgkmcnt(0)
	s_barrier
	s_setprio 1
	s_waitcnt lgkmcnt(0)
	v_mfma_f32_16x16x32_bf16 v[124:127], v[146:149], v[190:193], v[124:127]
	v_mfma_f32_16x16x32_bf16 v[120:123], v[162:165], v[190:193], v[120:123]
	v_mfma_f32_16x16x32_bf16 v[112:115], v[162:165], v[198:201], v[112:115]
	v_mfma_f32_16x16x32_bf16 v[116:119], v[146:149], v[198:201], v[116:119]
	v_mfma_f32_16x16x32_bf16 v[108:111], v[146:149], v[206:209], v[108:111]
	v_mfma_f32_16x16x32_bf16 v[104:107], v[162:165], v[206:209], v[104:107]
	v_mfma_f32_16x16x32_bf16 v[96:99], v[162:165], v[214:217], v[96:99]
	v_mfma_f32_16x16x32_bf16 v[100:103], v[146:149], v[214:217], v[100:103]
	v_mfma_f32_16x16x32_bf16 v[124:127], v[158:161], v[194:197], v[124:127]
	v_mfma_f32_16x16x32_bf16 v[120:123], v[166:169], v[194:197], v[120:123]
	v_mfma_f32_16x16x32_bf16 v[112:115], v[166:169], v[202:205], v[112:115]
	v_mfma_f32_16x16x32_bf16 v[116:119], v[158:161], v[202:205], v[116:119]
	v_mfma_f32_16x16x32_bf16 v[108:111], v[158:161], v[210:213], v[108:111]
	v_mfma_f32_16x16x32_bf16 v[104:107], v[166:169], v[210:213], v[104:107]
	v_mfma_f32_16x16x32_bf16 v[96:99], v[166:169], v[218:221], v[96:99]
	v_mfma_f32_16x16x32_bf16 v[100:103], v[158:161], v[218:221], v[100:103]
	s_setprio 0
	s_setprio 1
	v_mfma_f32_16x16x32_bf16 v[80:83], v[170:173], v[190:193], v[80:83]
	v_mfma_f32_16x16x32_bf16 v[72:75], v[178:181], v[190:193], v[72:75]
	v_mfma_f32_16x16x32_bf16 v[60:63], v[178:181], v[198:201], v[60:63]
	v_mfma_f32_16x16x32_bf16 v[68:71], v[170:173], v[198:201], v[68:71]
	v_mfma_f32_16x16x32_bf16 v[52:55], v[170:173], v[206:209], v[52:55]
	v_mfma_f32_16x16x32_bf16 v[48:51], v[178:181], v[206:209], v[48:51]
	v_mfma_f32_16x16x32_bf16 v[32:35], v[178:181], v[214:217], v[32:35]
	v_mfma_f32_16x16x32_bf16 v[36:39], v[170:173], v[214:217], v[36:39]
	v_mfma_f32_16x16x32_bf16 v[80:83], v[174:177], v[194:197], v[80:83]
	v_mfma_f32_16x16x32_bf16 v[72:75], v[186:189], v[194:197], v[72:75]
	v_mfma_f32_16x16x32_bf16 v[60:63], v[186:189], v[202:205], v[60:63]
	v_mfma_f32_16x16x32_bf16 v[68:71], v[174:177], v[202:205], v[68:71]
	v_mfma_f32_16x16x32_bf16 v[52:55], v[174:177], v[210:213], v[52:55]
	v_mfma_f32_16x16x32_bf16 v[48:51], v[186:189], v[210:213], v[48:51]
	v_mfma_f32_16x16x32_bf16 v[32:35], v[186:189], v[218:221], v[32:35]
	v_mfma_f32_16x16x32_bf16 v[36:39], v[174:177], v[218:221], v[36:39]
	s_setprio 0
	s_barrier
; #define PG8_STAGE(bufoff, gbase, voff) do { _Pragma("unroll") for (int _i = 0; _i < 2; ++_i) \
;         __builtin_amdgcn_global_load_lds((const unsigned*)((const char*)(gbase) + (voff)[_i]), (LAS unsigned*)(lds + (bufoff) + ldsw + _i * 8192), 16, 0, 0); } while (0)
; #define PG8_LDA(dst, b, h) do { _Pragma("unroll") for (int m = 0; m < 4; ++m) _Pragma("unroll") for (int k = 0; k < 2; ++k) dst[m][k] = *(const LAS bf16x8*)(lds + PG8_SA(b, h) + aoff + m * 2048 + k * 1024); } while (0)
; #define PG8_MMA(ai, bj, At, Bt) do { __builtin_amdgcn_s_setprio(1); _Pragma("unroll") for (int m = 0; m < 4; ++m) _Pragma("unroll") for (int n = 0; n < 2; ++n) _Pragma("unroll") for (int k = 0; k < 2; ++k) \
;         acc[ai][bj][m][n] = __builtin_amdgcn_mfma_f32_16x16x32_bf16(Bt[n][k], At[m][k], acc[ai][bj][m][n], 0, 0, 0); __builtin_amdgcn_s_setprio(0); } while (0)
; #define PG8_WAIT_V(n) asm volatile("s_waitcnt vmcnt(" #n ")" ::: "memory")
; #define PG8_WAIT_L(n) asm volatile("s_waitcnt lgkmcnt(" #n ")" ::: "memory")
; #define PG8_BAR __builtin_amdgcn_s_barrier()
; #define PG8_SCHED __builtin_amdgcn_sched_barrier(0)
; template <class Epi, bool ALIGN_EPI = PG8_ALIGN>
; __device__ __forceinline__ void gemm_phase(LAS unsigned char* lds, const Gemm g, const StaticOrder S, const Epi E) {
;     ...
;             PG8_LDA(At, 1, 1); PG8_STAGE(PG8_SB(1, 0), b3, voffB); PG8_STAGE(PG8_SB(1, 1), b3 + hstepB, voffB); PG8_STAGE(PG8_SA(1, 0), a3, voffA);
;             PG8_WAIT_V(8); PG8_WAIT_L(0); PG8_BAR; PG8_MMA(1, 0, At, B0); PG8_MMA(1, 1, At, B1); PG8_BAR; PG8_SCHED;
;         }
;         if (ALIGN_EPI) { if (wr == 0) PG8_BAR; }
	s_add_i32 s54, s76, s34
	v_lshl_add_u64 v[182:183], v[182:183], 0, s[2:3]
	s_mov_b32 m0, s54
	ds_read_b128 v[190:193], v145 offset:49152
	ds_read_b128 v[194:197], v145 offset:50176
	ds_read_b128 v[198:201], v145 offset:51200
	ds_read_b128 v[202:205], v145 offset:52224
	ds_read_b128 v[206:209], v145 offset:53248
	ds_read_b128 v[210:213], v145 offset:54272
	ds_read_b128 v[214:217], v145 offset:55296
	ds_read_b128 v[218:221], v145 offset:56320
	global_load_lds_dwordx4 v[182:183], off
	s_add_i32 m0, s54, 0x2000
	s_add_u32 s52, s52, 0x80080
	v_lshl_add_u64 v[182:183], v[222:223], 0, s[2:3]
	s_addc_u32 s53, s53, 0
	s_add_i32 s54, s77, s34
	global_load_lds_dwordx4 v[182:183], off
	v_lshl_add_u64 v[182:183], s[52:53], 0, v[130:131]
	s_mov_b32 m0, s54
	s_nop 0
	global_load_lds_dwordx4 v[182:183], off
	v_lshl_add_u64 v[182:183], s[52:53], 0, v[134:135]
	s_add_i32 m0, s54, 0x2000
	s_nop 0
	global_load_lds_dwordx4 v[182:183], off
	v_lshl_add_u64 v[182:183], v[224:225], 0, s[2:3]
	s_mov_b32 m0, s61
	s_nop 0
	global_load_lds_dwordx4 v[182:183], off
	v_lshl_add_u64 v[182:183], v[226:227], 0, s[2:3]
	s_mov_b32 m0, s62
	s_nop 0
	global_load_lds_dwordx4 v[182:183], off
	s_waitcnt vmcnt(8)
	s_waitcnt lgkmcnt(0)
	s_barrier
	s_setprio 1
	s_waitcnt lgkmcnt(0)
	v_mfma_f32_16x16x32_bf16 v[92:95], v[146:149], v[190:193], v[92:95]
	v_mfma_f32_16x16x32_bf16 v[88:91], v[162:165], v[190:193], v[88:91]
	v_mfma_f32_16x16x32_bf16 v[76:79], v[162:165], v[198:201], v[76:79]
	v_mfma_f32_16x16x32_bf16 v[84:87], v[146:149], v[198:201], v[84:87]
	v_mfma_f32_16x16x32_bf16 v[64:67], v[146:149], v[206:209], v[64:67]
	v_mfma_f32_16x16x32_bf16 v[56:59], v[162:165], v[206:209], v[56:59]
	v_mfma_f32_16x16x32_bf16 v[40:43], v[162:165], v[214:217], v[40:43]
	v_mfma_f32_16x16x32_bf16 v[44:47], v[146:149], v[214:217], v[44:47]
	v_mfma_f32_16x16x32_bf16 v[92:95], v[158:161], v[194:197], v[92:95]
	v_mfma_f32_16x16x32_bf16 v[88:91], v[166:169], v[194:197], v[88:91]
	v_mfma_f32_16x16x32_bf16 v[76:79], v[166:169], v[202:205], v[76:79]
	v_mfma_f32_16x16x32_bf16 v[84:87], v[158:161], v[202:205], v[84:87]
	v_mfma_f32_16x16x32_bf16 v[64:67], v[158:161], v[210:213], v[64:67]
	v_mfma_f32_16x16x32_bf16 v[56:59], v[166:169], v[210:213], v[56:59]
	v_mfma_f32_16x16x32_bf16 v[40:43], v[166:169], v[218:221], v[40:43]
	v_mfma_f32_16x16x32_bf16 v[44:47], v[158:161], v[218:221], v[44:47]
	s_setprio 0
	s_setprio 1
	v_mfma_f32_16x16x32_bf16 v[28:31], v[170:173], v[190:193], v[28:31]
	v_mfma_f32_16x16x32_bf16 v[24:27], v[178:181], v[190:193], v[24:27]
	v_mfma_f32_16x16x32_bf16 v[16:19], v[178:181], v[198:201], v[16:19]
	v_mfma_f32_16x16x32_bf16 v[20:23], v[170:173], v[198:201], v[20:23]
	v_mfma_f32_16x16x32_bf16 v[12:15], v[170:173], v[206:209], v[12:15]
	v_mfma_f32_16x16x32_bf16 v[8:11], v[178:181], v[206:209], v[8:11]
	v_mfma_f32_16x16x32_bf16 v[0:3], v[178:181], v[214:217], v[0:3]
	v_mfma_f32_16x16x32_bf16 v[4:7], v[170:173], v[214:217], v[4:7]
	v_mfma_f32_16x16x32_bf16 v[28:31], v[174:177], v[194:197], v[28:31]
	v_mfma_f32_16x16x32_bf16 v[24:27], v[186:189], v[194:197], v[24:27]
	v_mfma_f32_16x16x32_bf16 v[16:19], v[186:189], v[202:205], v[16:19]
	v_mfma_f32_16x16x32_bf16 v[20:23], v[174:177], v[202:205], v[20:23]
	v_mfma_f32_16x16x32_bf16 v[12:15], v[174:177], v[210:213], v[12:15]
	v_mfma_f32_16x16x32_bf16 v[8:11], v[186:189], v[210:213], v[8:11]
	v_mfma_f32_16x16x32_bf16 v[0:3], v[186:189], v[218:221], v[0:3]
	v_mfma_f32_16x16x32_bf16 v[4:7], v[174:177], v[218:221], v[4:7]
	s_setprio 0
	s_barrier
	s_add_i32 s75, s75, 2
	s_add_u32 s50, s50, 0x100
	s_addc_u32 s51, s51, 0
	s_add_u32 s73, s73, 0x100
	s_addc_u32 s74, s74, 0
	s_cmp_gt_u32 s75, 29
	s_cbranch_scc0 .LBB0_1324
	s_and_b64 vcc, exec, s[6:7]
	s_cbranch_vccz .LBB0_1327
	s_barrier

; #define PG8_STAGE(bufoff, gbase, voff) do { _Pragma("unroll") for (int _i = 0; _i < 2; ++_i) \
;         __builtin_amdgcn_global_load_lds((const unsigned*)((const char*)(gbase) + (voff)[_i]), (LAS unsigned*)(lds + (bufoff) + ldsw + _i * 8192), 16, 0, 0); } while (0)
; #define PG8_LDA(dst, b, h) do { _Pragma("unroll") for (int m = 0; m < 4; ++m) _Pragma("unroll") for (int k = 0; k < 2; ++k) dst[m][k] = *(const LAS bf16x8*)(lds + PG8_SA(b, h) + aoff + m * 2048 + k * 1024); } while (0)
; #define PG8_LDB(dst, b, h) do { _Pragma("unroll") for (int n = 0; n < 2; ++n) _Pragma("unroll") for (int k = 0; k < 2; ++k) dst[n][k] = *(const LAS bf16x8*)(lds + PG8_SB(b, h) + boff + n * 2048 + k * 1024); } while (0)
; #define PG8_MMA(ai, bj, At, Bt) do { __builtin_amdgcn_s_setprio(1); _Pragma("unroll") for (int m = 0; m < 4; ++m) _Pragma("unroll") for (int n = 0; n < 2; ++n) _Pragma("unroll") for (int k = 0; k < 2; ++k) \
;         acc[ai][bj][m][n] = __builtin_amdgcn_mfma_f32_16x16x32_bf16(Bt[n][k], At[m][k], acc[ai][bj][m][n], 0, 0, 0); __builtin_amdgcn_s_setprio(0); } while (0)
; #define PG8_WAIT_V(n) asm volatile("s_waitcnt vmcnt(" #n ")" ::: "memory")
; #define PG8_WAIT_L(n) asm volatile("s_waitcnt lgkmcnt(" #n ")" ::: "memory")
; #define PG8_BAR __builtin_amdgcn_s_barrier()
; #define PG8_SCHED __builtin_amdgcn_sched_barrier(0)
; template <class Epi, bool ALIGN_EPI = PG8_ALIGN>
; __device__ __forceinline__ void gemm_phase(LAS unsigned char* lds, const Gemm g, const StaticOrder S, const Epi E) {
;     ...
;             const bool last = (t == nt - 2);
;             const char* a1 = cA + (size_t)(t + 1) * kstep;
;             const char* a2 = last ? nA : cA + (size_t)(t + 2) * kstep; const char* b2 = last ? nB : cB + (size_t)(t + 2) * kstep;
;             const char* a3 = a2 + kstep; const char* b3 = b2 + kstep;
;             PG8_LDB(B0, 0, 0); PG8_LDB(B1, 0, 1); PG8_SCHED; PG8_LDA(At, 0, 0); PG8_STAGE(PG8_SA(1, 1), a1 + hstepA, voffA);
;             PG8_WAIT_V(8); PG8_WAIT_L(0); PG8_BAR; PG8_MMA(0, 0, At, B0); PG8_MMA(0, 1, At, B1); PG8_BAR; PG8_SCHED;
;             PG8_LDA(At, 0, 1); PG8_STAGE(PG8_SB(0, 0), b2, voffB); PG8_STAGE(PG8_SB(0, 1), b2 + hstepB, voffB); PG8_STAGE(PG8_SA(0, 0), a2, voffA);
.LBB0_1348:
	ds_read_b128 v[146:149], v143
	ds_read_b128 v[150:153], v143 offset:1024
	ds_read_b128 v[154:157], v143 offset:2048
	ds_read_b128 v[158:161], v143 offset:3072
	ds_read_b128 v[162:165], v144
	ds_read_b128 v[166:169], v144 offset:1024
	ds_read_b128 v[170:173], v144 offset:2048
	ds_read_b128 v[174:177], v144 offset:3072
	s_add_u32 s52, s50, 0xfff80080
	s_addc_u32 s53, s51, -1
	s_cmp_eq_u32 s75, 28
	s_cselect_b32 s55, s45, s53
	s_cselect_b32 s54, s71, s52
	s_cselect_b32 s53, s43, s74
	s_cselect_b32 s52, s72, s73
	v_lshl_add_u64 v[182:183], s[50:51], 0, v[136:137]
	s_add_i32 m0, s35, 0xc000
	ds_read_b128 v[178:181], v145
	ds_read_b128 v[186:189], v145 offset:1024
	ds_read_b128 v[190:193], v145 offset:2048
	ds_read_b128 v[194:197], v145 offset:3072
	ds_read_b128 v[198:201], v145 offset:4096
	ds_read_b128 v[202:205], v145 offset:5120
	ds_read_b128 v[206:209], v145 offset:6144
	ds_read_b128 v[210:213], v145 offset:7168
	global_load_lds_dwordx4 v[182:183], off
	v_lshl_add_u64 v[182:183], s[50:51], 0, v[138:139]
	s_add_i32 m0, s35, 0xe000
	s_nop 0
	global_load_lds_dwordx4 v[182:183], off
	s_waitcnt vmcnt(8)
	s_waitcnt lgkmcnt(0)
	s_barrier
	s_setprio 1
	s_waitcnt lgkmcnt(0)
	v_mfma_f32_16x16x32_bf16 v[124:127], v[146:149], v[178:181], v[124:127]
	v_mfma_f32_16x16x32_bf16 v[120:123], v[154:157], v[178:181], v[120:123]
	v_mfma_f32_16x16x32_bf16 v[112:115], v[154:157], v[190:193], v[112:115]
	v_mfma_f32_16x16x32_bf16 v[116:119], v[146:149], v[190:193], v[116:119]
	v_mfma_f32_16x16x32_bf16 v[108:111], v[146:149], v[198:201], v[108:111]
	v_mfma_f32_16x16x32_bf16 v[104:107], v[154:157], v[198:201], v[104:107]
	v_mfma_f32_16x16x32_bf16 v[96:99], v[154:157], v[206:209], v[96:99]
	v_mfma_f32_16x16x32_bf16 v[100:103], v[146:149], v[206:209], v[100:103]
	v_mfma_f32_16x16x32_bf16 v[124:127], v[150:153], v[186:189], v[124:127]
	v_mfma_f32_16x16x32_bf16 v[120:123], v[158:161], v[186:189], v[120:123]
	v_mfma_f32_16x16x32_bf16 v[112:115], v[158:161], v[194:197], v[112:115]
	v_mfma_f32_16x16x32_bf16 v[116:119], v[150:153], v[194:197], v[116:119]
	v_mfma_f32_16x16x32_bf16 v[108:111], v[150:153], v[202:205], v[108:111]
	v_mfma_f32_16x16x32_bf16 v[104:107], v[158:161], v[202:205], v[104:107]
	v_mfma_f32_16x16x32_bf16 v[96:99], v[158:161], v[210:213], v[96:99]
	v_mfma_f32_16x16x32_bf16 v[100:103], v[150:153], v[210:213], v[100:103]
	s_setprio 0
	s_setprio 1
	v_mfma_f32_16x16x32_bf16 v[80:83], v[162:165], v[178:181], v[80:83]
	v_mfma_f32_16x16x32_bf16 v[72:75], v[170:173], v[178:181], v[72:75]
	v_mfma_f32_16x16x32_bf16 v[60:63], v[170:173], v[190:193], v[60:63]
	v_mfma_f32_16x16x32_bf16 v[68:71], v[162:165], v[190:193], v[68:71]
	v_mfma_f32_16x16x32_bf16 v[52:55], v[162:165], v[198:201], v[52:55]
	v_mfma_f32_16x16x32_bf16 v[48:51], v[170:173], v[198:201], v[48:51]
	v_mfma_f32_16x16x32_bf16 v[32:35], v[170:173], v[206:209], v[32:35]
	v_mfma_f32_16x16x32_bf16 v[36:39], v[162:165], v[206:209], v[36:39]
	v_mfma_f32_16x16x32_bf16 v[80:83], v[166:169], v[186:189], v[80:83]
	v_mfma_f32_16x16x32_bf16 v[72:75], v[174:177], v[186:189], v[72:75]
	v_mfma_f32_16x16x32_bf16 v[60:63], v[174:177], v[194:197], v[60:63]
	v_mfma_f32_16x16x32_bf16 v[68:71], v[166:169], v[194:197], v[68:71]
	v_mfma_f32_16x16x32_bf16 v[52:55], v[166:169], v[202:205], v[52:55]
	v_mfma_f32_16x16x32_bf16 v[48:51], v[174:177], v[202:205], v[48:51]
	v_mfma_f32_16x16x32_bf16 v[32:35], v[174:177], v[210:213], v[32:35]
	v_mfma_f32_16x16x32_bf16 v[36:39], v[166:169], v[210:213], v[36:39]
	s_setprio 0
	s_barrier
	s_add_i32 s76, s64, s34
	v_lshl_add_u64 v[182:183], s[52:53], 0, v[130:131]
	s_mov_b32 m0, s76
	ds_read_b128 v[178:181], v145 offset:16384
	ds_read_b128 v[186:189], v145 offset:17408
	ds_read_b128 v[190:193], v145 offset:18432
	ds_read_b128 v[194:197], v145 offset:19456
	ds_read_b128 v[198:201], v145 offset:20480
	ds_read_b128 v[202:205], v145 offset:21504
	ds_read_b128 v[206:209], v145 offset:22528
	ds_read_b128 v[210:213], v145 offset:23552
	global_load_lds_dwordx4 v[182:183], off
	s_add_i32 m0, s76, 0x2000
	s_add_u32 s76, s52, 0x80000
	v_lshl_add_u64 v[214:215], s[52:53], 0, v[134:135]
	s_addc_u32 s77, s53, 0
	s_add_i32 s78, s65, s34
	global_load_lds_dwordx4 v[214:215], off
	v_lshl_add_u64 v[216:217], s[76:77], 0, v[130:131]
	s_mov_b32 m0, s78
	v_lshl_add_u64 v[218:219], s[54:55], 0, v[132:133]
	global_load_lds_dwordx4 v[216:217], off
	v_lshl_add_u64 v[216:217], s[76:77], 0, v[134:135]
	s_add_i32 m0, s78, 0x2000
	s_nop 0
	global_load_lds_dwordx4 v[216:217], off
	v_lshl_add_u64 v[216:217], s[54:55], 0, v[128:129]
	s_mov_b32 m0, s35
	s_nop 0
	global_load_lds_dwordx4 v[216:217], off
	s_mov_b32 m0, s39
	s_nop 0
	global_load_lds_dwordx4 v[218:219], off
	s_waitcnt vmcnt(8)
	s_waitcnt lgkmcnt(0)
	s_barrier
; #define PG8_STAGE(bufoff, gbase, voff) do { _Pragma("unroll") for (int _i = 0; _i < 2; ++_i) \
;         __builtin_amdgcn_global_load_lds((const unsigned*)((const char*)(gbase) + (voff)[_i]), (LAS unsigned*)(lds + (bufoff) + ldsw + _i * 8192), 16, 0, 0); } while (0)
; #define PG8_LDA(dst, b, h) do { _Pragma("unroll") for (int m = 0; m < 4; ++m) _Pragma("unroll") for (int k = 0; k < 2; ++k) dst[m][k] = *(const LAS bf16x8*)(lds + PG8_SA(b, h) + aoff + m * 2048 + k * 1024); } while (0)
; #define PG8_LDB(dst, b, h) do { _Pragma("unroll") for (int n = 0; n < 2; ++n) _Pragma("unroll") for (int k = 0; k < 2; ++k) dst[n][k] = *(const LAS bf16x8*)(lds + PG8_SB(b, h) + boff + n * 2048 + k * 1024); } while (0)
; #define PG8_MMA(ai, bj, At, Bt) do { __builtin_amdgcn_s_setprio(1); _Pragma("unroll") for (int m = 0; m < 4; ++m) _Pragma("unroll") for (int n = 0; n < 2; ++n) _Pragma("unroll") for (int k = 0; k < 2; ++k) \
;         acc[ai][bj][m][n] = __builtin_amdgcn_mfma_f32_16x16x32_bf16(Bt[n][k], At[m][k], acc[ai][bj][m][n], 0, 0, 0); __builtin_amdgcn_s_setprio(0); } while (0)
; #define PG8_WAIT_V(n) asm volatile("s_waitcnt vmcnt(" #n ")" ::: "memory")
; #define PG8_WAIT_L(n) asm volatile("s_waitcnt lgkmcnt(" #n ")" ::: "memory")
; #define PG8_BAR __builtin_amdgcn_s_barrier()
; #define PG8_SCHED __builtin_amdgcn_sched_barrier(0)
; template <class Epi, bool ALIGN_EPI = PG8_ALIGN>
; __device__ __forceinline__ void gemm_phase(LAS unsigned char* lds, const Gemm g, const StaticOrder S, const Epi E) {
;     ...
;             PG8_WAIT_V(8); PG8_WAIT_L(0); PG8_BAR; PG8_MMA(1, 0, At, B0); PG8_MMA(1, 1, At, B1); PG8_BAR; PG8_SCHED;
;             PG8_LDB(B0, 1, 0); PG8_LDB(B1, 1, 1); PG8_SCHED; PG8_LDA(At, 1, 0); PG8_STAGE(PG8_SA(0, 1), a2 + hstepA, voffA);
;             PG8_WAIT_V(8); PG8_WAIT_L(0); PG8_BAR; PG8_MMA(0, 0, At, B0); PG8_MMA(0, 1, At, B1); PG8_BAR; PG8_SCHED;
	s_setprio 1
	s_waitcnt lgkmcnt(0)
	v_mfma_f32_16x16x32_bf16 v[92:95], v[146:149], v[178:181], v[92:95]
	v_mfma_f32_16x16x32_bf16 v[88:91], v[154:157], v[178:181], v[88:91]
	v_mfma_f32_16x16x32_bf16 v[76:79], v[154:157], v[190:193], v[76:79]
	v_mfma_f32_16x16x32_bf16 v[84:87], v[146:149], v[190:193], v[84:87]
	v_mfma_f32_16x16x32_bf16 v[64:67], v[146:149], v[198:201], v[64:67]
	v_mfma_f32_16x16x32_bf16 v[56:59], v[154:157], v[198:201], v[56:59]
	v_mfma_f32_16x16x32_bf16 v[40:43], v[154:157], v[206:209], v[40:43]
	v_mfma_f32_16x16x32_bf16 v[44:47], v[146:149], v[206:209], v[44:47]
	v_mfma_f32_16x16x32_bf16 v[92:95], v[150:153], v[186:189], v[92:95]
	v_mfma_f32_16x16x32_bf16 v[88:91], v[158:161], v[186:189], v[88:91]
	v_mfma_f32_16x16x32_bf16 v[76:79], v[158:161], v[194:197], v[76:79]
	v_mfma_f32_16x16x32_bf16 v[84:87], v[150:153], v[194:197], v[84:87]
	v_mfma_f32_16x16x32_bf16 v[64:67], v[150:153], v[202:205], v[64:67]
	v_mfma_f32_16x16x32_bf16 v[56:59], v[158:161], v[202:205], v[56:59]
	v_mfma_f32_16x16x32_bf16 v[40:43], v[158:161], v[210:213], v[40:43]
	v_mfma_f32_16x16x32_bf16 v[44:47], v[150:153], v[210:213], v[44:47]
	s_setprio 0
	s_setprio 1
	v_mfma_f32_16x16x32_bf16 v[28:31], v[162:165], v[178:181], v[28:31]
	v_mfma_f32_16x16x32_bf16 v[24:27], v[170:173], v[178:181], v[24:27]
	v_mfma_f32_16x16x32_bf16 v[16:19], v[170:173], v[190:193], v[16:19]
	v_mfma_f32_16x16x32_bf16 v[20:23], v[162:165], v[190:193], v[20:23]
	v_mfma_f32_16x16x32_bf16 v[12:15], v[162:165], v[198:201], v[12:15]
	v_mfma_f32_16x16x32_bf16 v[8:11], v[170:173], v[198:201], v[8:11]
	v_mfma_f32_16x16x32_bf16 v[0:3], v[170:173], v[206:209], v[0:3]
	v_mfma_f32_16x16x32_bf16 v[4:7], v[162:165], v[206:209], v[4:7]
	v_mfma_f32_16x16x32_bf16 v[28:31], v[166:169], v[186:189], v[28:31]
	v_mfma_f32_16x16x32_bf16 v[24:27], v[174:177], v[186:189], v[24:27]
	v_mfma_f32_16x16x32_bf16 v[16:19], v[174:177], v[194:197], v[16:19]
	v_mfma_f32_16x16x32_bf16 v[20:23], v[166:169], v[194:197], v[20:23]
	v_mfma_f32_16x16x32_bf16 v[12:15], v[166:169], v[202:205], v[12:15]
	v_mfma_f32_16x16x32_bf16 v[8:11], v[174:177], v[202:205], v[8:11]
	v_mfma_f32_16x16x32_bf16 v[0:3], v[174:177], v[210:213], v[0:3]
	v_mfma_f32_16x16x32_bf16 v[4:7], v[166:169], v[210:213], v[4:7]
	s_setprio 0
	s_barrier
	s_add_i32 s76, 0, 0x18000
	s_add_i32 s77, 0, 0x1c000
	v_add_u32_e32 v158, s76, v141
	v_add_u32_e32 v174, s77, v141
	ds_read_b128 v[146:149], v158
	ds_read_b128 v[150:153], v158 offset:1024
	ds_read_b128 v[154:157], v158 offset:2048
	ds_read_b128 v[158:161], v158 offset:3072
	ds_read_b128 v[162:165], v174
	ds_read_b128 v[166:169], v174 offset:1024
	ds_read_b128 v[170:173], v174 offset:2048
	ds_read_b128 v[174:177], v174 offset:3072
	s_add_u32 s54, s54, 0x80000
	s_addc_u32 s55, s55, 0
	s_mov_b32 m0, s58
	v_lshl_add_u64 v[220:221], s[54:55], 0, v[128:129]
	ds_read_b128 v[178:181], v145 offset:32768
	ds_read_b128 v[186:189], v145 offset:33792
	ds_read_b128 v[190:193], v145 offset:34816
	ds_read_b128 v[194:197], v145 offset:35840
	ds_read_b128 v[198:201], v145 offset:36864
	ds_read_b128 v[202:205], v145 offset:37888
	ds_read_b128 v[206:209], v145 offset:38912
	ds_read_b128 v[210:213], v145 offset:39936
	global_load_lds_dwordx4 v[220:221], off
	v_lshl_add_u64 v[220:221], s[54:55], 0, v[132:133]
	s_mov_b32 m0, s59
	s_nop 0
	global_load_lds_dwordx4 v[220:221], off
	s_waitcnt vmcnt(8)
	s_waitcnt lgkmcnt(0)
	s_barrier
	s_setprio 1
	s_waitcnt lgkmcnt(0)
	v_mfma_f32_16x16x32_bf16 v[124:127], v[146:149], v[178:181], v[124:127]
	v_mfma_f32_16x16x32_bf16 v[120:123], v[154:157], v[178:181], v[120:123]
	v_mfma_f32_16x16x32_bf16 v[112:115], v[154:157], v[190:193], v[112:115]
	v_mfma_f32_16x16x32_bf16 v[116:119], v[146:149], v[190:193], v[116:119]
	v_mfma_f32_16x16x32_bf16 v[108:111], v[146:149], v[198:201], v[108:111]
	v_mfma_f32_16x16x32_bf16 v[104:107], v[154:157], v[198:201], v[104:107]
	v_mfma_f32_16x16x32_bf16 v[96:99], v[154:157], v[206:209], v[96:99]
	v_mfma_f32_16x16x32_bf16 v[100:103], v[146:149], v[206:209], v[100:103]
	v_mfma_f32_16x16x32_bf16 v[124:127], v[150:153], v[186:189], v[124:127]
	v_mfma_f32_16x16x32_bf16 v[120:123], v[158:161], v[186:189], v[120:123]
	v_mfma_f32_16x16x32_bf16 v[112:115], v[158:161], v[194:197], v[112:115]
	v_mfma_f32_16x16x32_bf16 v[116:119], v[150:153], v[194:197], v[116:119]
	v_mfma_f32_16x16x32_bf16 v[108:111], v[150:153], v[202:205], v[108:111]
	v_mfma_f32_16x16x32_bf16 v[104:107], v[158:161], v[202:205], v[104:107]
	v_mfma_f32_16x16x32_bf16 v[96:99], v[158:161], v[210:213], v[96:99]
	v_mfma_f32_16x16x32_bf16 v[100:103], v[150:153], v[210:213], v[100:103]
	s_setprio 0
	s_setprio 1
	v_mfma_f32_16x16x32_bf16 v[80:83], v[162:165], v[178:181], v[80:83]
	v_mfma_f32_16x16x32_bf16 v[72:75], v[170:173], v[178:181], v[72:75]
	v_mfma_f32_16x16x32_bf16 v[60:63], v[170:173], v[190:193], v[60:63]
	v_mfma_f32_16x16x32_bf16 v[68:71], v[162:165], v[190:193], v[68:71]
	v_mfma_f32_16x16x32_bf16 v[52:55], v[162:165], v[198:201], v[52:55]
	v_mfma_f32_16x16x32_bf16 v[48:51], v[170:173], v[198:201], v[48:51]
	v_mfma_f32_16x16x32_bf16 v[32:35], v[170:173], v[206:209], v[32:35]
	v_mfma_f32_16x16x32_bf16 v[36:39], v[162:165], v[206:209], v[36:39]
	v_mfma_f32_16x16x32_bf16 v[80:83], v[166:169], v[186:189], v[80:83]
	v_mfma_f32_16x16x32_bf16 v[72:75], v[174:177], v[186:189], v[72:75]
	v_mfma_f32_16x16x32_bf16 v[60:63], v[174:177], v[194:197], v[60:63]
	v_mfma_f32_16x16x32_bf16 v[68:71], v[166:169], v[194:197], v[68:71]
	v_mfma_f32_16x16x32_bf16 v[52:55], v[166:169], v[202:205], v[52:55]
	v_mfma_f32_16x16x32_bf16 v[48:51], v[174:177], v[202:205], v[48:51]
	v_mfma_f32_16x16x32_bf16 v[32:35], v[174:177], v[210:213], v[32:35]
	v_mfma_f32_16x16x32_bf16 v[36:39], v[166:169], v[210:213], v[36:39]
	s_setprio 0
	s_barrier
; #define PG8_STAGE(bufoff, gbase, voff) do { _Pragma("unroll") for (int _i = 0; _i < 2; ++_i) \
;         __builtin_amdgcn_global_load_lds((const unsigned*)((const char*)(gbase) + (voff)[_i]), (LAS unsigned*)(lds + (bufoff) + ldsw + _i * 8192), 16, 0, 0); } while (0)
; #define PG8_LDA(dst, b, h) do { _Pragma("unroll") for (int m = 0; m < 4; ++m) _Pragma("unroll") for (int k = 0; k < 2; ++k) dst[m][k] = *(const LAS bf16x8*)(lds + PG8_SA(b, h) + aoff + m * 2048 + k * 1024); } while (0)
; #define PG8_MMA(ai, bj, At, Bt) do { __builtin_amdgcn_s_setprio(1); _Pragma("unroll") for (int m = 0; m < 4; ++m) _Pragma("unroll") for (int n = 0; n < 2; ++n) _Pragma("unroll") for (int k = 0; k < 2; ++k) \
;         acc[ai][bj][m][n] = __builtin_amdgcn_mfma_f32_16x16x32_bf16(Bt[n][k], At[m][k], acc[ai][bj][m][n], 0, 0, 0); __builtin_amdgcn_s_setprio(0); } while (0)
; #define PG8_WAIT_V(n) asm volatile("s_waitcnt vmcnt(" #n ")" ::: "memory")
; #define PG8_WAIT_L(n) asm volatile("s_waitcnt lgkmcnt(" #n ")" ::: "memory")
; #define PG8_BAR __builtin_amdgcn_s_barrier()
; #define PG8_SCHED __builtin_amdgcn_sched_barrier(0)
; template <class Epi, bool ALIGN_EPI = PG8_ALIGN>
; __device__ __forceinline__ void gemm_phase(LAS unsigned char* lds, const Gemm g, const StaticOrder S, const Epi E) {
;     ...
;             PG8_LDA(At, 1, 1); PG8_STAGE(PG8_SB(1, 0), b3, voffB); PG8_STAGE(PG8_SB(1, 1), b3 + hstepB, voffB); PG8_STAGE(PG8_SA(1, 0), a3, voffA);
;             PG8_WAIT_V(8); PG8_WAIT_L(0); PG8_BAR; PG8_MMA(1, 0, At, B0); PG8_MMA(1, 1, At, B1); PG8_BAR; PG8_SCHED;
;         }
;         if (ALIGN_EPI) { if (wr == 0) PG8_BAR; }
	s_add_i32 s54, s76, s34
	v_lshl_add_u64 v[182:183], v[182:183], 0, s[6:7]
	s_mov_b32 m0, s54
	ds_read_b128 v[178:181], v145 offset:49152
	ds_read_b128 v[186:189], v145 offset:50176
	ds_read_b128 v[190:193], v145 offset:51200
	ds_read_b128 v[194:197], v145 offset:52224
	ds_read_b128 v[198:201], v145 offset:53248
	ds_read_b128 v[202:205], v145 offset:54272
	ds_read_b128 v[206:209], v145 offset:55296
	ds_read_b128 v[210:213], v145 offset:56320
	global_load_lds_dwordx4 v[182:183], off
	s_add_i32 m0, s54, 0x2000
	s_add_u32 s52, s52, 0x80080
	v_lshl_add_u64 v[182:183], v[214:215], 0, s[6:7]
	s_addc_u32 s53, s53, 0
	s_add_i32 s54, s77, s34
	global_load_lds_dwordx4 v[182:183], off
	v_lshl_add_u64 v[182:183], s[52:53], 0, v[130:131]
	s_mov_b32 m0, s54
	s_nop 0
	global_load_lds_dwordx4 v[182:183], off
	v_lshl_add_u64 v[182:183], s[52:53], 0, v[134:135]
	s_add_i32 m0, s54, 0x2000
	s_nop 0
	global_load_lds_dwordx4 v[182:183], off
	v_lshl_add_u64 v[182:183], v[216:217], 0, s[6:7]
	s_mov_b32 m0, s61
	s_nop 0
	global_load_lds_dwordx4 v[182:183], off
	v_lshl_add_u64 v[182:183], v[218:219], 0, s[6:7]
	s_mov_b32 m0, s62
	s_nop 0
	global_load_lds_dwordx4 v[182:183], off
	s_waitcnt vmcnt(8)
	s_waitcnt lgkmcnt(0)
	s_barrier
	s_setprio 1
	s_waitcnt lgkmcnt(0)
	v_mfma_f32_16x16x32_bf16 v[92:95], v[146:149], v[178:181], v[92:95]
	v_mfma_f32_16x16x32_bf16 v[88:91], v[154:157], v[178:181], v[88:91]
	v_mfma_f32_16x16x32_bf16 v[76:79], v[154:157], v[190:193], v[76:79]
	v_mfma_f32_16x16x32_bf16 v[84:87], v[146:149], v[190:193], v[84:87]
	v_mfma_f32_16x16x32_bf16 v[64:67], v[146:149], v[198:201], v[64:67]
	v_mfma_f32_16x16x32_bf16 v[56:59], v[154:157], v[198:201], v[56:59]
	v_mfma_f32_16x16x32_bf16 v[40:43], v[154:157], v[206:209], v[40:43]
	v_mfma_f32_16x16x32_bf16 v[44:47], v[146:149], v[206:209], v[44:47]
	v_mfma_f32_16x16x32_bf16 v[92:95], v[150:153], v[186:189], v[92:95]
	v_mfma_f32_16x16x32_bf16 v[88:91], v[158:161], v[186:189], v[88:91]
	v_mfma_f32_16x16x32_bf16 v[76:79], v[158:161], v[194:197], v[76:79]
	v_mfma_f32_16x16x32_bf16 v[84:87], v[150:153], v[194:197], v[84:87]
	v_mfma_f32_16x16x32_bf16 v[64:67], v[150:153], v[202:205], v[64:67]
	v_mfma_f32_16x16x32_bf16 v[56:59], v[158:161], v[202:205], v[56:59]
	v_mfma_f32_16x16x32_bf16 v[40:43], v[158:161], v[210:213], v[40:43]
	v_mfma_f32_16x16x32_bf16 v[44:47], v[150:153], v[210:213], v[44:47]
	s_setprio 0
	s_setprio 1
	v_mfma_f32_16x16x32_bf16 v[28:31], v[162:165], v[178:181], v[28:31]
	v_mfma_f32_16x16x32_bf16 v[24:27], v[170:173], v[178:181], v[24:27]
	v_mfma_f32_16x16x32_bf16 v[16:19], v[170:173], v[190:193], v[16:19]
	v_mfma_f32_16x16x32_bf16 v[20:23], v[162:165], v[190:193], v[20:23]
	v_mfma_f32_16x16x32_bf16 v[12:15], v[162:165], v[198:201], v[12:15]
	v_mfma_f32_16x16x32_bf16 v[8:11], v[170:173], v[198:201], v[8:11]
	v_mfma_f32_16x16x32_bf16 v[0:3], v[170:173], v[206:209], v[0:3]
	v_mfma_f32_16x16x32_bf16 v[4:7], v[162:165], v[206:209], v[4:7]
	v_mfma_f32_16x16x32_bf16 v[28:31], v[166:169], v[186:189], v[28:31]
	v_mfma_f32_16x16x32_bf16 v[24:27], v[174:177], v[186:189], v[24:27]
	v_mfma_f32_16x16x32_bf16 v[16:19], v[174:177], v[194:197], v[16:19]
	v_mfma_f32_16x16x32_bf16 v[20:23], v[166:169], v[194:197], v[20:23]
	v_mfma_f32_16x16x32_bf16 v[12:15], v[166:169], v[202:205], v[12:15]
	v_mfma_f32_16x16x32_bf16 v[8:11], v[174:177], v[202:205], v[8:11]
	v_mfma_f32_16x16x32_bf16 v[0:3], v[174:177], v[210:213], v[0:3]
	v_mfma_f32_16x16x32_bf16 v[4:7], v[166:169], v[210:213], v[4:7]
	s_setprio 0
	s_barrier
	s_add_i32 s75, s75, 2
	s_add_u32 s50, s50, 0x100
	s_addc_u32 s51, s51, 0
	s_add_u32 s73, s73, 0x100
	s_addc_u32 s74, s74, 0
	s_cmp_gt_u32 s75, 29
	s_cbranch_scc0 .LBB0_1348
	s_and_b64 vcc, exec, s[8:9]
	s_cbranch_vccz .LBB0_1351
	s_barrier

; #define PG8_STAGE(bufoff, gbase, voff) do { _Pragma("unroll") for (int _i = 0; _i < 2; ++_i) \
;         __builtin_amdgcn_global_load_lds((const unsigned*)((const char*)(gbase) + (voff)[_i]), (LAS unsigned*)(lds + (bufoff) + ldsw + _i * 8192), 16, 0, 0); } while (0)
; #define PG8_LDA(dst, b, h) do { _Pragma("unroll") for (int m = 0; m < 4; ++m) _Pragma("unroll") for (int k = 0; k < 2; ++k) dst[m][k] = *(const LAS bf16x8*)(lds + PG8_SA(b, h) + aoff + m * 2048 + k * 1024); } while (0)
; #define PG8_LDB(dst, b, h) do { _Pragma("unroll") for (int n = 0; n < 2; ++n) _Pragma("unroll") for (int k = 0; k < 2; ++k) dst[n][k] = *(const LAS bf16x8*)(lds + PG8_SB(b, h) + boff + n * 2048 + k * 1024); } while (0)
; #define PG8_MMA(ai, bj, At, Bt) do { __builtin_amdgcn_s_setprio(1); _Pragma("unroll") for (int m = 0; m < 4; ++m) _Pragma("unroll") for (int n = 0; n < 2; ++n) _Pragma("unroll") for (int k = 0; k < 2; ++k) \
;         acc[ai][bj][m][n] = __builtin_amdgcn_mfma_f32_16x16x32_bf16(Bt[n][k], At[m][k], acc[ai][bj][m][n], 0, 0, 0); __builtin_amdgcn_s_setprio(0); } while (0)
; #define PG8_BAR __builtin_amdgcn_s_barrier()
; template <class Epi, bool ALIGN_EPI = PG8_ALIGN>
; __device__ __forceinline__ void gemm_phase(LAS unsigned char* lds, const Gemm g, const StaticOrder S, const Epi E) {
;     ...
;         const bool has_next = S.next(ui + 1, nxt);
;         const char* nA = has_next ? (const char*)g.A + (size_t)nxt.pm * tstepA : cA; const char* nB = has_next ? (const char*)g.Bt + (size_t)nxt.pn * tstepB : cB;
;         for (int t = 0; t < nt; t += 2) {
;             const bool last = (t == nt - 2);
;             const char* a1 = cA + (size_t)(t + 1) * kstep;
;             const char* a2 = last ? nA : cA + (size_t)(t + 2) * kstep; const char* b2 = last ? nB : cB + (size_t)(t + 2) * kstep;
;             const char* a3 = a2 + kstep; const char* b3 = b2 + kstep;
;             PG8_LDB(B0, 0, 0); PG8_LDB(B1, 0, 1); PG8_SCHED; PG8_LDA(At, 0, 0); PG8_STAGE(PG8_SA(1, 1), a1 + hstepA, voffA);
;             PG8_WAIT_V(8); PG8_WAIT_L(0); PG8_BAR; PG8_MMA(0, 0, At, B0); PG8_MMA(0, 1, At, B1); PG8_BAR; PG8_SCHED;
;             PG8_LDA(At, 0, 1); PG8_STAGE(PG8_SB(0, 0), b2, voffB); PG8_STAGE(PG8_SB(0, 1), b2 + hstepB, voffB); PG8_STAGE(PG8_SA(0, 0), a2, voffA);
;             PG8_WAIT_V(8); PG8_WAIT_L(0); PG8_BAR; PG8_MMA(1, 0, At, B0); PG8_MMA(1, 1, At, B1); PG8_BAR; PG8_SCHED;
.LBB0_1602:
	ds_read_b128 v[146:149], v151
	ds_read_b128 v[154:157], v151 offset:1024
	ds_read_b128 v[158:161], v151 offset:2048
	ds_read_b128 v[162:165], v151 offset:3072
	ds_read_b128 v[166:169], v152
	ds_read_b128 v[170:173], v152 offset:1024
	ds_read_b128 v[174:177], v152 offset:2048
	ds_read_b128 v[178:181], v152 offset:3072
	s_add_u32 s34, s36, 0xfffe0080
	s_addc_u32 s35, s37, -1
	s_cmp_eq_u32 s33, 4
	s_cselect_b32 s43, s13, s35
	s_cselect_b32 s42, s14, s34
	s_cselect_b32 s39, s16, s23
	s_cselect_b32 s38, s17, s21
	v_lshl_add_u64 v[182:183], s[36:37], 0, v[138:139]
	s_add_i32 m0, s29, 0xc000
	ds_read_b128 v[186:189], v153
	ds_read_b128 v[190:193], v153 offset:1024
	ds_read_b128 v[194:197], v153 offset:2048
	ds_read_b128 v[198:201], v153 offset:3072
	ds_read_b128 v[202:205], v153 offset:4096
	ds_read_b128 v[206:209], v153 offset:5120
	ds_read_b128 v[210:213], v153 offset:6144
	ds_read_b128 v[214:217], v153 offset:7168
	global_load_lds_dwordx4 v[182:183], off
	v_lshl_add_u64 v[182:183], s[36:37], 0, v[140:141]
	s_add_i32 m0, s29, 0xe000
	s_nop 0
	global_load_lds_dwordx4 v[182:183], off
	s_waitcnt vmcnt(8)
	s_waitcnt lgkmcnt(0)
	s_barrier
	s_setprio 1
	s_waitcnt lgkmcnt(0)
	v_mfma_f32_16x16x32_bf16 v[124:127], v[146:149], v[186:189], v[124:127]
	v_mfma_f32_16x16x32_bf16 v[120:123], v[158:161], v[186:189], v[120:123]
	v_mfma_f32_16x16x32_bf16 v[104:107], v[158:161], v[194:197], v[104:107]
	v_mfma_f32_16x16x32_bf16 v[108:111], v[146:149], v[194:197], v[108:111]
	v_mfma_f32_16x16x32_bf16 v[92:95], v[146:149], v[202:205], v[92:95]
	v_mfma_f32_16x16x32_bf16 v[88:91], v[158:161], v[202:205], v[88:91]
	v_mfma_f32_16x16x32_bf16 v[72:75], v[158:161], v[210:213], v[72:75]
	v_mfma_f32_16x16x32_bf16 v[76:79], v[146:149], v[210:213], v[76:79]
	v_mfma_f32_16x16x32_bf16 v[124:127], v[154:157], v[190:193], v[124:127]
	v_mfma_f32_16x16x32_bf16 v[120:123], v[162:165], v[190:193], v[120:123]
	v_mfma_f32_16x16x32_bf16 v[104:107], v[162:165], v[198:201], v[104:107]
	v_mfma_f32_16x16x32_bf16 v[108:111], v[154:157], v[198:201], v[108:111]
	v_mfma_f32_16x16x32_bf16 v[92:95], v[154:157], v[206:209], v[92:95]
	v_mfma_f32_16x16x32_bf16 v[88:91], v[162:165], v[206:209], v[88:91]
	v_mfma_f32_16x16x32_bf16 v[72:75], v[162:165], v[214:217], v[72:75]
	v_mfma_f32_16x16x32_bf16 v[76:79], v[154:157], v[214:217], v[76:79]
	s_setprio 0
	s_setprio 1
	v_mfma_f32_16x16x32_bf16 v[116:119], v[166:169], v[186:189], v[116:119]
	v_mfma_f32_16x16x32_bf16 v[112:115], v[174:177], v[186:189], v[112:115]
	v_mfma_f32_16x16x32_bf16 v[96:99], v[174:177], v[194:197], v[96:99]
	v_mfma_f32_16x16x32_bf16 v[100:103], v[166:169], v[194:197], v[100:103]
	v_mfma_f32_16x16x32_bf16 v[84:87], v[166:169], v[202:205], v[84:87]
	v_mfma_f32_16x16x32_bf16 v[80:83], v[174:177], v[202:205], v[80:83]
	v_mfma_f32_16x16x32_bf16 v[64:67], v[174:177], v[210:213], v[64:67]
	v_mfma_f32_16x16x32_bf16 v[68:71], v[166:169], v[210:213], v[68:71]
	v_mfma_f32_16x16x32_bf16 v[116:119], v[170:173], v[190:193], v[116:119]
	v_mfma_f32_16x16x32_bf16 v[112:115], v[178:181], v[190:193], v[112:115]
	v_mfma_f32_16x16x32_bf16 v[96:99], v[178:181], v[198:201], v[96:99]
	v_mfma_f32_16x16x32_bf16 v[100:103], v[170:173], v[198:201], v[100:103]
	v_mfma_f32_16x16x32_bf16 v[84:87], v[170:173], v[206:209], v[84:87]
	v_mfma_f32_16x16x32_bf16 v[80:83], v[178:181], v[206:209], v[80:83]
	v_mfma_f32_16x16x32_bf16 v[64:67], v[178:181], v[214:217], v[64:67]
	v_mfma_f32_16x16x32_bf16 v[68:71], v[170:173], v[214:217], v[68:71]
	s_setprio 0
	s_barrier
	s_add_i32 s34, s53, s44
	v_lshl_add_u64 v[182:183], s[38:39], 0, v[130:131]
	s_mov_b32 m0, s34
	ds_read_b128 v[186:189], v153 offset:16384
	ds_read_b128 v[190:193], v153 offset:17408
	ds_read_b128 v[194:197], v153 offset:18432
	ds_read_b128 v[198:201], v153 offset:19456
	ds_read_b128 v[202:205], v153 offset:20480
	ds_read_b128 v[206:209], v153 offset:21504
	ds_read_b128 v[210:213], v153 offset:22528
	ds_read_b128 v[214:217], v153 offset:23552
	global_load_lds_dwordx4 v[182:183], off
	s_add_i32 m0, s34, 0x2000
	s_add_u32 s34, s38, 0x20000
	v_lshl_add_u64 v[218:219], s[38:39], 0, v[134:135]
	s_addc_u32 s35, s39, 0
	s_add_i32 s55, s54, s44
	global_load_lds_dwordx4 v[218:219], off
	v_lshl_add_u64 v[220:221], s[34:35], 0, v[130:131]
	s_mov_b32 m0, s55
	v_lshl_add_u64 v[222:223], s[42:43], 0, v[132:133]
	global_load_lds_dwordx4 v[220:221], off
	v_lshl_add_u64 v[220:221], s[34:35], 0, v[134:135]
	s_add_i32 m0, s55, 0x2000
	s_nop 0
	global_load_lds_dwordx4 v[220:221], off
	v_lshl_add_u64 v[220:221], s[42:43], 0, v[128:129]
	s_mov_b32 m0, s29
	s_nop 0
	global_load_lds_dwordx4 v[220:221], off
	s_mov_b32 m0, s45
	s_nop 0
	global_load_lds_dwordx4 v[222:223], off
	s_waitcnt vmcnt(8)
	s_waitcnt lgkmcnt(0)
	s_barrier
; #define PG8_STAGE(bufoff, gbase, voff) do { _Pragma("unroll") for (int _i = 0; _i < 2; ++_i) \
;         __builtin_amdgcn_global_load_lds((const unsigned*)((const char*)(gbase) + (voff)[_i]), (LAS unsigned*)(lds + (bufoff) + ldsw + _i * 8192), 16, 0, 0); } while (0)
; #define PG8_LDA(dst, b, h) do { _Pragma("unroll") for (int m = 0; m < 4; ++m) _Pragma("unroll") for (int k = 0; k < 2; ++k) dst[m][k] = *(const LAS bf16x8*)(lds + PG8_SA(b, h) + aoff + m * 2048 + k * 1024); } while (0)
; #define PG8_LDB(dst, b, h) do { _Pragma("unroll") for (int n = 0; n < 2; ++n) _Pragma("unroll") for (int k = 0; k < 2; ++k) dst[n][k] = *(const LAS bf16x8*)(lds + PG8_SB(b, h) + boff + n * 2048 + k * 1024); } while (0)
; #define PG8_MMA(ai, bj, At, Bt) do { __builtin_amdgcn_s_setprio(1); _Pragma("unroll") for (int m = 0; m < 4; ++m) _Pragma("unroll") for (int n = 0; n < 2; ++n) _Pragma("unroll") for (int k = 0; k < 2; ++k) \
;         acc[ai][bj][m][n] = __builtin_amdgcn_mfma_f32_16x16x32_bf16(Bt[n][k], At[m][k], acc[ai][bj][m][n], 0, 0, 0); __builtin_amdgcn_s_setprio(0); } while (0)
; #define PG8_WAIT_V(n) asm volatile("s_waitcnt vmcnt(" #n ")" ::: "memory")
; #define PG8_WAIT_L(n) asm volatile("s_waitcnt lgkmcnt(" #n ")" ::: "memory")
; #define PG8_BAR __builtin_amdgcn_s_barrier()
; #define PG8_SCHED __builtin_amdgcn_sched_barrier(0)
; template <class Epi, bool ALIGN_EPI = PG8_ALIGN>
; __device__ __forceinline__ void gemm_phase(LAS unsigned char* lds, const Gemm g, const StaticOrder S, const Epi E) {
;     ...
;             PG8_WAIT_V(8); PG8_WAIT_L(0); PG8_BAR; PG8_MMA(1, 0, At, B0); PG8_MMA(1, 1, At, B1); PG8_BAR; PG8_SCHED;
;             PG8_LDB(B0, 1, 0); PG8_LDB(B1, 1, 1); PG8_SCHED; PG8_LDA(At, 1, 0); PG8_STAGE(PG8_SA(0, 1), a2 + hstepA, voffA);
;             PG8_WAIT_V(8); PG8_WAIT_L(0); PG8_BAR; PG8_MMA(0, 0, At, B0); PG8_MMA(0, 1, At, B1); PG8_BAR; PG8_SCHED;
	s_setprio 1
	s_waitcnt lgkmcnt(0)
	v_mfma_f32_16x16x32_bf16 v[60:63], v[146:149], v[186:189], v[60:63]
	v_mfma_f32_16x16x32_bf16 v[56:59], v[158:161], v[186:189], v[56:59]
	v_mfma_f32_16x16x32_bf16 v[40:43], v[158:161], v[194:197], v[40:43]
	v_mfma_f32_16x16x32_bf16 v[44:47], v[146:149], v[194:197], v[44:47]
	v_mfma_f32_16x16x32_bf16 v[28:31], v[146:149], v[202:205], v[28:31]
	v_mfma_f32_16x16x32_bf16 v[24:27], v[158:161], v[202:205], v[24:27]
	v_mfma_f32_16x16x32_bf16 v[8:11], v[158:161], v[210:213], v[8:11]
	v_mfma_f32_16x16x32_bf16 v[12:15], v[146:149], v[210:213], v[12:15]
	v_mfma_f32_16x16x32_bf16 v[60:63], v[154:157], v[190:193], v[60:63]
	v_mfma_f32_16x16x32_bf16 v[56:59], v[162:165], v[190:193], v[56:59]
	v_mfma_f32_16x16x32_bf16 v[40:43], v[162:165], v[198:201], v[40:43]
	v_mfma_f32_16x16x32_bf16 v[44:47], v[154:157], v[198:201], v[44:47]
	v_mfma_f32_16x16x32_bf16 v[28:31], v[154:157], v[206:209], v[28:31]
	v_mfma_f32_16x16x32_bf16 v[24:27], v[162:165], v[206:209], v[24:27]
	v_mfma_f32_16x16x32_bf16 v[8:11], v[162:165], v[214:217], v[8:11]
	v_mfma_f32_16x16x32_bf16 v[12:15], v[154:157], v[214:217], v[12:15]
	s_setprio 0
	s_setprio 1
	v_mfma_f32_16x16x32_bf16 v[52:55], v[166:169], v[186:189], v[52:55]
	v_mfma_f32_16x16x32_bf16 v[48:51], v[174:177], v[186:189], v[48:51]
	v_mfma_f32_16x16x32_bf16 v[32:35], v[174:177], v[194:197], v[32:35]
	v_mfma_f32_16x16x32_bf16 v[36:39], v[166:169], v[194:197], v[36:39]
	v_mfma_f32_16x16x32_bf16 v[20:23], v[166:169], v[202:205], v[20:23]
	v_mfma_f32_16x16x32_bf16 v[16:19], v[174:177], v[202:205], v[16:19]
	v_mfma_f32_16x16x32_bf16 v[0:3], v[174:177], v[210:213], v[0:3]
	v_mfma_f32_16x16x32_bf16 v[4:7], v[166:169], v[210:213], v[4:7]
	v_mfma_f32_16x16x32_bf16 v[52:55], v[170:173], v[190:193], v[52:55]
	v_mfma_f32_16x16x32_bf16 v[48:51], v[178:181], v[190:193], v[48:51]
	v_mfma_f32_16x16x32_bf16 v[32:35], v[178:181], v[198:201], v[32:35]
	v_mfma_f32_16x16x32_bf16 v[36:39], v[170:173], v[198:201], v[36:39]
	v_mfma_f32_16x16x32_bf16 v[20:23], v[170:173], v[206:209], v[20:23]
	v_mfma_f32_16x16x32_bf16 v[16:19], v[178:181], v[206:209], v[16:19]
	v_mfma_f32_16x16x32_bf16 v[0:3], v[178:181], v[214:217], v[0:3]
	v_mfma_f32_16x16x32_bf16 v[4:7], v[170:173], v[214:217], v[4:7]
	s_setprio 0
	s_barrier
	s_add_i32 s55, 0, 0x18000
	s_add_i32 s56, 0, 0x1c000
	v_add_u32_e32 v162, s55, v150
	v_add_u32_e32 v178, s56, v150
	ds_read_b128 v[146:149], v162
	ds_read_b128 v[154:157], v162 offset:1024
	ds_read_b128 v[158:161], v162 offset:2048
	ds_read_b128 v[162:165], v162 offset:3072
	ds_read_b128 v[166:169], v178
	ds_read_b128 v[170:173], v178 offset:1024
	ds_read_b128 v[174:177], v178 offset:2048
	ds_read_b128 v[178:181], v178 offset:3072
	s_add_u32 s34, s42, 0x20000
	s_addc_u32 s35, s43, 0
	s_mov_b32 m0, s46
	v_lshl_add_u64 v[224:225], s[34:35], 0, v[128:129]
	ds_read_b128 v[186:189], v153 offset:32768
	ds_read_b128 v[190:193], v153 offset:33792
	ds_read_b128 v[194:197], v153 offset:34816
	ds_read_b128 v[198:201], v153 offset:35840
	ds_read_b128 v[202:205], v153 offset:36864
	ds_read_b128 v[206:209], v153 offset:37888
	ds_read_b128 v[210:213], v153 offset:38912
	ds_read_b128 v[214:217], v153 offset:39936
	global_load_lds_dwordx4 v[224:225], off
	v_lshl_add_u64 v[224:225], s[34:35], 0, v[132:133]
	s_mov_b32 m0, s47
	s_nop 0
	global_load_lds_dwordx4 v[224:225], off
	s_waitcnt vmcnt(8)
	s_waitcnt lgkmcnt(0)
	s_barrier
	s_setprio 1
	s_waitcnt lgkmcnt(0)
	v_mfma_f32_16x16x32_bf16 v[124:127], v[146:149], v[186:189], v[124:127]
	v_mfma_f32_16x16x32_bf16 v[120:123], v[158:161], v[186:189], v[120:123]
	v_mfma_f32_16x16x32_bf16 v[104:107], v[158:161], v[194:197], v[104:107]
	v_mfma_f32_16x16x32_bf16 v[108:111], v[146:149], v[194:197], v[108:111]
	v_mfma_f32_16x16x32_bf16 v[92:95], v[146:149], v[202:205], v[92:95]
	v_mfma_f32_16x16x32_bf16 v[88:91], v[158:161], v[202:205], v[88:91]
	v_mfma_f32_16x16x32_bf16 v[72:75], v[158:161], v[210:213], v[72:75]
	v_mfma_f32_16x16x32_bf16 v[76:79], v[146:149], v[210:213], v[76:79]
	v_mfma_f32_16x16x32_bf16 v[124:127], v[154:157], v[190:193], v[124:127]
	v_mfma_f32_16x16x32_bf16 v[120:123], v[162:165], v[190:193], v[120:123]
	v_mfma_f32_16x16x32_bf16 v[104:107], v[162:165], v[198:201], v[104:107]
	v_mfma_f32_16x16x32_bf16 v[108:111], v[154:157], v[198:201], v[108:111]
	v_mfma_f32_16x16x32_bf16 v[92:95], v[154:157], v[206:209], v[92:95]
	v_mfma_f32_16x16x32_bf16 v[88:91], v[162:165], v[206:209], v[88:91]
	v_mfma_f32_16x16x32_bf16 v[72:75], v[162:165], v[214:217], v[72:75]
	v_mfma_f32_16x16x32_bf16 v[76:79], v[154:157], v[214:217], v[76:79]
	s_setprio 0
	s_setprio 1
	v_mfma_f32_16x16x32_bf16 v[116:119], v[166:169], v[186:189], v[116:119]
	v_mfma_f32_16x16x32_bf16 v[112:115], v[174:177], v[186:189], v[112:115]
	v_mfma_f32_16x16x32_bf16 v[96:99], v[174:177], v[194:197], v[96:99]
	v_mfma_f32_16x16x32_bf16 v[100:103], v[166:169], v[194:197], v[100:103]
	v_mfma_f32_16x16x32_bf16 v[84:87], v[166:169], v[202:205], v[84:87]
	v_mfma_f32_16x16x32_bf16 v[80:83], v[174:177], v[202:205], v[80:83]
	v_mfma_f32_16x16x32_bf16 v[64:67], v[174:177], v[210:213], v[64:67]
	v_mfma_f32_16x16x32_bf16 v[68:71], v[166:169], v[210:213], v[68:71]
	v_mfma_f32_16x16x32_bf16 v[116:119], v[170:173], v[190:193], v[116:119]
	v_mfma_f32_16x16x32_bf16 v[112:115], v[178:181], v[190:193], v[112:115]
	v_mfma_f32_16x16x32_bf16 v[96:99], v[178:181], v[198:201], v[96:99]
	v_mfma_f32_16x16x32_bf16 v[100:103], v[170:173], v[198:201], v[100:103]
	v_mfma_f32_16x16x32_bf16 v[84:87], v[170:173], v[206:209], v[84:87]
	v_mfma_f32_16x16x32_bf16 v[80:83], v[178:181], v[206:209], v[80:83]
	v_mfma_f32_16x16x32_bf16 v[64:67], v[178:181], v[214:217], v[64:67]
	v_mfma_f32_16x16x32_bf16 v[68:71], v[170:173], v[214:217], v[68:71]
	s_setprio 0
	s_barrier
; #define PG8_STAGE(bufoff, gbase, voff) do { _Pragma("unroll") for (int _i = 0; _i < 2; ++_i) \
;         __builtin_amdgcn_global_load_lds((const unsigned*)((const char*)(gbase) + (voff)[_i]), (LAS unsigned*)(lds + (bufoff) + ldsw + _i * 8192), 16, 0, 0); } while (0)
; #define PG8_LDA(dst, b, h) do { _Pragma("unroll") for (int m = 0; m < 4; ++m) _Pragma("unroll") for (int k = 0; k < 2; ++k) dst[m][k] = *(const LAS bf16x8*)(lds + PG8_SA(b, h) + aoff + m * 2048 + k * 1024); } while (0)
; #define PG8_MMA(ai, bj, At, Bt) do { __builtin_amdgcn_s_setprio(1); _Pragma("unroll") for (int m = 0; m < 4; ++m) _Pragma("unroll") for (int n = 0; n < 2; ++n) _Pragma("unroll") for (int k = 0; k < 2; ++k) \
;         acc[ai][bj][m][n] = __builtin_amdgcn_mfma_f32_16x16x32_bf16(Bt[n][k], At[m][k], acc[ai][bj][m][n], 0, 0, 0); __builtin_amdgcn_s_setprio(0); } while (0)
; #define PG8_WAIT_V(n) asm volatile("s_waitcnt vmcnt(" #n ")" ::: "memory")
; #define PG8_WAIT_L(n) asm volatile("s_waitcnt lgkmcnt(" #n ")" ::: "memory")
; #define PG8_BAR __builtin_amdgcn_s_barrier()
; #define PG8_SCHED __builtin_amdgcn_sched_barrier(0)
; template <class Epi, bool ALIGN_EPI = PG8_ALIGN>
; __device__ __forceinline__ void gemm_phase(LAS unsigned char* lds, const Gemm g, const StaticOrder S, const Epi E) {
;     ...
;             PG8_LDA(At, 1, 1); PG8_STAGE(PG8_SB(1, 0), b3, voffB); PG8_STAGE(PG8_SB(1, 1), b3 + hstepB, voffB); PG8_STAGE(PG8_SA(1, 0), a3, voffA);
;             PG8_WAIT_V(8); PG8_WAIT_L(0); PG8_BAR; PG8_MMA(1, 0, At, B0); PG8_MMA(1, 1, At, B1); PG8_BAR; PG8_SCHED;
;         }
;         if (ALIGN_EPI) { if (wr == 0) PG8_BAR; }
	s_add_i32 s34, s55, s44
	v_lshl_add_u64 v[182:183], v[182:183], 0, s[10:11]
	s_mov_b32 m0, s34
	ds_read_b128 v[186:189], v153 offset:49152
	ds_read_b128 v[190:193], v153 offset:50176
	ds_read_b128 v[194:197], v153 offset:51200
	ds_read_b128 v[198:201], v153 offset:52224
	ds_read_b128 v[202:205], v153 offset:53248
	ds_read_b128 v[206:209], v153 offset:54272
	ds_read_b128 v[210:213], v153 offset:55296
	ds_read_b128 v[214:217], v153 offset:56320
	global_load_lds_dwordx4 v[182:183], off
	s_add_i32 m0, s34, 0x2000
	s_add_u32 s34, s38, 0x20080
	v_lshl_add_u64 v[182:183], v[218:219], 0, s[10:11]
	s_addc_u32 s35, s39, 0
	s_add_i32 s38, s56, s44
	global_load_lds_dwordx4 v[182:183], off
	v_lshl_add_u64 v[182:183], s[34:35], 0, v[130:131]
	s_mov_b32 m0, s38
	s_nop 0
	global_load_lds_dwordx4 v[182:183], off
	v_lshl_add_u64 v[182:183], s[34:35], 0, v[134:135]
	s_add_i32 m0, s38, 0x2000
	s_nop 0
	global_load_lds_dwordx4 v[182:183], off
	v_lshl_add_u64 v[182:183], v[220:221], 0, s[10:11]
	s_mov_b32 m0, s50
	s_nop 0
	global_load_lds_dwordx4 v[182:183], off
	v_lshl_add_u64 v[182:183], v[222:223], 0, s[10:11]
	s_mov_b32 m0, s51
	s_nop 0
	global_load_lds_dwordx4 v[182:183], off
	s_waitcnt vmcnt(8)
	s_waitcnt lgkmcnt(0)
	s_barrier
	s_setprio 1
	s_waitcnt lgkmcnt(0)
	v_mfma_f32_16x16x32_bf16 v[60:63], v[146:149], v[186:189], v[60:63]
	v_mfma_f32_16x16x32_bf16 v[56:59], v[158:161], v[186:189], v[56:59]
	v_mfma_f32_16x16x32_bf16 v[40:43], v[158:161], v[194:197], v[40:43]
	v_mfma_f32_16x16x32_bf16 v[44:47], v[146:149], v[194:197], v[44:47]
	v_mfma_f32_16x16x32_bf16 v[28:31], v[146:149], v[202:205], v[28:31]
	v_mfma_f32_16x16x32_bf16 v[24:27], v[158:161], v[202:205], v[24:27]
	v_mfma_f32_16x16x32_bf16 v[8:11], v[158:161], v[210:213], v[8:11]
	v_mfma_f32_16x16x32_bf16 v[12:15], v[146:149], v[210:213], v[12:15]
	v_mfma_f32_16x16x32_bf16 v[60:63], v[154:157], v[190:193], v[60:63]
	v_mfma_f32_16x16x32_bf16 v[56:59], v[162:165], v[190:193], v[56:59]
	v_mfma_f32_16x16x32_bf16 v[40:43], v[162:165], v[198:201], v[40:43]
	v_mfma_f32_16x16x32_bf16 v[44:47], v[154:157], v[198:201], v[44:47]
	v_mfma_f32_16x16x32_bf16 v[28:31], v[154:157], v[206:209], v[28:31]
	v_mfma_f32_16x16x32_bf16 v[24:27], v[162:165], v[206:209], v[24:27]
	v_mfma_f32_16x16x32_bf16 v[8:11], v[162:165], v[214:217], v[8:11]
	v_mfma_f32_16x16x32_bf16 v[12:15], v[154:157], v[214:217], v[12:15]
	s_setprio 0
	s_setprio 1
	v_mfma_f32_16x16x32_bf16 v[52:55], v[166:169], v[186:189], v[52:55]
	v_mfma_f32_16x16x32_bf16 v[48:51], v[174:177], v[186:189], v[48:51]
	v_mfma_f32_16x16x32_bf16 v[32:35], v[174:177], v[194:197], v[32:35]
	v_mfma_f32_16x16x32_bf16 v[36:39], v[166:169], v[194:197], v[36:39]
	v_mfma_f32_16x16x32_bf16 v[20:23], v[166:169], v[202:205], v[20:23]
	v_mfma_f32_16x16x32_bf16 v[16:19], v[174:177], v[202:205], v[16:19]
	v_mfma_f32_16x16x32_bf16 v[0:3], v[174:177], v[210:213], v[0:3]
	v_mfma_f32_16x16x32_bf16 v[4:7], v[166:169], v[210:213], v[4:7]
	v_mfma_f32_16x16x32_bf16 v[52:55], v[170:173], v[190:193], v[52:55]
	v_mfma_f32_16x16x32_bf16 v[48:51], v[178:181], v[190:193], v[48:51]
	v_mfma_f32_16x16x32_bf16 v[32:35], v[178:181], v[198:201], v[32:35]
	v_mfma_f32_16x16x32_bf16 v[36:39], v[170:173], v[198:201], v[36:39]
	v_mfma_f32_16x16x32_bf16 v[20:23], v[170:173], v[206:209], v[20:23]
	v_mfma_f32_16x16x32_bf16 v[16:19], v[178:181], v[206:209], v[16:19]
	v_mfma_f32_16x16x32_bf16 v[0:3], v[178:181], v[214:217], v[0:3]
	v_mfma_f32_16x16x32_bf16 v[4:7], v[170:173], v[214:217], v[4:7]
	s_setprio 0
	s_barrier
	s_add_i32 s33, s33, 2
	s_add_u32 s36, s36, 0x100
	s_addc_u32 s37, s37, 0
	s_add_u32 s21, s21, 0x100
	s_addc_u32 s23, s23, 0
	s_cmp_gt_u32 s33, 5
	s_cbranch_scc0 .LBB0_1602
	s_and_b64 vcc, exec, s[18:19]
	s_cbranch_vccz .LBB0_1605
	s_barrier

; #define PG8_STAGE(bufoff, gbase, voff) do { _Pragma("unroll") for (int _i = 0; _i < 2; ++_i) \
;         __builtin_amdgcn_global_load_lds((const unsigned*)((const char*)(gbase) + (voff)[_i]), (LAS unsigned*)(lds + (bufoff) + ldsw + _i * 8192), 16, 0, 0); } while (0)
; #define PG8_LDA(dst, b, h) do { _Pragma("unroll") for (int m = 0; m < 4; ++m) _Pragma("unroll") for (int k = 0; k < 2; ++k) dst[m][k] = *(const LAS bf16x8*)(lds + PG8_SA(b, h) + aoff + m * 2048 + k * 1024); } while (0)
; #define PG8_LDB(dst, b, h) do { _Pragma("unroll") for (int n = 0; n < 2; ++n) _Pragma("unroll") for (int k = 0; k < 2; ++k) dst[n][k] = *(const LAS bf16x8*)(lds + PG8_SB(b, h) + boff + n * 2048 + k * 1024); } while (0)
; #define PG8_MMA(ai, bj, At, Bt) do { __builtin_amdgcn_s_setprio(1); _Pragma("unroll") for (int m = 0; m < 4; ++m) _Pragma("unroll") for (int n = 0; n < 2; ++n) _Pragma("unroll") for (int k = 0; k < 2; ++k) \
;         acc[ai][bj][m][n] = __builtin_amdgcn_mfma_f32_16x16x32_bf16(Bt[n][k], At[m][k], acc[ai][bj][m][n], 0, 0, 0); __builtin_amdgcn_s_setprio(0); } while (0)
; #define PG8_BAR __builtin_amdgcn_s_barrier()
; template <class Epi, bool ALIGN_EPI = PG8_ALIGN>
; __device__ __forceinline__ void gemm_phase(LAS unsigned char* lds, const Gemm g, const StaticOrder S, const Epi E) {
;     ...
;         const bool has_next = S.next(ui + 1, nxt);
;         const char* nA = has_next ? (const char*)g.A + (size_t)nxt.pm * tstepA : cA; const char* nB = has_next ? (const char*)g.Bt + (size_t)nxt.pn * tstepB : cB;
;         for (int t = 0; t < nt; t += 2) {
;             const bool last = (t == nt - 2);
;             const char* a1 = cA + (size_t)(t + 1) * kstep;
;             const char* a2 = last ? nA : cA + (size_t)(t + 2) * kstep; const char* b2 = last ? nB : cB + (size_t)(t + 2) * kstep;
;             const char* a3 = a2 + kstep; const char* b3 = b2 + kstep;
;             PG8_LDB(B0, 0, 0); PG8_LDB(B1, 0, 1); PG8_SCHED; PG8_LDA(At, 0, 0); PG8_STAGE(PG8_SA(1, 1), a1 + hstepA, voffA);
;             PG8_WAIT_V(8); PG8_WAIT_L(0); PG8_BAR; PG8_MMA(0, 0, At, B0); PG8_MMA(0, 1, At, B1); PG8_BAR; PG8_SCHED;
;             PG8_LDA(At, 0, 1); PG8_STAGE(PG8_SB(0, 0), b2, voffB); PG8_STAGE(PG8_SB(0, 1), b2 + hstepB, voffB); PG8_STAGE(PG8_SA(0, 0), a2, voffA);
;             PG8_WAIT_V(8); PG8_WAIT_L(0); PG8_BAR; PG8_MMA(1, 0, At, B0); PG8_MMA(1, 1, At, B1); PG8_BAR; PG8_SCHED;
.LBB0_1689:
	ds_read_b128 v[144:147], v155
	ds_read_b128 v[148:151], v155 offset:1024
	ds_read_b128 v[160:163], v155 offset:2048
	ds_read_b128 v[164:167], v155 offset:3072
	ds_read_b128 v[168:171], v156
	ds_read_b128 v[172:175], v156 offset:1024
	ds_read_b128 v[176:179], v156 offset:2048
	ds_read_b128 v[180:183], v156 offset:3072
	s_add_u32 s28, s12, 0xfff80080
	s_addc_u32 s29, s13, -1
	s_cmp_eq_u32 s53, 28
	s_cselect_b32 s37, s14, s29
	s_cselect_b32 s36, s23, s28
	s_cselect_b32 s29, s21, s52
	s_cselect_b32 s28, s50, s51
	v_lshl_add_u64 v[218:219], s[12:13], 0, v[136:137]
	s_add_i32 m0, s34, 0xc000
	ds_read_b128 v[186:189], v157
	ds_read_b128 v[190:193], v157 offset:1024
	ds_read_b128 v[194:197], v157 offset:2048
	ds_read_b128 v[198:201], v157 offset:3072
	ds_read_b128 v[202:205], v157 offset:4096
	ds_read_b128 v[206:209], v157 offset:5120
	ds_read_b128 v[210:213], v157 offset:6144
	ds_read_b128 v[214:217], v157 offset:7168
	global_load_lds_dwordx4 v[218:219], off
	v_lshl_add_u64 v[218:219], s[12:13], 0, v[138:139]
	s_add_i32 m0, s34, 0xe000
	s_nop 0
	global_load_lds_dwordx4 v[218:219], off
	s_waitcnt vmcnt(8)
	s_waitcnt lgkmcnt(0)
	s_barrier
	s_setprio 1
	s_waitcnt lgkmcnt(0)
	v_mfma_f32_16x16x32_bf16 v[124:127], v[144:147], v[186:189], v[124:127]
	v_mfma_f32_16x16x32_bf16 v[120:123], v[160:163], v[186:189], v[120:123]
	v_mfma_f32_16x16x32_bf16 v[104:107], v[160:163], v[194:197], v[104:107]
	v_mfma_f32_16x16x32_bf16 v[108:111], v[144:147], v[194:197], v[108:111]
	v_mfma_f32_16x16x32_bf16 v[92:95], v[144:147], v[202:205], v[92:95]
	v_mfma_f32_16x16x32_bf16 v[88:91], v[160:163], v[202:205], v[88:91]
	v_mfma_f32_16x16x32_bf16 v[72:75], v[160:163], v[210:213], v[72:75]
	v_mfma_f32_16x16x32_bf16 v[76:79], v[144:147], v[210:213], v[76:79]
	v_mfma_f32_16x16x32_bf16 v[124:127], v[148:151], v[190:193], v[124:127]
	v_mfma_f32_16x16x32_bf16 v[120:123], v[164:167], v[190:193], v[120:123]
	v_mfma_f32_16x16x32_bf16 v[104:107], v[164:167], v[198:201], v[104:107]
	v_mfma_f32_16x16x32_bf16 v[108:111], v[148:151], v[198:201], v[108:111]
	v_mfma_f32_16x16x32_bf16 v[92:95], v[148:151], v[206:209], v[92:95]
	v_mfma_f32_16x16x32_bf16 v[88:91], v[164:167], v[206:209], v[88:91]
	v_mfma_f32_16x16x32_bf16 v[72:75], v[164:167], v[214:217], v[72:75]
	v_mfma_f32_16x16x32_bf16 v[76:79], v[148:151], v[214:217], v[76:79]
	s_setprio 0
	s_setprio 1
	v_mfma_f32_16x16x32_bf16 v[116:119], v[168:171], v[186:189], v[116:119]
	v_mfma_f32_16x16x32_bf16 v[112:115], v[176:179], v[186:189], v[112:115]
	v_mfma_f32_16x16x32_bf16 v[96:99], v[176:179], v[194:197], v[96:99]
	v_mfma_f32_16x16x32_bf16 v[100:103], v[168:171], v[194:197], v[100:103]
	v_mfma_f32_16x16x32_bf16 v[84:87], v[168:171], v[202:205], v[84:87]
	v_mfma_f32_16x16x32_bf16 v[80:83], v[176:179], v[202:205], v[80:83]
	v_mfma_f32_16x16x32_bf16 v[64:67], v[176:179], v[210:213], v[64:67]
	v_mfma_f32_16x16x32_bf16 v[68:71], v[168:171], v[210:213], v[68:71]
	v_mfma_f32_16x16x32_bf16 v[116:119], v[172:175], v[190:193], v[116:119]
	v_mfma_f32_16x16x32_bf16 v[112:115], v[180:183], v[190:193], v[112:115]
	v_mfma_f32_16x16x32_bf16 v[96:99], v[180:183], v[198:201], v[96:99]
	v_mfma_f32_16x16x32_bf16 v[100:103], v[172:175], v[198:201], v[100:103]
	v_mfma_f32_16x16x32_bf16 v[84:87], v[172:175], v[206:209], v[84:87]
	v_mfma_f32_16x16x32_bf16 v[80:83], v[180:183], v[206:209], v[80:83]
	v_mfma_f32_16x16x32_bf16 v[64:67], v[180:183], v[214:217], v[64:67]
	v_mfma_f32_16x16x32_bf16 v[68:71], v[172:175], v[214:217], v[68:71]
	s_setprio 0
	s_barrier
	s_add_i32 s54, s46, s16
	v_lshl_add_u64 v[218:219], s[28:29], 0, v[132:133]
	s_mov_b32 m0, s54
	ds_read_b128 v[186:189], v157 offset:16384
	ds_read_b128 v[190:193], v157 offset:17408
	ds_read_b128 v[194:197], v157 offset:18432
	ds_read_b128 v[198:201], v157 offset:19456
	ds_read_b128 v[202:205], v157 offset:20480
	ds_read_b128 v[206:209], v157 offset:21504
	ds_read_b128 v[210:213], v157 offset:22528
	ds_read_b128 v[214:217], v157 offset:23552
	global_load_lds_dwordx4 v[218:219], off
	s_add_i32 m0, s54, 0x2000
	s_add_u32 s54, s28, 0x80000
	v_lshl_add_u64 v[220:221], s[28:29], 0, v[128:129]
	s_addc_u32 s55, s29, 0
	s_add_i32 s56, s47, s16
	global_load_lds_dwordx4 v[220:221], off
	v_lshl_add_u64 v[222:223], s[54:55], 0, v[132:133]
	s_mov_b32 m0, s56
	v_lshl_add_u64 v[224:225], s[36:37], 0, v[130:131]
	global_load_lds_dwordx4 v[222:223], off
	v_lshl_add_u64 v[222:223], s[54:55], 0, v[128:129]
	s_add_i32 m0, s56, 0x2000
	s_nop 0
	global_load_lds_dwordx4 v[222:223], off
	v_lshl_add_u64 v[222:223], s[36:37], 0, v[134:135]
	s_mov_b32 m0, s34
	s_nop 0
	global_load_lds_dwordx4 v[222:223], off
	s_mov_b32 m0, s35
	s_nop 0
	global_load_lds_dwordx4 v[224:225], off
	s_waitcnt vmcnt(8)
	s_waitcnt lgkmcnt(0)
	s_barrier
; #define PG8_STAGE(bufoff, gbase, voff) do { _Pragma("unroll") for (int _i = 0; _i < 2; ++_i) \
;         __builtin_amdgcn_global_load_lds((const unsigned*)((const char*)(gbase) + (voff)[_i]), (LAS unsigned*)(lds + (bufoff) + ldsw + _i * 8192), 16, 0, 0); } while (0)
; #define PG8_LDA(dst, b, h) do { _Pragma("unroll") for (int m = 0; m < 4; ++m) _Pragma("unroll") for (int k = 0; k < 2; ++k) dst[m][k] = *(const LAS bf16x8*)(lds + PG8_SA(b, h) + aoff + m * 2048 + k * 1024); } while (0)
; #define PG8_LDB(dst, b, h) do { _Pragma("unroll") for (int n = 0; n < 2; ++n) _Pragma("unroll") for (int k = 0; k < 2; ++k) dst[n][k] = *(const LAS bf16x8*)(lds + PG8_SB(b, h) + boff + n * 2048 + k * 1024); } while (0)
; #define PG8_MMA(ai, bj, At, Bt) do { __builtin_amdgcn_s_setprio(1); _Pragma("unroll") for (int m = 0; m < 4; ++m) _Pragma("unroll") for (int n = 0; n < 2; ++n) _Pragma("unroll") for (int k = 0; k < 2; ++k) \
;         acc[ai][bj][m][n] = __builtin_amdgcn_mfma_f32_16x16x32_bf16(Bt[n][k], At[m][k], acc[ai][bj][m][n], 0, 0, 0); __builtin_amdgcn_s_setprio(0); } while (0)
; #define PG8_WAIT_V(n) asm volatile("s_waitcnt vmcnt(" #n ")" ::: "memory")
; #define PG8_WAIT_L(n) asm volatile("s_waitcnt lgkmcnt(" #n ")" ::: "memory")
; #define PG8_BAR __builtin_amdgcn_s_barrier()
; #define PG8_SCHED __builtin_amdgcn_sched_barrier(0)
; template <class Epi, bool ALIGN_EPI = PG8_ALIGN>
; __device__ __forceinline__ void gemm_phase(LAS unsigned char* lds, const Gemm g, const StaticOrder S, const Epi E) {
;     ...
;             PG8_WAIT_V(8); PG8_WAIT_L(0); PG8_BAR; PG8_MMA(1, 0, At, B0); PG8_MMA(1, 1, At, B1); PG8_BAR; PG8_SCHED;
;             PG8_LDB(B0, 1, 0); PG8_LDB(B1, 1, 1); PG8_SCHED; PG8_LDA(At, 1, 0); PG8_STAGE(PG8_SA(0, 1), a2 + hstepA, voffA);
;             PG8_WAIT_V(8); PG8_WAIT_L(0); PG8_BAR; PG8_MMA(0, 0, At, B0); PG8_MMA(0, 1, At, B1); PG8_BAR; PG8_SCHED;
	s_setprio 1
	s_waitcnt lgkmcnt(0)
	v_mfma_f32_16x16x32_bf16 v[60:63], v[144:147], v[186:189], v[60:63]
	v_mfma_f32_16x16x32_bf16 v[56:59], v[160:163], v[186:189], v[56:59]
	v_mfma_f32_16x16x32_bf16 v[40:43], v[160:163], v[194:197], v[40:43]
	v_mfma_f32_16x16x32_bf16 v[44:47], v[144:147], v[194:197], v[44:47]
	v_mfma_f32_16x16x32_bf16 v[28:31], v[144:147], v[202:205], v[28:31]
	v_mfma_f32_16x16x32_bf16 v[24:27], v[160:163], v[202:205], v[24:27]
	v_mfma_f32_16x16x32_bf16 v[8:11], v[160:163], v[210:213], v[8:11]
	v_mfma_f32_16x16x32_bf16 v[12:15], v[144:147], v[210:213], v[12:15]
	v_mfma_f32_16x16x32_bf16 v[60:63], v[148:151], v[190:193], v[60:63]
	v_mfma_f32_16x16x32_bf16 v[56:59], v[164:167], v[190:193], v[56:59]
	v_mfma_f32_16x16x32_bf16 v[40:43], v[164:167], v[198:201], v[40:43]
	v_mfma_f32_16x16x32_bf16 v[44:47], v[148:151], v[198:201], v[44:47]
	v_mfma_f32_16x16x32_bf16 v[28:31], v[148:151], v[206:209], v[28:31]
	v_mfma_f32_16x16x32_bf16 v[24:27], v[164:167], v[206:209], v[24:27]
	v_mfma_f32_16x16x32_bf16 v[8:11], v[164:167], v[214:217], v[8:11]
	v_mfma_f32_16x16x32_bf16 v[12:15], v[148:151], v[214:217], v[12:15]
	s_setprio 0
	s_setprio 1
	v_mfma_f32_16x16x32_bf16 v[52:55], v[168:171], v[186:189], v[52:55]
	v_mfma_f32_16x16x32_bf16 v[48:51], v[176:179], v[186:189], v[48:51]
	v_mfma_f32_16x16x32_bf16 v[32:35], v[176:179], v[194:197], v[32:35]
	v_mfma_f32_16x16x32_bf16 v[36:39], v[168:171], v[194:197], v[36:39]
	v_mfma_f32_16x16x32_bf16 v[20:23], v[168:171], v[202:205], v[20:23]
	v_mfma_f32_16x16x32_bf16 v[16:19], v[176:179], v[202:205], v[16:19]
	v_mfma_f32_16x16x32_bf16 v[0:3], v[176:179], v[210:213], v[0:3]
	v_mfma_f32_16x16x32_bf16 v[4:7], v[168:171], v[210:213], v[4:7]
	v_mfma_f32_16x16x32_bf16 v[52:55], v[172:175], v[190:193], v[52:55]
	v_mfma_f32_16x16x32_bf16 v[48:51], v[180:183], v[190:193], v[48:51]
	v_mfma_f32_16x16x32_bf16 v[32:35], v[180:183], v[198:201], v[32:35]
	v_mfma_f32_16x16x32_bf16 v[36:39], v[172:175], v[198:201], v[36:39]
	v_mfma_f32_16x16x32_bf16 v[20:23], v[172:175], v[206:209], v[20:23]
	v_mfma_f32_16x16x32_bf16 v[16:19], v[180:183], v[206:209], v[16:19]
	v_mfma_f32_16x16x32_bf16 v[0:3], v[180:183], v[214:217], v[0:3]
	v_mfma_f32_16x16x32_bf16 v[4:7], v[172:175], v[214:217], v[4:7]
	s_setprio 0
	s_barrier
	s_add_i32 s54, 0, 0x18000
	v_add_u32_e32 v159, s54, v153
	s_add_i32 s55, 0, 0x1c000
	ds_read_b128 v[144:147], v159
	ds_read_b128 v[148:151], v159 offset:1024
	ds_read_b128 v[160:163], v159 offset:2048
	ds_read_b128 v[164:167], v159 offset:3072
	v_add_u32_e32 v159, s55, v153
	ds_read_b128 v[168:171], v159
	ds_read_b128 v[172:175], v159 offset:1024
	ds_read_b128 v[176:179], v159 offset:2048
	ds_read_b128 v[180:183], v159 offset:3072
	s_add_u32 s36, s36, 0x80000
	s_addc_u32 s37, s37, 0
	s_mov_b32 m0, s38
	v_lshl_add_u64 v[226:227], s[36:37], 0, v[134:135]
	ds_read_b128 v[186:189], v157 offset:32768
	ds_read_b128 v[190:193], v157 offset:33792
	ds_read_b128 v[194:197], v157 offset:34816
	ds_read_b128 v[198:201], v157 offset:35840
	ds_read_b128 v[202:205], v157 offset:36864
	ds_read_b128 v[206:209], v157 offset:37888
	ds_read_b128 v[210:213], v157 offset:38912
	ds_read_b128 v[214:217], v157 offset:39936
	global_load_lds_dwordx4 v[226:227], off
	v_lshl_add_u64 v[226:227], s[36:37], 0, v[130:131]
	s_mov_b32 m0, s39
	s_nop 0
	global_load_lds_dwordx4 v[226:227], off
	s_waitcnt vmcnt(8)
	s_waitcnt lgkmcnt(0)
	s_barrier
	s_setprio 1
	s_waitcnt lgkmcnt(0)
	v_mfma_f32_16x16x32_bf16 v[124:127], v[144:147], v[186:189], v[124:127]
	v_mfma_f32_16x16x32_bf16 v[120:123], v[160:163], v[186:189], v[120:123]
	v_mfma_f32_16x16x32_bf16 v[104:107], v[160:163], v[194:197], v[104:107]
	v_mfma_f32_16x16x32_bf16 v[108:111], v[144:147], v[194:197], v[108:111]
	v_mfma_f32_16x16x32_bf16 v[92:95], v[144:147], v[202:205], v[92:95]
	v_mfma_f32_16x16x32_bf16 v[88:91], v[160:163], v[202:205], v[88:91]
	v_mfma_f32_16x16x32_bf16 v[72:75], v[160:163], v[210:213], v[72:75]
	v_mfma_f32_16x16x32_bf16 v[76:79], v[144:147], v[210:213], v[76:79]
	v_mfma_f32_16x16x32_bf16 v[124:127], v[148:151], v[190:193], v[124:127]
	v_mfma_f32_16x16x32_bf16 v[120:123], v[164:167], v[190:193], v[120:123]
	v_mfma_f32_16x16x32_bf16 v[104:107], v[164:167], v[198:201], v[104:107]
	v_mfma_f32_16x16x32_bf16 v[108:111], v[148:151], v[198:201], v[108:111]
	v_mfma_f32_16x16x32_bf16 v[92:95], v[148:151], v[206:209], v[92:95]
	v_mfma_f32_16x16x32_bf16 v[88:91], v[164:167], v[206:209], v[88:91]
	v_mfma_f32_16x16x32_bf16 v[72:75], v[164:167], v[214:217], v[72:75]
	v_mfma_f32_16x16x32_bf16 v[76:79], v[148:151], v[214:217], v[76:79]
	s_setprio 0
	s_setprio 1
	v_mfma_f32_16x16x32_bf16 v[116:119], v[168:171], v[186:189], v[116:119]
	v_mfma_f32_16x16x32_bf16 v[112:115], v[176:179], v[186:189], v[112:115]
	v_mfma_f32_16x16x32_bf16 v[96:99], v[176:179], v[194:197], v[96:99]
	v_mfma_f32_16x16x32_bf16 v[100:103], v[168:171], v[194:197], v[100:103]
	v_mfma_f32_16x16x32_bf16 v[84:87], v[168:171], v[202:205], v[84:87]
	v_mfma_f32_16x16x32_bf16 v[80:83], v[176:179], v[202:205], v[80:83]
	v_mfma_f32_16x16x32_bf16 v[64:67], v[176:179], v[210:213], v[64:67]
	v_mfma_f32_16x16x32_bf16 v[68:71], v[168:171], v[210:213], v[68:71]
	v_mfma_f32_16x16x32_bf16 v[116:119], v[172:175], v[190:193], v[116:119]
	v_mfma_f32_16x16x32_bf16 v[112:115], v[180:183], v[190:193], v[112:115]
	v_mfma_f32_16x16x32_bf16 v[96:99], v[180:183], v[198:201], v[96:99]
	v_mfma_f32_16x16x32_bf16 v[100:103], v[172:175], v[198:201], v[100:103]
	v_mfma_f32_16x16x32_bf16 v[84:87], v[172:175], v[206:209], v[84:87]
	v_mfma_f32_16x16x32_bf16 v[80:83], v[180:183], v[206:209], v[80:83]
	v_mfma_f32_16x16x32_bf16 v[64:67], v[180:183], v[214:217], v[64:67]
	v_mfma_f32_16x16x32_bf16 v[68:71], v[172:175], v[214:217], v[68:71]
	s_setprio 0
	s_barrier
; #define PG8_STAGE(bufoff, gbase, voff) do { _Pragma("unroll") for (int _i = 0; _i < 2; ++_i) \
;         __builtin_amdgcn_global_load_lds((const unsigned*)((const char*)(gbase) + (voff)[_i]), (LAS unsigned*)(lds + (bufoff) + ldsw + _i * 8192), 16, 0, 0); } while (0)
; #define PG8_LDA(dst, b, h) do { _Pragma("unroll") for (int m = 0; m < 4; ++m) _Pragma("unroll") for (int k = 0; k < 2; ++k) dst[m][k] = *(const LAS bf16x8*)(lds + PG8_SA(b, h) + aoff + m * 2048 + k * 1024); } while (0)
; #define PG8_MMA(ai, bj, At, Bt) do { __builtin_amdgcn_s_setprio(1); _Pragma("unroll") for (int m = 0; m < 4; ++m) _Pragma("unroll") for (int n = 0; n < 2; ++n) _Pragma("unroll") for (int k = 0; k < 2; ++k) \
;         acc[ai][bj][m][n] = __builtin_amdgcn_mfma_f32_16x16x32_bf16(Bt[n][k], At[m][k], acc[ai][bj][m][n], 0, 0, 0); __builtin_amdgcn_s_setprio(0); } while (0)
; #define PG8_WAIT_V(n) asm volatile("s_waitcnt vmcnt(" #n ")" ::: "memory")
; #define PG8_WAIT_L(n) asm volatile("s_waitcnt lgkmcnt(" #n ")" ::: "memory")
; #define PG8_BAR __builtin_amdgcn_s_barrier()
; #define PG8_SCHED __builtin_amdgcn_sched_barrier(0)
; template <class Epi, bool ALIGN_EPI = PG8_ALIGN>
; __device__ __forceinline__ void gemm_phase(LAS unsigned char* lds, const Gemm g, const StaticOrder S, const Epi E) {
;     ...
;             PG8_LDA(At, 1, 1); PG8_STAGE(PG8_SB(1, 0), b3, voffB); PG8_STAGE(PG8_SB(1, 1), b3 + hstepB, voffB); PG8_STAGE(PG8_SA(1, 0), a3, voffA);
;             PG8_WAIT_V(8); PG8_WAIT_L(0); PG8_BAR; PG8_MMA(1, 0, At, B0); PG8_MMA(1, 1, At, B1); PG8_BAR; PG8_SCHED;
;         }
;         if (ALIGN_EPI) { if (wr == 0) PG8_BAR; }
	s_add_i32 s36, s54, s16
	v_lshl_add_u64 v[218:219], v[218:219], 0, s[10:11]
	s_mov_b32 m0, s36
	ds_read_b128 v[186:189], v157 offset:49152
	ds_read_b128 v[190:193], v157 offset:50176
	ds_read_b128 v[194:197], v157 offset:51200
	ds_read_b128 v[198:201], v157 offset:52224
	ds_read_b128 v[202:205], v157 offset:53248
	ds_read_b128 v[206:209], v157 offset:54272
	ds_read_b128 v[210:213], v157 offset:55296
	ds_read_b128 v[214:217], v157 offset:56320
	global_load_lds_dwordx4 v[218:219], off
	s_add_i32 m0, s36, 0x2000
	s_add_u32 s28, s28, 0x80080
	v_lshl_add_u64 v[218:219], v[220:221], 0, s[10:11]
	s_addc_u32 s29, s29, 0
	s_add_i32 s36, s55, s16
	global_load_lds_dwordx4 v[218:219], off
	v_lshl_add_u64 v[218:219], s[28:29], 0, v[132:133]
	s_mov_b32 m0, s36
	s_nop 0
	global_load_lds_dwordx4 v[218:219], off
	v_lshl_add_u64 v[218:219], s[28:29], 0, v[128:129]
	s_add_i32 m0, s36, 0x2000
	s_nop 0
	global_load_lds_dwordx4 v[218:219], off
	v_lshl_add_u64 v[218:219], v[222:223], 0, s[10:11]
	s_mov_b32 m0, s43
	s_nop 0
	global_load_lds_dwordx4 v[218:219], off
	v_lshl_add_u64 v[218:219], v[224:225], 0, s[10:11]
	s_mov_b32 m0, s44
	s_nop 0
	global_load_lds_dwordx4 v[218:219], off
	s_waitcnt vmcnt(8)
	s_waitcnt lgkmcnt(0)
	s_barrier
	s_setprio 1
	s_waitcnt lgkmcnt(0)
	v_mfma_f32_16x16x32_bf16 v[60:63], v[144:147], v[186:189], v[60:63]
	v_mfma_f32_16x16x32_bf16 v[56:59], v[160:163], v[186:189], v[56:59]
	v_mfma_f32_16x16x32_bf16 v[40:43], v[160:163], v[194:197], v[40:43]
	v_mfma_f32_16x16x32_bf16 v[44:47], v[144:147], v[194:197], v[44:47]
	v_mfma_f32_16x16x32_bf16 v[28:31], v[144:147], v[202:205], v[28:31]
	v_mfma_f32_16x16x32_bf16 v[24:27], v[160:163], v[202:205], v[24:27]
	v_mfma_f32_16x16x32_bf16 v[8:11], v[160:163], v[210:213], v[8:11]
	v_mfma_f32_16x16x32_bf16 v[12:15], v[144:147], v[210:213], v[12:15]
	v_mfma_f32_16x16x32_bf16 v[60:63], v[148:151], v[190:193], v[60:63]
	v_mfma_f32_16x16x32_bf16 v[56:59], v[164:167], v[190:193], v[56:59]
	v_mfma_f32_16x16x32_bf16 v[40:43], v[164:167], v[198:201], v[40:43]
	v_mfma_f32_16x16x32_bf16 v[44:47], v[148:151], v[198:201], v[44:47]
	v_mfma_f32_16x16x32_bf16 v[28:31], v[148:151], v[206:209], v[28:31]
	v_mfma_f32_16x16x32_bf16 v[24:27], v[164:167], v[206:209], v[24:27]
	v_mfma_f32_16x16x32_bf16 v[8:11], v[164:167], v[214:217], v[8:11]
	v_mfma_f32_16x16x32_bf16 v[12:15], v[148:151], v[214:217], v[12:15]
	s_setprio 0
	s_setprio 1
	v_mfma_f32_16x16x32_bf16 v[52:55], v[168:171], v[186:189], v[52:55]
	v_mfma_f32_16x16x32_bf16 v[48:51], v[176:179], v[186:189], v[48:51]
	v_mfma_f32_16x16x32_bf16 v[32:35], v[176:179], v[194:197], v[32:35]
	v_mfma_f32_16x16x32_bf16 v[36:39], v[168:171], v[194:197], v[36:39]
	v_mfma_f32_16x16x32_bf16 v[20:23], v[168:171], v[202:205], v[20:23]
	v_mfma_f32_16x16x32_bf16 v[16:19], v[176:179], v[202:205], v[16:19]
	v_mfma_f32_16x16x32_bf16 v[0:3], v[176:179], v[210:213], v[0:3]
	v_mfma_f32_16x16x32_bf16 v[4:7], v[168:171], v[210:213], v[4:7]
	v_mfma_f32_16x16x32_bf16 v[52:55], v[172:175], v[190:193], v[52:55]
	v_mfma_f32_16x16x32_bf16 v[48:51], v[180:183], v[190:193], v[48:51]
	v_mfma_f32_16x16x32_bf16 v[32:35], v[180:183], v[198:201], v[32:35]
	v_mfma_f32_16x16x32_bf16 v[36:39], v[172:175], v[198:201], v[36:39]
	v_mfma_f32_16x16x32_bf16 v[20:23], v[172:175], v[206:209], v[20:23]
	v_mfma_f32_16x16x32_bf16 v[16:19], v[180:183], v[206:209], v[16:19]
	v_mfma_f32_16x16x32_bf16 v[0:3], v[180:183], v[214:217], v[0:3]
	v_mfma_f32_16x16x32_bf16 v[4:7], v[172:175], v[214:217], v[4:7]
	s_setprio 0
	s_barrier
	s_add_i32 s53, s53, 2
	s_add_u32 s12, s12, 0x100
	s_addc_u32 s13, s13, 0
	s_add_u32 s51, s51, 0x100
	s_addc_u32 s52, s52, 0
	s_cmp_gt_u32 s53, 29
	s_cbranch_scc0 .LBB0_1689
	s_and_b64 vcc, exec, s[18:19]
	s_cbranch_vccz .LBB0_1692
	s_barrier

; #define PG8_STAGE(bufoff, gbase, voff) do { _Pragma("unroll") for (int _i = 0; _i < 2; ++_i) \
;         __builtin_amdgcn_global_load_lds((const unsigned*)((const char*)(gbase) + (voff)[_i]), (LAS unsigned*)(lds + (bufoff) + ldsw + _i * 8192), 16, 0, 0); } while (0)
; #define PG8_LDA(dst, b, h) do { _Pragma("unroll") for (int m = 0; m < 4; ++m) _Pragma("unroll") for (int k = 0; k < 2; ++k) dst[m][k] = *(const LAS bf16x8*)(lds + PG8_SA(b, h) + aoff + m * 2048 + k * 1024); } while (0)
; #define PG8_LDB(dst, b, h) do { _Pragma("unroll") for (int n = 0; n < 2; ++n) _Pragma("unroll") for (int k = 0; k < 2; ++k) dst[n][k] = *(const LAS bf16x8*)(lds + PG8_SB(b, h) + boff + n * 2048 + k * 1024); } while (0)
; #define PG8_MMA(ai, bj, At, Bt) do { __builtin_amdgcn_s_setprio(1); _Pragma("unroll") for (int m = 0; m < 4; ++m) _Pragma("unroll") for (int n = 0; n < 2; ++n) _Pragma("unroll") for (int k = 0; k < 2; ++k) \
;         acc[ai][bj][m][n] = __builtin_amdgcn_mfma_f32_16x16x32_bf16(Bt[n][k], At[m][k], acc[ai][bj][m][n], 0, 0, 0); __builtin_amdgcn_s_setprio(0); } while (0)
; #define PG8_BAR __builtin_amdgcn_s_barrier()
; template <class Epi, bool ALIGN_EPI = PG8_ALIGN>
; __device__ __forceinline__ void gemm_phase(LAS unsigned char* lds, const Gemm g, const StaticOrder S, const Epi E) {
;     ...
;         const bool has_next = S.next(ui + 1, nxt);
;         const char* nA = has_next ? (const char*)g.A + (size_t)nxt.pm * tstepA : cA; const char* nB = has_next ? (const char*)g.Bt + (size_t)nxt.pn * tstepB : cB;
;         for (int t = 0; t < nt; t += 2) {
;             const bool last = (t == nt - 2);
;             const char* a1 = cA + (size_t)(t + 1) * kstep;
;             const char* a2 = last ? nA : cA + (size_t)(t + 2) * kstep; const char* b2 = last ? nB : cB + (size_t)(t + 2) * kstep;
;             const char* a3 = a2 + kstep; const char* b3 = b2 + kstep;
;             PG8_LDB(B0, 0, 0); PG8_LDB(B1, 0, 1); PG8_SCHED; PG8_LDA(At, 0, 0); PG8_STAGE(PG8_SA(1, 1), a1 + hstepA, voffA);
;             PG8_WAIT_V(8); PG8_WAIT_L(0); PG8_BAR; PG8_MMA(0, 0, At, B0); PG8_MMA(0, 1, At, B1); PG8_BAR; PG8_SCHED;
;             PG8_LDA(At, 0, 1); PG8_STAGE(PG8_SB(0, 0), b2, voffB); PG8_STAGE(PG8_SB(0, 1), b2 + hstepB, voffB); PG8_STAGE(PG8_SA(0, 0), a2, voffA);
;             PG8_WAIT_V(8); PG8_WAIT_L(0); PG8_BAR; PG8_MMA(1, 0, At, B0); PG8_MMA(1, 1, At, B1); PG8_BAR; PG8_SCHED;
.LBB0_1772:
	ds_read_b128 v[146:149], v153
	ds_read_b128 v[156:159], v153 offset:1024
	ds_read_b128 v[160:163], v153 offset:2048
	ds_read_b128 v[164:167], v153 offset:3072
	ds_read_b128 v[168:171], v154
	ds_read_b128 v[172:175], v154 offset:1024
	ds_read_b128 v[176:179], v154 offset:2048
	ds_read_b128 v[180:183], v154 offset:3072
	s_add_u32 s26, s24, 0xffea0080
	s_addc_u32 s27, s25, -1
	s_cmpk_eq_i32 s52, 0x54
	s_cselect_b32 s29, s3, s27
	s_cselect_b32 s28, s2, s26
	s_cselect_b32 s27, s23, s51
	s_cselect_b32 s26, s22, s50
	v_lshl_add_u64 v[150:151], s[24:25], 0, v[138:139]
	s_add_i32 m0, s33, 0xc000
	ds_read_b128 v[184:187], v155
	ds_read_b128 v[188:191], v155 offset:1024
	ds_read_b128 v[192:195], v155 offset:2048
	ds_read_b128 v[196:199], v155 offset:3072
	ds_read_b128 v[200:203], v155 offset:4096
	ds_read_b128 v[204:207], v155 offset:5120
	ds_read_b128 v[208:211], v155 offset:6144
	ds_read_b128 v[212:215], v155 offset:7168
	global_load_lds_dwordx4 v[150:151], off
	v_lshl_add_u64 v[150:151], s[24:25], 0, v[140:141]
	s_add_i32 m0, s33, 0xe000
	s_nop 0
	global_load_lds_dwordx4 v[150:151], off
	s_waitcnt vmcnt(8)
	s_waitcnt lgkmcnt(0)
	s_barrier
	s_setprio 1
	s_waitcnt lgkmcnt(0)
	v_mfma_f32_16x16x32_bf16 v[124:127], v[146:149], v[184:187], v[124:127]
	v_mfma_f32_16x16x32_bf16 v[120:123], v[160:163], v[184:187], v[120:123]
	v_mfma_f32_16x16x32_bf16 v[104:107], v[160:163], v[192:195], v[104:107]
	v_mfma_f32_16x16x32_bf16 v[108:111], v[146:149], v[192:195], v[108:111]
	v_mfma_f32_16x16x32_bf16 v[92:95], v[146:149], v[200:203], v[92:95]
	v_mfma_f32_16x16x32_bf16 v[88:91], v[160:163], v[200:203], v[88:91]
	v_mfma_f32_16x16x32_bf16 v[72:75], v[160:163], v[208:211], v[72:75]
	v_mfma_f32_16x16x32_bf16 v[76:79], v[146:149], v[208:211], v[76:79]
	v_mfma_f32_16x16x32_bf16 v[124:127], v[156:159], v[188:191], v[124:127]
	v_mfma_f32_16x16x32_bf16 v[120:123], v[164:167], v[188:191], v[120:123]
	v_mfma_f32_16x16x32_bf16 v[104:107], v[164:167], v[196:199], v[104:107]
	v_mfma_f32_16x16x32_bf16 v[108:111], v[156:159], v[196:199], v[108:111]
	v_mfma_f32_16x16x32_bf16 v[92:95], v[156:159], v[204:207], v[92:95]
	v_mfma_f32_16x16x32_bf16 v[88:91], v[164:167], v[204:207], v[88:91]
	v_mfma_f32_16x16x32_bf16 v[72:75], v[164:167], v[212:215], v[72:75]
	v_mfma_f32_16x16x32_bf16 v[76:79], v[156:159], v[212:215], v[76:79]
	s_setprio 0
	s_setprio 1
	v_mfma_f32_16x16x32_bf16 v[116:119], v[168:171], v[184:187], v[116:119]
	v_mfma_f32_16x16x32_bf16 v[112:115], v[176:179], v[184:187], v[112:115]
	v_mfma_f32_16x16x32_bf16 v[96:99], v[176:179], v[192:195], v[96:99]
	v_mfma_f32_16x16x32_bf16 v[100:103], v[168:171], v[192:195], v[100:103]
	v_mfma_f32_16x16x32_bf16 v[84:87], v[168:171], v[200:203], v[84:87]
	v_mfma_f32_16x16x32_bf16 v[80:83], v[176:179], v[200:203], v[80:83]
	v_mfma_f32_16x16x32_bf16 v[64:67], v[176:179], v[208:211], v[64:67]
	v_mfma_f32_16x16x32_bf16 v[68:71], v[168:171], v[208:211], v[68:71]
	v_mfma_f32_16x16x32_bf16 v[116:119], v[172:175], v[188:191], v[116:119]
	v_mfma_f32_16x16x32_bf16 v[112:115], v[180:183], v[188:191], v[112:115]
	v_mfma_f32_16x16x32_bf16 v[96:99], v[180:183], v[196:199], v[96:99]
	v_mfma_f32_16x16x32_bf16 v[100:103], v[172:175], v[196:199], v[100:103]
	v_mfma_f32_16x16x32_bf16 v[84:87], v[172:175], v[204:207], v[84:87]
	v_mfma_f32_16x16x32_bf16 v[80:83], v[180:183], v[204:207], v[80:83]
	v_mfma_f32_16x16x32_bf16 v[64:67], v[180:183], v[212:215], v[64:67]
	v_mfma_f32_16x16x32_bf16 v[68:71], v[172:175], v[212:215], v[68:71]
	s_setprio 0
	s_barrier
	s_add_i32 s53, s41, s17
	v_lshl_add_u64 v[150:151], s[26:27], 0, v[130:131]
	s_mov_b32 m0, s53
	ds_read_b128 v[184:187], v155 offset:16384
	ds_read_b128 v[188:191], v155 offset:17408
	ds_read_b128 v[192:195], v155 offset:18432
	ds_read_b128 v[196:199], v155 offset:19456
	ds_read_b128 v[200:203], v155 offset:20480
	ds_read_b128 v[204:207], v155 offset:21504
	ds_read_b128 v[208:211], v155 offset:22528
	ds_read_b128 v[212:215], v155 offset:23552
	global_load_lds_dwordx4 v[150:151], off
	s_add_i32 m0, s53, 0x2000
	s_add_u32 s54, s26, 0x160000
	v_lshl_add_u64 v[216:217], s[26:27], 0, v[134:135]
	s_addc_u32 s55, s27, 0
	s_add_i32 s53, s42, s17
	global_load_lds_dwordx4 v[216:217], off
	v_lshl_add_u64 v[218:219], s[54:55], 0, v[130:131]
	s_mov_b32 m0, s53
	v_lshl_add_u64 v[220:221], s[28:29], 0, v[132:133]
	global_load_lds_dwordx4 v[218:219], off
	v_lshl_add_u64 v[218:219], s[54:55], 0, v[134:135]
	s_add_i32 m0, s53, 0x2000
	s_nop 0
	global_load_lds_dwordx4 v[218:219], off
	v_lshl_add_u64 v[218:219], s[28:29], 0, v[128:129]
	s_mov_b32 m0, s33
	s_nop 0
	global_load_lds_dwordx4 v[218:219], off
	s_mov_b32 m0, s34
	s_nop 0
	global_load_lds_dwordx4 v[220:221], off
	s_waitcnt vmcnt(8)
	s_waitcnt lgkmcnt(0)
	s_barrier
; #define PG8_STAGE(bufoff, gbase, voff) do { _Pragma("unroll") for (int _i = 0; _i < 2; ++_i) \
;         __builtin_amdgcn_global_load_lds((const unsigned*)((const char*)(gbase) + (voff)[_i]), (LAS unsigned*)(lds + (bufoff) + ldsw + _i * 8192), 16, 0, 0); } while (0)
; #define PG8_LDA(dst, b, h) do { _Pragma("unroll") for (int m = 0; m < 4; ++m) _Pragma("unroll") for (int k = 0; k < 2; ++k) dst[m][k] = *(const LAS bf16x8*)(lds + PG8_SA(b, h) + aoff + m * 2048 + k * 1024); } while (0)
; #define PG8_LDB(dst, b, h) do { _Pragma("unroll") for (int n = 0; n < 2; ++n) _Pragma("unroll") for (int k = 0; k < 2; ++k) dst[n][k] = *(const LAS bf16x8*)(lds + PG8_SB(b, h) + boff + n * 2048 + k * 1024); } while (0)
; #define PG8_MMA(ai, bj, At, Bt) do { __builtin_amdgcn_s_setprio(1); _Pragma("unroll") for (int m = 0; m < 4; ++m) _Pragma("unroll") for (int n = 0; n < 2; ++n) _Pragma("unroll") for (int k = 0; k < 2; ++k) \
;         acc[ai][bj][m][n] = __builtin_amdgcn_mfma_f32_16x16x32_bf16(Bt[n][k], At[m][k], acc[ai][bj][m][n], 0, 0, 0); __builtin_amdgcn_s_setprio(0); } while (0)
; #define PG8_WAIT_V(n) asm volatile("s_waitcnt vmcnt(" #n ")" ::: "memory")
; #define PG8_WAIT_L(n) asm volatile("s_waitcnt lgkmcnt(" #n ")" ::: "memory")
; #define PG8_BAR __builtin_amdgcn_s_barrier()
; #define PG8_SCHED __builtin_amdgcn_sched_barrier(0)
; template <class Epi, bool ALIGN_EPI = PG8_ALIGN>
; __device__ __forceinline__ void gemm_phase(LAS unsigned char* lds, const Gemm g, const StaticOrder S, const Epi E) {
;     ...
;             PG8_WAIT_V(8); PG8_WAIT_L(0); PG8_BAR; PG8_MMA(1, 0, At, B0); PG8_MMA(1, 1, At, B1); PG8_BAR; PG8_SCHED;
;             PG8_LDB(B0, 1, 0); PG8_LDB(B1, 1, 1); PG8_SCHED; PG8_LDA(At, 1, 0); PG8_STAGE(PG8_SA(0, 1), a2 + hstepA, voffA);
;             PG8_WAIT_V(8); PG8_WAIT_L(0); PG8_BAR; PG8_MMA(0, 0, At, B0); PG8_MMA(0, 1, At, B1); PG8_BAR; PG8_SCHED;
	s_setprio 1
	s_waitcnt lgkmcnt(0)
	v_mfma_f32_16x16x32_bf16 v[60:63], v[146:149], v[184:187], v[60:63]
	v_mfma_f32_16x16x32_bf16 v[56:59], v[160:163], v[184:187], v[56:59]
	v_mfma_f32_16x16x32_bf16 v[40:43], v[160:163], v[192:195], v[40:43]
	v_mfma_f32_16x16x32_bf16 v[44:47], v[146:149], v[192:195], v[44:47]
	v_mfma_f32_16x16x32_bf16 v[28:31], v[146:149], v[200:203], v[28:31]
	v_mfma_f32_16x16x32_bf16 v[24:27], v[160:163], v[200:203], v[24:27]
	v_mfma_f32_16x16x32_bf16 v[8:11], v[160:163], v[208:211], v[8:11]
	v_mfma_f32_16x16x32_bf16 v[12:15], v[146:149], v[208:211], v[12:15]
	v_mfma_f32_16x16x32_bf16 v[60:63], v[156:159], v[188:191], v[60:63]
	v_mfma_f32_16x16x32_bf16 v[56:59], v[164:167], v[188:191], v[56:59]
	v_mfma_f32_16x16x32_bf16 v[40:43], v[164:167], v[196:199], v[40:43]
	v_mfma_f32_16x16x32_bf16 v[44:47], v[156:159], v[196:199], v[44:47]
	v_mfma_f32_16x16x32_bf16 v[28:31], v[156:159], v[204:207], v[28:31]
	v_mfma_f32_16x16x32_bf16 v[24:27], v[164:167], v[204:207], v[24:27]
	v_mfma_f32_16x16x32_bf16 v[8:11], v[164:167], v[212:215], v[8:11]
	v_mfma_f32_16x16x32_bf16 v[12:15], v[156:159], v[212:215], v[12:15]
	s_setprio 0
	s_setprio 1
	v_mfma_f32_16x16x32_bf16 v[52:55], v[168:171], v[184:187], v[52:55]
	v_mfma_f32_16x16x32_bf16 v[48:51], v[176:179], v[184:187], v[48:51]
	v_mfma_f32_16x16x32_bf16 v[32:35], v[176:179], v[192:195], v[32:35]
	v_mfma_f32_16x16x32_bf16 v[36:39], v[168:171], v[192:195], v[36:39]
	v_mfma_f32_16x16x32_bf16 v[20:23], v[168:171], v[200:203], v[20:23]
	v_mfma_f32_16x16x32_bf16 v[16:19], v[176:179], v[200:203], v[16:19]
	v_mfma_f32_16x16x32_bf16 v[0:3], v[176:179], v[208:211], v[0:3]
	v_mfma_f32_16x16x32_bf16 v[4:7], v[168:171], v[208:211], v[4:7]
	v_mfma_f32_16x16x32_bf16 v[52:55], v[172:175], v[188:191], v[52:55]
	v_mfma_f32_16x16x32_bf16 v[48:51], v[180:183], v[188:191], v[48:51]
	v_mfma_f32_16x16x32_bf16 v[32:35], v[180:183], v[196:199], v[32:35]
	v_mfma_f32_16x16x32_bf16 v[36:39], v[172:175], v[196:199], v[36:39]
	v_mfma_f32_16x16x32_bf16 v[20:23], v[172:175], v[204:207], v[20:23]
	v_mfma_f32_16x16x32_bf16 v[16:19], v[180:183], v[204:207], v[16:19]
	v_mfma_f32_16x16x32_bf16 v[0:3], v[180:183], v[212:215], v[0:3]
	v_mfma_f32_16x16x32_bf16 v[4:7], v[172:175], v[212:215], v[4:7]
	s_setprio 0
	s_barrier
	s_add_i32 s53, 0, 0x18000
	s_add_i32 s54, 0, 0x1c000
	v_add_u32_e32 v164, s53, v152
	v_add_u32_e32 v180, s54, v152
	ds_read_b128 v[146:149], v164
	ds_read_b128 v[156:159], v164 offset:1024
	ds_read_b128 v[160:163], v164 offset:2048
	ds_read_b128 v[164:167], v164 offset:3072
	ds_read_b128 v[168:171], v180
	ds_read_b128 v[172:175], v180 offset:1024
	ds_read_b128 v[176:179], v180 offset:2048
	ds_read_b128 v[180:183], v180 offset:3072
	s_add_u32 s28, s28, 0x160000
	s_addc_u32 s29, s29, 0
	s_mov_b32 m0, s35
	v_lshl_add_u64 v[222:223], s[28:29], 0, v[128:129]
	ds_read_b128 v[184:187], v155 offset:32768
	ds_read_b128 v[188:191], v155 offset:33792
	ds_read_b128 v[192:195], v155 offset:34816
	ds_read_b128 v[196:199], v155 offset:35840
	ds_read_b128 v[200:203], v155 offset:36864
	ds_read_b128 v[204:207], v155 offset:37888
	ds_read_b128 v[208:211], v155 offset:38912
	ds_read_b128 v[212:215], v155 offset:39936
	global_load_lds_dwordx4 v[222:223], off
	v_lshl_add_u64 v[222:223], s[28:29], 0, v[132:133]
	s_mov_b32 m0, s36
	s_nop 0
	global_load_lds_dwordx4 v[222:223], off
	s_waitcnt vmcnt(8)
	s_waitcnt lgkmcnt(0)
	s_barrier
	s_setprio 1
	s_waitcnt lgkmcnt(0)
	v_mfma_f32_16x16x32_bf16 v[124:127], v[146:149], v[184:187], v[124:127]
	v_mfma_f32_16x16x32_bf16 v[120:123], v[160:163], v[184:187], v[120:123]
	v_mfma_f32_16x16x32_bf16 v[104:107], v[160:163], v[192:195], v[104:107]
	v_mfma_f32_16x16x32_bf16 v[108:111], v[146:149], v[192:195], v[108:111]
	v_mfma_f32_16x16x32_bf16 v[92:95], v[146:149], v[200:203], v[92:95]
	v_mfma_f32_16x16x32_bf16 v[88:91], v[160:163], v[200:203], v[88:91]
	v_mfma_f32_16x16x32_bf16 v[72:75], v[160:163], v[208:211], v[72:75]
	v_mfma_f32_16x16x32_bf16 v[76:79], v[146:149], v[208:211], v[76:79]
	v_mfma_f32_16x16x32_bf16 v[124:127], v[156:159], v[188:191], v[124:127]
	v_mfma_f32_16x16x32_bf16 v[120:123], v[164:167], v[188:191], v[120:123]
	v_mfma_f32_16x16x32_bf16 v[104:107], v[164:167], v[196:199], v[104:107]
	v_mfma_f32_16x16x32_bf16 v[108:111], v[156:159], v[196:199], v[108:111]
	v_mfma_f32_16x16x32_bf16 v[92:95], v[156:159], v[204:207], v[92:95]
	v_mfma_f32_16x16x32_bf16 v[88:91], v[164:167], v[204:207], v[88:91]
	v_mfma_f32_16x16x32_bf16 v[72:75], v[164:167], v[212:215], v[72:75]
	v_mfma_f32_16x16x32_bf16 v[76:79], v[156:159], v[212:215], v[76:79]
	s_setprio 0
	s_setprio 1
	v_mfma_f32_16x16x32_bf16 v[116:119], v[168:171], v[184:187], v[116:119]
	v_mfma_f32_16x16x32_bf16 v[112:115], v[176:179], v[184:187], v[112:115]
	v_mfma_f32_16x16x32_bf16 v[96:99], v[176:179], v[192:195], v[96:99]
	v_mfma_f32_16x16x32_bf16 v[100:103], v[168:171], v[192:195], v[100:103]
	v_mfma_f32_16x16x32_bf16 v[84:87], v[168:171], v[200:203], v[84:87]
	v_mfma_f32_16x16x32_bf16 v[80:83], v[176:179], v[200:203], v[80:83]
	v_mfma_f32_16x16x32_bf16 v[64:67], v[176:179], v[208:211], v[64:67]
	v_mfma_f32_16x16x32_bf16 v[68:71], v[168:171], v[208:211], v[68:71]
	v_mfma_f32_16x16x32_bf16 v[116:119], v[172:175], v[188:191], v[116:119]
	v_mfma_f32_16x16x32_bf16 v[112:115], v[180:183], v[188:191], v[112:115]
	v_mfma_f32_16x16x32_bf16 v[96:99], v[180:183], v[196:199], v[96:99]
	v_mfma_f32_16x16x32_bf16 v[100:103], v[172:175], v[196:199], v[100:103]
	v_mfma_f32_16x16x32_bf16 v[84:87], v[172:175], v[204:207], v[84:87]
	v_mfma_f32_16x16x32_bf16 v[80:83], v[180:183], v[204:207], v[80:83]
	v_mfma_f32_16x16x32_bf16 v[64:67], v[180:183], v[212:215], v[64:67]
	v_mfma_f32_16x16x32_bf16 v[68:71], v[172:175], v[212:215], v[68:71]
	s_setprio 0
	s_barrier
; #define PG8_STAGE(bufoff, gbase, voff) do { _Pragma("unroll") for (int _i = 0; _i < 2; ++_i) \
;         __builtin_amdgcn_global_load_lds((const unsigned*)((const char*)(gbase) + (voff)[_i]), (LAS unsigned*)(lds + (bufoff) + ldsw + _i * 8192), 16, 0, 0); } while (0)
; #define PG8_LDA(dst, b, h) do { _Pragma("unroll") for (int m = 0; m < 4; ++m) _Pragma("unroll") for (int k = 0; k < 2; ++k) dst[m][k] = *(const LAS bf16x8*)(lds + PG8_SA(b, h) + aoff + m * 2048 + k * 1024); } while (0)
; #define PG8_MMA(ai, bj, At, Bt) do { __builtin_amdgcn_s_setprio(1); _Pragma("unroll") for (int m = 0; m < 4; ++m) _Pragma("unroll") for (int n = 0; n < 2; ++n) _Pragma("unroll") for (int k = 0; k < 2; ++k) \
;         acc[ai][bj][m][n] = __builtin_amdgcn_mfma_f32_16x16x32_bf16(Bt[n][k], At[m][k], acc[ai][bj][m][n], 0, 0, 0); __builtin_amdgcn_s_setprio(0); } while (0)
; #define PG8_WAIT_V(n) asm volatile("s_waitcnt vmcnt(" #n ")" ::: "memory")
; #define PG8_WAIT_L(n) asm volatile("s_waitcnt lgkmcnt(" #n ")" ::: "memory")
; #define PG8_BAR __builtin_amdgcn_s_barrier()
; #define PG8_SCHED __builtin_amdgcn_sched_barrier(0)
; template <class Epi, bool ALIGN_EPI = PG8_ALIGN>
; __device__ __forceinline__ void gemm_phase(LAS unsigned char* lds, const Gemm g, const StaticOrder S, const Epi E) {
;     ...
;             PG8_LDA(At, 1, 1); PG8_STAGE(PG8_SB(1, 0), b3, voffB); PG8_STAGE(PG8_SB(1, 1), b3 + hstepB, voffB); PG8_STAGE(PG8_SA(1, 0), a3, voffA);
;             PG8_WAIT_V(8); PG8_WAIT_L(0); PG8_BAR; PG8_MMA(1, 0, At, B0); PG8_MMA(1, 1, At, B1); PG8_BAR; PG8_SCHED;
;         }
;         if (ALIGN_EPI) { if (wr == 0) PG8_BAR; }
	s_add_i32 s28, s53, s17
	v_lshl_add_u64 v[150:151], v[150:151], 0, s[8:9]
	s_mov_b32 m0, s28
	ds_read_b128 v[184:187], v155 offset:49152
	ds_read_b128 v[188:191], v155 offset:50176
	ds_read_b128 v[192:195], v155 offset:51200
	ds_read_b128 v[196:199], v155 offset:52224
	ds_read_b128 v[200:203], v155 offset:53248
	ds_read_b128 v[204:207], v155 offset:54272
	ds_read_b128 v[208:211], v155 offset:55296
	ds_read_b128 v[212:215], v155 offset:56320
	global_load_lds_dwordx4 v[150:151], off
	s_add_i32 m0, s28, 0x2000
	s_add_u32 s26, s26, 0x160080
	v_lshl_add_u64 v[150:151], v[216:217], 0, s[8:9]
	s_addc_u32 s27, s27, 0
	s_add_i32 s28, s54, s17
	global_load_lds_dwordx4 v[150:151], off
	v_lshl_add_u64 v[150:151], s[26:27], 0, v[130:131]
	s_mov_b32 m0, s28
	s_nop 0
	global_load_lds_dwordx4 v[150:151], off
	v_lshl_add_u64 v[150:151], s[26:27], 0, v[134:135]
	s_add_i32 m0, s28, 0x2000
	s_nop 0
	global_load_lds_dwordx4 v[150:151], off
	v_lshl_add_u64 v[150:151], v[218:219], 0, s[8:9]
	s_mov_b32 m0, s38
	s_nop 0
	global_load_lds_dwordx4 v[150:151], off
	v_lshl_add_u64 v[150:151], v[220:221], 0, s[8:9]
	s_mov_b32 m0, s39
	s_nop 0
	global_load_lds_dwordx4 v[150:151], off
	s_waitcnt vmcnt(8)
	s_waitcnt lgkmcnt(0)
	s_barrier
	s_setprio 1
	s_waitcnt lgkmcnt(0)
	v_mfma_f32_16x16x32_bf16 v[60:63], v[146:149], v[184:187], v[60:63]
	v_mfma_f32_16x16x32_bf16 v[56:59], v[160:163], v[184:187], v[56:59]
	v_mfma_f32_16x16x32_bf16 v[40:43], v[160:163], v[192:195], v[40:43]
	v_mfma_f32_16x16x32_bf16 v[44:47], v[146:149], v[192:195], v[44:47]
	v_mfma_f32_16x16x32_bf16 v[28:31], v[146:149], v[200:203], v[28:31]
	v_mfma_f32_16x16x32_bf16 v[24:27], v[160:163], v[200:203], v[24:27]
	v_mfma_f32_16x16x32_bf16 v[8:11], v[160:163], v[208:211], v[8:11]
	v_mfma_f32_16x16x32_bf16 v[12:15], v[146:149], v[208:211], v[12:15]
	v_mfma_f32_16x16x32_bf16 v[60:63], v[156:159], v[188:191], v[60:63]
	v_mfma_f32_16x16x32_bf16 v[56:59], v[164:167], v[188:191], v[56:59]
	v_mfma_f32_16x16x32_bf16 v[40:43], v[164:167], v[196:199], v[40:43]
	v_mfma_f32_16x16x32_bf16 v[44:47], v[156:159], v[196:199], v[44:47]
	v_mfma_f32_16x16x32_bf16 v[28:31], v[156:159], v[204:207], v[28:31]
	v_mfma_f32_16x16x32_bf16 v[24:27], v[164:167], v[204:207], v[24:27]
	v_mfma_f32_16x16x32_bf16 v[8:11], v[164:167], v[212:215], v[8:11]
	v_mfma_f32_16x16x32_bf16 v[12:15], v[156:159], v[212:215], v[12:15]
	s_setprio 0
	s_setprio 1
	v_mfma_f32_16x16x32_bf16 v[52:55], v[168:171], v[184:187], v[52:55]
	v_mfma_f32_16x16x32_bf16 v[48:51], v[176:179], v[184:187], v[48:51]
	v_mfma_f32_16x16x32_bf16 v[32:35], v[176:179], v[192:195], v[32:35]
	v_mfma_f32_16x16x32_bf16 v[36:39], v[168:171], v[192:195], v[36:39]
	v_mfma_f32_16x16x32_bf16 v[20:23], v[168:171], v[200:203], v[20:23]
	v_mfma_f32_16x16x32_bf16 v[16:19], v[176:179], v[200:203], v[16:19]
	v_mfma_f32_16x16x32_bf16 v[0:3], v[176:179], v[208:211], v[0:3]
	v_mfma_f32_16x16x32_bf16 v[4:7], v[168:171], v[208:211], v[4:7]
	v_mfma_f32_16x16x32_bf16 v[52:55], v[172:175], v[188:191], v[52:55]
	v_mfma_f32_16x16x32_bf16 v[48:51], v[180:183], v[188:191], v[48:51]
	v_mfma_f32_16x16x32_bf16 v[32:35], v[180:183], v[196:199], v[32:35]
	v_mfma_f32_16x16x32_bf16 v[36:39], v[172:175], v[196:199], v[36:39]
	v_mfma_f32_16x16x32_bf16 v[20:23], v[172:175], v[204:207], v[20:23]
	v_mfma_f32_16x16x32_bf16 v[16:19], v[180:183], v[204:207], v[16:19]
	v_mfma_f32_16x16x32_bf16 v[0:3], v[180:183], v[212:215], v[0:3]
	v_mfma_f32_16x16x32_bf16 v[4:7], v[172:175], v[212:215], v[4:7]
	s_setprio 0
	s_barrier
	s_add_i32 s52, s52, 2
	s_add_u32 s24, s24, 0x100
	s_addc_u32 s25, s25, 0
	s_add_u32 s50, s50, 0x100
	s_addc_u32 s51, s51, 0
	s_cmpk_gt_u32 s52, 0x55
	s_cbranch_scc0 .LBB0_1772
	s_and_b64 vcc, exec, s[10:11]
	s_cbranch_vccz .LBB0_1775
	s_barrier
